# one static s_setprio 1 for waves 4-7 at kernel entry, all per-segment priority flips in the GEMM loops deleted
# speedup vs baseline: 1.0106x; 1.0106x over previous
; #define LAS __attribute__((address_space(3)))
; __global__ void __launch_bounds__(512, 2) fwd_kernel(Args args) {
;     extern __shared__ __attribute__((aligned(16))) unsigned char lds_raw[];
;     LAS unsigned char* lds = (LAS unsigned char*)lds_raw;
;     if (threadIdx.x < 16) ((LAS unsigned*)(lds + 131072))[threadIdx.x] = 0u;
;     __syncthreads();
;     XcdBarrier xbar; xbar.bar = (unsigned*)(args.ws + WS_BAR); xbar.x = 0; xbar.st = (volatile LAS unsigned*)(lds + 131072);
;     for (int ph = args.ph_lo; ph < args.ph_hi; ++ph) {
_Z10fwd_kernel4Args:
	s_load_dwordx2 s[74:75], s[0:1], 0xc8
	v_and_b32_e32 v222, 0x3ff, v0
	s_mov_b64 s[78:79], s[0:1]
	v_cmp_gt_u32_e32 vcc, 16, v222
	s_and_saveexec_b64 s[0:1], vcc
	v_lshl_add_u32 v1, v222, 2, 0
	v_add_u32_e32 v1, 0x20000, v1
	v_mov_b32_e32 v2, 0
	ds_write_b32 v1, v2
	s_or_b64 exec, exec, s[0:1]
	s_waitcnt lgkmcnt(0)
	v_readfirstlane_b32 s98, v222
	s_nop 3
	s_lshr_b32 s98, s98, 8
	s_cmp_eq_u32 s98, 1
	s_cbranch_scc0 .Lprio_done
	s_setprio 1
.Lprio_done:
	s_cmp_ge_i32 s74, s75
	s_barrier
	s_cbranch_scc0 .LBB0_3
	s_getpc_b64 s[98:99]

; #define PG8_STAGE(bufoff, gbase, voff) do { _Pragma("unroll") for (int _i = 0; _i < 2; ++_i) \
;         __builtin_amdgcn_global_load_lds((const unsigned*)((const char*)(gbase) + (voff)[_i]), (LAS unsigned*)(lds + (bufoff) + ldsw + _i * 8192), 16, 0, 0); } while (0)
; #define PG8_LDA(dst, b, h) do { _Pragma("unroll") for (int m = 0; m < 4; ++m) _Pragma("unroll") for (int k = 0; k < 2; ++k) dst[m][k] = *(const LAS bf16x8*)(lds + PG8_SA(b, h) + aoff + m * 2048 + k * 1024); } while (0)
; #define PG8_LDB(dst, b, h) do { _Pragma("unroll") for (int n = 0; n < 2; ++n) _Pragma("unroll") for (int k = 0; k < 2; ++k) dst[n][k] = *(const LAS bf16x8*)(lds + PG8_SB(b, h) + boff + n * 2048 + k * 1024); } while (0)
; #define PG8_MMA(ai, bj, At, Bt) do { __builtin_amdgcn_s_setprio(1); _Pragma("unroll") for (int k = 0; k < 2; ++k) _Pragma("unroll") for (int m = 0; m < 4; ++m) _Pragma("unroll") for (int n = 0; n < 2; ++n) \
;         acc[ai][bj][m][n] = __builtin_amdgcn_mfma_f32_16x16x32_bf16(Bt[n][k], At[m][k], acc[ai][bj][m][n], 0, 0, 0); __builtin_amdgcn_s_setprio(0); } while (0)
; #define PG8_WAIT_V(n) asm volatile("s_waitcnt vmcnt(" #n ")" ::: "memory")
; #define PG8_WAIT_L(n) asm volatile("s_waitcnt lgkmcnt(" #n ")" ::: "memory")
; #define PG8_BAR __builtin_amdgcn_s_barrier()
; #define PG8_SCHED __builtin_amdgcn_sched_barrier(0)
; template <class Epi, bool ALIGN_EPI>
; __device__ __forceinline__ void gemm_phase(LAS unsigned char* lds, const Gemm g, const StaticOrder& S, const Epi& E, const int tid) {
;     ...
;             PG8_LDB(B0, 0, 0); PG8_LDB(B1, 0, 1); PG8_SCHED; PG8_LDA(At, 0, 0); PG8_STAGE(PG8_SA(1, 1), a1 + hA, voffA);
;             PG8_WAIT_V(8); PG8_WAIT_L(0); PG8_BAR; PG8_MMA(0, 0, At, B0); PG8_MMA(0, 1, At, B1); PG8_BAR; PG8_SCHED;
;             PG8_LDA(At, 0, 1); PG8_STAGE(PG8_SB(0, 0), b2, voffB); PG8_STAGE(PG8_SB(0, 1), b2 + hB, voffB); PG8_STAGE(PG8_SA(0, 0), a2, voffA);
;             PG8_WAIT_V(8); PG8_WAIT_L(0); PG8_BAR; PG8_MMA(1, 0, At, B0); PG8_MMA(1, 1, At, B1); PG8_BAR; PG8_SCHED;
.LBB0_234:
	s_andn2_b64 vcc, exec, s[36:37]
	s_waitcnt lgkmcnt(0)
	s_cbranch_vccnz .LBB0_238
	s_add_u32 s12, s46, 0x100
	v_lshl_add_u64 v[128:129], v[128:129], 0, s[92:93]
	s_addc_u32 s13, s47, 0
	s_mov_b32 s46, 0
	s_add_i32 s47, s46, 2
	s_cmp_eq_u32 s60, s46
	s_cselect_b64 vcc, -1, 0
	s_cselect_b32 s71, s15, s13
	s_cselect_b32 s70, s14, s12
	s_add_i32 s46, 0, 0x14000
	v_lshl_add_u64 v[130:131], v[128:129], 0, s[92:93]
	v_add_u32_e32 v142, s33, v218
	v_add_u32_e32 v166, s46, v218
	v_cndmask_b32_e32 v159, v131, v165, vcc
	v_cndmask_b32_e32 v158, v130, v164, vcc
	ds_read_b128 v[130:133], v142
	ds_read_b128 v[134:137], v142 offset:1024
	ds_read_b128 v[138:141], v142 offset:2048
	ds_read_b128 v[142:145], v142 offset:3072
	ds_read_b128 v[146:149], v166
	ds_read_b128 v[150:153], v166 offset:1024
	ds_read_b128 v[154:157], v166 offset:2048
	ds_read_b128 v[186:189], v166 offset:3072
	v_lshl_add_u64 v[166:167], v[128:129], 0, v[160:161]
	s_add_i32 m0, s53, 0xc000
	ds_read_b128 v[190:193], v219
	ds_read_b128 v[194:197], v219 offset:1024
	ds_read_b128 v[198:201], v219 offset:2048
	ds_read_b128 v[202:205], v219 offset:3072
	ds_read_b128 v[206:209], v219 offset:4096
	ds_read_b128 v[210:213], v219 offset:5120
	ds_read_b128 v[240:243], v219 offset:6144
	ds_read_b128 v[244:247], v219 offset:7168
	global_load_lds_dwordx4 v[166:167], off
	v_lshl_add_u64 v[166:167], v[128:129], 0, v[162:163]
	s_add_i32 m0, s53, 0xe000
	s_nop 0
	global_load_lds_dwordx4 v[166:167], off
	s_waitcnt vmcnt(8)
	s_waitcnt lgkmcnt(0)
	s_barrier
	s_waitcnt lgkmcnt(0)
	v_mfma_f32_16x16x32_bf16 v[120:123], v[130:133], v[190:193], 0
	v_mfma_f32_16x16x32_bf16 v[124:127], v[138:141], v[190:193], 0
	v_mfma_f32_16x16x32_bf16 v[108:111], v[130:133], v[198:201], 0
	v_mfma_f32_16x16x32_bf16 v[104:107], v[138:141], v[198:201], 0
	v_mfma_f32_16x16x32_bf16 v[92:95], v[130:133], v[206:209], 0
	v_mfma_f32_16x16x32_bf16 v[88:91], v[138:141], v[206:209], 0
	v_mfma_f32_16x16x32_bf16 v[76:79], v[130:133], v[240:243], 0
	v_mfma_f32_16x16x32_bf16 v[72:75], v[138:141], v[240:243], 0
	v_mfma_f32_16x16x32_bf16 v[120:123], v[134:137], v[194:197], v[120:123]
	v_mfma_f32_16x16x32_bf16 v[124:127], v[142:145], v[194:197], v[124:127]
	v_mfma_f32_16x16x32_bf16 v[108:111], v[134:137], v[202:205], v[108:111]
	v_mfma_f32_16x16x32_bf16 v[104:107], v[142:145], v[202:205], v[104:107]
	v_mfma_f32_16x16x32_bf16 v[92:95], v[134:137], v[210:213], v[92:95]
	v_mfma_f32_16x16x32_bf16 v[88:91], v[142:145], v[210:213], v[88:91]
	v_mfma_f32_16x16x32_bf16 v[76:79], v[134:137], v[244:247], v[76:79]
	v_mfma_f32_16x16x32_bf16 v[72:75], v[142:145], v[244:247], v[72:75]
	v_mfma_f32_16x16x32_bf16 v[116:119], v[146:149], v[190:193], 0
	v_mfma_f32_16x16x32_bf16 v[112:115], v[154:157], v[190:193], 0
	v_mfma_f32_16x16x32_bf16 v[100:103], v[146:149], v[198:201], 0
	v_mfma_f32_16x16x32_bf16 v[96:99], v[154:157], v[198:201], 0
	v_mfma_f32_16x16x32_bf16 v[84:87], v[146:149], v[206:209], 0
	v_mfma_f32_16x16x32_bf16 v[80:83], v[154:157], v[206:209], 0
	v_mfma_f32_16x16x32_bf16 v[68:71], v[146:149], v[240:243], 0
	v_mfma_f32_16x16x32_bf16 v[64:67], v[154:157], v[240:243], 0
	v_mfma_f32_16x16x32_bf16 v[116:119], v[150:153], v[194:197], v[116:119]
	v_mfma_f32_16x16x32_bf16 v[112:115], v[186:189], v[194:197], v[112:115]
	v_mfma_f32_16x16x32_bf16 v[100:103], v[150:153], v[202:205], v[100:103]
	v_mfma_f32_16x16x32_bf16 v[96:99], v[186:189], v[202:205], v[96:99]
	v_mfma_f32_16x16x32_bf16 v[84:87], v[150:153], v[210:213], v[84:87]
	v_mfma_f32_16x16x32_bf16 v[80:83], v[186:189], v[210:213], v[80:83]
	v_mfma_f32_16x16x32_bf16 v[68:71], v[150:153], v[244:247], v[68:71]
	v_mfma_f32_16x16x32_bf16 v[64:67], v[186:189], v[244:247], v[64:67]
	s_barrier
	s_add_i32 s72, s33, s52
	v_lshl_add_u64 v[166:167], s[70:71], 0, v[180:181]
	s_mov_b32 m0, s72
	ds_read_b128 v[190:193], v219 offset:16384
	ds_read_b128 v[194:197], v219 offset:17408
	ds_read_b128 v[198:201], v219 offset:18432
	ds_read_b128 v[202:205], v219 offset:19456
	ds_read_b128 v[206:209], v219 offset:20480
	ds_read_b128 v[210:213], v219 offset:21504
	ds_read_b128 v[240:243], v219 offset:22528
	ds_read_b128 v[244:247], v219 offset:23552
	global_load_lds_dwordx4 v[166:167], off
	s_add_i32 m0, s72, 0x2000
	v_lshl_add_u64 v[214:215], s[70:71], 0, v[184:185]
	s_add_u32 s70, s70, s49
	s_addc_u32 s71, s71, 0
	s_add_i32 s46, s46, s52
	global_load_lds_dwordx4 v[214:215], off
	v_lshl_add_u64 v[220:221], s[70:71], 0, v[180:181]
	s_mov_b32 m0, s46
	v_lshl_add_u64 v[226:227], s[70:71], 0, v[184:185]
	global_load_lds_dwordx4 v[220:221], off
	s_add_i32 m0, s46, 0x2000
	v_lshl_add_u64 v[248:249], v[158:159], 0, v[178:179]
	global_load_lds_dwordx4 v[226:227], off
	s_mov_b32 m0, s53
	v_lshl_add_u64 v[250:251], v[158:159], 0, v[182:183]
	global_load_lds_dwordx4 v[248:249], off
	s_mov_b32 m0, s54
	s_nop 0
	global_load_lds_dwordx4 v[250:251], off
	s_waitcnt vmcnt(8)
	s_waitcnt lgkmcnt(0)
	s_barrier
; #define PG8_STAGE(bufoff, gbase, voff) do { _Pragma("unroll") for (int _i = 0; _i < 2; ++_i) \
;         __builtin_amdgcn_global_load_lds((const unsigned*)((const char*)(gbase) + (voff)[_i]), (LAS unsigned*)(lds + (bufoff) + ldsw + _i * 8192), 16, 0, 0); } while (0)
; #define PG8_LDA(dst, b, h) do { _Pragma("unroll") for (int m = 0; m < 4; ++m) _Pragma("unroll") for (int k = 0; k < 2; ++k) dst[m][k] = *(const LAS bf16x8*)(lds + PG8_SA(b, h) + aoff + m * 2048 + k * 1024); } while (0)
; #define PG8_LDB(dst, b, h) do { _Pragma("unroll") for (int n = 0; n < 2; ++n) _Pragma("unroll") for (int k = 0; k < 2; ++k) dst[n][k] = *(const LAS bf16x8*)(lds + PG8_SB(b, h) + boff + n * 2048 + k * 1024); } while (0)
; #define PG8_MMA(ai, bj, At, Bt) do { __builtin_amdgcn_s_setprio(1); _Pragma("unroll") for (int k = 0; k < 2; ++k) _Pragma("unroll") for (int m = 0; m < 4; ++m) _Pragma("unroll") for (int n = 0; n < 2; ++n) \
;         acc[ai][bj][m][n] = __builtin_amdgcn_mfma_f32_16x16x32_bf16(Bt[n][k], At[m][k], acc[ai][bj][m][n], 0, 0, 0); __builtin_amdgcn_s_setprio(0); } while (0)
; #define PG8_WAIT_V(n) asm volatile("s_waitcnt vmcnt(" #n ")" ::: "memory")
; #define PG8_WAIT_L(n) asm volatile("s_waitcnt lgkmcnt(" #n ")" ::: "memory")
; #define PG8_BAR __builtin_amdgcn_s_barrier()
; #define PG8_SCHED __builtin_amdgcn_sched_barrier(0)
; template <class Epi, bool ALIGN_EPI>
; __device__ __forceinline__ void gemm_phase(LAS unsigned char* lds, const Gemm g, const StaticOrder& S, const Epi& E, const int tid) {
;     ...
;             PG8_WAIT_V(8); PG8_WAIT_L(0); PG8_BAR; PG8_MMA(1, 0, At, B0); PG8_MMA(1, 1, At, B1); PG8_BAR; PG8_SCHED;
;             PG8_LDB(B0, 1, 0); PG8_LDB(B1, 1, 1); PG8_SCHED; PG8_LDA(At, 1, 0); PG8_STAGE(PG8_SA(0, 1), a2 + hA, voffA);
;             PG8_WAIT_V(8); PG8_WAIT_L(0); PG8_BAR; PG8_MMA(0, 0, At, B0); PG8_MMA(0, 1, At, B1); PG8_BAR; PG8_SCHED;
	s_waitcnt lgkmcnt(0)
	v_mfma_f32_16x16x32_bf16 v[60:63], v[130:133], v[190:193], 0
	v_mfma_f32_16x16x32_bf16 v[56:59], v[138:141], v[190:193], 0
	v_mfma_f32_16x16x32_bf16 v[44:47], v[130:133], v[198:201], 0
	v_mfma_f32_16x16x32_bf16 v[40:43], v[138:141], v[198:201], 0
	v_mfma_f32_16x16x32_bf16 v[28:31], v[130:133], v[206:209], 0
	v_mfma_f32_16x16x32_bf16 v[24:27], v[138:141], v[206:209], 0
	v_mfma_f32_16x16x32_bf16 v[12:15], v[130:133], v[240:243], 0
	v_mfma_f32_16x16x32_bf16 v[8:11], v[138:141], v[240:243], 0
	v_mfma_f32_16x16x32_bf16 v[60:63], v[134:137], v[194:197], v[60:63]
	v_mfma_f32_16x16x32_bf16 v[56:59], v[142:145], v[194:197], v[56:59]
	v_mfma_f32_16x16x32_bf16 v[44:47], v[134:137], v[202:205], v[44:47]
	v_mfma_f32_16x16x32_bf16 v[40:43], v[142:145], v[202:205], v[40:43]
	v_mfma_f32_16x16x32_bf16 v[28:31], v[134:137], v[210:213], v[28:31]
	v_mfma_f32_16x16x32_bf16 v[24:27], v[142:145], v[210:213], v[24:27]
	v_mfma_f32_16x16x32_bf16 v[12:15], v[134:137], v[244:247], v[12:15]
	v_mfma_f32_16x16x32_bf16 v[8:11], v[142:145], v[244:247], v[8:11]
	v_mfma_f32_16x16x32_bf16 v[52:55], v[146:149], v[190:193], 0
	v_mfma_f32_16x16x32_bf16 v[48:51], v[154:157], v[190:193], 0
	v_mfma_f32_16x16x32_bf16 v[36:39], v[146:149], v[198:201], 0
	v_mfma_f32_16x16x32_bf16 v[32:35], v[154:157], v[198:201], 0
	v_mfma_f32_16x16x32_bf16 v[20:23], v[146:149], v[206:209], 0
	v_mfma_f32_16x16x32_bf16 v[16:19], v[154:157], v[206:209], 0
	v_mfma_f32_16x16x32_bf16 v[4:7], v[146:149], v[240:243], 0
	v_mfma_f32_16x16x32_bf16 v[0:3], v[154:157], v[240:243], 0
	v_mfma_f32_16x16x32_bf16 v[52:55], v[150:153], v[194:197], v[52:55]
	v_mfma_f32_16x16x32_bf16 v[48:51], v[186:189], v[194:197], v[48:51]
	v_mfma_f32_16x16x32_bf16 v[36:39], v[150:153], v[202:205], v[36:39]
	v_mfma_f32_16x16x32_bf16 v[32:35], v[186:189], v[202:205], v[32:35]
	v_mfma_f32_16x16x32_bf16 v[20:23], v[150:153], v[210:213], v[20:23]
	v_mfma_f32_16x16x32_bf16 v[16:19], v[186:189], v[210:213], v[16:19]
	v_mfma_f32_16x16x32_bf16 v[4:7], v[150:153], v[244:247], v[4:7]
	v_mfma_f32_16x16x32_bf16 v[0:3], v[186:189], v[244:247], v[0:3]
	s_barrier
	s_add_i32 s46, 0, 0x18000
	s_add_i32 s70, 0, 0x1c000
	v_add_u32_e32 v142, s46, v218
	v_add_u32_e32 v168, s70, v218
	ds_read_b128 v[130:133], v142
	ds_read_b128 v[134:137], v142 offset:1024
	ds_read_b128 v[138:141], v142 offset:2048
	ds_read_b128 v[142:145], v142 offset:3072
	ds_read_b128 v[146:149], v168
	ds_read_b128 v[150:153], v168 offset:1024
	ds_read_b128 v[154:157], v168 offset:2048
	ds_read_b128 v[186:189], v168 offset:3072
	v_lshl_add_u64 v[158:159], v[158:159], 0, s[94:95]
	s_mov_b32 m0, s55
	v_lshl_add_u64 v[252:253], v[158:159], 0, v[178:179]
	ds_read_b128 v[190:193], v219 offset:32768
	ds_read_b128 v[194:197], v219 offset:33792
	ds_read_b128 v[198:201], v219 offset:34816
	ds_read_b128 v[202:205], v219 offset:35840
	ds_read_b128 v[206:209], v219 offset:36864
	ds_read_b128 v[210:213], v219 offset:37888
	ds_read_b128 v[240:243], v219 offset:38912
	ds_read_b128 v[244:247], v219 offset:39936
	global_load_lds_dwordx4 v[252:253], off
	v_lshl_add_u64 v[158:159], v[158:159], 0, v[182:183]
	s_mov_b32 m0, s56
	s_nop 0
	global_load_lds_dwordx4 v[158:159], off
	s_waitcnt vmcnt(8)
	s_waitcnt lgkmcnt(0)
	s_barrier
	s_waitcnt lgkmcnt(0)
	v_mfma_f32_16x16x32_bf16 v[120:123], v[130:133], v[190:193], v[120:123]
	v_mfma_f32_16x16x32_bf16 v[124:127], v[138:141], v[190:193], v[124:127]
	v_mfma_f32_16x16x32_bf16 v[108:111], v[130:133], v[198:201], v[108:111]
	v_mfma_f32_16x16x32_bf16 v[104:107], v[138:141], v[198:201], v[104:107]
	v_mfma_f32_16x16x32_bf16 v[92:95], v[130:133], v[206:209], v[92:95]
	v_mfma_f32_16x16x32_bf16 v[88:91], v[138:141], v[206:209], v[88:91]
	v_mfma_f32_16x16x32_bf16 v[76:79], v[130:133], v[240:243], v[76:79]
	v_mfma_f32_16x16x32_bf16 v[72:75], v[138:141], v[240:243], v[72:75]
	v_mfma_f32_16x16x32_bf16 v[120:123], v[134:137], v[194:197], v[120:123]
	v_mfma_f32_16x16x32_bf16 v[124:127], v[142:145], v[194:197], v[124:127]
	v_mfma_f32_16x16x32_bf16 v[108:111], v[134:137], v[202:205], v[108:111]
	v_mfma_f32_16x16x32_bf16 v[104:107], v[142:145], v[202:205], v[104:107]
	v_mfma_f32_16x16x32_bf16 v[92:95], v[134:137], v[210:213], v[92:95]
	v_mfma_f32_16x16x32_bf16 v[88:91], v[142:145], v[210:213], v[88:91]
	v_mfma_f32_16x16x32_bf16 v[76:79], v[134:137], v[244:247], v[76:79]
	v_mfma_f32_16x16x32_bf16 v[72:75], v[142:145], v[244:247], v[72:75]
	v_mfma_f32_16x16x32_bf16 v[116:119], v[146:149], v[190:193], v[116:119]
	v_mfma_f32_16x16x32_bf16 v[112:115], v[154:157], v[190:193], v[112:115]
	v_mfma_f32_16x16x32_bf16 v[100:103], v[146:149], v[198:201], v[100:103]
	v_mfma_f32_16x16x32_bf16 v[96:99], v[154:157], v[198:201], v[96:99]
	v_mfma_f32_16x16x32_bf16 v[84:87], v[146:149], v[206:209], v[84:87]
	v_mfma_f32_16x16x32_bf16 v[80:83], v[154:157], v[206:209], v[80:83]
	v_mfma_f32_16x16x32_bf16 v[68:71], v[146:149], v[240:243], v[68:71]
	v_mfma_f32_16x16x32_bf16 v[64:67], v[154:157], v[240:243], v[64:67]
	v_mfma_f32_16x16x32_bf16 v[116:119], v[150:153], v[194:197], v[116:119]
	v_mfma_f32_16x16x32_bf16 v[112:115], v[186:189], v[194:197], v[112:115]
	v_mfma_f32_16x16x32_bf16 v[100:103], v[150:153], v[202:205], v[100:103]
	v_mfma_f32_16x16x32_bf16 v[96:99], v[186:189], v[202:205], v[96:99]
	v_mfma_f32_16x16x32_bf16 v[84:87], v[150:153], v[210:213], v[84:87]
	v_mfma_f32_16x16x32_bf16 v[80:83], v[186:189], v[210:213], v[80:83]
	v_mfma_f32_16x16x32_bf16 v[68:71], v[150:153], v[244:247], v[68:71]
	v_mfma_f32_16x16x32_bf16 v[64:67], v[186:189], v[244:247], v[64:67]
	s_barrier
; #define PG8_STAGE(bufoff, gbase, voff) do { _Pragma("unroll") for (int _i = 0; _i < 2; ++_i) \
;         __builtin_amdgcn_global_load_lds((const unsigned*)((const char*)(gbase) + (voff)[_i]), (LAS unsigned*)(lds + (bufoff) + ldsw + _i * 8192), 16, 0, 0); } while (0)
; #define PG8_LDA(dst, b, h) do { _Pragma("unroll") for (int m = 0; m < 4; ++m) _Pragma("unroll") for (int k = 0; k < 2; ++k) dst[m][k] = *(const LAS bf16x8*)(lds + PG8_SA(b, h) + aoff + m * 2048 + k * 1024); } while (0)
; #define PG8_LDB(dst, b, h) do { _Pragma("unroll") for (int n = 0; n < 2; ++n) _Pragma("unroll") for (int k = 0; k < 2; ++k) dst[n][k] = *(const LAS bf16x8*)(lds + PG8_SB(b, h) + boff + n * 2048 + k * 1024); } while (0)
; #define PG8_WAIT_V(n) asm volatile("s_waitcnt vmcnt(" #n ")" ::: "memory")
; #define PG8_BAR __builtin_amdgcn_s_barrier()
; template <class Epi, bool ALIGN_EPI>
; __device__ __forceinline__ void gemm_phase(LAS unsigned char* lds, const Gemm g, const StaticOrder& S, const Epi& E, const int tid) {
;     ...
;         for (int t = 0; t < nt; t += 2) {
;             const bool last = (t == nt - 2);
;             const char* a1 = cA + (size_t)(t + 1) * kstep;
;             const char* a2 = last ? nA : cA + (size_t)(t + 2) * kstep; const char* b2 = last ? nB : cB + (size_t)(t + 2) * kstep;
;             const char* a3 = a2 + kstep; const char* b3 = b2 + kstep;
;             PG8_LDB(B0, 0, 0); PG8_LDB(B1, 0, 1); PG8_SCHED; PG8_LDA(At, 0, 0); PG8_STAGE(PG8_SA(1, 1), a1 + hA, voffA);
;             PG8_WAIT_V(8); PG8_WAIT_L(0); PG8_BAR; PG8_MMA(0, 0, At, B0); PG8_MMA(0, 1, At, B1); PG8_BAR; PG8_SCHED;
;             PG8_LDA(At, 0, 1); PG8_STAGE(PG8_SB(0, 0), b2, voffB); PG8_STAGE(PG8_SB(0, 1), b2 + hB, voffB); PG8_STAGE(PG8_SA(0, 0), a2, voffA);
;             PG8_WAIT_V(8); PG8_WAIT_L(0); PG8_BAR; PG8_MMA(1, 0, At, B0); PG8_MMA(1, 1, At, B1); PG8_BAR; PG8_SCHED;
;             PG8_LDB(B0, 1, 0); PG8_LDB(B1, 1, 1); PG8_SCHED; PG8_LDA(At, 1, 0); PG8_STAGE(PG8_SA(0, 1), a2 + hA, voffA);
;             PG8_WAIT_V(8); PG8_WAIT_L(0); PG8_BAR; PG8_MMA(0, 0, At, B0); PG8_MMA(0, 1, At, B1); PG8_BAR; PG8_SCHED;
;             PG8_LDA(At, 1, 1); PG8_STAGE(PG8_SB(1, 0), b3, voffB); PG8_STAGE(PG8_SB(1, 1), b3 + hB, voffB); PG8_STAGE(PG8_SA(1, 0), a3, voffA);
;             PG8_WAIT_V(8); PG8_WAIT_L(0); PG8_BAR; PG8_MMA(1, 0, At, B0); PG8_MMA(1, 1, At, B1); PG8_BAR; PG8_SCHED;
	s_add_i32 s46, s46, s52
	v_lshl_add_u64 v[158:159], v[166:167], 0, s[92:93]
	s_mov_b32 m0, s46
	ds_read_b128 v[190:193], v219 offset:49152
	ds_read_b128 v[194:197], v219 offset:50176
	ds_read_b128 v[198:201], v219 offset:51200
	ds_read_b128 v[202:205], v219 offset:52224
	ds_read_b128 v[206:209], v219 offset:53248
	ds_read_b128 v[210:213], v219 offset:54272
	ds_read_b128 v[240:243], v219 offset:55296
	ds_read_b128 v[244:247], v219 offset:56320
	global_load_lds_dwordx4 v[158:159], off
	v_lshl_add_u64 v[158:159], v[214:215], 0, s[92:93]
	s_add_i32 m0, s46, 0x2000
	s_add_i32 s46, s70, s52
	global_load_lds_dwordx4 v[158:159], off
	v_lshl_add_u64 v[158:159], v[220:221], 0, s[92:93]
	s_mov_b32 m0, s46
	s_nop 0
	global_load_lds_dwordx4 v[158:159], off
	v_lshl_add_u64 v[158:159], v[226:227], 0, s[92:93]
	s_add_i32 m0, s46, 0x2000
	s_nop 0
	global_load_lds_dwordx4 v[158:159], off
	v_lshl_add_u64 v[158:159], v[248:249], 0, s[92:93]
	s_mov_b32 m0, s57
	s_nop 0
	global_load_lds_dwordx4 v[158:159], off
	v_lshl_add_u64 v[158:159], v[250:251], 0, s[92:93]
	s_mov_b32 m0, s58
	s_nop 0
	global_load_lds_dwordx4 v[158:159], off
	s_waitcnt vmcnt(8)
	s_waitcnt lgkmcnt(0)
	s_barrier
	s_waitcnt lgkmcnt(0)
	v_mfma_f32_16x16x32_bf16 v[60:63], v[130:133], v[190:193], v[60:63]
	v_mfma_f32_16x16x32_bf16 v[56:59], v[138:141], v[190:193], v[56:59]
	v_mfma_f32_16x16x32_bf16 v[44:47], v[130:133], v[198:201], v[44:47]
	v_mfma_f32_16x16x32_bf16 v[40:43], v[138:141], v[198:201], v[40:43]
	v_mfma_f32_16x16x32_bf16 v[28:31], v[130:133], v[206:209], v[28:31]
	v_mfma_f32_16x16x32_bf16 v[24:27], v[138:141], v[206:209], v[24:27]
	v_mfma_f32_16x16x32_bf16 v[12:15], v[130:133], v[240:243], v[12:15]
	v_mfma_f32_16x16x32_bf16 v[8:11], v[138:141], v[240:243], v[8:11]
	v_mfma_f32_16x16x32_bf16 v[60:63], v[134:137], v[194:197], v[60:63]
	v_mfma_f32_16x16x32_bf16 v[56:59], v[142:145], v[194:197], v[56:59]
	v_mfma_f32_16x16x32_bf16 v[44:47], v[134:137], v[202:205], v[44:47]
	v_mfma_f32_16x16x32_bf16 v[40:43], v[142:145], v[202:205], v[40:43]
	v_mfma_f32_16x16x32_bf16 v[28:31], v[134:137], v[210:213], v[28:31]
	v_mfma_f32_16x16x32_bf16 v[24:27], v[142:145], v[210:213], v[24:27]
	v_mfma_f32_16x16x32_bf16 v[12:15], v[134:137], v[244:247], v[12:15]
	v_mfma_f32_16x16x32_bf16 v[8:11], v[142:145], v[244:247], v[8:11]
	v_mfma_f32_16x16x32_bf16 v[52:55], v[146:149], v[190:193], v[52:55]
	v_mfma_f32_16x16x32_bf16 v[48:51], v[154:157], v[190:193], v[48:51]
	v_mfma_f32_16x16x32_bf16 v[36:39], v[146:149], v[198:201], v[36:39]
	v_mfma_f32_16x16x32_bf16 v[32:35], v[154:157], v[198:201], v[32:35]
	v_mfma_f32_16x16x32_bf16 v[20:23], v[146:149], v[206:209], v[20:23]
	v_mfma_f32_16x16x32_bf16 v[16:19], v[154:157], v[206:209], v[16:19]
	v_mfma_f32_16x16x32_bf16 v[4:7], v[146:149], v[240:243], v[4:7]
	v_mfma_f32_16x16x32_bf16 v[0:3], v[154:157], v[240:243], v[0:3]
	v_mfma_f32_16x16x32_bf16 v[52:55], v[150:153], v[194:197], v[52:55]
	v_mfma_f32_16x16x32_bf16 v[48:51], v[186:189], v[194:197], v[48:51]
	v_mfma_f32_16x16x32_bf16 v[36:39], v[150:153], v[202:205], v[36:39]
	v_mfma_f32_16x16x32_bf16 v[32:35], v[186:189], v[202:205], v[32:35]
	v_mfma_f32_16x16x32_bf16 v[20:23], v[150:153], v[210:213], v[20:23]
	v_mfma_f32_16x16x32_bf16 v[16:19], v[186:189], v[210:213], v[16:19]
	v_mfma_f32_16x16x32_bf16 v[4:7], v[150:153], v[244:247], v[4:7]
	v_mfma_f32_16x16x32_bf16 v[0:3], v[186:189], v[244:247], v[0:3]
	s_barrier
	s_add_u32 s12, s12, 0x100
	s_addc_u32 s13, s13, 0
	v_lshl_add_u64 v[128:129], v[128:129], 0, s[80:81]
	s_cmp_ge_u32 s47, s48
	s_mov_b32 s46, s47
	s_cbranch_scc1 .Lpl1_after
.LBB0_236:
	s_add_i32 s47, s46, 2
	s_cmp_eq_u32 s60, s46
	s_cselect_b64 vcc, -1, 0
	s_cselect_b32 s71, s15, s13
	s_cselect_b32 s70, s14, s12
	s_add_i32 s46, 0, 0x14000
	v_lshl_add_u64 v[130:131], v[128:129], 0, s[92:93]
	v_add_u32_e32 v142, s33, v218
	v_add_u32_e32 v166, s46, v218
	v_cndmask_b32_e32 v159, v131, v165, vcc
	v_cndmask_b32_e32 v158, v130, v164, vcc
	ds_read_b128 v[130:133], v142
	ds_read_b128 v[134:137], v142 offset:1024
	ds_read_b128 v[138:141], v142 offset:2048
	ds_read_b128 v[142:145], v142 offset:3072
	ds_read_b128 v[146:149], v166
	ds_read_b128 v[150:153], v166 offset:1024
	ds_read_b128 v[154:157], v166 offset:2048
	ds_read_b128 v[186:189], v166 offset:3072
	v_lshl_add_u64 v[166:167], v[128:129], 0, v[160:161]
	s_add_i32 m0, s53, 0xc000
	ds_read_b128 v[190:193], v219
	ds_read_b128 v[194:197], v219 offset:1024
	ds_read_b128 v[198:201], v219 offset:2048
	ds_read_b128 v[202:205], v219 offset:3072
	ds_read_b128 v[206:209], v219 offset:4096
	ds_read_b128 v[210:213], v219 offset:5120
	ds_read_b128 v[240:243], v219 offset:6144
	ds_read_b128 v[244:247], v219 offset:7168
	global_load_lds_dwordx4 v[166:167], off
	v_lshl_add_u64 v[166:167], v[128:129], 0, v[162:163]
	s_add_i32 m0, s53, 0xe000
	s_nop 0
	global_load_lds_dwordx4 v[166:167], off
	s_waitcnt vmcnt(8)
	s_waitcnt lgkmcnt(0)
	s_barrier
; #define PG8_STAGE(bufoff, gbase, voff) do { _Pragma("unroll") for (int _i = 0; _i < 2; ++_i) \
;         __builtin_amdgcn_global_load_lds((const unsigned*)((const char*)(gbase) + (voff)[_i]), (LAS unsigned*)(lds + (bufoff) + ldsw + _i * 8192), 16, 0, 0); } while (0)
; #define PG8_LDA(dst, b, h) do { _Pragma("unroll") for (int m = 0; m < 4; ++m) _Pragma("unroll") for (int k = 0; k < 2; ++k) dst[m][k] = *(const LAS bf16x8*)(lds + PG8_SA(b, h) + aoff + m * 2048 + k * 1024); } while (0)
; #define PG8_MMA(ai, bj, At, Bt) do { __builtin_amdgcn_s_setprio(1); _Pragma("unroll") for (int k = 0; k < 2; ++k) _Pragma("unroll") for (int m = 0; m < 4; ++m) _Pragma("unroll") for (int n = 0; n < 2; ++n) \
;         acc[ai][bj][m][n] = __builtin_amdgcn_mfma_f32_16x16x32_bf16(Bt[n][k], At[m][k], acc[ai][bj][m][n], 0, 0, 0); __builtin_amdgcn_s_setprio(0); } while (0)
; #define PG8_WAIT_V(n) asm volatile("s_waitcnt vmcnt(" #n ")" ::: "memory")
; #define PG8_WAIT_L(n) asm volatile("s_waitcnt lgkmcnt(" #n ")" ::: "memory")
; #define PG8_BAR __builtin_amdgcn_s_barrier()
; #define PG8_SCHED __builtin_amdgcn_sched_barrier(0)
; template <class Epi, bool ALIGN_EPI>
; __device__ __forceinline__ void gemm_phase(LAS unsigned char* lds, const Gemm g, const StaticOrder& S, const Epi& E, const int tid) {
;     ...
;             PG8_WAIT_V(8); PG8_WAIT_L(0); PG8_BAR; PG8_MMA(0, 0, At, B0); PG8_MMA(0, 1, At, B1); PG8_BAR; PG8_SCHED;
;             PG8_LDA(At, 0, 1); PG8_STAGE(PG8_SB(0, 0), b2, voffB); PG8_STAGE(PG8_SB(0, 1), b2 + hB, voffB); PG8_STAGE(PG8_SA(0, 0), a2, voffA);
;             PG8_WAIT_V(8); PG8_WAIT_L(0); PG8_BAR; PG8_MMA(1, 0, At, B0); PG8_MMA(1, 1, At, B1); PG8_BAR; PG8_SCHED;
	s_waitcnt lgkmcnt(0)
	v_mfma_f32_16x16x32_bf16 v[120:123], v[130:133], v[190:193], v[120:123]
	v_mfma_f32_16x16x32_bf16 v[124:127], v[138:141], v[190:193], v[124:127]
	v_mfma_f32_16x16x32_bf16 v[108:111], v[130:133], v[198:201], v[108:111]
	v_mfma_f32_16x16x32_bf16 v[104:107], v[138:141], v[198:201], v[104:107]
	v_mfma_f32_16x16x32_bf16 v[92:95], v[130:133], v[206:209], v[92:95]
	v_mfma_f32_16x16x32_bf16 v[88:91], v[138:141], v[206:209], v[88:91]
	v_mfma_f32_16x16x32_bf16 v[76:79], v[130:133], v[240:243], v[76:79]
	v_mfma_f32_16x16x32_bf16 v[72:75], v[138:141], v[240:243], v[72:75]
	v_mfma_f32_16x16x32_bf16 v[120:123], v[134:137], v[194:197], v[120:123]
	v_mfma_f32_16x16x32_bf16 v[124:127], v[142:145], v[194:197], v[124:127]
	v_mfma_f32_16x16x32_bf16 v[108:111], v[134:137], v[202:205], v[108:111]
	v_mfma_f32_16x16x32_bf16 v[104:107], v[142:145], v[202:205], v[104:107]
	v_mfma_f32_16x16x32_bf16 v[92:95], v[134:137], v[210:213], v[92:95]
	v_mfma_f32_16x16x32_bf16 v[88:91], v[142:145], v[210:213], v[88:91]
	v_mfma_f32_16x16x32_bf16 v[76:79], v[134:137], v[244:247], v[76:79]
	v_mfma_f32_16x16x32_bf16 v[72:75], v[142:145], v[244:247], v[72:75]
	v_mfma_f32_16x16x32_bf16 v[116:119], v[146:149], v[190:193], v[116:119]
	v_mfma_f32_16x16x32_bf16 v[112:115], v[154:157], v[190:193], v[112:115]
	v_mfma_f32_16x16x32_bf16 v[100:103], v[146:149], v[198:201], v[100:103]
	v_mfma_f32_16x16x32_bf16 v[96:99], v[154:157], v[198:201], v[96:99]
	v_mfma_f32_16x16x32_bf16 v[84:87], v[146:149], v[206:209], v[84:87]
	v_mfma_f32_16x16x32_bf16 v[80:83], v[154:157], v[206:209], v[80:83]
	v_mfma_f32_16x16x32_bf16 v[68:71], v[146:149], v[240:243], v[68:71]
	v_mfma_f32_16x16x32_bf16 v[64:67], v[154:157], v[240:243], v[64:67]
	v_mfma_f32_16x16x32_bf16 v[116:119], v[150:153], v[194:197], v[116:119]
	v_mfma_f32_16x16x32_bf16 v[112:115], v[186:189], v[194:197], v[112:115]
	v_mfma_f32_16x16x32_bf16 v[100:103], v[150:153], v[202:205], v[100:103]
	v_mfma_f32_16x16x32_bf16 v[96:99], v[186:189], v[202:205], v[96:99]
	v_mfma_f32_16x16x32_bf16 v[84:87], v[150:153], v[210:213], v[84:87]
	v_mfma_f32_16x16x32_bf16 v[80:83], v[186:189], v[210:213], v[80:83]
	v_mfma_f32_16x16x32_bf16 v[68:71], v[150:153], v[244:247], v[68:71]
	v_mfma_f32_16x16x32_bf16 v[64:67], v[186:189], v[244:247], v[64:67]
	s_barrier
	s_add_i32 s72, s33, s52
	v_lshl_add_u64 v[166:167], s[70:71], 0, v[180:181]
	s_mov_b32 m0, s72
	ds_read_b128 v[190:193], v219 offset:16384
	ds_read_b128 v[194:197], v219 offset:17408
	ds_read_b128 v[198:201], v219 offset:18432
	ds_read_b128 v[202:205], v219 offset:19456
	ds_read_b128 v[206:209], v219 offset:20480
	ds_read_b128 v[210:213], v219 offset:21504
	ds_read_b128 v[240:243], v219 offset:22528
	ds_read_b128 v[244:247], v219 offset:23552
	global_load_lds_dwordx4 v[166:167], off
	s_add_i32 m0, s72, 0x2000
	v_lshl_add_u64 v[214:215], s[70:71], 0, v[184:185]
	s_add_u32 s70, s70, s49
	s_addc_u32 s71, s71, 0
	s_add_i32 s46, s46, s52
	global_load_lds_dwordx4 v[214:215], off
	v_lshl_add_u64 v[220:221], s[70:71], 0, v[180:181]
	s_mov_b32 m0, s46
	v_lshl_add_u64 v[226:227], s[70:71], 0, v[184:185]
	global_load_lds_dwordx4 v[220:221], off
	s_add_i32 m0, s46, 0x2000
	v_lshl_add_u64 v[248:249], v[158:159], 0, v[178:179]
	global_load_lds_dwordx4 v[226:227], off
	s_mov_b32 m0, s53
	v_lshl_add_u64 v[250:251], v[158:159], 0, v[182:183]
	global_load_lds_dwordx4 v[248:249], off
	s_mov_b32 m0, s54
	s_nop 0
	global_load_lds_dwordx4 v[250:251], off
	s_waitcnt vmcnt(8)
	s_waitcnt lgkmcnt(0)
	s_barrier
	s_waitcnt lgkmcnt(0)
	v_mfma_f32_16x16x32_bf16 v[60:63], v[130:133], v[190:193], v[60:63]
	v_mfma_f32_16x16x32_bf16 v[56:59], v[138:141], v[190:193], v[56:59]
	v_mfma_f32_16x16x32_bf16 v[44:47], v[130:133], v[198:201], v[44:47]
	v_mfma_f32_16x16x32_bf16 v[40:43], v[138:141], v[198:201], v[40:43]
	v_mfma_f32_16x16x32_bf16 v[28:31], v[130:133], v[206:209], v[28:31]
	v_mfma_f32_16x16x32_bf16 v[24:27], v[138:141], v[206:209], v[24:27]
	v_mfma_f32_16x16x32_bf16 v[12:15], v[130:133], v[240:243], v[12:15]
	v_mfma_f32_16x16x32_bf16 v[8:11], v[138:141], v[240:243], v[8:11]
	v_mfma_f32_16x16x32_bf16 v[60:63], v[134:137], v[194:197], v[60:63]
	v_mfma_f32_16x16x32_bf16 v[56:59], v[142:145], v[194:197], v[56:59]
	v_mfma_f32_16x16x32_bf16 v[44:47], v[134:137], v[202:205], v[44:47]
	v_mfma_f32_16x16x32_bf16 v[40:43], v[142:145], v[202:205], v[40:43]
	v_mfma_f32_16x16x32_bf16 v[28:31], v[134:137], v[210:213], v[28:31]
	v_mfma_f32_16x16x32_bf16 v[24:27], v[142:145], v[210:213], v[24:27]
	v_mfma_f32_16x16x32_bf16 v[12:15], v[134:137], v[244:247], v[12:15]
	v_mfma_f32_16x16x32_bf16 v[8:11], v[142:145], v[244:247], v[8:11]
	v_mfma_f32_16x16x32_bf16 v[52:55], v[146:149], v[190:193], v[52:55]
	v_mfma_f32_16x16x32_bf16 v[48:51], v[154:157], v[190:193], v[48:51]
	v_mfma_f32_16x16x32_bf16 v[36:39], v[146:149], v[198:201], v[36:39]
	v_mfma_f32_16x16x32_bf16 v[32:35], v[154:157], v[198:201], v[32:35]
	v_mfma_f32_16x16x32_bf16 v[20:23], v[146:149], v[206:209], v[20:23]
	v_mfma_f32_16x16x32_bf16 v[16:19], v[154:157], v[206:209], v[16:19]
	v_mfma_f32_16x16x32_bf16 v[4:7], v[146:149], v[240:243], v[4:7]
	v_mfma_f32_16x16x32_bf16 v[0:3], v[154:157], v[240:243], v[0:3]
	v_mfma_f32_16x16x32_bf16 v[52:55], v[150:153], v[194:197], v[52:55]
	v_mfma_f32_16x16x32_bf16 v[48:51], v[186:189], v[194:197], v[48:51]
	v_mfma_f32_16x16x32_bf16 v[36:39], v[150:153], v[202:205], v[36:39]
	v_mfma_f32_16x16x32_bf16 v[32:35], v[186:189], v[202:205], v[32:35]
	v_mfma_f32_16x16x32_bf16 v[20:23], v[150:153], v[210:213], v[20:23]
	v_mfma_f32_16x16x32_bf16 v[16:19], v[186:189], v[210:213], v[16:19]
	v_mfma_f32_16x16x32_bf16 v[4:7], v[150:153], v[244:247], v[4:7]
	v_mfma_f32_16x16x32_bf16 v[0:3], v[186:189], v[244:247], v[0:3]
	s_barrier
; #define PG8_STAGE(bufoff, gbase, voff) do { _Pragma("unroll") for (int _i = 0; _i < 2; ++_i) \
;         __builtin_amdgcn_global_load_lds((const unsigned*)((const char*)(gbase) + (voff)[_i]), (LAS unsigned*)(lds + (bufoff) + ldsw + _i * 8192), 16, 0, 0); } while (0)
; #define PG8_LDA(dst, b, h) do { _Pragma("unroll") for (int m = 0; m < 4; ++m) _Pragma("unroll") for (int k = 0; k < 2; ++k) dst[m][k] = *(const LAS bf16x8*)(lds + PG8_SA(b, h) + aoff + m * 2048 + k * 1024); } while (0)
; #define PG8_LDB(dst, b, h) do { _Pragma("unroll") for (int n = 0; n < 2; ++n) _Pragma("unroll") for (int k = 0; k < 2; ++k) dst[n][k] = *(const LAS bf16x8*)(lds + PG8_SB(b, h) + boff + n * 2048 + k * 1024); } while (0)
; #define PG8_MMA(ai, bj, At, Bt) do { __builtin_amdgcn_s_setprio(1); _Pragma("unroll") for (int k = 0; k < 2; ++k) _Pragma("unroll") for (int m = 0; m < 4; ++m) _Pragma("unroll") for (int n = 0; n < 2; ++n) \
;         acc[ai][bj][m][n] = __builtin_amdgcn_mfma_f32_16x16x32_bf16(Bt[n][k], At[m][k], acc[ai][bj][m][n], 0, 0, 0); __builtin_amdgcn_s_setprio(0); } while (0)
; #define PG8_WAIT_V(n) asm volatile("s_waitcnt vmcnt(" #n ")" ::: "memory")
; #define PG8_WAIT_L(n) asm volatile("s_waitcnt lgkmcnt(" #n ")" ::: "memory")
; #define PG8_BAR __builtin_amdgcn_s_barrier()
; #define PG8_SCHED __builtin_amdgcn_sched_barrier(0)
; template <class Epi, bool ALIGN_EPI>
; __device__ __forceinline__ void gemm_phase(LAS unsigned char* lds, const Gemm g, const StaticOrder& S, const Epi& E, const int tid) {
;     ...
;             PG8_LDB(B0, 1, 0); PG8_LDB(B1, 1, 1); PG8_SCHED; PG8_LDA(At, 1, 0); PG8_STAGE(PG8_SA(0, 1), a2 + hA, voffA);
;             PG8_WAIT_V(8); PG8_WAIT_L(0); PG8_BAR; PG8_MMA(0, 0, At, B0); PG8_MMA(0, 1, At, B1); PG8_BAR; PG8_SCHED;
;             PG8_LDA(At, 1, 1); PG8_STAGE(PG8_SB(1, 0), b3, voffB); PG8_STAGE(PG8_SB(1, 1), b3 + hB, voffB); PG8_STAGE(PG8_SA(1, 0), a3, voffA);
;             PG8_WAIT_V(8); PG8_WAIT_L(0); PG8_BAR; PG8_MMA(1, 0, At, B0); PG8_MMA(1, 1, At, B1); PG8_BAR; PG8_SCHED;
	s_add_i32 s46, 0, 0x18000
	s_add_i32 s70, 0, 0x1c000
	v_add_u32_e32 v142, s46, v218
	v_add_u32_e32 v168, s70, v218
	ds_read_b128 v[130:133], v142
	ds_read_b128 v[134:137], v142 offset:1024
	ds_read_b128 v[138:141], v142 offset:2048
	ds_read_b128 v[142:145], v142 offset:3072
	ds_read_b128 v[146:149], v168
	ds_read_b128 v[150:153], v168 offset:1024
	ds_read_b128 v[154:157], v168 offset:2048
	ds_read_b128 v[186:189], v168 offset:3072
	v_lshl_add_u64 v[158:159], v[158:159], 0, s[94:95]
	s_mov_b32 m0, s55
	v_lshl_add_u64 v[252:253], v[158:159], 0, v[178:179]
	ds_read_b128 v[190:193], v219 offset:32768
	ds_read_b128 v[194:197], v219 offset:33792
	ds_read_b128 v[198:201], v219 offset:34816
	ds_read_b128 v[202:205], v219 offset:35840
	ds_read_b128 v[206:209], v219 offset:36864
	ds_read_b128 v[210:213], v219 offset:37888
	ds_read_b128 v[240:243], v219 offset:38912
	ds_read_b128 v[244:247], v219 offset:39936
	global_load_lds_dwordx4 v[252:253], off
	v_lshl_add_u64 v[158:159], v[158:159], 0, v[182:183]
	s_mov_b32 m0, s56
	s_nop 0
	global_load_lds_dwordx4 v[158:159], off
	s_waitcnt vmcnt(8)
	s_waitcnt lgkmcnt(0)
	s_barrier
	s_waitcnt lgkmcnt(0)
	v_mfma_f32_16x16x32_bf16 v[120:123], v[130:133], v[190:193], v[120:123]
	v_mfma_f32_16x16x32_bf16 v[124:127], v[138:141], v[190:193], v[124:127]
	v_mfma_f32_16x16x32_bf16 v[108:111], v[130:133], v[198:201], v[108:111]
	v_mfma_f32_16x16x32_bf16 v[104:107], v[138:141], v[198:201], v[104:107]
	v_mfma_f32_16x16x32_bf16 v[92:95], v[130:133], v[206:209], v[92:95]
	v_mfma_f32_16x16x32_bf16 v[88:91], v[138:141], v[206:209], v[88:91]
	v_mfma_f32_16x16x32_bf16 v[76:79], v[130:133], v[240:243], v[76:79]
	v_mfma_f32_16x16x32_bf16 v[72:75], v[138:141], v[240:243], v[72:75]
	v_mfma_f32_16x16x32_bf16 v[120:123], v[134:137], v[194:197], v[120:123]
	v_mfma_f32_16x16x32_bf16 v[124:127], v[142:145], v[194:197], v[124:127]
	v_mfma_f32_16x16x32_bf16 v[108:111], v[134:137], v[202:205], v[108:111]
	v_mfma_f32_16x16x32_bf16 v[104:107], v[142:145], v[202:205], v[104:107]
	v_mfma_f32_16x16x32_bf16 v[92:95], v[134:137], v[210:213], v[92:95]
	v_mfma_f32_16x16x32_bf16 v[88:91], v[142:145], v[210:213], v[88:91]
	v_mfma_f32_16x16x32_bf16 v[76:79], v[134:137], v[244:247], v[76:79]
	v_mfma_f32_16x16x32_bf16 v[72:75], v[142:145], v[244:247], v[72:75]
	v_mfma_f32_16x16x32_bf16 v[116:119], v[146:149], v[190:193], v[116:119]
	v_mfma_f32_16x16x32_bf16 v[112:115], v[154:157], v[190:193], v[112:115]
	v_mfma_f32_16x16x32_bf16 v[100:103], v[146:149], v[198:201], v[100:103]
	v_mfma_f32_16x16x32_bf16 v[96:99], v[154:157], v[198:201], v[96:99]
	v_mfma_f32_16x16x32_bf16 v[84:87], v[146:149], v[206:209], v[84:87]
	v_mfma_f32_16x16x32_bf16 v[80:83], v[154:157], v[206:209], v[80:83]
	v_mfma_f32_16x16x32_bf16 v[68:71], v[146:149], v[240:243], v[68:71]
	v_mfma_f32_16x16x32_bf16 v[64:67], v[154:157], v[240:243], v[64:67]
	v_mfma_f32_16x16x32_bf16 v[116:119], v[150:153], v[194:197], v[116:119]
	v_mfma_f32_16x16x32_bf16 v[112:115], v[186:189], v[194:197], v[112:115]
	v_mfma_f32_16x16x32_bf16 v[100:103], v[150:153], v[202:205], v[100:103]
	v_mfma_f32_16x16x32_bf16 v[96:99], v[186:189], v[202:205], v[96:99]
	v_mfma_f32_16x16x32_bf16 v[84:87], v[150:153], v[210:213], v[84:87]
	v_mfma_f32_16x16x32_bf16 v[80:83], v[186:189], v[210:213], v[80:83]
	v_mfma_f32_16x16x32_bf16 v[68:71], v[150:153], v[244:247], v[68:71]
	v_mfma_f32_16x16x32_bf16 v[64:67], v[186:189], v[244:247], v[64:67]
	s_barrier
	s_add_i32 s46, s46, s52
	v_lshl_add_u64 v[158:159], v[166:167], 0, s[92:93]
	s_mov_b32 m0, s46
	ds_read_b128 v[190:193], v219 offset:49152
	ds_read_b128 v[194:197], v219 offset:50176
	ds_read_b128 v[198:201], v219 offset:51200
	ds_read_b128 v[202:205], v219 offset:52224
	ds_read_b128 v[206:209], v219 offset:53248
	ds_read_b128 v[210:213], v219 offset:54272
	ds_read_b128 v[240:243], v219 offset:55296
	ds_read_b128 v[244:247], v219 offset:56320
	global_load_lds_dwordx4 v[158:159], off
	v_lshl_add_u64 v[158:159], v[214:215], 0, s[92:93]
	s_add_i32 m0, s46, 0x2000
	s_add_i32 s46, s70, s52
	global_load_lds_dwordx4 v[158:159], off
	v_lshl_add_u64 v[158:159], v[220:221], 0, s[92:93]
	s_mov_b32 m0, s46
	s_nop 0
	global_load_lds_dwordx4 v[158:159], off
	v_lshl_add_u64 v[158:159], v[226:227], 0, s[92:93]
	s_add_i32 m0, s46, 0x2000
	s_nop 0
	global_load_lds_dwordx4 v[158:159], off
	v_lshl_add_u64 v[158:159], v[248:249], 0, s[92:93]
	s_mov_b32 m0, s57
	s_nop 0
	global_load_lds_dwordx4 v[158:159], off
	v_lshl_add_u64 v[158:159], v[250:251], 0, s[92:93]
	s_mov_b32 m0, s58
	s_nop 0
	global_load_lds_dwordx4 v[158:159], off
	s_waitcnt vmcnt(8)
	s_waitcnt lgkmcnt(0)
	s_barrier
	s_waitcnt lgkmcnt(0)
	v_mfma_f32_16x16x32_bf16 v[60:63], v[130:133], v[190:193], v[60:63]
	v_mfma_f32_16x16x32_bf16 v[56:59], v[138:141], v[190:193], v[56:59]
	v_mfma_f32_16x16x32_bf16 v[44:47], v[130:133], v[198:201], v[44:47]
	v_mfma_f32_16x16x32_bf16 v[40:43], v[138:141], v[198:201], v[40:43]
	v_mfma_f32_16x16x32_bf16 v[28:31], v[130:133], v[206:209], v[28:31]
	v_mfma_f32_16x16x32_bf16 v[24:27], v[138:141], v[206:209], v[24:27]
	v_mfma_f32_16x16x32_bf16 v[12:15], v[130:133], v[240:243], v[12:15]
	v_mfma_f32_16x16x32_bf16 v[8:11], v[138:141], v[240:243], v[8:11]
	v_mfma_f32_16x16x32_bf16 v[60:63], v[134:137], v[194:197], v[60:63]
	v_mfma_f32_16x16x32_bf16 v[56:59], v[142:145], v[194:197], v[56:59]
	v_mfma_f32_16x16x32_bf16 v[44:47], v[134:137], v[202:205], v[44:47]
	v_mfma_f32_16x16x32_bf16 v[40:43], v[142:145], v[202:205], v[40:43]
	v_mfma_f32_16x16x32_bf16 v[28:31], v[134:137], v[210:213], v[28:31]
	v_mfma_f32_16x16x32_bf16 v[24:27], v[142:145], v[210:213], v[24:27]
	v_mfma_f32_16x16x32_bf16 v[12:15], v[134:137], v[244:247], v[12:15]
	v_mfma_f32_16x16x32_bf16 v[8:11], v[142:145], v[244:247], v[8:11]
	v_mfma_f32_16x16x32_bf16 v[52:55], v[146:149], v[190:193], v[52:55]
	v_mfma_f32_16x16x32_bf16 v[48:51], v[154:157], v[190:193], v[48:51]
	v_mfma_f32_16x16x32_bf16 v[36:39], v[146:149], v[198:201], v[36:39]
	v_mfma_f32_16x16x32_bf16 v[32:35], v[154:157], v[198:201], v[32:35]
	v_mfma_f32_16x16x32_bf16 v[20:23], v[146:149], v[206:209], v[20:23]
	v_mfma_f32_16x16x32_bf16 v[16:19], v[154:157], v[206:209], v[16:19]
	v_mfma_f32_16x16x32_bf16 v[4:7], v[146:149], v[240:243], v[4:7]
	v_mfma_f32_16x16x32_bf16 v[0:3], v[154:157], v[240:243], v[0:3]
	v_mfma_f32_16x16x32_bf16 v[52:55], v[150:153], v[194:197], v[52:55]
	v_mfma_f32_16x16x32_bf16 v[48:51], v[186:189], v[194:197], v[48:51]
	v_mfma_f32_16x16x32_bf16 v[36:39], v[150:153], v[202:205], v[36:39]
	v_mfma_f32_16x16x32_bf16 v[32:35], v[186:189], v[202:205], v[32:35]
	v_mfma_f32_16x16x32_bf16 v[20:23], v[150:153], v[210:213], v[20:23]
	v_mfma_f32_16x16x32_bf16 v[16:19], v[186:189], v[210:213], v[16:19]
	v_mfma_f32_16x16x32_bf16 v[4:7], v[150:153], v[244:247], v[4:7]
	v_mfma_f32_16x16x32_bf16 v[0:3], v[186:189], v[244:247], v[0:3]
	s_barrier
	s_add_u32 s12, s12, 0x100
	s_addc_u32 s13, s13, 0
	v_lshl_add_u64 v[128:129], v[128:129], 0, s[80:81]
	s_cmp_ge_u32 s47, s48
	s_mov_b32 s46, s47
	s_cbranch_scc0 .LBB0_236

; #define PG8_STAGE(bufoff, gbase, voff) do { _Pragma("unroll") for (int _i = 0; _i < 2; ++_i) \
;         __builtin_amdgcn_global_load_lds((const unsigned*)((const char*)(gbase) + (voff)[_i]), (LAS unsigned*)(lds + (bufoff) + ldsw + _i * 8192), 16, 0, 0); } while (0)
; #define PG8_LDA(dst, b, h) do { _Pragma("unroll") for (int m = 0; m < 4; ++m) _Pragma("unroll") for (int k = 0; k < 2; ++k) dst[m][k] = *(const LAS bf16x8*)(lds + PG8_SA(b, h) + aoff + m * 2048 + k * 1024); } while (0)
; #define PG8_LDB(dst, b, h) do { _Pragma("unroll") for (int n = 0; n < 2; ++n) _Pragma("unroll") for (int k = 0; k < 2; ++k) dst[n][k] = *(const LAS bf16x8*)(lds + PG8_SB(b, h) + boff + n * 2048 + k * 1024); } while (0)
; #define PG8_MMA(ai, bj, At, Bt) do { __builtin_amdgcn_s_setprio(1); _Pragma("unroll") for (int k = 0; k < 2; ++k) _Pragma("unroll") for (int m = 0; m < 4; ++m) _Pragma("unroll") for (int n = 0; n < 2; ++n) \
;         acc[ai][bj][m][n] = __builtin_amdgcn_mfma_f32_16x16x32_bf16(Bt[n][k], At[m][k], acc[ai][bj][m][n], 0, 0, 0); __builtin_amdgcn_s_setprio(0); } while (0)
; #define PG8_WAIT_V(n) asm volatile("s_waitcnt vmcnt(" #n ")" ::: "memory")
; #define PG8_WAIT_L(n) asm volatile("s_waitcnt lgkmcnt(" #n ")" ::: "memory")
; #define PG8_BAR __builtin_amdgcn_s_barrier()
; #define PG8_SCHED __builtin_amdgcn_sched_barrier(0)
; template <class Epi, bool ALIGN_EPI>
; __device__ __forceinline__ void gemm_phase(LAS unsigned char* lds, const Gemm g, const StaticOrder& S, const Epi& E, const int tid) {
;     ...
;             PG8_LDB(B0, 0, 0); PG8_LDB(B1, 0, 1); PG8_SCHED; PG8_LDA(At, 0, 0); PG8_STAGE(PG8_SA(1, 1), a1 + hA, voffA);
;             PG8_WAIT_V(8); PG8_WAIT_L(0); PG8_BAR; PG8_MMA(0, 0, At, B0); PG8_MMA(0, 1, At, B1); PG8_BAR; PG8_SCHED;
;             PG8_LDA(At, 0, 1); PG8_STAGE(PG8_SB(0, 0), b2, voffB); PG8_STAGE(PG8_SB(0, 1), b2 + hB, voffB); PG8_STAGE(PG8_SA(0, 0), a2, voffA);
;             PG8_WAIT_V(8); PG8_WAIT_L(0); PG8_BAR; PG8_MMA(1, 0, At, B0); PG8_MMA(1, 1, At, B1); PG8_BAR; PG8_SCHED;
.LBB0_272:
	s_andn2_b64 vcc, exec, s[36:37]
	s_cbranch_vccnz .LBB0_276
	s_add_u32 s10, s14, 0x100
	v_lshl_add_u64 v[128:129], v[128:129], 0, s[92:93]
	s_addc_u32 s11, s15, 0
	s_mov_b32 s14, 0
	s_add_i32 s15, s14, 2
	s_cmp_eq_u32 s57, s14
	s_cselect_b64 vcc, -1, 0
	s_cselect_b32 s69, s13, s11
	s_cselect_b32 s68, s12, s10
	s_add_i32 s14, 0, 0x14000
	v_lshl_add_u64 v[130:131], v[128:129], 0, s[92:93]
	v_add_u32_e32 v142, s33, v239
	v_add_u32_e32 v158, s14, v239
	v_cndmask_b32_e32 v167, v131, v191, vcc
	v_cndmask_b32_e32 v166, v130, v190, vcc
	ds_read_b128 v[130:133], v142
	ds_read_b128 v[134:137], v142 offset:1024
	ds_read_b128 v[138:141], v142 offset:2048
	ds_read_b128 v[142:145], v142 offset:3072
	ds_read_b128 v[146:149], v158
	ds_read_b128 v[150:153], v158 offset:1024
	ds_read_b128 v[154:157], v158 offset:2048
	ds_read_b128 v[158:161], v158 offset:3072
	v_lshl_add_u64 v[220:221], v[128:129], 0, v[186:187]
	s_add_i32 m0, s51, 0xc000
	ds_read_b128 v[162:165], v171
	ds_read_b128 v[192:195], v171 offset:1024
	ds_read_b128 v[196:199], v171 offset:2048
	ds_read_b128 v[200:203], v171 offset:3072
	ds_read_b128 v[204:207], v171 offset:4096
	ds_read_b128 v[208:211], v171 offset:5120
	ds_read_b128 v[212:215], v171 offset:6144
	ds_read_b128 v[216:219], v171 offset:7168
	global_load_lds_dwordx4 v[220:221], off
	v_lshl_add_u64 v[220:221], v[128:129], 0, v[188:189]
	s_add_i32 m0, s51, 0xe000
	s_nop 0
	global_load_lds_dwordx4 v[220:221], off
	s_waitcnt vmcnt(8)
	s_waitcnt lgkmcnt(0)
	s_barrier
	s_waitcnt lgkmcnt(0)
	v_mfma_f32_16x16x32_bf16 v[124:127], v[130:133], v[162:165], 0
	v_mfma_f32_16x16x32_bf16 v[120:123], v[138:141], v[162:165], 0
	v_mfma_f32_16x16x32_bf16 v[108:111], v[130:133], v[196:199], 0
	v_mfma_f32_16x16x32_bf16 v[104:107], v[138:141], v[196:199], 0
	v_mfma_f32_16x16x32_bf16 v[92:95], v[130:133], v[204:207], 0
	v_mfma_f32_16x16x32_bf16 v[88:91], v[138:141], v[204:207], 0
	v_mfma_f32_16x16x32_bf16 v[76:79], v[130:133], v[212:215], 0
	v_mfma_f32_16x16x32_bf16 v[72:75], v[138:141], v[212:215], 0
	v_mfma_f32_16x16x32_bf16 v[124:127], v[134:137], v[192:195], v[124:127]
	v_mfma_f32_16x16x32_bf16 v[120:123], v[142:145], v[192:195], v[120:123]
	v_mfma_f32_16x16x32_bf16 v[108:111], v[134:137], v[200:203], v[108:111]
	v_mfma_f32_16x16x32_bf16 v[104:107], v[142:145], v[200:203], v[104:107]
	v_mfma_f32_16x16x32_bf16 v[92:95], v[134:137], v[208:211], v[92:95]
	v_mfma_f32_16x16x32_bf16 v[88:91], v[142:145], v[208:211], v[88:91]
	v_mfma_f32_16x16x32_bf16 v[76:79], v[134:137], v[216:219], v[76:79]
	v_mfma_f32_16x16x32_bf16 v[72:75], v[142:145], v[216:219], v[72:75]
	v_mfma_f32_16x16x32_bf16 v[116:119], v[146:149], v[162:165], 0
	v_mfma_f32_16x16x32_bf16 v[112:115], v[154:157], v[162:165], 0
	v_mfma_f32_16x16x32_bf16 v[100:103], v[146:149], v[196:199], 0
	v_mfma_f32_16x16x32_bf16 v[96:99], v[154:157], v[196:199], 0
	v_mfma_f32_16x16x32_bf16 v[84:87], v[146:149], v[204:207], 0
	v_mfma_f32_16x16x32_bf16 v[80:83], v[154:157], v[204:207], 0
	v_mfma_f32_16x16x32_bf16 v[68:71], v[146:149], v[212:215], 0
	v_mfma_f32_16x16x32_bf16 v[64:67], v[154:157], v[212:215], 0
	v_mfma_f32_16x16x32_bf16 v[116:119], v[150:153], v[192:195], v[116:119]
	v_mfma_f32_16x16x32_bf16 v[112:115], v[158:161], v[192:195], v[112:115]
	v_mfma_f32_16x16x32_bf16 v[100:103], v[150:153], v[200:203], v[100:103]
	v_mfma_f32_16x16x32_bf16 v[96:99], v[158:161], v[200:203], v[96:99]
	v_mfma_f32_16x16x32_bf16 v[84:87], v[150:153], v[208:211], v[84:87]
	v_mfma_f32_16x16x32_bf16 v[80:83], v[158:161], v[208:211], v[80:83]
	v_mfma_f32_16x16x32_bf16 v[68:71], v[150:153], v[216:219], v[68:71]
	v_mfma_f32_16x16x32_bf16 v[64:67], v[158:161], v[216:219], v[64:67]
	s_barrier
	s_add_i32 s70, s33, s47
	v_lshl_add_u64 v[220:221], s[68:69], 0, v[180:181]
	s_mov_b32 m0, s70
	ds_read_b128 v[162:165], v171 offset:16384
	ds_read_b128 v[192:195], v171 offset:17408
	ds_read_b128 v[196:199], v171 offset:18432
	ds_read_b128 v[200:203], v171 offset:19456
	ds_read_b128 v[204:207], v171 offset:20480
	ds_read_b128 v[208:211], v171 offset:21504
	ds_read_b128 v[212:215], v171 offset:22528
	ds_read_b128 v[216:219], v171 offset:23552
	global_load_lds_dwordx4 v[220:221], off
	s_add_i32 m0, s70, 0x2000
	v_lshl_add_u64 v[226:227], s[68:69], 0, v[184:185]
	s_add_u32 s68, s68, s49
	s_addc_u32 s69, s69, 0
	s_add_i32 s14, s14, s47
	global_load_lds_dwordx4 v[226:227], off
	v_lshl_add_u64 v[240:241], s[68:69], 0, v[180:181]
	s_mov_b32 m0, s14
	v_lshl_add_u64 v[242:243], s[68:69], 0, v[184:185]
	global_load_lds_dwordx4 v[240:241], off
	s_add_i32 m0, s14, 0x2000
	v_lshl_add_u64 v[244:245], v[166:167], 0, v[178:179]
	global_load_lds_dwordx4 v[242:243], off
	s_mov_b32 m0, s51
	v_lshl_add_u64 v[246:247], v[166:167], 0, v[182:183]
	global_load_lds_dwordx4 v[244:245], off
	s_mov_b32 m0, s52
	s_nop 0
	global_load_lds_dwordx4 v[246:247], off
	s_waitcnt vmcnt(8)
	s_waitcnt lgkmcnt(0)
	s_barrier
; #define PG8_STAGE(bufoff, gbase, voff) do { _Pragma("unroll") for (int _i = 0; _i < 2; ++_i) \
;         __builtin_amdgcn_global_load_lds((const unsigned*)((const char*)(gbase) + (voff)[_i]), (LAS unsigned*)(lds + (bufoff) + ldsw + _i * 8192), 16, 0, 0); } while (0)
; #define PG8_LDA(dst, b, h) do { _Pragma("unroll") for (int m = 0; m < 4; ++m) _Pragma("unroll") for (int k = 0; k < 2; ++k) dst[m][k] = *(const LAS bf16x8*)(lds + PG8_SA(b, h) + aoff + m * 2048 + k * 1024); } while (0)
; #define PG8_LDB(dst, b, h) do { _Pragma("unroll") for (int n = 0; n < 2; ++n) _Pragma("unroll") for (int k = 0; k < 2; ++k) dst[n][k] = *(const LAS bf16x8*)(lds + PG8_SB(b, h) + boff + n * 2048 + k * 1024); } while (0)
; #define PG8_MMA(ai, bj, At, Bt) do { __builtin_amdgcn_s_setprio(1); _Pragma("unroll") for (int k = 0; k < 2; ++k) _Pragma("unroll") for (int m = 0; m < 4; ++m) _Pragma("unroll") for (int n = 0; n < 2; ++n) \
;         acc[ai][bj][m][n] = __builtin_amdgcn_mfma_f32_16x16x32_bf16(Bt[n][k], At[m][k], acc[ai][bj][m][n], 0, 0, 0); __builtin_amdgcn_s_setprio(0); } while (0)
; #define PG8_WAIT_V(n) asm volatile("s_waitcnt vmcnt(" #n ")" ::: "memory")
; #define PG8_WAIT_L(n) asm volatile("s_waitcnt lgkmcnt(" #n ")" ::: "memory")
; #define PG8_BAR __builtin_amdgcn_s_barrier()
; #define PG8_SCHED __builtin_amdgcn_sched_barrier(0)
; template <class Epi, bool ALIGN_EPI>
; __device__ __forceinline__ void gemm_phase(LAS unsigned char* lds, const Gemm g, const StaticOrder& S, const Epi& E, const int tid) {
;     ...
;             PG8_WAIT_V(8); PG8_WAIT_L(0); PG8_BAR; PG8_MMA(1, 0, At, B0); PG8_MMA(1, 1, At, B1); PG8_BAR; PG8_SCHED;
;             PG8_LDB(B0, 1, 0); PG8_LDB(B1, 1, 1); PG8_SCHED; PG8_LDA(At, 1, 0); PG8_STAGE(PG8_SA(0, 1), a2 + hA, voffA);
;             PG8_WAIT_V(8); PG8_WAIT_L(0); PG8_BAR; PG8_MMA(0, 0, At, B0); PG8_MMA(0, 1, At, B1); PG8_BAR; PG8_SCHED;
	s_waitcnt lgkmcnt(0)
	v_mfma_f32_16x16x32_bf16 v[60:63], v[130:133], v[162:165], 0
	v_mfma_f32_16x16x32_bf16 v[56:59], v[138:141], v[162:165], 0
	v_mfma_f32_16x16x32_bf16 v[44:47], v[130:133], v[196:199], 0
	v_mfma_f32_16x16x32_bf16 v[40:43], v[138:141], v[196:199], 0
	v_mfma_f32_16x16x32_bf16 v[28:31], v[130:133], v[204:207], 0
	v_mfma_f32_16x16x32_bf16 v[24:27], v[138:141], v[204:207], 0
	v_mfma_f32_16x16x32_bf16 v[12:15], v[130:133], v[212:215], 0
	v_mfma_f32_16x16x32_bf16 v[8:11], v[138:141], v[212:215], 0
	v_mfma_f32_16x16x32_bf16 v[60:63], v[134:137], v[192:195], v[60:63]
	v_mfma_f32_16x16x32_bf16 v[56:59], v[142:145], v[192:195], v[56:59]
	v_mfma_f32_16x16x32_bf16 v[44:47], v[134:137], v[200:203], v[44:47]
	v_mfma_f32_16x16x32_bf16 v[40:43], v[142:145], v[200:203], v[40:43]
	v_mfma_f32_16x16x32_bf16 v[28:31], v[134:137], v[208:211], v[28:31]
	v_mfma_f32_16x16x32_bf16 v[24:27], v[142:145], v[208:211], v[24:27]
	v_mfma_f32_16x16x32_bf16 v[12:15], v[134:137], v[216:219], v[12:15]
	v_mfma_f32_16x16x32_bf16 v[8:11], v[142:145], v[216:219], v[8:11]
	v_mfma_f32_16x16x32_bf16 v[52:55], v[146:149], v[162:165], 0
	v_mfma_f32_16x16x32_bf16 v[48:51], v[154:157], v[162:165], 0
	v_mfma_f32_16x16x32_bf16 v[36:39], v[146:149], v[196:199], 0
	v_mfma_f32_16x16x32_bf16 v[32:35], v[154:157], v[196:199], 0
	v_mfma_f32_16x16x32_bf16 v[20:23], v[146:149], v[204:207], 0
	v_mfma_f32_16x16x32_bf16 v[16:19], v[154:157], v[204:207], 0
	v_mfma_f32_16x16x32_bf16 v[4:7], v[146:149], v[212:215], 0
	v_mfma_f32_16x16x32_bf16 v[0:3], v[154:157], v[212:215], 0
	v_mfma_f32_16x16x32_bf16 v[52:55], v[150:153], v[192:195], v[52:55]
	v_mfma_f32_16x16x32_bf16 v[48:51], v[158:161], v[192:195], v[48:51]
	v_mfma_f32_16x16x32_bf16 v[36:39], v[150:153], v[200:203], v[36:39]
	v_mfma_f32_16x16x32_bf16 v[32:35], v[158:161], v[200:203], v[32:35]
	v_mfma_f32_16x16x32_bf16 v[20:23], v[150:153], v[208:211], v[20:23]
	v_mfma_f32_16x16x32_bf16 v[16:19], v[158:161], v[208:211], v[16:19]
	v_mfma_f32_16x16x32_bf16 v[4:7], v[150:153], v[216:219], v[4:7]
	v_mfma_f32_16x16x32_bf16 v[0:3], v[158:161], v[216:219], v[0:3]
	s_barrier
	s_add_i32 s14, 0, 0x18000
	s_add_i32 s68, 0, 0x1c000
	v_add_u32_e32 v142, s14, v239
	v_add_u32_e32 v158, s68, v239
	ds_read_b128 v[130:133], v142
	ds_read_b128 v[134:137], v142 offset:1024
	ds_read_b128 v[138:141], v142 offset:2048
	ds_read_b128 v[142:145], v142 offset:3072
	ds_read_b128 v[146:149], v158
	ds_read_b128 v[150:153], v158 offset:1024
	ds_read_b128 v[154:157], v158 offset:2048
	ds_read_b128 v[158:161], v158 offset:3072
	v_lshl_add_u64 v[166:167], v[166:167], 0, s[94:95]
	s_mov_b32 m0, s53
	v_lshl_add_u64 v[248:249], v[166:167], 0, v[178:179]
	ds_read_b128 v[162:165], v171 offset:32768
	ds_read_b128 v[192:195], v171 offset:33792
	ds_read_b128 v[196:199], v171 offset:34816
	ds_read_b128 v[200:203], v171 offset:35840
	ds_read_b128 v[204:207], v171 offset:36864
	ds_read_b128 v[208:211], v171 offset:37888
	ds_read_b128 v[212:215], v171 offset:38912
	ds_read_b128 v[216:219], v171 offset:39936
	global_load_lds_dwordx4 v[248:249], off
	v_lshl_add_u64 v[166:167], v[166:167], 0, v[182:183]
	s_mov_b32 m0, s54
	s_nop 0
	global_load_lds_dwordx4 v[166:167], off
	s_waitcnt vmcnt(8)
	s_waitcnt lgkmcnt(0)
	s_barrier
	s_waitcnt lgkmcnt(0)
	v_mfma_f32_16x16x32_bf16 v[124:127], v[130:133], v[162:165], v[124:127]
	v_mfma_f32_16x16x32_bf16 v[120:123], v[138:141], v[162:165], v[120:123]
	v_mfma_f32_16x16x32_bf16 v[108:111], v[130:133], v[196:199], v[108:111]
	v_mfma_f32_16x16x32_bf16 v[104:107], v[138:141], v[196:199], v[104:107]
	v_mfma_f32_16x16x32_bf16 v[92:95], v[130:133], v[204:207], v[92:95]
	v_mfma_f32_16x16x32_bf16 v[88:91], v[138:141], v[204:207], v[88:91]
	v_mfma_f32_16x16x32_bf16 v[76:79], v[130:133], v[212:215], v[76:79]
	v_mfma_f32_16x16x32_bf16 v[72:75], v[138:141], v[212:215], v[72:75]
	v_mfma_f32_16x16x32_bf16 v[124:127], v[134:137], v[192:195], v[124:127]
	v_mfma_f32_16x16x32_bf16 v[120:123], v[142:145], v[192:195], v[120:123]
	v_mfma_f32_16x16x32_bf16 v[108:111], v[134:137], v[200:203], v[108:111]
	v_mfma_f32_16x16x32_bf16 v[104:107], v[142:145], v[200:203], v[104:107]
	v_mfma_f32_16x16x32_bf16 v[92:95], v[134:137], v[208:211], v[92:95]
	v_mfma_f32_16x16x32_bf16 v[88:91], v[142:145], v[208:211], v[88:91]
	v_mfma_f32_16x16x32_bf16 v[76:79], v[134:137], v[216:219], v[76:79]
	v_mfma_f32_16x16x32_bf16 v[72:75], v[142:145], v[216:219], v[72:75]
	v_mfma_f32_16x16x32_bf16 v[116:119], v[146:149], v[162:165], v[116:119]
	v_mfma_f32_16x16x32_bf16 v[112:115], v[154:157], v[162:165], v[112:115]
	v_mfma_f32_16x16x32_bf16 v[100:103], v[146:149], v[196:199], v[100:103]
	v_mfma_f32_16x16x32_bf16 v[96:99], v[154:157], v[196:199], v[96:99]
	v_mfma_f32_16x16x32_bf16 v[84:87], v[146:149], v[204:207], v[84:87]
	v_mfma_f32_16x16x32_bf16 v[80:83], v[154:157], v[204:207], v[80:83]
	v_mfma_f32_16x16x32_bf16 v[68:71], v[146:149], v[212:215], v[68:71]
	v_mfma_f32_16x16x32_bf16 v[64:67], v[154:157], v[212:215], v[64:67]
	v_mfma_f32_16x16x32_bf16 v[116:119], v[150:153], v[192:195], v[116:119]
	v_mfma_f32_16x16x32_bf16 v[112:115], v[158:161], v[192:195], v[112:115]
	v_mfma_f32_16x16x32_bf16 v[100:103], v[150:153], v[200:203], v[100:103]
	v_mfma_f32_16x16x32_bf16 v[96:99], v[158:161], v[200:203], v[96:99]
	v_mfma_f32_16x16x32_bf16 v[84:87], v[150:153], v[208:211], v[84:87]
	v_mfma_f32_16x16x32_bf16 v[80:83], v[158:161], v[208:211], v[80:83]
	v_mfma_f32_16x16x32_bf16 v[68:71], v[150:153], v[216:219], v[68:71]
	v_mfma_f32_16x16x32_bf16 v[64:67], v[158:161], v[216:219], v[64:67]
	s_barrier
; #define PG8_STAGE(bufoff, gbase, voff) do { _Pragma("unroll") for (int _i = 0; _i < 2; ++_i) \
;         __builtin_amdgcn_global_load_lds((const unsigned*)((const char*)(gbase) + (voff)[_i]), (LAS unsigned*)(lds + (bufoff) + ldsw + _i * 8192), 16, 0, 0); } while (0)
; #define PG8_LDA(dst, b, h) do { _Pragma("unroll") for (int m = 0; m < 4; ++m) _Pragma("unroll") for (int k = 0; k < 2; ++k) dst[m][k] = *(const LAS bf16x8*)(lds + PG8_SA(b, h) + aoff + m * 2048 + k * 1024); } while (0)
; #define PG8_LDB(dst, b, h) do { _Pragma("unroll") for (int n = 0; n < 2; ++n) _Pragma("unroll") for (int k = 0; k < 2; ++k) dst[n][k] = *(const LAS bf16x8*)(lds + PG8_SB(b, h) + boff + n * 2048 + k * 1024); } while (0)
; #define PG8_WAIT_V(n) asm volatile("s_waitcnt vmcnt(" #n ")" ::: "memory")
; #define PG8_BAR __builtin_amdgcn_s_barrier()
; template <class Epi, bool ALIGN_EPI>
; __device__ __forceinline__ void gemm_phase(LAS unsigned char* lds, const Gemm g, const StaticOrder& S, const Epi& E, const int tid) {
;     ...
;         for (int t = 0; t < nt; t += 2) {
;             const bool last = (t == nt - 2);
;             const char* a1 = cA + (size_t)(t + 1) * kstep;
;             const char* a2 = last ? nA : cA + (size_t)(t + 2) * kstep; const char* b2 = last ? nB : cB + (size_t)(t + 2) * kstep;
;             const char* a3 = a2 + kstep; const char* b3 = b2 + kstep;
;             PG8_LDB(B0, 0, 0); PG8_LDB(B1, 0, 1); PG8_SCHED; PG8_LDA(At, 0, 0); PG8_STAGE(PG8_SA(1, 1), a1 + hA, voffA);
;             PG8_WAIT_V(8); PG8_WAIT_L(0); PG8_BAR; PG8_MMA(0, 0, At, B0); PG8_MMA(0, 1, At, B1); PG8_BAR; PG8_SCHED;
;             PG8_LDA(At, 0, 1); PG8_STAGE(PG8_SB(0, 0), b2, voffB); PG8_STAGE(PG8_SB(0, 1), b2 + hB, voffB); PG8_STAGE(PG8_SA(0, 0), a2, voffA);
;             PG8_WAIT_V(8); PG8_WAIT_L(0); PG8_BAR; PG8_MMA(1, 0, At, B0); PG8_MMA(1, 1, At, B1); PG8_BAR; PG8_SCHED;
;             PG8_LDB(B0, 1, 0); PG8_LDB(B1, 1, 1); PG8_SCHED; PG8_LDA(At, 1, 0); PG8_STAGE(PG8_SA(0, 1), a2 + hA, voffA);
;             PG8_WAIT_V(8); PG8_WAIT_L(0); PG8_BAR; PG8_MMA(0, 0, At, B0); PG8_MMA(0, 1, At, B1); PG8_BAR; PG8_SCHED;
;             PG8_LDA(At, 1, 1); PG8_STAGE(PG8_SB(1, 0), b3, voffB); PG8_STAGE(PG8_SB(1, 1), b3 + hB, voffB); PG8_STAGE(PG8_SA(1, 0), a3, voffA);
;             PG8_WAIT_V(8); PG8_WAIT_L(0); PG8_BAR; PG8_MMA(1, 0, At, B0); PG8_MMA(1, 1, At, B1); PG8_BAR; PG8_SCHED;
	s_add_i32 s14, s14, s47
	v_lshl_add_u64 v[166:167], v[220:221], 0, s[92:93]
	s_mov_b32 m0, s14
	ds_read_b128 v[162:165], v171 offset:49152
	ds_read_b128 v[192:195], v171 offset:50176
	ds_read_b128 v[196:199], v171 offset:51200
	ds_read_b128 v[200:203], v171 offset:52224
	ds_read_b128 v[204:207], v171 offset:53248
	ds_read_b128 v[208:211], v171 offset:54272
	ds_read_b128 v[212:215], v171 offset:55296
	ds_read_b128 v[216:219], v171 offset:56320
	global_load_lds_dwordx4 v[166:167], off
	v_lshl_add_u64 v[166:167], v[226:227], 0, s[92:93]
	s_add_i32 m0, s14, 0x2000
	s_add_i32 s14, s68, s47
	global_load_lds_dwordx4 v[166:167], off
	v_lshl_add_u64 v[166:167], v[240:241], 0, s[92:93]
	s_mov_b32 m0, s14
	s_nop 0
	global_load_lds_dwordx4 v[166:167], off
	v_lshl_add_u64 v[166:167], v[242:243], 0, s[92:93]
	s_add_i32 m0, s14, 0x2000
	s_nop 0
	global_load_lds_dwordx4 v[166:167], off
	v_lshl_add_u64 v[166:167], v[244:245], 0, s[92:93]
	s_mov_b32 m0, s55
	s_nop 0
	global_load_lds_dwordx4 v[166:167], off
	v_lshl_add_u64 v[166:167], v[246:247], 0, s[92:93]
	s_mov_b32 m0, s56
	s_nop 0
	global_load_lds_dwordx4 v[166:167], off
	s_waitcnt vmcnt(8)
	s_waitcnt lgkmcnt(0)
	s_barrier
	s_waitcnt lgkmcnt(0)
	v_mfma_f32_16x16x32_bf16 v[60:63], v[130:133], v[162:165], v[60:63]
	v_mfma_f32_16x16x32_bf16 v[56:59], v[138:141], v[162:165], v[56:59]
	v_mfma_f32_16x16x32_bf16 v[44:47], v[130:133], v[196:199], v[44:47]
	v_mfma_f32_16x16x32_bf16 v[40:43], v[138:141], v[196:199], v[40:43]
	v_mfma_f32_16x16x32_bf16 v[28:31], v[130:133], v[204:207], v[28:31]
	v_mfma_f32_16x16x32_bf16 v[24:27], v[138:141], v[204:207], v[24:27]
	v_mfma_f32_16x16x32_bf16 v[12:15], v[130:133], v[212:215], v[12:15]
	v_mfma_f32_16x16x32_bf16 v[8:11], v[138:141], v[212:215], v[8:11]
	v_mfma_f32_16x16x32_bf16 v[60:63], v[134:137], v[192:195], v[60:63]
	v_mfma_f32_16x16x32_bf16 v[56:59], v[142:145], v[192:195], v[56:59]
	v_mfma_f32_16x16x32_bf16 v[44:47], v[134:137], v[200:203], v[44:47]
	v_mfma_f32_16x16x32_bf16 v[40:43], v[142:145], v[200:203], v[40:43]
	v_mfma_f32_16x16x32_bf16 v[28:31], v[134:137], v[208:211], v[28:31]
	v_mfma_f32_16x16x32_bf16 v[24:27], v[142:145], v[208:211], v[24:27]
	v_mfma_f32_16x16x32_bf16 v[12:15], v[134:137], v[216:219], v[12:15]
	v_mfma_f32_16x16x32_bf16 v[8:11], v[142:145], v[216:219], v[8:11]
	v_mfma_f32_16x16x32_bf16 v[52:55], v[146:149], v[162:165], v[52:55]
	v_mfma_f32_16x16x32_bf16 v[48:51], v[154:157], v[162:165], v[48:51]
	v_mfma_f32_16x16x32_bf16 v[36:39], v[146:149], v[196:199], v[36:39]
	v_mfma_f32_16x16x32_bf16 v[32:35], v[154:157], v[196:199], v[32:35]
	v_mfma_f32_16x16x32_bf16 v[20:23], v[146:149], v[204:207], v[20:23]
	v_mfma_f32_16x16x32_bf16 v[16:19], v[154:157], v[204:207], v[16:19]
	v_mfma_f32_16x16x32_bf16 v[4:7], v[146:149], v[212:215], v[4:7]
	v_mfma_f32_16x16x32_bf16 v[0:3], v[154:157], v[212:215], v[0:3]
	v_mfma_f32_16x16x32_bf16 v[52:55], v[150:153], v[192:195], v[52:55]
	v_mfma_f32_16x16x32_bf16 v[48:51], v[158:161], v[192:195], v[48:51]
	v_mfma_f32_16x16x32_bf16 v[36:39], v[150:153], v[200:203], v[36:39]
	v_mfma_f32_16x16x32_bf16 v[32:35], v[158:161], v[200:203], v[32:35]
	v_mfma_f32_16x16x32_bf16 v[20:23], v[150:153], v[208:211], v[20:23]
	v_mfma_f32_16x16x32_bf16 v[16:19], v[158:161], v[208:211], v[16:19]
	v_mfma_f32_16x16x32_bf16 v[4:7], v[150:153], v[216:219], v[4:7]
	v_mfma_f32_16x16x32_bf16 v[0:3], v[158:161], v[216:219], v[0:3]
	s_barrier
	s_add_u32 s10, s10, 0x100
	s_addc_u32 s11, s11, 0
	v_lshl_add_u64 v[128:129], v[128:129], 0, s[80:81]
	s_cmp_ge_u32 s15, s48
	s_mov_b32 s14, s15
	s_cbranch_scc1 .Lpl2_after
.LBB0_274:
	s_add_i32 s15, s14, 2
	s_cmp_eq_u32 s57, s14
	s_cselect_b64 vcc, -1, 0
	s_cselect_b32 s69, s13, s11
	s_cselect_b32 s68, s12, s10
	s_add_i32 s14, 0, 0x14000
	v_lshl_add_u64 v[130:131], v[128:129], 0, s[92:93]
	v_add_u32_e32 v142, s33, v239
	v_add_u32_e32 v158, s14, v239
	v_cndmask_b32_e32 v167, v131, v191, vcc
	v_cndmask_b32_e32 v166, v130, v190, vcc
	ds_read_b128 v[130:133], v142
	ds_read_b128 v[134:137], v142 offset:1024
	ds_read_b128 v[138:141], v142 offset:2048
	ds_read_b128 v[142:145], v142 offset:3072
	ds_read_b128 v[146:149], v158
	ds_read_b128 v[150:153], v158 offset:1024
	ds_read_b128 v[154:157], v158 offset:2048
	ds_read_b128 v[158:161], v158 offset:3072
	v_lshl_add_u64 v[220:221], v[128:129], 0, v[186:187]
	s_add_i32 m0, s51, 0xc000
	ds_read_b128 v[162:165], v171
	ds_read_b128 v[192:195], v171 offset:1024
	ds_read_b128 v[196:199], v171 offset:2048
	ds_read_b128 v[200:203], v171 offset:3072
	ds_read_b128 v[204:207], v171 offset:4096
	ds_read_b128 v[208:211], v171 offset:5120
	ds_read_b128 v[212:215], v171 offset:6144
	ds_read_b128 v[216:219], v171 offset:7168
	global_load_lds_dwordx4 v[220:221], off
	v_lshl_add_u64 v[220:221], v[128:129], 0, v[188:189]
	s_add_i32 m0, s51, 0xe000
	s_nop 0
	global_load_lds_dwordx4 v[220:221], off
	s_waitcnt vmcnt(8)
	s_waitcnt lgkmcnt(0)
	s_barrier
; #define PG8_STAGE(bufoff, gbase, voff) do { _Pragma("unroll") for (int _i = 0; _i < 2; ++_i) \
;         __builtin_amdgcn_global_load_lds((const unsigned*)((const char*)(gbase) + (voff)[_i]), (LAS unsigned*)(lds + (bufoff) + ldsw + _i * 8192), 16, 0, 0); } while (0)
; #define PG8_LDA(dst, b, h) do { _Pragma("unroll") for (int m = 0; m < 4; ++m) _Pragma("unroll") for (int k = 0; k < 2; ++k) dst[m][k] = *(const LAS bf16x8*)(lds + PG8_SA(b, h) + aoff + m * 2048 + k * 1024); } while (0)
; #define PG8_MMA(ai, bj, At, Bt) do { __builtin_amdgcn_s_setprio(1); _Pragma("unroll") for (int k = 0; k < 2; ++k) _Pragma("unroll") for (int m = 0; m < 4; ++m) _Pragma("unroll") for (int n = 0; n < 2; ++n) \
;         acc[ai][bj][m][n] = __builtin_amdgcn_mfma_f32_16x16x32_bf16(Bt[n][k], At[m][k], acc[ai][bj][m][n], 0, 0, 0); __builtin_amdgcn_s_setprio(0); } while (0)
; #define PG8_WAIT_V(n) asm volatile("s_waitcnt vmcnt(" #n ")" ::: "memory")
; #define PG8_WAIT_L(n) asm volatile("s_waitcnt lgkmcnt(" #n ")" ::: "memory")
; #define PG8_BAR __builtin_amdgcn_s_barrier()
; #define PG8_SCHED __builtin_amdgcn_sched_barrier(0)
; template <class Epi, bool ALIGN_EPI>
; __device__ __forceinline__ void gemm_phase(LAS unsigned char* lds, const Gemm g, const StaticOrder& S, const Epi& E, const int tid) {
;     ...
;             PG8_WAIT_V(8); PG8_WAIT_L(0); PG8_BAR; PG8_MMA(0, 0, At, B0); PG8_MMA(0, 1, At, B1); PG8_BAR; PG8_SCHED;
;             PG8_LDA(At, 0, 1); PG8_STAGE(PG8_SB(0, 0), b2, voffB); PG8_STAGE(PG8_SB(0, 1), b2 + hB, voffB); PG8_STAGE(PG8_SA(0, 0), a2, voffA);
;             PG8_WAIT_V(8); PG8_WAIT_L(0); PG8_BAR; PG8_MMA(1, 0, At, B0); PG8_MMA(1, 1, At, B1); PG8_BAR; PG8_SCHED;
	s_waitcnt lgkmcnt(0)
	v_mfma_f32_16x16x32_bf16 v[124:127], v[130:133], v[162:165], v[124:127]
	v_mfma_f32_16x16x32_bf16 v[120:123], v[138:141], v[162:165], v[120:123]
	v_mfma_f32_16x16x32_bf16 v[108:111], v[130:133], v[196:199], v[108:111]
	v_mfma_f32_16x16x32_bf16 v[104:107], v[138:141], v[196:199], v[104:107]
	v_mfma_f32_16x16x32_bf16 v[92:95], v[130:133], v[204:207], v[92:95]
	v_mfma_f32_16x16x32_bf16 v[88:91], v[138:141], v[204:207], v[88:91]
	v_mfma_f32_16x16x32_bf16 v[76:79], v[130:133], v[212:215], v[76:79]
	v_mfma_f32_16x16x32_bf16 v[72:75], v[138:141], v[212:215], v[72:75]
	v_mfma_f32_16x16x32_bf16 v[124:127], v[134:137], v[192:195], v[124:127]
	v_mfma_f32_16x16x32_bf16 v[120:123], v[142:145], v[192:195], v[120:123]
	v_mfma_f32_16x16x32_bf16 v[108:111], v[134:137], v[200:203], v[108:111]
	v_mfma_f32_16x16x32_bf16 v[104:107], v[142:145], v[200:203], v[104:107]
	v_mfma_f32_16x16x32_bf16 v[92:95], v[134:137], v[208:211], v[92:95]
	v_mfma_f32_16x16x32_bf16 v[88:91], v[142:145], v[208:211], v[88:91]
	v_mfma_f32_16x16x32_bf16 v[76:79], v[134:137], v[216:219], v[76:79]
	v_mfma_f32_16x16x32_bf16 v[72:75], v[142:145], v[216:219], v[72:75]
	v_mfma_f32_16x16x32_bf16 v[116:119], v[146:149], v[162:165], v[116:119]
	v_mfma_f32_16x16x32_bf16 v[112:115], v[154:157], v[162:165], v[112:115]
	v_mfma_f32_16x16x32_bf16 v[100:103], v[146:149], v[196:199], v[100:103]
	v_mfma_f32_16x16x32_bf16 v[96:99], v[154:157], v[196:199], v[96:99]
	v_mfma_f32_16x16x32_bf16 v[84:87], v[146:149], v[204:207], v[84:87]
	v_mfma_f32_16x16x32_bf16 v[80:83], v[154:157], v[204:207], v[80:83]
	v_mfma_f32_16x16x32_bf16 v[68:71], v[146:149], v[212:215], v[68:71]
	v_mfma_f32_16x16x32_bf16 v[64:67], v[154:157], v[212:215], v[64:67]
	v_mfma_f32_16x16x32_bf16 v[116:119], v[150:153], v[192:195], v[116:119]
	v_mfma_f32_16x16x32_bf16 v[112:115], v[158:161], v[192:195], v[112:115]
	v_mfma_f32_16x16x32_bf16 v[100:103], v[150:153], v[200:203], v[100:103]
	v_mfma_f32_16x16x32_bf16 v[96:99], v[158:161], v[200:203], v[96:99]
	v_mfma_f32_16x16x32_bf16 v[84:87], v[150:153], v[208:211], v[84:87]
	v_mfma_f32_16x16x32_bf16 v[80:83], v[158:161], v[208:211], v[80:83]
	v_mfma_f32_16x16x32_bf16 v[68:71], v[150:153], v[216:219], v[68:71]
	v_mfma_f32_16x16x32_bf16 v[64:67], v[158:161], v[216:219], v[64:67]
	s_barrier
	s_add_i32 s70, s33, s47
	v_lshl_add_u64 v[220:221], s[68:69], 0, v[180:181]
	s_mov_b32 m0, s70
	ds_read_b128 v[162:165], v171 offset:16384
	ds_read_b128 v[192:195], v171 offset:17408
	ds_read_b128 v[196:199], v171 offset:18432
	ds_read_b128 v[200:203], v171 offset:19456
	ds_read_b128 v[204:207], v171 offset:20480
	ds_read_b128 v[208:211], v171 offset:21504
	ds_read_b128 v[212:215], v171 offset:22528
	ds_read_b128 v[216:219], v171 offset:23552
	global_load_lds_dwordx4 v[220:221], off
	s_add_i32 m0, s70, 0x2000
	v_lshl_add_u64 v[226:227], s[68:69], 0, v[184:185]
	s_add_u32 s68, s68, s49
	s_addc_u32 s69, s69, 0
	s_add_i32 s14, s14, s47
	global_load_lds_dwordx4 v[226:227], off
	v_lshl_add_u64 v[240:241], s[68:69], 0, v[180:181]
	s_mov_b32 m0, s14
	v_lshl_add_u64 v[242:243], s[68:69], 0, v[184:185]
	global_load_lds_dwordx4 v[240:241], off
	s_add_i32 m0, s14, 0x2000
	v_lshl_add_u64 v[244:245], v[166:167], 0, v[178:179]
	global_load_lds_dwordx4 v[242:243], off
	s_mov_b32 m0, s51
	v_lshl_add_u64 v[246:247], v[166:167], 0, v[182:183]
	global_load_lds_dwordx4 v[244:245], off
	s_mov_b32 m0, s52
	s_nop 0
	global_load_lds_dwordx4 v[246:247], off
	s_waitcnt vmcnt(8)
	s_waitcnt lgkmcnt(0)
	s_barrier
	s_waitcnt lgkmcnt(0)
	v_mfma_f32_16x16x32_bf16 v[60:63], v[130:133], v[162:165], v[60:63]
	v_mfma_f32_16x16x32_bf16 v[56:59], v[138:141], v[162:165], v[56:59]
	v_mfma_f32_16x16x32_bf16 v[44:47], v[130:133], v[196:199], v[44:47]
	v_mfma_f32_16x16x32_bf16 v[40:43], v[138:141], v[196:199], v[40:43]
	v_mfma_f32_16x16x32_bf16 v[28:31], v[130:133], v[204:207], v[28:31]
	v_mfma_f32_16x16x32_bf16 v[24:27], v[138:141], v[204:207], v[24:27]
	v_mfma_f32_16x16x32_bf16 v[12:15], v[130:133], v[212:215], v[12:15]
	v_mfma_f32_16x16x32_bf16 v[8:11], v[138:141], v[212:215], v[8:11]
	v_mfma_f32_16x16x32_bf16 v[60:63], v[134:137], v[192:195], v[60:63]
	v_mfma_f32_16x16x32_bf16 v[56:59], v[142:145], v[192:195], v[56:59]
	v_mfma_f32_16x16x32_bf16 v[44:47], v[134:137], v[200:203], v[44:47]
	v_mfma_f32_16x16x32_bf16 v[40:43], v[142:145], v[200:203], v[40:43]
	v_mfma_f32_16x16x32_bf16 v[28:31], v[134:137], v[208:211], v[28:31]
	v_mfma_f32_16x16x32_bf16 v[24:27], v[142:145], v[208:211], v[24:27]
	v_mfma_f32_16x16x32_bf16 v[12:15], v[134:137], v[216:219], v[12:15]
	v_mfma_f32_16x16x32_bf16 v[8:11], v[142:145], v[216:219], v[8:11]
	v_mfma_f32_16x16x32_bf16 v[52:55], v[146:149], v[162:165], v[52:55]
	v_mfma_f32_16x16x32_bf16 v[48:51], v[154:157], v[162:165], v[48:51]
	v_mfma_f32_16x16x32_bf16 v[36:39], v[146:149], v[196:199], v[36:39]
	v_mfma_f32_16x16x32_bf16 v[32:35], v[154:157], v[196:199], v[32:35]
	v_mfma_f32_16x16x32_bf16 v[20:23], v[146:149], v[204:207], v[20:23]
	v_mfma_f32_16x16x32_bf16 v[16:19], v[154:157], v[204:207], v[16:19]
	v_mfma_f32_16x16x32_bf16 v[4:7], v[146:149], v[212:215], v[4:7]
	v_mfma_f32_16x16x32_bf16 v[0:3], v[154:157], v[212:215], v[0:3]
	v_mfma_f32_16x16x32_bf16 v[52:55], v[150:153], v[192:195], v[52:55]
	v_mfma_f32_16x16x32_bf16 v[48:51], v[158:161], v[192:195], v[48:51]
	v_mfma_f32_16x16x32_bf16 v[36:39], v[150:153], v[200:203], v[36:39]
	v_mfma_f32_16x16x32_bf16 v[32:35], v[158:161], v[200:203], v[32:35]
	v_mfma_f32_16x16x32_bf16 v[20:23], v[150:153], v[208:211], v[20:23]
	v_mfma_f32_16x16x32_bf16 v[16:19], v[158:161], v[208:211], v[16:19]
	v_mfma_f32_16x16x32_bf16 v[4:7], v[150:153], v[216:219], v[4:7]
	v_mfma_f32_16x16x32_bf16 v[0:3], v[158:161], v[216:219], v[0:3]
	s_barrier
; #define PG8_STAGE(bufoff, gbase, voff) do { _Pragma("unroll") for (int _i = 0; _i < 2; ++_i) \
;         __builtin_amdgcn_global_load_lds((const unsigned*)((const char*)(gbase) + (voff)[_i]), (LAS unsigned*)(lds + (bufoff) + ldsw + _i * 8192), 16, 0, 0); } while (0)
; #define PG8_LDA(dst, b, h) do { _Pragma("unroll") for (int m = 0; m < 4; ++m) _Pragma("unroll") for (int k = 0; k < 2; ++k) dst[m][k] = *(const LAS bf16x8*)(lds + PG8_SA(b, h) + aoff + m * 2048 + k * 1024); } while (0)
; #define PG8_LDB(dst, b, h) do { _Pragma("unroll") for (int n = 0; n < 2; ++n) _Pragma("unroll") for (int k = 0; k < 2; ++k) dst[n][k] = *(const LAS bf16x8*)(lds + PG8_SB(b, h) + boff + n * 2048 + k * 1024); } while (0)
; #define PG8_MMA(ai, bj, At, Bt) do { __builtin_amdgcn_s_setprio(1); _Pragma("unroll") for (int k = 0; k < 2; ++k) _Pragma("unroll") for (int m = 0; m < 4; ++m) _Pragma("unroll") for (int n = 0; n < 2; ++n) \
;         acc[ai][bj][m][n] = __builtin_amdgcn_mfma_f32_16x16x32_bf16(Bt[n][k], At[m][k], acc[ai][bj][m][n], 0, 0, 0); __builtin_amdgcn_s_setprio(0); } while (0)
; #define PG8_WAIT_V(n) asm volatile("s_waitcnt vmcnt(" #n ")" ::: "memory")
; #define PG8_WAIT_L(n) asm volatile("s_waitcnt lgkmcnt(" #n ")" ::: "memory")
; #define PG8_BAR __builtin_amdgcn_s_barrier()
; #define PG8_SCHED __builtin_amdgcn_sched_barrier(0)
; template <class Epi, bool ALIGN_EPI>
; __device__ __forceinline__ void gemm_phase(LAS unsigned char* lds, const Gemm g, const StaticOrder& S, const Epi& E, const int tid) {
;     ...
;             PG8_LDB(B0, 1, 0); PG8_LDB(B1, 1, 1); PG8_SCHED; PG8_LDA(At, 1, 0); PG8_STAGE(PG8_SA(0, 1), a2 + hA, voffA);
;             PG8_WAIT_V(8); PG8_WAIT_L(0); PG8_BAR; PG8_MMA(0, 0, At, B0); PG8_MMA(0, 1, At, B1); PG8_BAR; PG8_SCHED;
;             PG8_LDA(At, 1, 1); PG8_STAGE(PG8_SB(1, 0), b3, voffB); PG8_STAGE(PG8_SB(1, 1), b3 + hB, voffB); PG8_STAGE(PG8_SA(1, 0), a3, voffA);
;             PG8_WAIT_V(8); PG8_WAIT_L(0); PG8_BAR; PG8_MMA(1, 0, At, B0); PG8_MMA(1, 1, At, B1); PG8_BAR; PG8_SCHED;
	s_add_i32 s14, 0, 0x18000
	s_add_i32 s68, 0, 0x1c000
	v_add_u32_e32 v142, s14, v239
	v_add_u32_e32 v158, s68, v239
	ds_read_b128 v[130:133], v142
	ds_read_b128 v[134:137], v142 offset:1024
	ds_read_b128 v[138:141], v142 offset:2048
	ds_read_b128 v[142:145], v142 offset:3072
	ds_read_b128 v[146:149], v158
	ds_read_b128 v[150:153], v158 offset:1024
	ds_read_b128 v[154:157], v158 offset:2048
	ds_read_b128 v[158:161], v158 offset:3072
	v_lshl_add_u64 v[166:167], v[166:167], 0, s[94:95]
	s_mov_b32 m0, s53
	v_lshl_add_u64 v[248:249], v[166:167], 0, v[178:179]
	ds_read_b128 v[162:165], v171 offset:32768
	ds_read_b128 v[192:195], v171 offset:33792
	ds_read_b128 v[196:199], v171 offset:34816
	ds_read_b128 v[200:203], v171 offset:35840
	ds_read_b128 v[204:207], v171 offset:36864
	ds_read_b128 v[208:211], v171 offset:37888
	ds_read_b128 v[212:215], v171 offset:38912
	ds_read_b128 v[216:219], v171 offset:39936
	global_load_lds_dwordx4 v[248:249], off
	v_lshl_add_u64 v[166:167], v[166:167], 0, v[182:183]
	s_mov_b32 m0, s54
	s_nop 0
	global_load_lds_dwordx4 v[166:167], off
	s_waitcnt vmcnt(8)
	s_waitcnt lgkmcnt(0)
	s_barrier
	s_waitcnt lgkmcnt(0)
	v_mfma_f32_16x16x32_bf16 v[124:127], v[130:133], v[162:165], v[124:127]
	v_mfma_f32_16x16x32_bf16 v[120:123], v[138:141], v[162:165], v[120:123]
	v_mfma_f32_16x16x32_bf16 v[108:111], v[130:133], v[196:199], v[108:111]
	v_mfma_f32_16x16x32_bf16 v[104:107], v[138:141], v[196:199], v[104:107]
	v_mfma_f32_16x16x32_bf16 v[92:95], v[130:133], v[204:207], v[92:95]
	v_mfma_f32_16x16x32_bf16 v[88:91], v[138:141], v[204:207], v[88:91]
	v_mfma_f32_16x16x32_bf16 v[76:79], v[130:133], v[212:215], v[76:79]
	v_mfma_f32_16x16x32_bf16 v[72:75], v[138:141], v[212:215], v[72:75]
	v_mfma_f32_16x16x32_bf16 v[124:127], v[134:137], v[192:195], v[124:127]
	v_mfma_f32_16x16x32_bf16 v[120:123], v[142:145], v[192:195], v[120:123]
	v_mfma_f32_16x16x32_bf16 v[108:111], v[134:137], v[200:203], v[108:111]
	v_mfma_f32_16x16x32_bf16 v[104:107], v[142:145], v[200:203], v[104:107]
	v_mfma_f32_16x16x32_bf16 v[92:95], v[134:137], v[208:211], v[92:95]
	v_mfma_f32_16x16x32_bf16 v[88:91], v[142:145], v[208:211], v[88:91]
	v_mfma_f32_16x16x32_bf16 v[76:79], v[134:137], v[216:219], v[76:79]
	v_mfma_f32_16x16x32_bf16 v[72:75], v[142:145], v[216:219], v[72:75]
	v_mfma_f32_16x16x32_bf16 v[116:119], v[146:149], v[162:165], v[116:119]
	v_mfma_f32_16x16x32_bf16 v[112:115], v[154:157], v[162:165], v[112:115]
	v_mfma_f32_16x16x32_bf16 v[100:103], v[146:149], v[196:199], v[100:103]
	v_mfma_f32_16x16x32_bf16 v[96:99], v[154:157], v[196:199], v[96:99]
	v_mfma_f32_16x16x32_bf16 v[84:87], v[146:149], v[204:207], v[84:87]
	v_mfma_f32_16x16x32_bf16 v[80:83], v[154:157], v[204:207], v[80:83]
	v_mfma_f32_16x16x32_bf16 v[68:71], v[146:149], v[212:215], v[68:71]
	v_mfma_f32_16x16x32_bf16 v[64:67], v[154:157], v[212:215], v[64:67]
	v_mfma_f32_16x16x32_bf16 v[116:119], v[150:153], v[192:195], v[116:119]
	v_mfma_f32_16x16x32_bf16 v[112:115], v[158:161], v[192:195], v[112:115]
	v_mfma_f32_16x16x32_bf16 v[100:103], v[150:153], v[200:203], v[100:103]
	v_mfma_f32_16x16x32_bf16 v[96:99], v[158:161], v[200:203], v[96:99]
	v_mfma_f32_16x16x32_bf16 v[84:87], v[150:153], v[208:211], v[84:87]
	v_mfma_f32_16x16x32_bf16 v[80:83], v[158:161], v[208:211], v[80:83]
	v_mfma_f32_16x16x32_bf16 v[68:71], v[150:153], v[216:219], v[68:71]
	v_mfma_f32_16x16x32_bf16 v[64:67], v[158:161], v[216:219], v[64:67]
	s_barrier
	s_add_i32 s14, s14, s47
	v_lshl_add_u64 v[166:167], v[220:221], 0, s[92:93]
	s_mov_b32 m0, s14
	ds_read_b128 v[162:165], v171 offset:49152
	ds_read_b128 v[192:195], v171 offset:50176
	ds_read_b128 v[196:199], v171 offset:51200
	ds_read_b128 v[200:203], v171 offset:52224
	ds_read_b128 v[204:207], v171 offset:53248
	ds_read_b128 v[208:211], v171 offset:54272
	ds_read_b128 v[212:215], v171 offset:55296
	ds_read_b128 v[216:219], v171 offset:56320
	global_load_lds_dwordx4 v[166:167], off
	v_lshl_add_u64 v[166:167], v[226:227], 0, s[92:93]
	s_add_i32 m0, s14, 0x2000
	s_add_i32 s14, s68, s47
	global_load_lds_dwordx4 v[166:167], off
	v_lshl_add_u64 v[166:167], v[240:241], 0, s[92:93]
	s_mov_b32 m0, s14
	s_nop 0
	global_load_lds_dwordx4 v[166:167], off
	v_lshl_add_u64 v[166:167], v[242:243], 0, s[92:93]
	s_add_i32 m0, s14, 0x2000
	s_nop 0
	global_load_lds_dwordx4 v[166:167], off
	v_lshl_add_u64 v[166:167], v[244:245], 0, s[92:93]
	s_mov_b32 m0, s55
	s_nop 0
	global_load_lds_dwordx4 v[166:167], off
	v_lshl_add_u64 v[166:167], v[246:247], 0, s[92:93]
	s_mov_b32 m0, s56
	s_nop 0
	global_load_lds_dwordx4 v[166:167], off
	s_waitcnt vmcnt(8)
	s_waitcnt lgkmcnt(0)
	s_barrier
	s_waitcnt lgkmcnt(0)
	v_mfma_f32_16x16x32_bf16 v[60:63], v[130:133], v[162:165], v[60:63]
	v_mfma_f32_16x16x32_bf16 v[56:59], v[138:141], v[162:165], v[56:59]
	v_mfma_f32_16x16x32_bf16 v[44:47], v[130:133], v[196:199], v[44:47]
	v_mfma_f32_16x16x32_bf16 v[40:43], v[138:141], v[196:199], v[40:43]
	v_mfma_f32_16x16x32_bf16 v[28:31], v[130:133], v[204:207], v[28:31]
	v_mfma_f32_16x16x32_bf16 v[24:27], v[138:141], v[204:207], v[24:27]
	v_mfma_f32_16x16x32_bf16 v[12:15], v[130:133], v[212:215], v[12:15]
	v_mfma_f32_16x16x32_bf16 v[8:11], v[138:141], v[212:215], v[8:11]
	v_mfma_f32_16x16x32_bf16 v[60:63], v[134:137], v[192:195], v[60:63]
	v_mfma_f32_16x16x32_bf16 v[56:59], v[142:145], v[192:195], v[56:59]
	v_mfma_f32_16x16x32_bf16 v[44:47], v[134:137], v[200:203], v[44:47]
	v_mfma_f32_16x16x32_bf16 v[40:43], v[142:145], v[200:203], v[40:43]
	v_mfma_f32_16x16x32_bf16 v[28:31], v[134:137], v[208:211], v[28:31]
	v_mfma_f32_16x16x32_bf16 v[24:27], v[142:145], v[208:211], v[24:27]
	v_mfma_f32_16x16x32_bf16 v[12:15], v[134:137], v[216:219], v[12:15]
	v_mfma_f32_16x16x32_bf16 v[8:11], v[142:145], v[216:219], v[8:11]
	v_mfma_f32_16x16x32_bf16 v[52:55], v[146:149], v[162:165], v[52:55]
	v_mfma_f32_16x16x32_bf16 v[48:51], v[154:157], v[162:165], v[48:51]
	v_mfma_f32_16x16x32_bf16 v[36:39], v[146:149], v[196:199], v[36:39]
	v_mfma_f32_16x16x32_bf16 v[32:35], v[154:157], v[196:199], v[32:35]
	v_mfma_f32_16x16x32_bf16 v[20:23], v[146:149], v[204:207], v[20:23]
	v_mfma_f32_16x16x32_bf16 v[16:19], v[154:157], v[204:207], v[16:19]
	v_mfma_f32_16x16x32_bf16 v[4:7], v[146:149], v[212:215], v[4:7]
	v_mfma_f32_16x16x32_bf16 v[0:3], v[154:157], v[212:215], v[0:3]
	v_mfma_f32_16x16x32_bf16 v[52:55], v[150:153], v[192:195], v[52:55]
	v_mfma_f32_16x16x32_bf16 v[48:51], v[158:161], v[192:195], v[48:51]
	v_mfma_f32_16x16x32_bf16 v[36:39], v[150:153], v[200:203], v[36:39]
	v_mfma_f32_16x16x32_bf16 v[32:35], v[158:161], v[200:203], v[32:35]
	v_mfma_f32_16x16x32_bf16 v[20:23], v[150:153], v[208:211], v[20:23]
	v_mfma_f32_16x16x32_bf16 v[16:19], v[158:161], v[208:211], v[16:19]
	v_mfma_f32_16x16x32_bf16 v[4:7], v[150:153], v[216:219], v[4:7]
	v_mfma_f32_16x16x32_bf16 v[0:3], v[158:161], v[216:219], v[0:3]
	s_barrier
	s_add_u32 s10, s10, 0x100
	s_addc_u32 s11, s11, 0
	v_lshl_add_u64 v[128:129], v[128:129], 0, s[80:81]
	s_cmp_ge_u32 s15, s48
	s_mov_b32 s14, s15
	s_cbranch_scc0 .LBB0_274

; __device__ __forceinline__ unsigned cvt_pk_bf16(float lo, float hi) { unsigned r; asm volatile("v_cvt_pk_bf16_f32 %0, %1, %2" : "=v"(r) : "v"(lo), "v"(hi)); return r; }
; __device__ __forceinline__ float siluf_(float x) { return x * sigmoidf_(x); }
; #define PG8_STAGE(bufoff, gbase, voff) do { _Pragma("unroll") for (int _i = 0; _i < 2; ++_i) \
;         __builtin_amdgcn_global_load_lds((const unsigned*)((const char*)(gbase) + (voff)[_i]), (LAS unsigned*)(lds + (bufoff) + ldsw + _i * 8192), 16, 0, 0); } while (0)
; #define PG8_LDA(dst, b, h) do { _Pragma("unroll") for (int m = 0; m < 4; ++m) _Pragma("unroll") for (int k = 0; k < 2; ++k) dst[m][k] = *(const LAS bf16x8*)(lds + PG8_SA(b, h) + aoff + m * 2048 + k * 1024); } while (0)
; #define PG8_LDB(dst, b, h) do { _Pragma("unroll") for (int n = 0; n < 2; ++n) _Pragma("unroll") for (int k = 0; k < 2; ++k) dst[n][k] = *(const LAS bf16x8*)(lds + PG8_SB(b, h) + boff + n * 2048 + k * 1024); } while (0)
; #define PG8_BAR __builtin_amdgcn_s_barrier()
;     __device__ __forceinline__ void operator()(const f32x4 (&acc)[2][2][4][2], const Unit& u, int wr, int wc, int fr, int fq) const {
;         const int row0 = u.pm * BM + wr * 64 + fr, col0 = u.pn * HALF + wc * 32 + 8 * fq;
;         float rsv[2][4]; load_rstd(rsv, ssq, row0);
; #pragma unroll
;         for (int ai = 0; ai < 2; ++ai)
; #pragma unroll
;             for (int m = 0; m < 4; ++m) { const int row = row0 + ai * HALF + m * 16; bf16_t* rowp = O + (size_t)row * ldc + col0; const float rs = rsv[ai][m];
;                 f32x4 v0, v1;
; #pragma unroll
;                 for (int j = 0; j < 4; ++j) { v0[j] = siluf_(acc[ai][0][m][0][j] * rs) * (acc[ai][1][m][0][j] * rs); v1[j] = siluf_(acc[ai][0][m][1][j] * rs) * (acc[ai][1][m][1][j] * rs); }
;                 u32x4 w; w.x = cvt_pk_bf16(v0[0], v0[1]); w.y = cvt_pk_bf16(v0[2], v0[3]); w.z = cvt_pk_bf16(v1[0], v1[1]); w.w = cvt_pk_bf16(v1[2], v1[3]);
;                 *(u32x4*)rowp = w; }
; template <class Epi, bool ALIGN_EPI>
; __device__ __forceinline__ void gemm_phase(LAS unsigned char* lds, const Gemm g, const StaticOrder& S, const Epi& E, const int tid) {
;     ...
;             PG8_LDB(B0, 0, 0); PG8_LDB(B1, 0, 1); PG8_SCHED; PG8_LDA(At, 0, 0); PG8_STAGE(PG8_SA(1, 1), a1 + hA, voffA);
;             PG8_WAIT_V(8); PG8_WAIT_L(0); PG8_BAR; PG8_MMA(0, 0, At, B0); PG8_MMA(0, 1, At, B1); PG8_BAR; PG8_SCHED;
.Lgu_first_epi:
	s_add_i32 s11, s10, 2
	s_cmp_eq_u32 s58, s10
	v_lshl_add_u64 v[146:147], v[142:143], 0, s[92:93]
	s_cselect_b64 vcc, -1, 0
	v_add_u32_e32 v150, s33, v151
	s_add_i32 s10, 0, 0x14000
	v_cndmask_b32_e32 v167, v147, v139, vcc
	v_cndmask_b32_e32 v166, v146, v138, vcc
	ds_read_b128 v[146:149], v150
	ds_read_b128 v[154:157], v150 offset:1024
	ds_read_b128 v[158:161], v150 offset:2048
	ds_read_b128 v[162:165], v150 offset:3072
	v_add_u32_e32 v150, s10, v151
	ds_read_b128 v[176:179], v150
	ds_read_b128 v[180:183], v150 offset:1024
	ds_read_b128 v[184:187], v150 offset:2048
	ds_read_b128 v[188:191], v150 offset:3072
	v_cndmask_b32_e32 v221, v145, v141, vcc
	v_cndmask_b32_e32 v220, v144, v140, vcc
	v_lshl_add_u64 v[226:227], v[142:143], 0, v[134:135]
	s_add_i32 m0, s51, 0xc000
	ds_read_b128 v[192:195], v153
	ds_read_b128 v[196:199], v153 offset:1024
	ds_read_b128 v[200:203], v153 offset:2048
	ds_read_b128 v[204:207], v153 offset:3072
	ds_read_b128 v[208:211], v153 offset:4096
	ds_read_b128 v[212:215], v153 offset:5120
	ds_read_b128 v[216:219], v153 offset:6144
	ds_read_b128 v[240:243], v153 offset:7168
	global_load_lds_dwordx4 v[226:227], off
	v_lshl_add_u64 v[226:227], v[142:143], 0, v[136:137]
	s_add_i32 m0, s51, 0xe000
	s_nop 0
	global_load_lds_dwordx4 v[226:227], off
	s_waitcnt vmcnt(12)
	s_waitcnt lgkmcnt(0)
	s_barrier
	s_waitcnt lgkmcnt(0)
	v_mfma_f32_16x16x32_bf16 v[120:123], v[146:149], v[192:195], 0
	s_lshl_b32 s98, s28, 5
	s_mov_b32 s99, 0
	s_mov_b32 s100, 0xbfb8aa3b
	s_mov_b32 s101, 0xbfb8aa3b
	v_mul_f32_e32 v56, v238, v56
	v_mul_f32_e32 v57, v238, v57
	v_mul_f32_e32 v58, v238, v58
	v_mul_f32_e32 v59, v238, v59
	v_mul_f32_e32 v60, v238, v60
	v_mul_f32_e32 v61, v238, v61
	v_mfma_f32_16x16x32_bf16 v[112:115], v[158:161], v[192:195], 0
	v_mul_f32_e32 v62, v238, v62
	v_mul_f32_e32 v63, v238, v63
	v_mul_f32_e32 v224, s100, v56
	v_mul_f32_e32 v225, s101, v57
	v_mul_f32_e32 v228, s100, v58
	v_mul_f32_e32 v229, s101, v59
	v_exp_f32_e32 v224, v224
	v_exp_f32_e32 v225, v225
	v_exp_f32_e32 v228, v228
	v_exp_f32_e32 v229, v229
	v_mfma_f32_16x16x32_bf16 v[104:107], v[146:149], v[200:203], 0
	v_add_f32_e32 v224, 1.0, v224
	v_add_f32_e32 v225, 1.0, v225
	v_add_f32_e32 v228, 1.0, v228
	v_add_f32_e32 v229, 1.0, v229
	v_rcp_f32_e32 v224, v224
	v_rcp_f32_e32 v225, v225
	v_rcp_f32_e32 v228, v228
	v_rcp_f32_e32 v229, v229
	v_nop
	v_mul_f32_e32 v56, v224, v56
	v_mfma_f32_16x16x32_bf16 v[96:99], v[158:161], v[200:203], 0
	v_mul_f32_e32 v57, v225, v57
	v_mul_f32_e32 v58, v228, v58
	v_mul_f32_e32 v59, v229, v59
	v_mul_f32_e32 v56, v60, v56
	v_mul_f32_e32 v57, v61, v57
	v_mul_f32_e32 v58, v62, v58
	v_mul_f32_e32 v59, v63, v59
	v_mul_f32_e32 v48, v238, v48
	v_mul_f32_e32 v49, v238, v49
	v_mul_f32_e32 v50, v238, v50
	v_mfma_f32_16x16x32_bf16 v[88:91], v[146:149], v[208:211], 0
	v_mul_f32_e32 v51, v238, v51
	v_mul_f32_e32 v52, v238, v52
	v_mul_f32_e32 v53, v238, v53
	v_mul_f32_e32 v54, v238, v54
	v_mul_f32_e32 v55, v238, v55
	v_mul_f32_e32 v224, s100, v48
	v_mul_f32_e32 v225, s101, v49
	v_mul_f32_e32 v228, s100, v50
	v_mul_f32_e32 v229, s101, v51
	v_exp_f32_e32 v224, v224
	v_mfma_f32_16x16x32_bf16 v[80:83], v[158:161], v[208:211], 0
	v_exp_f32_e32 v225, v225
	v_exp_f32_e32 v228, v228
	v_exp_f32_e32 v229, v229
	v_add_f32_e32 v224, 1.0, v224
	v_add_f32_e32 v225, 1.0, v225
	v_add_f32_e32 v228, 1.0, v228
	v_add_f32_e32 v229, 1.0, v229
	v_rcp_f32_e32 v224, v224
	v_rcp_f32_e32 v225, v225
	v_rcp_f32_e32 v228, v228
	v_mfma_f32_16x16x32_bf16 v[72:75], v[146:149], v[216:219], 0
	v_rcp_f32_e32 v229, v229
	v_nop
	v_mul_f32_e32 v48, v224, v48
	v_mul_f32_e32 v49, v225, v49
	v_mul_f32_e32 v50, v228, v50
	v_mul_f32_e32 v51, v229, v51
	v_mul_f32_e32 v48, v52, v48
	v_mul_f32_e32 v49, v53, v49
	v_mul_f32_e32 v50, v54, v50
	v_mul_f32_e32 v51, v55, v51
	v_mfma_f32_16x16x32_bf16 v[64:67], v[158:161], v[216:219], 0
	v_cvt_pk_bf16_f32 v56, v56, v57
	v_cvt_pk_bf16_f32 v57, v58, v59
	v_cvt_pk_bf16_f32 v58, v48, v49
	v_cvt_pk_bf16_f32 v59, v50, v51
	global_store_dwordx4 v[232:233], v[56:59], off
	v_lshl_add_u64 v[232:233], v[232:233], 0, s[98:99]
	v_mul_f32_e32 v40, v239, v40
	v_mul_f32_e32 v41, v239, v41
	v_mul_f32_e32 v42, v239, v42
	v_mul_f32_e32 v43, v239, v43
	v_mfma_f32_16x16x32_bf16 v[120:123], v[154:157], v[196:199], v[120:123]
	v_mul_f32_e32 v44, v239, v44
	v_mul_f32_e32 v45, v239, v45
	v_mul_f32_e32 v46, v239, v46
	v_mul_f32_e32 v47, v239, v47
	v_mul_f32_e32 v224, s100, v40
	v_mul_f32_e32 v225, s101, v41
	v_mul_f32_e32 v228, s100, v42
	v_mul_f32_e32 v229, s101, v43
	v_exp_f32_e32 v224, v224
	v_exp_f32_e32 v225, v225
	v_mfma_f32_16x16x32_bf16 v[112:115], v[162:165], v[196:199], v[112:115]
	v_exp_f32_e32 v228, v228
	v_exp_f32_e32 v229, v229
	v_add_f32_e32 v224, 1.0, v224
	v_add_f32_e32 v225, 1.0, v225
	v_add_f32_e32 v228, 1.0, v228
	v_add_f32_e32 v229, 1.0, v229
	v_rcp_f32_e32 v224, v224
	v_rcp_f32_e32 v225, v225
	v_rcp_f32_e32 v228, v228
	v_rcp_f32_e32 v229, v229
	v_mfma_f32_16x16x32_bf16 v[104:107], v[154:157], v[204:207], v[104:107]
	v_nop
	v_mul_f32_e32 v40, v224, v40
	v_mul_f32_e32 v41, v225, v41
	v_mul_f32_e32 v42, v228, v42
	v_mul_f32_e32 v43, v229, v43
	v_mul_f32_e32 v40, v44, v40
	v_mul_f32_e32 v41, v45, v41
	v_mul_f32_e32 v42, v46, v42
	v_mul_f32_e32 v43, v47, v43
	v_mul_f32_e32 v32, v239, v32
	v_mfma_f32_16x16x32_bf16 v[96:99], v[162:165], v[204:207], v[96:99]
	v_mul_f32_e32 v33, v239, v33
	v_mul_f32_e32 v34, v239, v34
	v_mul_f32_e32 v35, v239, v35
	v_mul_f32_e32 v36, v239, v36
	v_mul_f32_e32 v37, v239, v37
	v_mul_f32_e32 v38, v239, v38
	v_mul_f32_e32 v39, v239, v39
	v_mul_f32_e32 v224, s100, v32
	v_mul_f32_e32 v225, s101, v33
	v_mul_f32_e32 v228, s100, v34
; __device__ __forceinline__ unsigned cvt_pk_bf16(float lo, float hi) { unsigned r; asm volatile("v_cvt_pk_bf16_f32 %0, %1, %2" : "=v"(r) : "v"(lo), "v"(hi)); return r; }
; __device__ __forceinline__ float siluf_(float x) { return x * sigmoidf_(x); }
; #define PG8_MMA(ai, bj, At, Bt) do { __builtin_amdgcn_s_setprio(1); _Pragma("unroll") for (int k = 0; k < 2; ++k) _Pragma("unroll") for (int m = 0; m < 4; ++m) _Pragma("unroll") for (int n = 0; n < 2; ++n) \
;         acc[ai][bj][m][n] = __builtin_amdgcn_mfma_f32_16x16x32_bf16(Bt[n][k], At[m][k], acc[ai][bj][m][n], 0, 0, 0); __builtin_amdgcn_s_setprio(0); } while (0)
; #define PG8_WAIT_V(n) asm volatile("s_waitcnt vmcnt(" #n ")" ::: "memory")
; #define PG8_WAIT_L(n) asm volatile("s_waitcnt lgkmcnt(" #n ")" ::: "memory")
; #define PG8_BAR __builtin_amdgcn_s_barrier()
; #define PG8_SCHED __builtin_amdgcn_sched_barrier(0)
;     __device__ __forceinline__ void operator()(const f32x4 (&acc)[2][2][4][2], const Unit& u, int wr, int wc, int fr, int fq) const {
;     ...
;             for (int m = 0; m < 4; ++m) { const int row = row0 + ai * HALF + m * 16; bf16_t* rowp = O + (size_t)row * ldc + col0; const float rs = rsv[ai][m];
;                 f32x4 v0, v1;
; #pragma unroll
;                 for (int j = 0; j < 4; ++j) { v0[j] = siluf_(acc[ai][0][m][0][j] * rs) * (acc[ai][1][m][0][j] * rs); v1[j] = siluf_(acc[ai][0][m][1][j] * rs) * (acc[ai][1][m][1][j] * rs); }
;                 u32x4 w; w.x = cvt_pk_bf16(v0[0], v0[1]); w.y = cvt_pk_bf16(v0[2], v0[3]); w.z = cvt_pk_bf16(v1[0], v1[1]); w.w = cvt_pk_bf16(v1[2], v1[3]);
;                 *(u32x4*)rowp = w; }
; template <class Epi, bool ALIGN_EPI>
; __device__ __forceinline__ void gemm_phase(LAS unsigned char* lds, const Gemm g, const StaticOrder& S, const Epi& E, const int tid) {
;     ...
;             PG8_WAIT_V(8); PG8_WAIT_L(0); PG8_BAR; PG8_MMA(0, 0, At, B0); PG8_MMA(0, 1, At, B1); PG8_BAR; PG8_SCHED;
	v_mfma_f32_16x16x32_bf16 v[88:91], v[154:157], v[212:215], v[88:91]
	v_mul_f32_e32 v229, s101, v35
	v_exp_f32_e32 v224, v224
	v_exp_f32_e32 v225, v225
	v_exp_f32_e32 v228, v228
	v_exp_f32_e32 v229, v229
	v_add_f32_e32 v224, 1.0, v224
	v_add_f32_e32 v225, 1.0, v225
	v_add_f32_e32 v228, 1.0, v228
	v_add_f32_e32 v229, 1.0, v229
	v_rcp_f32_e32 v224, v224
	v_mfma_f32_16x16x32_bf16 v[80:83], v[162:165], v[212:215], v[80:83]
	v_rcp_f32_e32 v225, v225
	v_rcp_f32_e32 v228, v228
	v_rcp_f32_e32 v229, v229
	v_nop
	v_mul_f32_e32 v32, v224, v32
	v_mul_f32_e32 v33, v225, v33
	v_mul_f32_e32 v34, v228, v34
	v_mul_f32_e32 v35, v229, v35
	v_mul_f32_e32 v32, v36, v32
	v_mul_f32_e32 v33, v37, v33
	v_mfma_f32_16x16x32_bf16 v[72:75], v[154:157], v[240:243], v[72:75]
	v_mul_f32_e32 v34, v38, v34
	v_mul_f32_e32 v35, v39, v35
	v_cvt_pk_bf16_f32 v40, v40, v41
	v_cvt_pk_bf16_f32 v41, v42, v43
	v_cvt_pk_bf16_f32 v42, v32, v33
	v_cvt_pk_bf16_f32 v43, v34, v35
	global_store_dwordx4 v[232:233], v[40:43], off
	v_lshl_add_u64 v[232:233], v[232:233], 0, s[98:99]
	v_mul_f32_e32 v24, v230, v24
	v_mul_f32_e32 v25, v230, v25
	v_mfma_f32_16x16x32_bf16 v[64:67], v[162:165], v[240:243], v[64:67]
	v_mul_f32_e32 v26, v230, v26
	v_mul_f32_e32 v27, v230, v27
	v_mul_f32_e32 v28, v230, v28
	v_mul_f32_e32 v29, v230, v29
	v_mul_f32_e32 v30, v230, v30
	v_mul_f32_e32 v31, v230, v31
	v_mul_f32_e32 v224, s100, v24
	v_mul_f32_e32 v225, s101, v25
	v_mul_f32_e32 v228, s100, v26
	v_mul_f32_e32 v229, s101, v27
	v_mfma_f32_16x16x32_bf16 v[124:127], v[176:179], v[192:195], 0
	v_exp_f32_e32 v224, v224
	v_exp_f32_e32 v225, v225
	v_exp_f32_e32 v228, v228
	v_exp_f32_e32 v229, v229
	v_add_f32_e32 v224, 1.0, v224
	v_add_f32_e32 v225, 1.0, v225
	v_add_f32_e32 v228, 1.0, v228
	v_add_f32_e32 v229, 1.0, v229
	v_rcp_f32_e32 v224, v224
	v_rcp_f32_e32 v225, v225
	v_mfma_f32_16x16x32_bf16 v[116:119], v[184:187], v[192:195], 0
	v_rcp_f32_e32 v228, v228
	v_rcp_f32_e32 v229, v229
	v_nop
	v_mul_f32_e32 v24, v224, v24
	v_mul_f32_e32 v25, v225, v25
	v_mul_f32_e32 v26, v228, v26
	v_mul_f32_e32 v27, v229, v27
	v_mul_f32_e32 v24, v28, v24
	v_mul_f32_e32 v25, v29, v25
	v_mul_f32_e32 v26, v30, v26
	v_mfma_f32_16x16x32_bf16 v[108:111], v[176:179], v[200:203], 0
	v_mul_f32_e32 v27, v31, v27
	v_mul_f32_e32 v16, v230, v16
	v_mul_f32_e32 v17, v230, v17
	v_mul_f32_e32 v18, v230, v18
	v_mul_f32_e32 v19, v230, v19
	v_mul_f32_e32 v20, v230, v20
	v_mul_f32_e32 v21, v230, v21
	v_mul_f32_e32 v22, v230, v22
	v_mul_f32_e32 v23, v230, v23
	v_mul_f32_e32 v224, s100, v16
	v_mfma_f32_16x16x32_bf16 v[100:103], v[184:187], v[200:203], 0
	v_mul_f32_e32 v225, s101, v17
	v_mul_f32_e32 v228, s100, v18
	v_mul_f32_e32 v229, s101, v19
	v_exp_f32_e32 v224, v224
	v_exp_f32_e32 v225, v225
	v_exp_f32_e32 v228, v228
	v_exp_f32_e32 v229, v229
	v_add_f32_e32 v224, 1.0, v224
	v_add_f32_e32 v225, 1.0, v225
	v_add_f32_e32 v228, 1.0, v228
	v_mfma_f32_16x16x32_bf16 v[92:95], v[176:179], v[208:211], 0
	v_add_f32_e32 v229, 1.0, v229
	v_rcp_f32_e32 v224, v224
	v_rcp_f32_e32 v225, v225
	v_rcp_f32_e32 v228, v228
	v_rcp_f32_e32 v229, v229
	v_nop
	v_mul_f32_e32 v16, v224, v16
	v_mul_f32_e32 v17, v225, v17
	v_mul_f32_e32 v18, v228, v18
	v_mul_f32_e32 v19, v229, v19
	v_mfma_f32_16x16x32_bf16 v[84:87], v[184:187], v[208:211], 0
	v_mul_f32_e32 v16, v20, v16
	v_mul_f32_e32 v17, v21, v17
	v_mul_f32_e32 v18, v22, v18
	v_mul_f32_e32 v19, v23, v19
	v_cvt_pk_bf16_f32 v24, v24, v25
	v_cvt_pk_bf16_f32 v25, v26, v27
	v_cvt_pk_bf16_f32 v26, v16, v17
	v_cvt_pk_bf16_f32 v27, v18, v19
	global_store_dwordx4 v[232:233], v[24:27], off
	v_lshl_add_u64 v[232:233], v[232:233], 0, s[98:99]
	v_mfma_f32_16x16x32_bf16 v[76:79], v[176:179], v[216:219], 0
	v_mul_f32_e32 v8, v231, v8
	v_mul_f32_e32 v9, v231, v9
	v_mul_f32_e32 v10, v231, v10
	v_mul_f32_e32 v11, v231, v11
	v_mul_f32_e32 v12, v231, v12
	v_mul_f32_e32 v13, v231, v13
	v_mul_f32_e32 v14, v231, v14
	v_mul_f32_e32 v15, v231, v15
	v_mul_f32_e32 v224, s100, v8
	v_mul_f32_e32 v225, s101, v9
	v_mfma_f32_16x16x32_bf16 v[68:71], v[184:187], v[216:219], 0
	v_mul_f32_e32 v228, s100, v10
	v_mul_f32_e32 v229, s101, v11
	v_exp_f32_e32 v224, v224
	v_exp_f32_e32 v225, v225
	v_exp_f32_e32 v228, v228
	v_exp_f32_e32 v229, v229
	v_add_f32_e32 v224, 1.0, v224
	v_add_f32_e32 v225, 1.0, v225
	v_add_f32_e32 v228, 1.0, v228
	v_add_f32_e32 v229, 1.0, v229
	v_mfma_f32_16x16x32_bf16 v[124:127], v[180:183], v[196:199], v[124:127]
	v_rcp_f32_e32 v224, v224
	v_rcp_f32_e32 v225, v225
	v_rcp_f32_e32 v228, v228
	v_rcp_f32_e32 v229, v229
	v_nop
	v_mul_f32_e32 v8, v224, v8
	v_mul_f32_e32 v9, v225, v9
	v_mul_f32_e32 v10, v228, v10
	v_mul_f32_e32 v11, v229, v11
	v_mul_f32_e32 v8, v12, v8
	v_mfma_f32_16x16x32_bf16 v[116:119], v[188:191], v[196:199], v[116:119]
	v_mul_f32_e32 v9, v13, v9
	v_mul_f32_e32 v10, v14, v10
	v_mul_f32_e32 v11, v15, v11
	v_mul_f32_e32 v4, v231, v4
	v_mul_f32_e32 v5, v231, v5
	v_mul_f32_e32 v6, v231, v6
	v_mul_f32_e32 v7, v231, v7
	v_mul_f32_e32 v0, v231, v0
	v_mul_f32_e32 v1, v231, v1
	v_mul_f32_e32 v2, v231, v2
	v_mfma_f32_16x16x32_bf16 v[108:111], v[180:183], v[204:207], v[108:111]
	v_mul_f32_e32 v3, v231, v3
	v_mul_f32_e32 v224, s100, v4
	v_mul_f32_e32 v225, s101, v5
	v_mul_f32_e32 v228, s100, v6
	v_mul_f32_e32 v229, s101, v7
	v_exp_f32_e32 v224, v224
	v_exp_f32_e32 v225, v225
	v_exp_f32_e32 v228, v228
	v_exp_f32_e32 v229, v229
	v_add_f32_e32 v224, 1.0, v224
	v_mfma_f32_16x16x32_bf16 v[100:103], v[188:191], v[204:207], v[100:103]
	v_add_f32_e32 v225, 1.0, v225
	v_add_f32_e32 v228, 1.0, v228
	v_add_f32_e32 v229, 1.0, v229
	v_rcp_f32_e32 v224, v224
	v_rcp_f32_e32 v225, v225
	v_rcp_f32_e32 v228, v228
	v_rcp_f32_e32 v229, v229
	v_nop
	v_mul_f32_e32 v4, v224, v4
	v_mul_f32_e32 v5, v225, v5
	v_mfma_f32_16x16x32_bf16 v[92:95], v[180:183], v[212:215], v[92:95]
	v_mul_f32_e32 v6, v228, v6
	v_mul_f32_e32 v7, v229, v7
	v_mul_f32_e32 v4, v0, v4
	v_mul_f32_e32 v5, v1, v5
	v_mul_f32_e32 v6, v2, v6
	v_mul_f32_e32 v7, v3, v7
	v_cvt_pk_bf16_f32 v8, v8, v9
	v_cvt_pk_bf16_f32 v9, v10, v11
	v_cvt_pk_bf16_f32 v10, v4, v5
	v_cvt_pk_bf16_f32 v11, v6, v7
	v_mfma_f32_16x16x32_bf16 v[84:87], v[188:191], v[212:215], v[84:87]
	global_store_dwordx4 v[232:233], v[8:11], off
	v_mfma_f32_16x16x32_bf16 v[76:79], v[180:183], v[240:243], v[76:79]
	v_mfma_f32_16x16x32_bf16 v[68:71], v[188:191], v[240:243], v[68:71]
	s_barrier
; #define PG8_STAGE(bufoff, gbase, voff) do { _Pragma("unroll") for (int _i = 0; _i < 2; ++_i) \
;         __builtin_amdgcn_global_load_lds((const unsigned*)((const char*)(gbase) + (voff)[_i]), (LAS unsigned*)(lds + (bufoff) + ldsw + _i * 8192), 16, 0, 0); } while (0)
; #define PG8_LDA(dst, b, h) do { _Pragma("unroll") for (int m = 0; m < 4; ++m) _Pragma("unroll") for (int k = 0; k < 2; ++k) dst[m][k] = *(const LAS bf16x8*)(lds + PG8_SA(b, h) + aoff + m * 2048 + k * 1024); } while (0)
; #define PG8_LDB(dst, b, h) do { _Pragma("unroll") for (int n = 0; n < 2; ++n) _Pragma("unroll") for (int k = 0; k < 2; ++k) dst[n][k] = *(const LAS bf16x8*)(lds + PG8_SB(b, h) + boff + n * 2048 + k * 1024); } while (0)
; #define PG8_MMA(ai, bj, At, Bt) do { __builtin_amdgcn_s_setprio(1); _Pragma("unroll") for (int k = 0; k < 2; ++k) _Pragma("unroll") for (int m = 0; m < 4; ++m) _Pragma("unroll") for (int n = 0; n < 2; ++n) \
;         acc[ai][bj][m][n] = __builtin_amdgcn_mfma_f32_16x16x32_bf16(Bt[n][k], At[m][k], acc[ai][bj][m][n], 0, 0, 0); __builtin_amdgcn_s_setprio(0); } while (0)
; #define PG8_WAIT_V(n) asm volatile("s_waitcnt vmcnt(" #n ")" ::: "memory")
; #define PG8_WAIT_L(n) asm volatile("s_waitcnt lgkmcnt(" #n ")" ::: "memory")
; #define PG8_BAR __builtin_amdgcn_s_barrier()
; #define PG8_SCHED __builtin_amdgcn_sched_barrier(0)
; template <class Epi, bool ALIGN_EPI>
; __device__ __forceinline__ void gemm_phase(LAS unsigned char* lds, const Gemm g, const StaticOrder& S, const Epi& E, const int tid) {
;     ...
;             PG8_LDA(At, 0, 1); PG8_STAGE(PG8_SB(0, 0), b2, voffB); PG8_STAGE(PG8_SB(0, 1), b2 + hB, voffB); PG8_STAGE(PG8_SA(0, 0), a2, voffA);
;             PG8_WAIT_V(8); PG8_WAIT_L(0); PG8_BAR; PG8_MMA(1, 0, At, B0); PG8_MMA(1, 1, At, B1); PG8_BAR; PG8_SCHED;
;             PG8_LDB(B0, 1, 0); PG8_LDB(B1, 1, 1); PG8_SCHED; PG8_LDA(At, 1, 0); PG8_STAGE(PG8_SA(0, 1), a2 + hA, voffA);
;             PG8_WAIT_V(8); PG8_WAIT_L(0); PG8_BAR; PG8_MMA(0, 0, At, B0); PG8_MMA(0, 1, At, B1); PG8_BAR; PG8_SCHED;
	s_add_i32 s65, s33, s45
	v_lshl_add_u64 v[226:227], v[220:221], 0, v[168:169]
	s_mov_b32 m0, s65
	ds_read_b128 v[192:195], v153 offset:16384
	ds_read_b128 v[196:199], v153 offset:17408
	ds_read_b128 v[200:203], v153 offset:18432
	ds_read_b128 v[204:207], v153 offset:19456
	ds_read_b128 v[208:211], v153 offset:20480
	ds_read_b128 v[212:215], v153 offset:21504
	ds_read_b128 v[216:219], v153 offset:22528
	ds_read_b128 v[240:243], v153 offset:23552
	global_load_lds_dwordx4 v[226:227], off
	v_lshl_add_u64 v[244:245], v[220:221], 0, v[128:129]
	s_add_i32 m0, s65, 0x2000
	v_lshl_add_u64 v[220:221], v[220:221], 0, s[12:13]
	s_add_i32 s10, s10, s45
	global_load_lds_dwordx4 v[244:245], off
	v_lshl_add_u64 v[246:247], v[220:221], 0, v[168:169]
	s_mov_b32 m0, s10
	v_lshl_add_u64 v[220:221], v[220:221], 0, v[128:129]
	global_load_lds_dwordx4 v[246:247], off
	s_add_i32 m0, s10, 0x2000
	v_lshl_add_u64 v[248:249], v[166:167], 0, v[132:133]
	global_load_lds_dwordx4 v[220:221], off
	s_mov_b32 m0, s51
	v_lshl_add_u64 v[250:251], v[166:167], 0, v[130:131]
	global_load_lds_dwordx4 v[248:249], off
	s_mov_b32 m0, s52
	s_nop 0
	global_load_lds_dwordx4 v[250:251], off
	s_waitcnt vmcnt(16)
	s_waitcnt lgkmcnt(0)
	s_barrier
	s_waitcnt lgkmcnt(0)
	v_mfma_f32_16x16x32_bf16 v[56:59], v[146:149], v[192:195], 0
	v_mfma_f32_16x16x32_bf16 v[48:51], v[158:161], v[192:195], 0
	v_mfma_f32_16x16x32_bf16 v[40:43], v[146:149], v[200:203], 0
	v_mfma_f32_16x16x32_bf16 v[32:35], v[158:161], v[200:203], 0
	v_mfma_f32_16x16x32_bf16 v[24:27], v[146:149], v[208:211], 0
	v_mfma_f32_16x16x32_bf16 v[16:19], v[158:161], v[208:211], 0
	v_mfma_f32_16x16x32_bf16 v[8:11], v[146:149], v[216:219], 0
	v_mfma_f32_16x16x32_bf16 v[4:7], v[158:161], v[216:219], 0
	v_mfma_f32_16x16x32_bf16 v[56:59], v[154:157], v[196:199], v[56:59]
	v_mfma_f32_16x16x32_bf16 v[48:51], v[162:165], v[196:199], v[48:51]
	v_mfma_f32_16x16x32_bf16 v[40:43], v[154:157], v[204:207], v[40:43]
	v_mfma_f32_16x16x32_bf16 v[32:35], v[162:165], v[204:207], v[32:35]
	v_mfma_f32_16x16x32_bf16 v[24:27], v[154:157], v[212:215], v[24:27]
	v_mfma_f32_16x16x32_bf16 v[16:19], v[162:165], v[212:215], v[16:19]
	v_mfma_f32_16x16x32_bf16 v[8:11], v[154:157], v[240:243], v[8:11]
	v_mfma_f32_16x16x32_bf16 v[4:7], v[162:165], v[240:243], v[4:7]
	v_mfma_f32_16x16x32_bf16 v[60:63], v[176:179], v[192:195], 0
	v_mfma_f32_16x16x32_bf16 v[52:55], v[184:187], v[192:195], 0
	v_mfma_f32_16x16x32_bf16 v[44:47], v[176:179], v[200:203], 0
	v_mfma_f32_16x16x32_bf16 v[36:39], v[184:187], v[200:203], 0
	v_mfma_f32_16x16x32_bf16 v[28:31], v[176:179], v[208:211], 0
	v_mfma_f32_16x16x32_bf16 v[20:23], v[184:187], v[208:211], 0
	v_mfma_f32_16x16x32_bf16 v[12:15], v[176:179], v[216:219], 0
	v_mfma_f32_16x16x32_bf16 v[0:3], v[184:187], v[216:219], 0
	v_mfma_f32_16x16x32_bf16 v[60:63], v[180:183], v[196:199], v[60:63]
	v_mfma_f32_16x16x32_bf16 v[52:55], v[188:191], v[196:199], v[52:55]
	v_mfma_f32_16x16x32_bf16 v[44:47], v[180:183], v[204:207], v[44:47]
	v_mfma_f32_16x16x32_bf16 v[36:39], v[188:191], v[204:207], v[36:39]
	v_mfma_f32_16x16x32_bf16 v[28:31], v[180:183], v[212:215], v[28:31]
	v_mfma_f32_16x16x32_bf16 v[20:23], v[188:191], v[212:215], v[20:23]
	v_mfma_f32_16x16x32_bf16 v[12:15], v[180:183], v[240:243], v[12:15]
	v_mfma_f32_16x16x32_bf16 v[0:3], v[188:191], v[240:243], v[0:3]
	s_barrier
	s_add_i32 s10, 0, 0x18000
	v_add_u32_e32 v150, s10, v151
	s_add_i32 s65, 0, 0x1c000
	ds_read_b128 v[146:149], v150
	ds_read_b128 v[154:157], v150 offset:1024
	ds_read_b128 v[158:161], v150 offset:2048
	ds_read_b128 v[162:165], v150 offset:3072
	v_add_u32_e32 v150, s65, v151
	ds_read_b128 v[176:179], v150
	ds_read_b128 v[180:183], v150 offset:1024
	ds_read_b128 v[184:187], v150 offset:2048
	ds_read_b128 v[188:191], v150 offset:3072
	v_lshl_add_u64 v[166:167], v[166:167], 0, s[94:95]
	s_mov_b32 m0, s53
	v_lshl_add_u64 v[252:253], v[166:167], 0, v[132:133]
	ds_read_b128 v[192:195], v153 offset:32768
	ds_read_b128 v[196:199], v153 offset:33792
	ds_read_b128 v[200:203], v153 offset:34816
	ds_read_b128 v[204:207], v153 offset:35840
	ds_read_b128 v[208:211], v153 offset:36864
	ds_read_b128 v[212:215], v153 offset:37888
	ds_read_b128 v[216:219], v153 offset:38912
	ds_read_b128 v[240:243], v153 offset:39936
	global_load_lds_dwordx4 v[252:253], off
	v_lshl_add_u64 v[166:167], v[166:167], 0, v[130:131]
	s_mov_b32 m0, s54
	s_nop 0
	global_load_lds_dwordx4 v[166:167], off
	s_waitcnt vmcnt(12)
	s_waitcnt lgkmcnt(0)
	s_barrier
	s_waitcnt lgkmcnt(0)
	v_mfma_f32_16x16x32_bf16 v[120:123], v[146:149], v[192:195], v[120:123]
	v_mfma_f32_16x16x32_bf16 v[112:115], v[158:161], v[192:195], v[112:115]
	v_mfma_f32_16x16x32_bf16 v[104:107], v[146:149], v[200:203], v[104:107]
	v_mfma_f32_16x16x32_bf16 v[96:99], v[158:161], v[200:203], v[96:99]
	v_mfma_f32_16x16x32_bf16 v[88:91], v[146:149], v[208:211], v[88:91]
	v_mfma_f32_16x16x32_bf16 v[80:83], v[158:161], v[208:211], v[80:83]
	v_mfma_f32_16x16x32_bf16 v[72:75], v[146:149], v[216:219], v[72:75]
	v_mfma_f32_16x16x32_bf16 v[64:67], v[158:161], v[216:219], v[64:67]
	v_mfma_f32_16x16x32_bf16 v[120:123], v[154:157], v[196:199], v[120:123]
	v_mfma_f32_16x16x32_bf16 v[112:115], v[162:165], v[196:199], v[112:115]
	v_mfma_f32_16x16x32_bf16 v[104:107], v[154:157], v[204:207], v[104:107]
	v_mfma_f32_16x16x32_bf16 v[96:99], v[162:165], v[204:207], v[96:99]
	v_mfma_f32_16x16x32_bf16 v[88:91], v[154:157], v[212:215], v[88:91]
	v_mfma_f32_16x16x32_bf16 v[80:83], v[162:165], v[212:215], v[80:83]
	v_mfma_f32_16x16x32_bf16 v[72:75], v[154:157], v[240:243], v[72:75]
	v_mfma_f32_16x16x32_bf16 v[64:67], v[162:165], v[240:243], v[64:67]
	v_mfma_f32_16x16x32_bf16 v[124:127], v[176:179], v[192:195], v[124:127]
	v_mfma_f32_16x16x32_bf16 v[116:119], v[184:187], v[192:195], v[116:119]
	v_mfma_f32_16x16x32_bf16 v[108:111], v[176:179], v[200:203], v[108:111]
	v_mfma_f32_16x16x32_bf16 v[100:103], v[184:187], v[200:203], v[100:103]
	v_mfma_f32_16x16x32_bf16 v[92:95], v[176:179], v[208:211], v[92:95]
	v_mfma_f32_16x16x32_bf16 v[84:87], v[184:187], v[208:211], v[84:87]
	v_mfma_f32_16x16x32_bf16 v[76:79], v[176:179], v[216:219], v[76:79]
	v_mfma_f32_16x16x32_bf16 v[68:71], v[184:187], v[216:219], v[68:71]
	v_mfma_f32_16x16x32_bf16 v[124:127], v[180:183], v[196:199], v[124:127]
	v_mfma_f32_16x16x32_bf16 v[116:119], v[188:191], v[196:199], v[116:119]
	v_mfma_f32_16x16x32_bf16 v[108:111], v[180:183], v[204:207], v[108:111]
	v_mfma_f32_16x16x32_bf16 v[100:103], v[188:191], v[204:207], v[100:103]
	v_mfma_f32_16x16x32_bf16 v[92:95], v[180:183], v[212:215], v[92:95]
	v_mfma_f32_16x16x32_bf16 v[84:87], v[188:191], v[212:215], v[84:87]
	v_mfma_f32_16x16x32_bf16 v[76:79], v[180:183], v[240:243], v[76:79]
	v_mfma_f32_16x16x32_bf16 v[68:71], v[188:191], v[240:243], v[68:71]
	s_barrier
; #define PG8_STAGE(bufoff, gbase, voff) do { _Pragma("unroll") for (int _i = 0; _i < 2; ++_i) \
;         __builtin_amdgcn_global_load_lds((const unsigned*)((const char*)(gbase) + (voff)[_i]), (LAS unsigned*)(lds + (bufoff) + ldsw + _i * 8192), 16, 0, 0); } while (0)
; #define PG8_LDA(dst, b, h) do { _Pragma("unroll") for (int m = 0; m < 4; ++m) _Pragma("unroll") for (int k = 0; k < 2; ++k) dst[m][k] = *(const LAS bf16x8*)(lds + PG8_SA(b, h) + aoff + m * 2048 + k * 1024); } while (0)
; #define PG8_LDB(dst, b, h) do { _Pragma("unroll") for (int n = 0; n < 2; ++n) _Pragma("unroll") for (int k = 0; k < 2; ++k) dst[n][k] = *(const LAS bf16x8*)(lds + PG8_SB(b, h) + boff + n * 2048 + k * 1024); } while (0)
; #define PG8_MMA(ai, bj, At, Bt) do { __builtin_amdgcn_s_setprio(1); _Pragma("unroll") for (int k = 0; k < 2; ++k) _Pragma("unroll") for (int m = 0; m < 4; ++m) _Pragma("unroll") for (int n = 0; n < 2; ++n) \
;         acc[ai][bj][m][n] = __builtin_amdgcn_mfma_f32_16x16x32_bf16(Bt[n][k], At[m][k], acc[ai][bj][m][n], 0, 0, 0); __builtin_amdgcn_s_setprio(0); } while (0)
; #define PG8_WAIT_V(n) asm volatile("s_waitcnt vmcnt(" #n ")" ::: "memory")
; #define PG8_BAR __builtin_amdgcn_s_barrier()
; template <class Epi, bool ALIGN_EPI>
; __device__ __forceinline__ void gemm_phase(LAS unsigned char* lds, const Gemm g, const StaticOrder& S, const Epi& E, const int tid) {
;     ...
;             PG8_LDB(B0, 0, 0); PG8_LDB(B1, 0, 1); PG8_SCHED; PG8_LDA(At, 0, 0); PG8_STAGE(PG8_SA(1, 1), a1 + hA, voffA);
;             PG8_WAIT_V(8); PG8_WAIT_L(0); PG8_BAR; PG8_MMA(0, 0, At, B0); PG8_MMA(0, 1, At, B1); PG8_BAR; PG8_SCHED;
;             PG8_LDA(At, 0, 1); PG8_STAGE(PG8_SB(0, 0), b2, voffB); PG8_STAGE(PG8_SB(0, 1), b2 + hB, voffB); PG8_STAGE(PG8_SA(0, 0), a2, voffA);
;             PG8_WAIT_V(8); PG8_WAIT_L(0); PG8_BAR; PG8_MMA(1, 0, At, B0); PG8_MMA(1, 1, At, B1); PG8_BAR; PG8_SCHED;
;             PG8_LDB(B0, 1, 0); PG8_LDB(B1, 1, 1); PG8_SCHED; PG8_LDA(At, 1, 0); PG8_STAGE(PG8_SA(0, 1), a2 + hA, voffA);
;             PG8_WAIT_V(8); PG8_WAIT_L(0); PG8_BAR; PG8_MMA(0, 0, At, B0); PG8_MMA(0, 1, At, B1); PG8_BAR; PG8_SCHED;
;             PG8_LDA(At, 1, 1); PG8_STAGE(PG8_SB(1, 0), b3, voffB); PG8_STAGE(PG8_SB(1, 1), b3 + hB, voffB); PG8_STAGE(PG8_SA(1, 0), a3, voffA);
;             PG8_WAIT_V(8); PG8_WAIT_L(0); PG8_BAR; PG8_MMA(1, 0, At, B0); PG8_MMA(1, 1, At, B1); PG8_BAR; PG8_SCHED;
	s_add_i32 s10, s10, s45
	v_lshl_add_u64 v[166:167], v[226:227], 0, s[92:93]
	s_mov_b32 m0, s10
	ds_read_b128 v[192:195], v153 offset:49152
	ds_read_b128 v[196:199], v153 offset:50176
	ds_read_b128 v[200:203], v153 offset:51200
	ds_read_b128 v[204:207], v153 offset:52224
	ds_read_b128 v[208:211], v153 offset:53248
	ds_read_b128 v[212:215], v153 offset:54272
	ds_read_b128 v[216:219], v153 offset:55296
	ds_read_b128 v[240:243], v153 offset:56320
	global_load_lds_dwordx4 v[166:167], off
	v_lshl_add_u64 v[166:167], v[244:245], 0, s[92:93]
	s_add_i32 m0, s10, 0x2000
	s_add_i32 s10, s65, s45
	global_load_lds_dwordx4 v[166:167], off
	v_lshl_add_u64 v[166:167], v[246:247], 0, s[92:93]
	s_mov_b32 m0, s10
	s_nop 0
	global_load_lds_dwordx4 v[166:167], off
	v_lshl_add_u64 v[166:167], v[220:221], 0, s[92:93]
	s_add_i32 m0, s10, 0x2000
	s_nop 0
	global_load_lds_dwordx4 v[166:167], off
	v_lshl_add_u64 v[166:167], v[248:249], 0, s[92:93]
	s_mov_b32 m0, s56
	s_nop 0
	global_load_lds_dwordx4 v[166:167], off
	v_lshl_add_u64 v[166:167], v[250:251], 0, s[92:93]
	s_mov_b32 m0, s57
	s_nop 0
	global_load_lds_dwordx4 v[166:167], off
	s_waitcnt vmcnt(8)
	s_waitcnt lgkmcnt(0)
	s_barrier
	s_waitcnt lgkmcnt(0)
	v_mfma_f32_16x16x32_bf16 v[56:59], v[146:149], v[192:195], v[56:59]
	v_mfma_f32_16x16x32_bf16 v[48:51], v[158:161], v[192:195], v[48:51]
	v_mfma_f32_16x16x32_bf16 v[40:43], v[146:149], v[200:203], v[40:43]
	v_mfma_f32_16x16x32_bf16 v[32:35], v[158:161], v[200:203], v[32:35]
	v_mfma_f32_16x16x32_bf16 v[24:27], v[146:149], v[208:211], v[24:27]
	v_mfma_f32_16x16x32_bf16 v[16:19], v[158:161], v[208:211], v[16:19]
	v_mfma_f32_16x16x32_bf16 v[8:11], v[146:149], v[216:219], v[8:11]
	v_mfma_f32_16x16x32_bf16 v[4:7], v[158:161], v[216:219], v[4:7]
	v_mfma_f32_16x16x32_bf16 v[56:59], v[154:157], v[196:199], v[56:59]
	v_mfma_f32_16x16x32_bf16 v[48:51], v[162:165], v[196:199], v[48:51]
	v_mfma_f32_16x16x32_bf16 v[40:43], v[154:157], v[204:207], v[40:43]
	v_mfma_f32_16x16x32_bf16 v[32:35], v[162:165], v[204:207], v[32:35]
	v_mfma_f32_16x16x32_bf16 v[24:27], v[154:157], v[212:215], v[24:27]
	v_mfma_f32_16x16x32_bf16 v[16:19], v[162:165], v[212:215], v[16:19]
	v_mfma_f32_16x16x32_bf16 v[8:11], v[154:157], v[240:243], v[8:11]
	v_mfma_f32_16x16x32_bf16 v[4:7], v[162:165], v[240:243], v[4:7]
	v_mfma_f32_16x16x32_bf16 v[60:63], v[176:179], v[192:195], v[60:63]
	v_mfma_f32_16x16x32_bf16 v[52:55], v[184:187], v[192:195], v[52:55]
	v_mfma_f32_16x16x32_bf16 v[44:47], v[176:179], v[200:203], v[44:47]
	v_mfma_f32_16x16x32_bf16 v[36:39], v[184:187], v[200:203], v[36:39]
	v_mfma_f32_16x16x32_bf16 v[28:31], v[176:179], v[208:211], v[28:31]
	v_mfma_f32_16x16x32_bf16 v[20:23], v[184:187], v[208:211], v[20:23]
	v_mfma_f32_16x16x32_bf16 v[12:15], v[176:179], v[216:219], v[12:15]
	v_mfma_f32_16x16x32_bf16 v[0:3], v[184:187], v[216:219], v[0:3]
	v_mfma_f32_16x16x32_bf16 v[60:63], v[180:183], v[196:199], v[60:63]
	v_mfma_f32_16x16x32_bf16 v[52:55], v[188:191], v[196:199], v[52:55]
	v_mfma_f32_16x16x32_bf16 v[44:47], v[180:183], v[204:207], v[44:47]
	v_mfma_f32_16x16x32_bf16 v[36:39], v[188:191], v[204:207], v[36:39]
	v_mfma_f32_16x16x32_bf16 v[28:31], v[180:183], v[212:215], v[28:31]
	v_mfma_f32_16x16x32_bf16 v[20:23], v[188:191], v[212:215], v[20:23]
	v_mfma_f32_16x16x32_bf16 v[12:15], v[180:183], v[240:243], v[12:15]
	v_mfma_f32_16x16x32_bf16 v[0:3], v[188:191], v[240:243], v[0:3]
	s_barrier
	v_lshl_add_u64 v[142:143], v[142:143], 0, s[80:81]
	v_lshl_add_u64 v[144:145], v[144:145], 0, s[80:81]
	s_mov_b32 s10, s11
	s_cmp_eq_u32 s10, s58
	s_cbranch_scc1 .Lgu_last
	s_branch .LBB0_308
.Lgu_first:
	s_add_i32 s11, s10, 2
	s_cmp_eq_u32 s58, s10
	v_lshl_add_u64 v[146:147], v[142:143], 0, s[92:93]
	s_cselect_b64 vcc, -1, 0
	v_add_u32_e32 v150, s33, v151
	s_add_i32 s10, 0, 0x14000
	v_cndmask_b32_e32 v167, v147, v139, vcc
	v_cndmask_b32_e32 v166, v146, v138, vcc
	ds_read_b128 v[146:149], v150
	ds_read_b128 v[154:157], v150 offset:1024
	ds_read_b128 v[158:161], v150 offset:2048
	ds_read_b128 v[162:165], v150 offset:3072
	v_add_u32_e32 v150, s10, v151
	ds_read_b128 v[176:179], v150
	ds_read_b128 v[180:183], v150 offset:1024
	ds_read_b128 v[184:187], v150 offset:2048
	ds_read_b128 v[188:191], v150 offset:3072
	v_cndmask_b32_e32 v221, v145, v141, vcc
	v_cndmask_b32_e32 v220, v144, v140, vcc
	v_lshl_add_u64 v[226:227], v[142:143], 0, v[134:135]
	s_add_i32 m0, s51, 0xc000
	ds_read_b128 v[192:195], v153
	ds_read_b128 v[196:199], v153 offset:1024
	ds_read_b128 v[200:203], v153 offset:2048
	ds_read_b128 v[204:207], v153 offset:3072
	ds_read_b128 v[208:211], v153 offset:4096
	ds_read_b128 v[212:215], v153 offset:5120
	ds_read_b128 v[216:219], v153 offset:6144
	ds_read_b128 v[240:243], v153 offset:7168
	global_load_lds_dwordx4 v[226:227], off
	v_lshl_add_u64 v[226:227], v[142:143], 0, v[136:137]
	s_add_i32 m0, s51, 0xe000
	s_nop 0
	global_load_lds_dwordx4 v[226:227], off
	s_waitcnt vmcnt(8)
	s_waitcnt lgkmcnt(0)
	s_barrier
; #define PG8_STAGE(bufoff, gbase, voff) do { _Pragma("unroll") for (int _i = 0; _i < 2; ++_i) \
;         __builtin_amdgcn_global_load_lds((const unsigned*)((const char*)(gbase) + (voff)[_i]), (LAS unsigned*)(lds + (bufoff) + ldsw + _i * 8192), 16, 0, 0); } while (0)
; #define PG8_LDA(dst, b, h) do { _Pragma("unroll") for (int m = 0; m < 4; ++m) _Pragma("unroll") for (int k = 0; k < 2; ++k) dst[m][k] = *(const LAS bf16x8*)(lds + PG8_SA(b, h) + aoff + m * 2048 + k * 1024); } while (0)
; #define PG8_LDB(dst, b, h) do { _Pragma("unroll") for (int n = 0; n < 2; ++n) _Pragma("unroll") for (int k = 0; k < 2; ++k) dst[n][k] = *(const LAS bf16x8*)(lds + PG8_SB(b, h) + boff + n * 2048 + k * 1024); } while (0)
; #define PG8_MMA(ai, bj, At, Bt) do { __builtin_amdgcn_s_setprio(1); _Pragma("unroll") for (int k = 0; k < 2; ++k) _Pragma("unroll") for (int m = 0; m < 4; ++m) _Pragma("unroll") for (int n = 0; n < 2; ++n) \
;         acc[ai][bj][m][n] = __builtin_amdgcn_mfma_f32_16x16x32_bf16(Bt[n][k], At[m][k], acc[ai][bj][m][n], 0, 0, 0); __builtin_amdgcn_s_setprio(0); } while (0)
; #define PG8_WAIT_V(n) asm volatile("s_waitcnt vmcnt(" #n ")" ::: "memory")
; #define PG8_WAIT_L(n) asm volatile("s_waitcnt lgkmcnt(" #n ")" ::: "memory")
; #define PG8_BAR __builtin_amdgcn_s_barrier()
; #define PG8_SCHED __builtin_amdgcn_sched_barrier(0)
; template <class Epi, bool ALIGN_EPI>
; __device__ __forceinline__ void gemm_phase(LAS unsigned char* lds, const Gemm g, const StaticOrder& S, const Epi& E, const int tid) {
;     ...
;             PG8_LDB(B0, 0, 0); PG8_LDB(B1, 0, 1); PG8_SCHED; PG8_LDA(At, 0, 0); PG8_STAGE(PG8_SA(1, 1), a1 + hA, voffA);
;             PG8_WAIT_V(8); PG8_WAIT_L(0); PG8_BAR; PG8_MMA(0, 0, At, B0); PG8_MMA(0, 1, At, B1); PG8_BAR; PG8_SCHED;
;             PG8_LDA(At, 0, 1); PG8_STAGE(PG8_SB(0, 0), b2, voffB); PG8_STAGE(PG8_SB(0, 1), b2 + hB, voffB); PG8_STAGE(PG8_SA(0, 0), a2, voffA);
;             PG8_WAIT_V(8); PG8_WAIT_L(0); PG8_BAR; PG8_MMA(1, 0, At, B0); PG8_MMA(1, 1, At, B1); PG8_BAR; PG8_SCHED;
	s_waitcnt lgkmcnt(0)
	v_mfma_f32_16x16x32_bf16 v[120:123], v[146:149], v[192:195], 0
	v_mfma_f32_16x16x32_bf16 v[112:115], v[158:161], v[192:195], 0
	v_mfma_f32_16x16x32_bf16 v[104:107], v[146:149], v[200:203], 0
	v_mfma_f32_16x16x32_bf16 v[96:99], v[158:161], v[200:203], 0
	v_mfma_f32_16x16x32_bf16 v[88:91], v[146:149], v[208:211], 0
	v_mfma_f32_16x16x32_bf16 v[80:83], v[158:161], v[208:211], 0
	v_mfma_f32_16x16x32_bf16 v[72:75], v[146:149], v[216:219], 0
	v_mfma_f32_16x16x32_bf16 v[64:67], v[158:161], v[216:219], 0
	v_mfma_f32_16x16x32_bf16 v[120:123], v[154:157], v[196:199], v[120:123]
	v_mfma_f32_16x16x32_bf16 v[112:115], v[162:165], v[196:199], v[112:115]
	v_mfma_f32_16x16x32_bf16 v[104:107], v[154:157], v[204:207], v[104:107]
	v_mfma_f32_16x16x32_bf16 v[96:99], v[162:165], v[204:207], v[96:99]
	v_mfma_f32_16x16x32_bf16 v[88:91], v[154:157], v[212:215], v[88:91]
	v_mfma_f32_16x16x32_bf16 v[80:83], v[162:165], v[212:215], v[80:83]
	v_mfma_f32_16x16x32_bf16 v[72:75], v[154:157], v[240:243], v[72:75]
	v_mfma_f32_16x16x32_bf16 v[64:67], v[162:165], v[240:243], v[64:67]
	v_mfma_f32_16x16x32_bf16 v[124:127], v[176:179], v[192:195], 0
	v_mfma_f32_16x16x32_bf16 v[116:119], v[184:187], v[192:195], 0
	v_mfma_f32_16x16x32_bf16 v[108:111], v[176:179], v[200:203], 0
	v_mfma_f32_16x16x32_bf16 v[100:103], v[184:187], v[200:203], 0
	v_mfma_f32_16x16x32_bf16 v[92:95], v[176:179], v[208:211], 0
	v_mfma_f32_16x16x32_bf16 v[84:87], v[184:187], v[208:211], 0
	v_mfma_f32_16x16x32_bf16 v[76:79], v[176:179], v[216:219], 0
	v_mfma_f32_16x16x32_bf16 v[68:71], v[184:187], v[216:219], 0
	v_mfma_f32_16x16x32_bf16 v[124:127], v[180:183], v[196:199], v[124:127]
	v_mfma_f32_16x16x32_bf16 v[116:119], v[188:191], v[196:199], v[116:119]
	v_mfma_f32_16x16x32_bf16 v[108:111], v[180:183], v[204:207], v[108:111]
	v_mfma_f32_16x16x32_bf16 v[100:103], v[188:191], v[204:207], v[100:103]
	v_mfma_f32_16x16x32_bf16 v[92:95], v[180:183], v[212:215], v[92:95]
	v_mfma_f32_16x16x32_bf16 v[84:87], v[188:191], v[212:215], v[84:87]
	v_mfma_f32_16x16x32_bf16 v[76:79], v[180:183], v[240:243], v[76:79]
	v_mfma_f32_16x16x32_bf16 v[68:71], v[188:191], v[240:243], v[68:71]
	s_barrier
	s_add_i32 s65, s33, s45
	v_lshl_add_u64 v[226:227], v[220:221], 0, v[168:169]
	s_mov_b32 m0, s65
	ds_read_b128 v[192:195], v153 offset:16384
	ds_read_b128 v[196:199], v153 offset:17408
	ds_read_b128 v[200:203], v153 offset:18432
	ds_read_b128 v[204:207], v153 offset:19456
	ds_read_b128 v[208:211], v153 offset:20480
	ds_read_b128 v[212:215], v153 offset:21504
	ds_read_b128 v[216:219], v153 offset:22528
	ds_read_b128 v[240:243], v153 offset:23552
	global_load_lds_dwordx4 v[226:227], off
	v_lshl_add_u64 v[244:245], v[220:221], 0, v[128:129]
	s_add_i32 m0, s65, 0x2000
	v_lshl_add_u64 v[220:221], v[220:221], 0, s[12:13]
	s_add_i32 s10, s10, s45
	global_load_lds_dwordx4 v[244:245], off
	v_lshl_add_u64 v[246:247], v[220:221], 0, v[168:169]
	s_mov_b32 m0, s10
	v_lshl_add_u64 v[220:221], v[220:221], 0, v[128:129]
	global_load_lds_dwordx4 v[246:247], off
	s_add_i32 m0, s10, 0x2000
	v_lshl_add_u64 v[248:249], v[166:167], 0, v[132:133]
	global_load_lds_dwordx4 v[220:221], off
	s_mov_b32 m0, s51
	v_lshl_add_u64 v[250:251], v[166:167], 0, v[130:131]
	global_load_lds_dwordx4 v[248:249], off
	s_mov_b32 m0, s52
	s_nop 0
	global_load_lds_dwordx4 v[250:251], off
	s_waitcnt vmcnt(8)
	s_waitcnt lgkmcnt(0)
	s_barrier
	s_waitcnt lgkmcnt(0)
	v_mfma_f32_16x16x32_bf16 v[56:59], v[146:149], v[192:195], 0
	v_mfma_f32_16x16x32_bf16 v[48:51], v[158:161], v[192:195], 0
	v_mfma_f32_16x16x32_bf16 v[40:43], v[146:149], v[200:203], 0
	v_mfma_f32_16x16x32_bf16 v[32:35], v[158:161], v[200:203], 0
	v_mfma_f32_16x16x32_bf16 v[24:27], v[146:149], v[208:211], 0
	v_mfma_f32_16x16x32_bf16 v[16:19], v[158:161], v[208:211], 0
	v_mfma_f32_16x16x32_bf16 v[8:11], v[146:149], v[216:219], 0
	v_mfma_f32_16x16x32_bf16 v[4:7], v[158:161], v[216:219], 0
	v_mfma_f32_16x16x32_bf16 v[56:59], v[154:157], v[196:199], v[56:59]
	v_mfma_f32_16x16x32_bf16 v[48:51], v[162:165], v[196:199], v[48:51]
	v_mfma_f32_16x16x32_bf16 v[40:43], v[154:157], v[204:207], v[40:43]
	v_mfma_f32_16x16x32_bf16 v[32:35], v[162:165], v[204:207], v[32:35]
	v_mfma_f32_16x16x32_bf16 v[24:27], v[154:157], v[212:215], v[24:27]
	v_mfma_f32_16x16x32_bf16 v[16:19], v[162:165], v[212:215], v[16:19]
	v_mfma_f32_16x16x32_bf16 v[8:11], v[154:157], v[240:243], v[8:11]
	v_mfma_f32_16x16x32_bf16 v[4:7], v[162:165], v[240:243], v[4:7]
	v_mfma_f32_16x16x32_bf16 v[60:63], v[176:179], v[192:195], 0
	v_mfma_f32_16x16x32_bf16 v[52:55], v[184:187], v[192:195], 0
	v_mfma_f32_16x16x32_bf16 v[44:47], v[176:179], v[200:203], 0
	v_mfma_f32_16x16x32_bf16 v[36:39], v[184:187], v[200:203], 0
	v_mfma_f32_16x16x32_bf16 v[28:31], v[176:179], v[208:211], 0
	v_mfma_f32_16x16x32_bf16 v[20:23], v[184:187], v[208:211], 0
	v_mfma_f32_16x16x32_bf16 v[12:15], v[176:179], v[216:219], 0
	v_mfma_f32_16x16x32_bf16 v[0:3], v[184:187], v[216:219], 0
	v_mfma_f32_16x16x32_bf16 v[60:63], v[180:183], v[196:199], v[60:63]
	v_mfma_f32_16x16x32_bf16 v[52:55], v[188:191], v[196:199], v[52:55]
	v_mfma_f32_16x16x32_bf16 v[44:47], v[180:183], v[204:207], v[44:47]
	v_mfma_f32_16x16x32_bf16 v[36:39], v[188:191], v[204:207], v[36:39]
	v_mfma_f32_16x16x32_bf16 v[28:31], v[180:183], v[212:215], v[28:31]
	v_mfma_f32_16x16x32_bf16 v[20:23], v[188:191], v[212:215], v[20:23]
	v_mfma_f32_16x16x32_bf16 v[12:15], v[180:183], v[240:243], v[12:15]
	v_mfma_f32_16x16x32_bf16 v[0:3], v[188:191], v[240:243], v[0:3]
	s_barrier
; #define PG8_STAGE(bufoff, gbase, voff) do { _Pragma("unroll") for (int _i = 0; _i < 2; ++_i) \
;         __builtin_amdgcn_global_load_lds((const unsigned*)((const char*)(gbase) + (voff)[_i]), (LAS unsigned*)(lds + (bufoff) + ldsw + _i * 8192), 16, 0, 0); } while (0)
; #define PG8_LDA(dst, b, h) do { _Pragma("unroll") for (int m = 0; m < 4; ++m) _Pragma("unroll") for (int k = 0; k < 2; ++k) dst[m][k] = *(const LAS bf16x8*)(lds + PG8_SA(b, h) + aoff + m * 2048 + k * 1024); } while (0)
; #define PG8_LDB(dst, b, h) do { _Pragma("unroll") for (int n = 0; n < 2; ++n) _Pragma("unroll") for (int k = 0; k < 2; ++k) dst[n][k] = *(const LAS bf16x8*)(lds + PG8_SB(b, h) + boff + n * 2048 + k * 1024); } while (0)
; #define PG8_MMA(ai, bj, At, Bt) do { __builtin_amdgcn_s_setprio(1); _Pragma("unroll") for (int k = 0; k < 2; ++k) _Pragma("unroll") for (int m = 0; m < 4; ++m) _Pragma("unroll") for (int n = 0; n < 2; ++n) \
;         acc[ai][bj][m][n] = __builtin_amdgcn_mfma_f32_16x16x32_bf16(Bt[n][k], At[m][k], acc[ai][bj][m][n], 0, 0, 0); __builtin_amdgcn_s_setprio(0); } while (0)
; #define PG8_WAIT_V(n) asm volatile("s_waitcnt vmcnt(" #n ")" ::: "memory")
; #define PG8_WAIT_L(n) asm volatile("s_waitcnt lgkmcnt(" #n ")" ::: "memory")
; #define PG8_BAR __builtin_amdgcn_s_barrier()
; #define PG8_SCHED __builtin_amdgcn_sched_barrier(0)
; template <class Epi, bool ALIGN_EPI>
; __device__ __forceinline__ void gemm_phase(LAS unsigned char* lds, const Gemm g, const StaticOrder& S, const Epi& E, const int tid) {
;     ...
;             PG8_LDB(B0, 1, 0); PG8_LDB(B1, 1, 1); PG8_SCHED; PG8_LDA(At, 1, 0); PG8_STAGE(PG8_SA(0, 1), a2 + hA, voffA);
;             PG8_WAIT_V(8); PG8_WAIT_L(0); PG8_BAR; PG8_MMA(0, 0, At, B0); PG8_MMA(0, 1, At, B1); PG8_BAR; PG8_SCHED;
;             PG8_LDA(At, 1, 1); PG8_STAGE(PG8_SB(1, 0), b3, voffB); PG8_STAGE(PG8_SB(1, 1), b3 + hB, voffB); PG8_STAGE(PG8_SA(1, 0), a3, voffA);
;             PG8_WAIT_V(8); PG8_WAIT_L(0); PG8_BAR; PG8_MMA(1, 0, At, B0); PG8_MMA(1, 1, At, B1); PG8_BAR; PG8_SCHED;
	s_add_i32 s10, 0, 0x18000
	v_add_u32_e32 v150, s10, v151
	s_add_i32 s65, 0, 0x1c000
	ds_read_b128 v[146:149], v150
	ds_read_b128 v[154:157], v150 offset:1024
	ds_read_b128 v[158:161], v150 offset:2048
	ds_read_b128 v[162:165], v150 offset:3072
	v_add_u32_e32 v150, s65, v151
	ds_read_b128 v[176:179], v150
	ds_read_b128 v[180:183], v150 offset:1024
	ds_read_b128 v[184:187], v150 offset:2048
	ds_read_b128 v[188:191], v150 offset:3072
	v_lshl_add_u64 v[166:167], v[166:167], 0, s[94:95]
	s_mov_b32 m0, s53
	v_lshl_add_u64 v[252:253], v[166:167], 0, v[132:133]
	ds_read_b128 v[192:195], v153 offset:32768
	ds_read_b128 v[196:199], v153 offset:33792
	ds_read_b128 v[200:203], v153 offset:34816
	ds_read_b128 v[204:207], v153 offset:35840
	ds_read_b128 v[208:211], v153 offset:36864
	ds_read_b128 v[212:215], v153 offset:37888
	ds_read_b128 v[216:219], v153 offset:38912
	ds_read_b128 v[240:243], v153 offset:39936
	global_load_lds_dwordx4 v[252:253], off
	v_lshl_add_u64 v[166:167], v[166:167], 0, v[130:131]
	s_mov_b32 m0, s54
	s_nop 0
	global_load_lds_dwordx4 v[166:167], off
	s_waitcnt vmcnt(8)
	s_waitcnt lgkmcnt(0)
	s_barrier
	s_waitcnt lgkmcnt(0)
	v_mfma_f32_16x16x32_bf16 v[120:123], v[146:149], v[192:195], v[120:123]
	v_mfma_f32_16x16x32_bf16 v[112:115], v[158:161], v[192:195], v[112:115]
	v_mfma_f32_16x16x32_bf16 v[104:107], v[146:149], v[200:203], v[104:107]
	v_mfma_f32_16x16x32_bf16 v[96:99], v[158:161], v[200:203], v[96:99]
	v_mfma_f32_16x16x32_bf16 v[88:91], v[146:149], v[208:211], v[88:91]
	v_mfma_f32_16x16x32_bf16 v[80:83], v[158:161], v[208:211], v[80:83]
	v_mfma_f32_16x16x32_bf16 v[72:75], v[146:149], v[216:219], v[72:75]
	v_mfma_f32_16x16x32_bf16 v[64:67], v[158:161], v[216:219], v[64:67]
	v_mfma_f32_16x16x32_bf16 v[120:123], v[154:157], v[196:199], v[120:123]
	v_mfma_f32_16x16x32_bf16 v[112:115], v[162:165], v[196:199], v[112:115]
	v_mfma_f32_16x16x32_bf16 v[104:107], v[154:157], v[204:207], v[104:107]
	v_mfma_f32_16x16x32_bf16 v[96:99], v[162:165], v[204:207], v[96:99]
	v_mfma_f32_16x16x32_bf16 v[88:91], v[154:157], v[212:215], v[88:91]
	v_mfma_f32_16x16x32_bf16 v[80:83], v[162:165], v[212:215], v[80:83]
	v_mfma_f32_16x16x32_bf16 v[72:75], v[154:157], v[240:243], v[72:75]
	v_mfma_f32_16x16x32_bf16 v[64:67], v[162:165], v[240:243], v[64:67]
	v_mfma_f32_16x16x32_bf16 v[124:127], v[176:179], v[192:195], v[124:127]
	v_mfma_f32_16x16x32_bf16 v[116:119], v[184:187], v[192:195], v[116:119]
	v_mfma_f32_16x16x32_bf16 v[108:111], v[176:179], v[200:203], v[108:111]
	v_mfma_f32_16x16x32_bf16 v[100:103], v[184:187], v[200:203], v[100:103]
	v_mfma_f32_16x16x32_bf16 v[92:95], v[176:179], v[208:211], v[92:95]
	v_mfma_f32_16x16x32_bf16 v[84:87], v[184:187], v[208:211], v[84:87]
	v_mfma_f32_16x16x32_bf16 v[76:79], v[176:179], v[216:219], v[76:79]
	v_mfma_f32_16x16x32_bf16 v[68:71], v[184:187], v[216:219], v[68:71]
	v_mfma_f32_16x16x32_bf16 v[124:127], v[180:183], v[196:199], v[124:127]
	v_mfma_f32_16x16x32_bf16 v[116:119], v[188:191], v[196:199], v[116:119]
	v_mfma_f32_16x16x32_bf16 v[108:111], v[180:183], v[204:207], v[108:111]
	v_mfma_f32_16x16x32_bf16 v[100:103], v[188:191], v[204:207], v[100:103]
	v_mfma_f32_16x16x32_bf16 v[92:95], v[180:183], v[212:215], v[92:95]
	v_mfma_f32_16x16x32_bf16 v[84:87], v[188:191], v[212:215], v[84:87]
	v_mfma_f32_16x16x32_bf16 v[76:79], v[180:183], v[240:243], v[76:79]
	v_mfma_f32_16x16x32_bf16 v[68:71], v[188:191], v[240:243], v[68:71]
	s_barrier
	s_add_i32 s10, s10, s45
	v_lshl_add_u64 v[166:167], v[226:227], 0, s[92:93]
	s_mov_b32 m0, s10
	ds_read_b128 v[192:195], v153 offset:49152
	ds_read_b128 v[196:199], v153 offset:50176
	ds_read_b128 v[200:203], v153 offset:51200
	ds_read_b128 v[204:207], v153 offset:52224
	ds_read_b128 v[208:211], v153 offset:53248
	ds_read_b128 v[212:215], v153 offset:54272
	ds_read_b128 v[216:219], v153 offset:55296
	ds_read_b128 v[240:243], v153 offset:56320
	global_load_lds_dwordx4 v[166:167], off
	v_lshl_add_u64 v[166:167], v[244:245], 0, s[92:93]
	s_add_i32 m0, s10, 0x2000
	s_add_i32 s10, s65, s45
	global_load_lds_dwordx4 v[166:167], off
	v_lshl_add_u64 v[166:167], v[246:247], 0, s[92:93]
	s_mov_b32 m0, s10
	s_nop 0
	global_load_lds_dwordx4 v[166:167], off
	v_lshl_add_u64 v[166:167], v[220:221], 0, s[92:93]
	s_add_i32 m0, s10, 0x2000
	s_nop 0
	global_load_lds_dwordx4 v[166:167], off
	v_lshl_add_u64 v[166:167], v[248:249], 0, s[92:93]
	s_mov_b32 m0, s56
	s_nop 0
	global_load_lds_dwordx4 v[166:167], off
	v_lshl_add_u64 v[166:167], v[250:251], 0, s[92:93]
	s_mov_b32 m0, s57
	s_nop 0
	global_load_lds_dwordx4 v[166:167], off
	s_waitcnt vmcnt(8)
	s_waitcnt lgkmcnt(0)
	s_barrier
	s_waitcnt lgkmcnt(0)
	v_mfma_f32_16x16x32_bf16 v[56:59], v[146:149], v[192:195], v[56:59]
	v_mfma_f32_16x16x32_bf16 v[48:51], v[158:161], v[192:195], v[48:51]
	v_mfma_f32_16x16x32_bf16 v[40:43], v[146:149], v[200:203], v[40:43]
	v_mfma_f32_16x16x32_bf16 v[32:35], v[158:161], v[200:203], v[32:35]
	v_mfma_f32_16x16x32_bf16 v[24:27], v[146:149], v[208:211], v[24:27]
	v_mfma_f32_16x16x32_bf16 v[16:19], v[158:161], v[208:211], v[16:19]
	v_mfma_f32_16x16x32_bf16 v[8:11], v[146:149], v[216:219], v[8:11]
	v_mfma_f32_16x16x32_bf16 v[4:7], v[158:161], v[216:219], v[4:7]
	v_mfma_f32_16x16x32_bf16 v[56:59], v[154:157], v[196:199], v[56:59]
	v_mfma_f32_16x16x32_bf16 v[48:51], v[162:165], v[196:199], v[48:51]
	v_mfma_f32_16x16x32_bf16 v[40:43], v[154:157], v[204:207], v[40:43]
	v_mfma_f32_16x16x32_bf16 v[32:35], v[162:165], v[204:207], v[32:35]
	v_mfma_f32_16x16x32_bf16 v[24:27], v[154:157], v[212:215], v[24:27]
	v_mfma_f32_16x16x32_bf16 v[16:19], v[162:165], v[212:215], v[16:19]
	v_mfma_f32_16x16x32_bf16 v[8:11], v[154:157], v[240:243], v[8:11]
	v_mfma_f32_16x16x32_bf16 v[4:7], v[162:165], v[240:243], v[4:7]
	v_mfma_f32_16x16x32_bf16 v[60:63], v[176:179], v[192:195], v[60:63]
	v_mfma_f32_16x16x32_bf16 v[52:55], v[184:187], v[192:195], v[52:55]
	v_mfma_f32_16x16x32_bf16 v[44:47], v[176:179], v[200:203], v[44:47]
	v_mfma_f32_16x16x32_bf16 v[36:39], v[184:187], v[200:203], v[36:39]
	v_mfma_f32_16x16x32_bf16 v[28:31], v[176:179], v[208:211], v[28:31]
	v_mfma_f32_16x16x32_bf16 v[20:23], v[184:187], v[208:211], v[20:23]
	v_mfma_f32_16x16x32_bf16 v[12:15], v[176:179], v[216:219], v[12:15]
	v_mfma_f32_16x16x32_bf16 v[0:3], v[184:187], v[216:219], v[0:3]
	v_mfma_f32_16x16x32_bf16 v[60:63], v[180:183], v[196:199], v[60:63]
	v_mfma_f32_16x16x32_bf16 v[52:55], v[188:191], v[196:199], v[52:55]
	v_mfma_f32_16x16x32_bf16 v[44:47], v[180:183], v[204:207], v[44:47]
	v_mfma_f32_16x16x32_bf16 v[36:39], v[188:191], v[204:207], v[36:39]
	v_mfma_f32_16x16x32_bf16 v[28:31], v[180:183], v[212:215], v[28:31]
	v_mfma_f32_16x16x32_bf16 v[20:23], v[188:191], v[212:215], v[20:23]
	v_mfma_f32_16x16x32_bf16 v[12:15], v[180:183], v[240:243], v[12:15]
	v_mfma_f32_16x16x32_bf16 v[0:3], v[188:191], v[240:243], v[0:3]
	s_barrier
	v_lshl_add_u64 v[142:143], v[142:143], 0, s[80:81]
	v_lshl_add_u64 v[144:145], v[144:145], 0, s[80:81]
	s_mov_b32 s10, s11
	s_cmp_eq_u32 s10, s58
	s_cbranch_scc1 .Lgu_last
; #define PG8_STAGE(bufoff, gbase, voff) do { _Pragma("unroll") for (int _i = 0; _i < 2; ++_i) \
;         __builtin_amdgcn_global_load_lds((const unsigned*)((const char*)(gbase) + (voff)[_i]), (LAS unsigned*)(lds + (bufoff) + ldsw + _i * 8192), 16, 0, 0); } while (0)
; #define PG8_LDA(dst, b, h) do { _Pragma("unroll") for (int m = 0; m < 4; ++m) _Pragma("unroll") for (int k = 0; k < 2; ++k) dst[m][k] = *(const LAS bf16x8*)(lds + PG8_SA(b, h) + aoff + m * 2048 + k * 1024); } while (0)
; #define PG8_LDB(dst, b, h) do { _Pragma("unroll") for (int n = 0; n < 2; ++n) _Pragma("unroll") for (int k = 0; k < 2; ++k) dst[n][k] = *(const LAS bf16x8*)(lds + PG8_SB(b, h) + boff + n * 2048 + k * 1024); } while (0)
; #define PG8_MMA(ai, bj, At, Bt) do { __builtin_amdgcn_s_setprio(1); _Pragma("unroll") for (int k = 0; k < 2; ++k) _Pragma("unroll") for (int m = 0; m < 4; ++m) _Pragma("unroll") for (int n = 0; n < 2; ++n) \
;         acc[ai][bj][m][n] = __builtin_amdgcn_mfma_f32_16x16x32_bf16(Bt[n][k], At[m][k], acc[ai][bj][m][n], 0, 0, 0); __builtin_amdgcn_s_setprio(0); } while (0)
; #define PG8_WAIT_V(n) asm volatile("s_waitcnt vmcnt(" #n ")" ::: "memory")
; #define PG8_WAIT_L(n) asm volatile("s_waitcnt lgkmcnt(" #n ")" ::: "memory")
; #define PG8_BAR __builtin_amdgcn_s_barrier()
; #define PG8_SCHED __builtin_amdgcn_sched_barrier(0)
; template <class Epi, bool ALIGN_EPI>
; __device__ __forceinline__ void gemm_phase(LAS unsigned char* lds, const Gemm g, const StaticOrder& S, const Epi& E, const int tid) {
;     ...
;             PG8_LDB(B0, 0, 0); PG8_LDB(B1, 0, 1); PG8_SCHED; PG8_LDA(At, 0, 0); PG8_STAGE(PG8_SA(1, 1), a1 + hA, voffA);
;             PG8_WAIT_V(8); PG8_WAIT_L(0); PG8_BAR; PG8_MMA(0, 0, At, B0); PG8_MMA(0, 1, At, B1); PG8_BAR; PG8_SCHED;
;             PG8_LDA(At, 0, 1); PG8_STAGE(PG8_SB(0, 0), b2, voffB); PG8_STAGE(PG8_SB(0, 1), b2 + hB, voffB); PG8_STAGE(PG8_SA(0, 0), a2, voffA);
.LBB0_308:
	s_add_i32 s11, s10, 2
	s_cmp_eq_u32 s58, s10
	v_lshl_add_u64 v[146:147], v[142:143], 0, s[92:93]
	s_cselect_b64 vcc, -1, 0
	v_add_u32_e32 v150, s33, v151
	s_add_i32 s10, 0, 0x14000
	v_cndmask_b32_e32 v167, v147, v139, vcc
	v_cndmask_b32_e32 v166, v146, v138, vcc
	ds_read_b128 v[146:149], v150
	ds_read_b128 v[154:157], v150 offset:1024
	ds_read_b128 v[158:161], v150 offset:2048
	ds_read_b128 v[162:165], v150 offset:3072
	v_add_u32_e32 v150, s10, v151
	ds_read_b128 v[176:179], v150
	ds_read_b128 v[180:183], v150 offset:1024
	ds_read_b128 v[184:187], v150 offset:2048
	ds_read_b128 v[188:191], v150 offset:3072
	v_cndmask_b32_e32 v221, v145, v141, vcc
	v_cndmask_b32_e32 v220, v144, v140, vcc
	v_lshl_add_u64 v[226:227], v[142:143], 0, v[134:135]
	s_add_i32 m0, s51, 0xc000
	ds_read_b128 v[192:195], v153
	ds_read_b128 v[196:199], v153 offset:1024
	ds_read_b128 v[200:203], v153 offset:2048
	ds_read_b128 v[204:207], v153 offset:3072
	ds_read_b128 v[208:211], v153 offset:4096
	ds_read_b128 v[212:215], v153 offset:5120
	ds_read_b128 v[216:219], v153 offset:6144
	ds_read_b128 v[240:243], v153 offset:7168
	global_load_lds_dwordx4 v[226:227], off
	v_lshl_add_u64 v[226:227], v[142:143], 0, v[136:137]
	s_add_i32 m0, s51, 0xe000
	s_nop 0
	global_load_lds_dwordx4 v[226:227], off
	s_waitcnt vmcnt(8)
	s_waitcnt lgkmcnt(0)
	s_barrier
	s_waitcnt lgkmcnt(0)
	v_mfma_f32_16x16x32_bf16 v[120:123], v[146:149], v[192:195], v[120:123]
	v_mfma_f32_16x16x32_bf16 v[112:115], v[158:161], v[192:195], v[112:115]
	v_mfma_f32_16x16x32_bf16 v[104:107], v[146:149], v[200:203], v[104:107]
	v_mfma_f32_16x16x32_bf16 v[96:99], v[158:161], v[200:203], v[96:99]
	v_mfma_f32_16x16x32_bf16 v[88:91], v[146:149], v[208:211], v[88:91]
	v_mfma_f32_16x16x32_bf16 v[80:83], v[158:161], v[208:211], v[80:83]
	v_mfma_f32_16x16x32_bf16 v[72:75], v[146:149], v[216:219], v[72:75]
	v_mfma_f32_16x16x32_bf16 v[64:67], v[158:161], v[216:219], v[64:67]
	v_mfma_f32_16x16x32_bf16 v[120:123], v[154:157], v[196:199], v[120:123]
	v_mfma_f32_16x16x32_bf16 v[112:115], v[162:165], v[196:199], v[112:115]
	v_mfma_f32_16x16x32_bf16 v[104:107], v[154:157], v[204:207], v[104:107]
	v_mfma_f32_16x16x32_bf16 v[96:99], v[162:165], v[204:207], v[96:99]
	v_mfma_f32_16x16x32_bf16 v[88:91], v[154:157], v[212:215], v[88:91]
	v_mfma_f32_16x16x32_bf16 v[80:83], v[162:165], v[212:215], v[80:83]
	v_mfma_f32_16x16x32_bf16 v[72:75], v[154:157], v[240:243], v[72:75]
	v_mfma_f32_16x16x32_bf16 v[64:67], v[162:165], v[240:243], v[64:67]
	v_mfma_f32_16x16x32_bf16 v[124:127], v[176:179], v[192:195], v[124:127]
	v_mfma_f32_16x16x32_bf16 v[116:119], v[184:187], v[192:195], v[116:119]
	v_mfma_f32_16x16x32_bf16 v[108:111], v[176:179], v[200:203], v[108:111]
	v_mfma_f32_16x16x32_bf16 v[100:103], v[184:187], v[200:203], v[100:103]
	v_mfma_f32_16x16x32_bf16 v[92:95], v[176:179], v[208:211], v[92:95]
	v_mfma_f32_16x16x32_bf16 v[84:87], v[184:187], v[208:211], v[84:87]
	v_mfma_f32_16x16x32_bf16 v[76:79], v[176:179], v[216:219], v[76:79]
	v_mfma_f32_16x16x32_bf16 v[68:71], v[184:187], v[216:219], v[68:71]
	v_mfma_f32_16x16x32_bf16 v[124:127], v[180:183], v[196:199], v[124:127]
	v_mfma_f32_16x16x32_bf16 v[116:119], v[188:191], v[196:199], v[116:119]
	v_mfma_f32_16x16x32_bf16 v[108:111], v[180:183], v[204:207], v[108:111]
	v_mfma_f32_16x16x32_bf16 v[100:103], v[188:191], v[204:207], v[100:103]
	v_mfma_f32_16x16x32_bf16 v[92:95], v[180:183], v[212:215], v[92:95]
	v_mfma_f32_16x16x32_bf16 v[84:87], v[188:191], v[212:215], v[84:87]
	v_mfma_f32_16x16x32_bf16 v[76:79], v[180:183], v[240:243], v[76:79]
	v_mfma_f32_16x16x32_bf16 v[68:71], v[188:191], v[240:243], v[68:71]
	s_barrier
	s_add_i32 s65, s33, s45
	v_lshl_add_u64 v[226:227], v[220:221], 0, v[168:169]
	s_mov_b32 m0, s65
	ds_read_b128 v[192:195], v153 offset:16384
	ds_read_b128 v[196:199], v153 offset:17408
	ds_read_b128 v[200:203], v153 offset:18432
	ds_read_b128 v[204:207], v153 offset:19456
	ds_read_b128 v[208:211], v153 offset:20480
	ds_read_b128 v[212:215], v153 offset:21504
	ds_read_b128 v[216:219], v153 offset:22528
	ds_read_b128 v[240:243], v153 offset:23552
	global_load_lds_dwordx4 v[226:227], off
	v_lshl_add_u64 v[244:245], v[220:221], 0, v[128:129]
	s_add_i32 m0, s65, 0x2000
	v_lshl_add_u64 v[220:221], v[220:221], 0, s[12:13]
	s_add_i32 s10, s10, s45
	global_load_lds_dwordx4 v[244:245], off
	v_lshl_add_u64 v[246:247], v[220:221], 0, v[168:169]
	s_mov_b32 m0, s10
	v_lshl_add_u64 v[220:221], v[220:221], 0, v[128:129]
	global_load_lds_dwordx4 v[246:247], off
	s_add_i32 m0, s10, 0x2000
	v_lshl_add_u64 v[248:249], v[166:167], 0, v[132:133]
	global_load_lds_dwordx4 v[220:221], off
	s_mov_b32 m0, s51
	v_lshl_add_u64 v[250:251], v[166:167], 0, v[130:131]
	global_load_lds_dwordx4 v[248:249], off
	s_mov_b32 m0, s52
	s_nop 0
	global_load_lds_dwordx4 v[250:251], off
	s_waitcnt vmcnt(8)
	s_waitcnt lgkmcnt(0)
	s_barrier
; #define PG8_STAGE(bufoff, gbase, voff) do { _Pragma("unroll") for (int _i = 0; _i < 2; ++_i) \
;         __builtin_amdgcn_global_load_lds((const unsigned*)((const char*)(gbase) + (voff)[_i]), (LAS unsigned*)(lds + (bufoff) + ldsw + _i * 8192), 16, 0, 0); } while (0)
; #define PG8_LDA(dst, b, h) do { _Pragma("unroll") for (int m = 0; m < 4; ++m) _Pragma("unroll") for (int k = 0; k < 2; ++k) dst[m][k] = *(const LAS bf16x8*)(lds + PG8_SA(b, h) + aoff + m * 2048 + k * 1024); } while (0)
; #define PG8_LDB(dst, b, h) do { _Pragma("unroll") for (int n = 0; n < 2; ++n) _Pragma("unroll") for (int k = 0; k < 2; ++k) dst[n][k] = *(const LAS bf16x8*)(lds + PG8_SB(b, h) + boff + n * 2048 + k * 1024); } while (0)
; #define PG8_MMA(ai, bj, At, Bt) do { __builtin_amdgcn_s_setprio(1); _Pragma("unroll") for (int k = 0; k < 2; ++k) _Pragma("unroll") for (int m = 0; m < 4; ++m) _Pragma("unroll") for (int n = 0; n < 2; ++n) \
;         acc[ai][bj][m][n] = __builtin_amdgcn_mfma_f32_16x16x32_bf16(Bt[n][k], At[m][k], acc[ai][bj][m][n], 0, 0, 0); __builtin_amdgcn_s_setprio(0); } while (0)
; #define PG8_WAIT_V(n) asm volatile("s_waitcnt vmcnt(" #n ")" ::: "memory")
; #define PG8_WAIT_L(n) asm volatile("s_waitcnt lgkmcnt(" #n ")" ::: "memory")
; #define PG8_BAR __builtin_amdgcn_s_barrier()
; #define PG8_SCHED __builtin_amdgcn_sched_barrier(0)
; template <class Epi, bool ALIGN_EPI>
; __device__ __forceinline__ void gemm_phase(LAS unsigned char* lds, const Gemm g, const StaticOrder& S, const Epi& E, const int tid) {
;     ...
;             PG8_WAIT_V(8); PG8_WAIT_L(0); PG8_BAR; PG8_MMA(1, 0, At, B0); PG8_MMA(1, 1, At, B1); PG8_BAR; PG8_SCHED;
;             PG8_LDB(B0, 1, 0); PG8_LDB(B1, 1, 1); PG8_SCHED; PG8_LDA(At, 1, 0); PG8_STAGE(PG8_SA(0, 1), a2 + hA, voffA);
;             PG8_WAIT_V(8); PG8_WAIT_L(0); PG8_BAR; PG8_MMA(0, 0, At, B0); PG8_MMA(0, 1, At, B1); PG8_BAR; PG8_SCHED;
	s_waitcnt lgkmcnt(0)
	v_mfma_f32_16x16x32_bf16 v[56:59], v[146:149], v[192:195], v[56:59]
	v_mfma_f32_16x16x32_bf16 v[48:51], v[158:161], v[192:195], v[48:51]
	v_mfma_f32_16x16x32_bf16 v[40:43], v[146:149], v[200:203], v[40:43]
	v_mfma_f32_16x16x32_bf16 v[32:35], v[158:161], v[200:203], v[32:35]
	v_mfma_f32_16x16x32_bf16 v[24:27], v[146:149], v[208:211], v[24:27]
	v_mfma_f32_16x16x32_bf16 v[16:19], v[158:161], v[208:211], v[16:19]
	v_mfma_f32_16x16x32_bf16 v[8:11], v[146:149], v[216:219], v[8:11]
	v_mfma_f32_16x16x32_bf16 v[4:7], v[158:161], v[216:219], v[4:7]
	v_mfma_f32_16x16x32_bf16 v[56:59], v[154:157], v[196:199], v[56:59]
	v_mfma_f32_16x16x32_bf16 v[48:51], v[162:165], v[196:199], v[48:51]
	v_mfma_f32_16x16x32_bf16 v[40:43], v[154:157], v[204:207], v[40:43]
	v_mfma_f32_16x16x32_bf16 v[32:35], v[162:165], v[204:207], v[32:35]
	v_mfma_f32_16x16x32_bf16 v[24:27], v[154:157], v[212:215], v[24:27]
	v_mfma_f32_16x16x32_bf16 v[16:19], v[162:165], v[212:215], v[16:19]
	v_mfma_f32_16x16x32_bf16 v[8:11], v[154:157], v[240:243], v[8:11]
	v_mfma_f32_16x16x32_bf16 v[4:7], v[162:165], v[240:243], v[4:7]
	v_mfma_f32_16x16x32_bf16 v[60:63], v[176:179], v[192:195], v[60:63]
	v_mfma_f32_16x16x32_bf16 v[52:55], v[184:187], v[192:195], v[52:55]
	v_mfma_f32_16x16x32_bf16 v[44:47], v[176:179], v[200:203], v[44:47]
	v_mfma_f32_16x16x32_bf16 v[36:39], v[184:187], v[200:203], v[36:39]
	v_mfma_f32_16x16x32_bf16 v[28:31], v[176:179], v[208:211], v[28:31]
	v_mfma_f32_16x16x32_bf16 v[20:23], v[184:187], v[208:211], v[20:23]
	v_mfma_f32_16x16x32_bf16 v[12:15], v[176:179], v[216:219], v[12:15]
	v_mfma_f32_16x16x32_bf16 v[0:3], v[184:187], v[216:219], v[0:3]
	v_mfma_f32_16x16x32_bf16 v[60:63], v[180:183], v[196:199], v[60:63]
	v_mfma_f32_16x16x32_bf16 v[52:55], v[188:191], v[196:199], v[52:55]
	v_mfma_f32_16x16x32_bf16 v[44:47], v[180:183], v[204:207], v[44:47]
	v_mfma_f32_16x16x32_bf16 v[36:39], v[188:191], v[204:207], v[36:39]
	v_mfma_f32_16x16x32_bf16 v[28:31], v[180:183], v[212:215], v[28:31]
	v_mfma_f32_16x16x32_bf16 v[20:23], v[188:191], v[212:215], v[20:23]
	v_mfma_f32_16x16x32_bf16 v[12:15], v[180:183], v[240:243], v[12:15]
	v_mfma_f32_16x16x32_bf16 v[0:3], v[188:191], v[240:243], v[0:3]
	s_barrier
	s_add_i32 s10, 0, 0x18000
	v_add_u32_e32 v150, s10, v151
	s_add_i32 s65, 0, 0x1c000
	ds_read_b128 v[146:149], v150
	ds_read_b128 v[154:157], v150 offset:1024
	ds_read_b128 v[158:161], v150 offset:2048
	ds_read_b128 v[162:165], v150 offset:3072
	v_add_u32_e32 v150, s65, v151
	ds_read_b128 v[176:179], v150
	ds_read_b128 v[180:183], v150 offset:1024
	ds_read_b128 v[184:187], v150 offset:2048
	ds_read_b128 v[188:191], v150 offset:3072
	v_lshl_add_u64 v[166:167], v[166:167], 0, s[94:95]
	s_mov_b32 m0, s53
	v_lshl_add_u64 v[252:253], v[166:167], 0, v[132:133]
	ds_read_b128 v[192:195], v153 offset:32768
	ds_read_b128 v[196:199], v153 offset:33792
	ds_read_b128 v[200:203], v153 offset:34816
	ds_read_b128 v[204:207], v153 offset:35840
	ds_read_b128 v[208:211], v153 offset:36864
	ds_read_b128 v[212:215], v153 offset:37888
	ds_read_b128 v[216:219], v153 offset:38912
	ds_read_b128 v[240:243], v153 offset:39936
	global_load_lds_dwordx4 v[252:253], off
	v_lshl_add_u64 v[166:167], v[166:167], 0, v[130:131]
	s_mov_b32 m0, s54
	s_nop 0
	global_load_lds_dwordx4 v[166:167], off
	s_waitcnt vmcnt(8)
	s_waitcnt lgkmcnt(0)
	s_barrier
	s_waitcnt lgkmcnt(0)
	v_mfma_f32_16x16x32_bf16 v[120:123], v[146:149], v[192:195], v[120:123]
	v_mfma_f32_16x16x32_bf16 v[112:115], v[158:161], v[192:195], v[112:115]
	v_mfma_f32_16x16x32_bf16 v[104:107], v[146:149], v[200:203], v[104:107]
	v_mfma_f32_16x16x32_bf16 v[96:99], v[158:161], v[200:203], v[96:99]
	v_mfma_f32_16x16x32_bf16 v[88:91], v[146:149], v[208:211], v[88:91]
	v_mfma_f32_16x16x32_bf16 v[80:83], v[158:161], v[208:211], v[80:83]
	v_mfma_f32_16x16x32_bf16 v[72:75], v[146:149], v[216:219], v[72:75]
	v_mfma_f32_16x16x32_bf16 v[64:67], v[158:161], v[216:219], v[64:67]
	v_mfma_f32_16x16x32_bf16 v[120:123], v[154:157], v[196:199], v[120:123]
	v_mfma_f32_16x16x32_bf16 v[112:115], v[162:165], v[196:199], v[112:115]
	v_mfma_f32_16x16x32_bf16 v[104:107], v[154:157], v[204:207], v[104:107]
	v_mfma_f32_16x16x32_bf16 v[96:99], v[162:165], v[204:207], v[96:99]
	v_mfma_f32_16x16x32_bf16 v[88:91], v[154:157], v[212:215], v[88:91]
	v_mfma_f32_16x16x32_bf16 v[80:83], v[162:165], v[212:215], v[80:83]
	v_mfma_f32_16x16x32_bf16 v[72:75], v[154:157], v[240:243], v[72:75]
	v_mfma_f32_16x16x32_bf16 v[64:67], v[162:165], v[240:243], v[64:67]
	v_mfma_f32_16x16x32_bf16 v[124:127], v[176:179], v[192:195], v[124:127]
	v_mfma_f32_16x16x32_bf16 v[116:119], v[184:187], v[192:195], v[116:119]
	v_mfma_f32_16x16x32_bf16 v[108:111], v[176:179], v[200:203], v[108:111]
	v_mfma_f32_16x16x32_bf16 v[100:103], v[184:187], v[200:203], v[100:103]
	v_mfma_f32_16x16x32_bf16 v[92:95], v[176:179], v[208:211], v[92:95]
	v_mfma_f32_16x16x32_bf16 v[84:87], v[184:187], v[208:211], v[84:87]
	v_mfma_f32_16x16x32_bf16 v[76:79], v[176:179], v[216:219], v[76:79]
	v_mfma_f32_16x16x32_bf16 v[68:71], v[184:187], v[216:219], v[68:71]
	v_mfma_f32_16x16x32_bf16 v[124:127], v[180:183], v[196:199], v[124:127]
	v_mfma_f32_16x16x32_bf16 v[116:119], v[188:191], v[196:199], v[116:119]
	v_mfma_f32_16x16x32_bf16 v[108:111], v[180:183], v[204:207], v[108:111]
	v_mfma_f32_16x16x32_bf16 v[100:103], v[188:191], v[204:207], v[100:103]
	v_mfma_f32_16x16x32_bf16 v[92:95], v[180:183], v[212:215], v[92:95]
	v_mfma_f32_16x16x32_bf16 v[84:87], v[188:191], v[212:215], v[84:87]
	v_mfma_f32_16x16x32_bf16 v[76:79], v[180:183], v[240:243], v[76:79]
	v_mfma_f32_16x16x32_bf16 v[68:71], v[188:191], v[240:243], v[68:71]
	s_barrier
; #define PG8_STAGE(bufoff, gbase, voff) do { _Pragma("unroll") for (int _i = 0; _i < 2; ++_i) \
;         __builtin_amdgcn_global_load_lds((const unsigned*)((const char*)(gbase) + (voff)[_i]), (LAS unsigned*)(lds + (bufoff) + ldsw + _i * 8192), 16, 0, 0); } while (0)
; #define PG8_LDA(dst, b, h) do { _Pragma("unroll") for (int m = 0; m < 4; ++m) _Pragma("unroll") for (int k = 0; k < 2; ++k) dst[m][k] = *(const LAS bf16x8*)(lds + PG8_SA(b, h) + aoff + m * 2048 + k * 1024); } while (0)
; #define PG8_LDB(dst, b, h) do { _Pragma("unroll") for (int n = 0; n < 2; ++n) _Pragma("unroll") for (int k = 0; k < 2; ++k) dst[n][k] = *(const LAS bf16x8*)(lds + PG8_SB(b, h) + boff + n * 2048 + k * 1024); } while (0)
; #define PG8_MMA(ai, bj, At, Bt) do { __builtin_amdgcn_s_setprio(1); _Pragma("unroll") for (int k = 0; k < 2; ++k) _Pragma("unroll") for (int m = 0; m < 4; ++m) _Pragma("unroll") for (int n = 0; n < 2; ++n) \
;         acc[ai][bj][m][n] = __builtin_amdgcn_mfma_f32_16x16x32_bf16(Bt[n][k], At[m][k], acc[ai][bj][m][n], 0, 0, 0); __builtin_amdgcn_s_setprio(0); } while (0)
; #define PG8_WAIT_V(n) asm volatile("s_waitcnt vmcnt(" #n ")" ::: "memory")
; #define PG8_WAIT_L(n) asm volatile("s_waitcnt lgkmcnt(" #n ")" ::: "memory")
; #define PG8_BAR __builtin_amdgcn_s_barrier()
; #define PG8_SCHED __builtin_amdgcn_sched_barrier(0)
; template <class Epi, bool ALIGN_EPI>
; __device__ __forceinline__ void gemm_phase(LAS unsigned char* lds, const Gemm g, const StaticOrder& S, const Epi& E, const int tid) {
;     ...
;             PG8_LDB(B0, 0, 0); PG8_LDB(B1, 0, 1); PG8_SCHED; PG8_LDA(At, 0, 0); PG8_STAGE(PG8_SA(1, 1), a1 + hA, voffA);
;     ...
;             PG8_LDA(At, 1, 1); PG8_STAGE(PG8_SB(1, 0), b3, voffB); PG8_STAGE(PG8_SB(1, 1), b3 + hB, voffB); PG8_STAGE(PG8_SA(1, 0), a3, voffA);
;             PG8_WAIT_V(8); PG8_WAIT_L(0); PG8_BAR; PG8_MMA(1, 0, At, B0); PG8_MMA(1, 1, At, B1); PG8_BAR; PG8_SCHED;
	s_add_i32 s10, s10, s45
	v_lshl_add_u64 v[166:167], v[226:227], 0, s[92:93]
	s_mov_b32 m0, s10
	ds_read_b128 v[192:195], v153 offset:49152
	ds_read_b128 v[196:199], v153 offset:50176
	ds_read_b128 v[200:203], v153 offset:51200
	ds_read_b128 v[204:207], v153 offset:52224
	ds_read_b128 v[208:211], v153 offset:53248
	ds_read_b128 v[212:215], v153 offset:54272
	ds_read_b128 v[216:219], v153 offset:55296
	ds_read_b128 v[240:243], v153 offset:56320
	global_load_lds_dwordx4 v[166:167], off
	v_lshl_add_u64 v[166:167], v[244:245], 0, s[92:93]
	s_add_i32 m0, s10, 0x2000
	s_add_i32 s10, s65, s45
	global_load_lds_dwordx4 v[166:167], off
	v_lshl_add_u64 v[166:167], v[246:247], 0, s[92:93]
	s_mov_b32 m0, s10
	s_nop 0
	global_load_lds_dwordx4 v[166:167], off
	v_lshl_add_u64 v[166:167], v[220:221], 0, s[92:93]
	s_add_i32 m0, s10, 0x2000
	s_nop 0
	global_load_lds_dwordx4 v[166:167], off
	v_lshl_add_u64 v[166:167], v[248:249], 0, s[92:93]
	s_mov_b32 m0, s56
	s_nop 0
	global_load_lds_dwordx4 v[166:167], off
	v_lshl_add_u64 v[166:167], v[250:251], 0, s[92:93]
	s_mov_b32 m0, s57
	s_nop 0
	global_load_lds_dwordx4 v[166:167], off
	s_waitcnt vmcnt(8)
	s_waitcnt lgkmcnt(0)
	s_barrier
	s_waitcnt lgkmcnt(0)
	v_mfma_f32_16x16x32_bf16 v[56:59], v[146:149], v[192:195], v[56:59]
	v_mfma_f32_16x16x32_bf16 v[48:51], v[158:161], v[192:195], v[48:51]
	v_mfma_f32_16x16x32_bf16 v[40:43], v[146:149], v[200:203], v[40:43]
	v_mfma_f32_16x16x32_bf16 v[32:35], v[158:161], v[200:203], v[32:35]
	v_mfma_f32_16x16x32_bf16 v[24:27], v[146:149], v[208:211], v[24:27]
	v_mfma_f32_16x16x32_bf16 v[16:19], v[158:161], v[208:211], v[16:19]
	v_mfma_f32_16x16x32_bf16 v[8:11], v[146:149], v[216:219], v[8:11]
	v_mfma_f32_16x16x32_bf16 v[4:7], v[158:161], v[216:219], v[4:7]
	v_mfma_f32_16x16x32_bf16 v[56:59], v[154:157], v[196:199], v[56:59]
	v_mfma_f32_16x16x32_bf16 v[48:51], v[162:165], v[196:199], v[48:51]
	v_mfma_f32_16x16x32_bf16 v[40:43], v[154:157], v[204:207], v[40:43]
	v_mfma_f32_16x16x32_bf16 v[32:35], v[162:165], v[204:207], v[32:35]
	v_mfma_f32_16x16x32_bf16 v[24:27], v[154:157], v[212:215], v[24:27]
	v_mfma_f32_16x16x32_bf16 v[16:19], v[162:165], v[212:215], v[16:19]
	v_mfma_f32_16x16x32_bf16 v[8:11], v[154:157], v[240:243], v[8:11]
	v_mfma_f32_16x16x32_bf16 v[4:7], v[162:165], v[240:243], v[4:7]
	v_mfma_f32_16x16x32_bf16 v[60:63], v[176:179], v[192:195], v[60:63]
	v_mfma_f32_16x16x32_bf16 v[52:55], v[184:187], v[192:195], v[52:55]
	v_mfma_f32_16x16x32_bf16 v[44:47], v[176:179], v[200:203], v[44:47]
	v_mfma_f32_16x16x32_bf16 v[36:39], v[184:187], v[200:203], v[36:39]
	v_mfma_f32_16x16x32_bf16 v[28:31], v[176:179], v[208:211], v[28:31]
	v_mfma_f32_16x16x32_bf16 v[20:23], v[184:187], v[208:211], v[20:23]
	v_mfma_f32_16x16x32_bf16 v[12:15], v[176:179], v[216:219], v[12:15]
	v_mfma_f32_16x16x32_bf16 v[0:3], v[184:187], v[216:219], v[0:3]
	v_mfma_f32_16x16x32_bf16 v[60:63], v[180:183], v[196:199], v[60:63]
	v_mfma_f32_16x16x32_bf16 v[52:55], v[188:191], v[196:199], v[52:55]
	v_mfma_f32_16x16x32_bf16 v[44:47], v[180:183], v[204:207], v[44:47]
	v_mfma_f32_16x16x32_bf16 v[36:39], v[188:191], v[204:207], v[36:39]
	v_mfma_f32_16x16x32_bf16 v[28:31], v[180:183], v[212:215], v[28:31]
	v_mfma_f32_16x16x32_bf16 v[20:23], v[188:191], v[212:215], v[20:23]
	v_mfma_f32_16x16x32_bf16 v[12:15], v[180:183], v[240:243], v[12:15]
	v_mfma_f32_16x16x32_bf16 v[0:3], v[188:191], v[240:243], v[0:3]
	s_barrier
	v_lshl_add_u64 v[142:143], v[142:143], 0, s[80:81]
	v_lshl_add_u64 v[144:145], v[144:145], 0, s[80:81]
	s_mov_b32 s10, s11
	s_cmp_lg_u32 s10, s58
	s_cbranch_scc1 .LBB0_308
.Lgu_last:
	s_add_i32 s11, s10, 2
	s_cmp_eq_u32 s58, s10
	v_lshl_add_u64 v[146:147], v[142:143], 0, s[92:93]
	s_cselect_b64 vcc, -1, 0
	v_add_u32_e32 v150, s33, v151
	s_add_i32 s10, 0, 0x14000
	v_cndmask_b32_e32 v167, v147, v139, vcc
	v_cndmask_b32_e32 v166, v146, v138, vcc
	ds_read_b128 v[146:149], v150
	ds_read_b128 v[154:157], v150 offset:1024
	ds_read_b128 v[158:161], v150 offset:2048
	ds_read_b128 v[162:165], v150 offset:3072
	v_add_u32_e32 v150, s10, v151
	ds_read_b128 v[176:179], v150
	ds_read_b128 v[180:183], v150 offset:1024
	ds_read_b128 v[184:187], v150 offset:2048
	ds_read_b128 v[188:191], v150 offset:3072
	v_cndmask_b32_e32 v221, v145, v141, vcc
	v_cndmask_b32_e32 v220, v144, v140, vcc
	v_lshl_add_u64 v[226:227], v[142:143], 0, v[134:135]
	s_add_i32 m0, s51, 0xc000
	ds_read_b128 v[192:195], v153
	ds_read_b128 v[196:199], v153 offset:1024
	ds_read_b128 v[200:203], v153 offset:2048
	ds_read_b128 v[204:207], v153 offset:3072
	ds_read_b128 v[208:211], v153 offset:4096
	ds_read_b128 v[212:215], v153 offset:5120
	ds_read_b128 v[216:219], v153 offset:6144
	ds_read_b128 v[240:243], v153 offset:7168
	global_load_lds_dwordx4 v[226:227], off
	v_lshl_add_u64 v[226:227], v[142:143], 0, v[136:137]
	s_add_i32 m0, s51, 0xe000
	s_nop 0
	global_load_lds_dwordx4 v[226:227], off
	s_waitcnt vmcnt(8)
	s_waitcnt lgkmcnt(0)
	s_barrier
; #define PG8_STAGE(bufoff, gbase, voff) do { _Pragma("unroll") for (int _i = 0; _i < 2; ++_i) \
;         __builtin_amdgcn_global_load_lds((const unsigned*)((const char*)(gbase) + (voff)[_i]), (LAS unsigned*)(lds + (bufoff) + ldsw + _i * 8192), 16, 0, 0); } while (0)
; #define PG8_LDA(dst, b, h) do { _Pragma("unroll") for (int m = 0; m < 4; ++m) _Pragma("unroll") for (int k = 0; k < 2; ++k) dst[m][k] = *(const LAS bf16x8*)(lds + PG8_SA(b, h) + aoff + m * 2048 + k * 1024); } while (0)
; #define PG8_MMA(ai, bj, At, Bt) do { __builtin_amdgcn_s_setprio(1); _Pragma("unroll") for (int k = 0; k < 2; ++k) _Pragma("unroll") for (int m = 0; m < 4; ++m) _Pragma("unroll") for (int n = 0; n < 2; ++n) \
;         acc[ai][bj][m][n] = __builtin_amdgcn_mfma_f32_16x16x32_bf16(Bt[n][k], At[m][k], acc[ai][bj][m][n], 0, 0, 0); __builtin_amdgcn_s_setprio(0); } while (0)
; #define PG8_WAIT_V(n) asm volatile("s_waitcnt vmcnt(" #n ")" ::: "memory")
; #define PG8_WAIT_L(n) asm volatile("s_waitcnt lgkmcnt(" #n ")" ::: "memory")
; #define PG8_BAR __builtin_amdgcn_s_barrier()
; #define PG8_SCHED __builtin_amdgcn_sched_barrier(0)
; template <class Epi, bool ALIGN_EPI>
; __device__ __forceinline__ void gemm_phase(LAS unsigned char* lds, const Gemm g, const StaticOrder& S, const Epi& E, const int tid) {
;     ...
;             PG8_WAIT_V(8); PG8_WAIT_L(0); PG8_BAR; PG8_MMA(0, 0, At, B0); PG8_MMA(0, 1, At, B1); PG8_BAR; PG8_SCHED;
;             PG8_LDA(At, 0, 1); PG8_STAGE(PG8_SB(0, 0), b2, voffB); PG8_STAGE(PG8_SB(0, 1), b2 + hB, voffB); PG8_STAGE(PG8_SA(0, 0), a2, voffA);
;             PG8_WAIT_V(8); PG8_WAIT_L(0); PG8_BAR; PG8_MMA(1, 0, At, B0); PG8_MMA(1, 1, At, B1); PG8_BAR; PG8_SCHED;
	s_waitcnt lgkmcnt(0)
	v_mfma_f32_16x16x32_bf16 v[120:123], v[146:149], v[192:195], v[120:123]
	v_mfma_f32_16x16x32_bf16 v[112:115], v[158:161], v[192:195], v[112:115]
	v_mfma_f32_16x16x32_bf16 v[104:107], v[146:149], v[200:203], v[104:107]
	v_mfma_f32_16x16x32_bf16 v[96:99], v[158:161], v[200:203], v[96:99]
	v_mfma_f32_16x16x32_bf16 v[88:91], v[146:149], v[208:211], v[88:91]
	v_mfma_f32_16x16x32_bf16 v[80:83], v[158:161], v[208:211], v[80:83]
	v_mfma_f32_16x16x32_bf16 v[72:75], v[146:149], v[216:219], v[72:75]
	v_mfma_f32_16x16x32_bf16 v[64:67], v[158:161], v[216:219], v[64:67]
	v_mfma_f32_16x16x32_bf16 v[120:123], v[154:157], v[196:199], v[120:123]
	v_mfma_f32_16x16x32_bf16 v[112:115], v[162:165], v[196:199], v[112:115]
	v_mfma_f32_16x16x32_bf16 v[104:107], v[154:157], v[204:207], v[104:107]
	v_mfma_f32_16x16x32_bf16 v[96:99], v[162:165], v[204:207], v[96:99]
	v_mfma_f32_16x16x32_bf16 v[88:91], v[154:157], v[212:215], v[88:91]
	v_mfma_f32_16x16x32_bf16 v[80:83], v[162:165], v[212:215], v[80:83]
	v_mfma_f32_16x16x32_bf16 v[72:75], v[154:157], v[240:243], v[72:75]
	v_mfma_f32_16x16x32_bf16 v[64:67], v[162:165], v[240:243], v[64:67]
	v_mfma_f32_16x16x32_bf16 v[124:127], v[176:179], v[192:195], v[124:127]
	v_mfma_f32_16x16x32_bf16 v[116:119], v[184:187], v[192:195], v[116:119]
	v_mfma_f32_16x16x32_bf16 v[108:111], v[176:179], v[200:203], v[108:111]
	v_mfma_f32_16x16x32_bf16 v[100:103], v[184:187], v[200:203], v[100:103]
	v_mfma_f32_16x16x32_bf16 v[92:95], v[176:179], v[208:211], v[92:95]
	v_mfma_f32_16x16x32_bf16 v[84:87], v[184:187], v[208:211], v[84:87]
	v_mfma_f32_16x16x32_bf16 v[76:79], v[176:179], v[216:219], v[76:79]
	v_mfma_f32_16x16x32_bf16 v[68:71], v[184:187], v[216:219], v[68:71]
	v_mfma_f32_16x16x32_bf16 v[124:127], v[180:183], v[196:199], v[124:127]
	v_mfma_f32_16x16x32_bf16 v[116:119], v[188:191], v[196:199], v[116:119]
	v_mfma_f32_16x16x32_bf16 v[108:111], v[180:183], v[204:207], v[108:111]
	v_mfma_f32_16x16x32_bf16 v[100:103], v[188:191], v[204:207], v[100:103]
	v_mfma_f32_16x16x32_bf16 v[92:95], v[180:183], v[212:215], v[92:95]
	v_mfma_f32_16x16x32_bf16 v[84:87], v[188:191], v[212:215], v[84:87]
	v_mfma_f32_16x16x32_bf16 v[76:79], v[180:183], v[240:243], v[76:79]
	v_mfma_f32_16x16x32_bf16 v[68:71], v[188:191], v[240:243], v[68:71]
	s_barrier
	s_add_i32 s65, s33, s45
	v_lshl_add_u64 v[226:227], v[220:221], 0, v[168:169]
	s_mov_b32 m0, s65
	ds_read_b128 v[192:195], v153 offset:16384
	ds_read_b128 v[196:199], v153 offset:17408
	ds_read_b128 v[200:203], v153 offset:18432
	ds_read_b128 v[204:207], v153 offset:19456
	ds_read_b128 v[208:211], v153 offset:20480
	ds_read_b128 v[212:215], v153 offset:21504
	ds_read_b128 v[216:219], v153 offset:22528
	ds_read_b128 v[240:243], v153 offset:23552
	global_load_lds_dwordx4 v[226:227], off
	v_lshl_add_u64 v[244:245], v[220:221], 0, v[128:129]
	s_add_i32 m0, s65, 0x2000
	v_lshl_add_u64 v[220:221], v[220:221], 0, s[12:13]
	s_add_i32 s10, s10, s45
	global_load_lds_dwordx4 v[244:245], off
	v_lshl_add_u64 v[246:247], v[220:221], 0, v[168:169]
	s_mov_b32 m0, s10
	v_lshl_add_u64 v[220:221], v[220:221], 0, v[128:129]
	global_load_lds_dwordx4 v[246:247], off
	s_add_i32 m0, s10, 0x2000
	v_lshl_add_u64 v[248:249], v[166:167], 0, v[132:133]
	global_load_lds_dwordx4 v[220:221], off
	s_mov_b32 m0, s51
	v_lshl_add_u64 v[250:251], v[166:167], 0, v[130:131]
	global_load_lds_dwordx4 v[248:249], off
	s_mov_b32 m0, s52
	s_nop 0
	global_load_lds_dwordx4 v[250:251], off
	s_waitcnt vmcnt(8)
	s_waitcnt lgkmcnt(0)
	s_barrier
	s_waitcnt lgkmcnt(0)
	v_mfma_f32_16x16x32_bf16 v[56:59], v[146:149], v[192:195], v[56:59]
	v_mfma_f32_16x16x32_bf16 v[48:51], v[158:161], v[192:195], v[48:51]
	v_mfma_f32_16x16x32_bf16 v[40:43], v[146:149], v[200:203], v[40:43]
	v_mfma_f32_16x16x32_bf16 v[32:35], v[158:161], v[200:203], v[32:35]
	v_mfma_f32_16x16x32_bf16 v[24:27], v[146:149], v[208:211], v[24:27]
	v_mfma_f32_16x16x32_bf16 v[16:19], v[158:161], v[208:211], v[16:19]
	v_mfma_f32_16x16x32_bf16 v[8:11], v[146:149], v[216:219], v[8:11]
	v_mfma_f32_16x16x32_bf16 v[4:7], v[158:161], v[216:219], v[4:7]
	v_mfma_f32_16x16x32_bf16 v[56:59], v[154:157], v[196:199], v[56:59]
	v_mfma_f32_16x16x32_bf16 v[48:51], v[162:165], v[196:199], v[48:51]
	v_mfma_f32_16x16x32_bf16 v[40:43], v[154:157], v[204:207], v[40:43]
	v_mfma_f32_16x16x32_bf16 v[32:35], v[162:165], v[204:207], v[32:35]
	v_mfma_f32_16x16x32_bf16 v[24:27], v[154:157], v[212:215], v[24:27]
	v_mfma_f32_16x16x32_bf16 v[16:19], v[162:165], v[212:215], v[16:19]
	v_mfma_f32_16x16x32_bf16 v[8:11], v[154:157], v[240:243], v[8:11]
	v_mfma_f32_16x16x32_bf16 v[4:7], v[162:165], v[240:243], v[4:7]
	v_mfma_f32_16x16x32_bf16 v[60:63], v[176:179], v[192:195], v[60:63]
	v_mfma_f32_16x16x32_bf16 v[52:55], v[184:187], v[192:195], v[52:55]
	v_mfma_f32_16x16x32_bf16 v[44:47], v[176:179], v[200:203], v[44:47]
	v_mfma_f32_16x16x32_bf16 v[36:39], v[184:187], v[200:203], v[36:39]
	v_mfma_f32_16x16x32_bf16 v[28:31], v[176:179], v[208:211], v[28:31]
	v_mfma_f32_16x16x32_bf16 v[20:23], v[184:187], v[208:211], v[20:23]
	v_mfma_f32_16x16x32_bf16 v[12:15], v[176:179], v[216:219], v[12:15]
	v_mfma_f32_16x16x32_bf16 v[0:3], v[184:187], v[216:219], v[0:3]
	v_mfma_f32_16x16x32_bf16 v[60:63], v[180:183], v[196:199], v[60:63]
	v_mfma_f32_16x16x32_bf16 v[52:55], v[188:191], v[196:199], v[52:55]
	v_mfma_f32_16x16x32_bf16 v[44:47], v[180:183], v[204:207], v[44:47]
	v_mfma_f32_16x16x32_bf16 v[36:39], v[188:191], v[204:207], v[36:39]
	v_mfma_f32_16x16x32_bf16 v[28:31], v[180:183], v[212:215], v[28:31]
	v_mfma_f32_16x16x32_bf16 v[20:23], v[188:191], v[212:215], v[20:23]
	v_mfma_f32_16x16x32_bf16 v[12:15], v[180:183], v[240:243], v[12:15]
	v_mfma_f32_16x16x32_bf16 v[0:3], v[188:191], v[240:243], v[0:3]
	s_barrier
; #define PG8_STAGE(bufoff, gbase, voff) do { _Pragma("unroll") for (int _i = 0; _i < 2; ++_i) \
;         __builtin_amdgcn_global_load_lds((const unsigned*)((const char*)(gbase) + (voff)[_i]), (LAS unsigned*)(lds + (bufoff) + ldsw + _i * 8192), 16, 0, 0); } while (0)
; #define PG8_LDA(dst, b, h) do { _Pragma("unroll") for (int m = 0; m < 4; ++m) _Pragma("unroll") for (int k = 0; k < 2; ++k) dst[m][k] = *(const LAS bf16x8*)(lds + PG8_SA(b, h) + aoff + m * 2048 + k * 1024); } while (0)
; #define PG8_LDB(dst, b, h) do { _Pragma("unroll") for (int n = 0; n < 2; ++n) _Pragma("unroll") for (int k = 0; k < 2; ++k) dst[n][k] = *(const LAS bf16x8*)(lds + PG8_SB(b, h) + boff + n * 2048 + k * 1024); } while (0)
; #define PG8_MMA(ai, bj, At, Bt) do { __builtin_amdgcn_s_setprio(1); _Pragma("unroll") for (int k = 0; k < 2; ++k) _Pragma("unroll") for (int m = 0; m < 4; ++m) _Pragma("unroll") for (int n = 0; n < 2; ++n) \
;         acc[ai][bj][m][n] = __builtin_amdgcn_mfma_f32_16x16x32_bf16(Bt[n][k], At[m][k], acc[ai][bj][m][n], 0, 0, 0); __builtin_amdgcn_s_setprio(0); } while (0)
; #define PG8_WAIT_V(n) asm volatile("s_waitcnt vmcnt(" #n ")" ::: "memory")
; #define PG8_WAIT_L(n) asm volatile("s_waitcnt lgkmcnt(" #n ")" ::: "memory")
; #define PG8_BAR __builtin_amdgcn_s_barrier()
; #define PG8_SCHED __builtin_amdgcn_sched_barrier(0)
; template <class Epi, bool ALIGN_EPI>
; __device__ __forceinline__ void gemm_phase(LAS unsigned char* lds, const Gemm g, const StaticOrder& S, const Epi& E, const int tid) {
;     ...
;             PG8_LDB(B0, 1, 0); PG8_LDB(B1, 1, 1); PG8_SCHED; PG8_LDA(At, 1, 0); PG8_STAGE(PG8_SA(0, 1), a2 + hA, voffA);
;             PG8_WAIT_V(8); PG8_WAIT_L(0); PG8_BAR; PG8_MMA(0, 0, At, B0); PG8_MMA(0, 1, At, B1); PG8_BAR; PG8_SCHED;
;             PG8_LDA(At, 1, 1); PG8_STAGE(PG8_SB(1, 0), b3, voffB); PG8_STAGE(PG8_SB(1, 1), b3 + hB, voffB); PG8_STAGE(PG8_SA(1, 0), a3, voffA);
	s_add_i32 s10, 0, 0x18000
	v_add_u32_e32 v150, s10, v151
	s_add_i32 s65, 0, 0x1c000
	ds_read_b128 v[146:149], v150
	ds_read_b128 v[154:157], v150 offset:1024
	ds_read_b128 v[158:161], v150 offset:2048
	ds_read_b128 v[162:165], v150 offset:3072
	v_add_u32_e32 v150, s65, v151
	ds_read_b128 v[176:179], v150
	ds_read_b128 v[180:183], v150 offset:1024
	ds_read_b128 v[184:187], v150 offset:2048
	ds_read_b128 v[188:191], v150 offset:3072
	v_lshl_add_u64 v[166:167], v[166:167], 0, s[94:95]
	s_mov_b32 m0, s53
	v_lshl_add_u64 v[252:253], v[166:167], 0, v[132:133]
	ds_read_b128 v[192:195], v153 offset:32768
	ds_read_b128 v[196:199], v153 offset:33792
	ds_read_b128 v[200:203], v153 offset:34816
	ds_read_b128 v[204:207], v153 offset:35840
	ds_read_b128 v[208:211], v153 offset:36864
	ds_read_b128 v[212:215], v153 offset:37888
	ds_read_b128 v[216:219], v153 offset:38912
	ds_read_b128 v[240:243], v153 offset:39936
	global_load_lds_dwordx4 v[252:253], off
	v_lshl_add_u64 v[166:167], v[166:167], 0, v[130:131]
	s_mov_b32 m0, s54
	s_nop 0
	global_load_lds_dwordx4 v[166:167], off
	s_waitcnt vmcnt(8)
	s_waitcnt lgkmcnt(0)
	s_barrier
	s_waitcnt lgkmcnt(0)
	v_mfma_f32_16x16x32_bf16 v[120:123], v[146:149], v[192:195], v[120:123]
	v_mfma_f32_16x16x32_bf16 v[112:115], v[158:161], v[192:195], v[112:115]
	v_mfma_f32_16x16x32_bf16 v[104:107], v[146:149], v[200:203], v[104:107]
	v_mfma_f32_16x16x32_bf16 v[96:99], v[158:161], v[200:203], v[96:99]
	v_mfma_f32_16x16x32_bf16 v[88:91], v[146:149], v[208:211], v[88:91]
	v_mfma_f32_16x16x32_bf16 v[80:83], v[158:161], v[208:211], v[80:83]
	v_mfma_f32_16x16x32_bf16 v[72:75], v[146:149], v[216:219], v[72:75]
	v_mfma_f32_16x16x32_bf16 v[64:67], v[158:161], v[216:219], v[64:67]
	v_mfma_f32_16x16x32_bf16 v[120:123], v[154:157], v[196:199], v[120:123]
	v_mfma_f32_16x16x32_bf16 v[112:115], v[162:165], v[196:199], v[112:115]
	v_mfma_f32_16x16x32_bf16 v[104:107], v[154:157], v[204:207], v[104:107]
	v_mfma_f32_16x16x32_bf16 v[96:99], v[162:165], v[204:207], v[96:99]
	v_mfma_f32_16x16x32_bf16 v[88:91], v[154:157], v[212:215], v[88:91]
	v_mfma_f32_16x16x32_bf16 v[80:83], v[162:165], v[212:215], v[80:83]
	v_mfma_f32_16x16x32_bf16 v[72:75], v[154:157], v[240:243], v[72:75]
	v_mfma_f32_16x16x32_bf16 v[64:67], v[162:165], v[240:243], v[64:67]
	v_mfma_f32_16x16x32_bf16 v[124:127], v[176:179], v[192:195], v[124:127]
	v_mfma_f32_16x16x32_bf16 v[116:119], v[184:187], v[192:195], v[116:119]
	v_mfma_f32_16x16x32_bf16 v[108:111], v[176:179], v[200:203], v[108:111]
	v_mfma_f32_16x16x32_bf16 v[100:103], v[184:187], v[200:203], v[100:103]
	v_mfma_f32_16x16x32_bf16 v[92:95], v[176:179], v[208:211], v[92:95]
	v_mfma_f32_16x16x32_bf16 v[84:87], v[184:187], v[208:211], v[84:87]
	v_mfma_f32_16x16x32_bf16 v[76:79], v[176:179], v[216:219], v[76:79]
	v_mfma_f32_16x16x32_bf16 v[68:71], v[184:187], v[216:219], v[68:71]
	v_mfma_f32_16x16x32_bf16 v[124:127], v[180:183], v[196:199], v[124:127]
	v_mfma_f32_16x16x32_bf16 v[116:119], v[188:191], v[196:199], v[116:119]
	v_mfma_f32_16x16x32_bf16 v[108:111], v[180:183], v[204:207], v[108:111]
	v_mfma_f32_16x16x32_bf16 v[100:103], v[188:191], v[204:207], v[100:103]
	v_mfma_f32_16x16x32_bf16 v[92:95], v[180:183], v[212:215], v[92:95]
	v_mfma_f32_16x16x32_bf16 v[84:87], v[188:191], v[212:215], v[84:87]
	v_mfma_f32_16x16x32_bf16 v[76:79], v[180:183], v[240:243], v[76:79]
	v_mfma_f32_16x16x32_bf16 v[68:71], v[188:191], v[240:243], v[68:71]
	s_barrier
	s_add_i32 s10, s10, s45
	v_lshl_add_u64 v[166:167], v[226:227], 0, s[92:93]
	s_mov_b32 m0, s10
	ds_read_b128 v[192:195], v153 offset:49152
	ds_read_b128 v[196:199], v153 offset:50176
	ds_read_b128 v[200:203], v153 offset:51200
	ds_read_b128 v[204:207], v153 offset:52224
	ds_read_b128 v[208:211], v153 offset:53248
	ds_read_b128 v[212:215], v153 offset:54272
	ds_read_b128 v[216:219], v153 offset:55296
	ds_read_b128 v[240:243], v153 offset:56320
	global_load_lds_dwordx4 v[166:167], off
	v_lshl_add_u64 v[166:167], v[244:245], 0, s[92:93]
	s_add_i32 m0, s10, 0x2000
	s_add_i32 s10, s65, s45
	global_load_lds_dwordx4 v[166:167], off
	v_lshl_add_u64 v[166:167], v[246:247], 0, s[92:93]
	s_mov_b32 m0, s10
	s_nop 0
	global_load_lds_dwordx4 v[166:167], off
	v_lshl_add_u64 v[166:167], v[220:221], 0, s[92:93]
	s_add_i32 m0, s10, 0x2000
	s_nop 0
	global_load_lds_dwordx4 v[166:167], off
	v_lshl_add_u64 v[166:167], v[248:249], 0, s[92:93]
	s_mov_b32 m0, s56
	s_nop 0
	global_load_lds_dwordx4 v[166:167], off
	v_lshl_add_u64 v[166:167], v[250:251], 0, s[92:93]
	s_mov_b32 m0, s57
	s_nop 0
	global_load_lds_dwordx4 v[166:167], off
	s_waitcnt vmcnt(8)
	s_waitcnt lgkmcnt(0)
	s_barrier
; __device__ __forceinline__ unsigned cvt_pk_bf16(float lo, float hi) { unsigned r; asm volatile("v_cvt_pk_bf16_f32 %0, %1, %2" : "=v"(r) : "v"(lo), "v"(hi)); return r; }
; __device__ __forceinline__ float siluf_(float x) { return x * sigmoidf_(x); }
; #define PG8_MMA(ai, bj, At, Bt) do { __builtin_amdgcn_s_setprio(1); _Pragma("unroll") for (int k = 0; k < 2; ++k) _Pragma("unroll") for (int m = 0; m < 4; ++m) _Pragma("unroll") for (int n = 0; n < 2; ++n) \
;         acc[ai][bj][m][n] = __builtin_amdgcn_mfma_f32_16x16x32_bf16(Bt[n][k], At[m][k], acc[ai][bj][m][n], 0, 0, 0); __builtin_amdgcn_s_setprio(0); } while (0)
; #define PG8_WAIT_V(n) asm volatile("s_waitcnt vmcnt(" #n ")" ::: "memory")
; #define PG8_WAIT_L(n) asm volatile("s_waitcnt lgkmcnt(" #n ")" ::: "memory")
; #define PG8_BAR __builtin_amdgcn_s_barrier()
; #define PG8_SCHED __builtin_amdgcn_sched_barrier(0)
;     __device__ __forceinline__ void operator()(const f32x4 (&acc)[2][2][4][2], const Unit& u, int wr, int wc, int fr, int fq) const {
;     ...
;             for (int m = 0; m < 4; ++m) { const int row = row0 + ai * HALF + m * 16; bf16_t* rowp = O + (size_t)row * ldc + col0; const float rs = rsv[ai][m];
;                 f32x4 v0, v1;
; #pragma unroll
;                 for (int j = 0; j < 4; ++j) { v0[j] = siluf_(acc[ai][0][m][0][j] * rs) * (acc[ai][1][m][0][j] * rs); v1[j] = siluf_(acc[ai][0][m][1][j] * rs) * (acc[ai][1][m][1][j] * rs); }
;                 u32x4 w; w.x = cvt_pk_bf16(v0[0], v0[1]); w.y = cvt_pk_bf16(v0[2], v0[3]); w.z = cvt_pk_bf16(v1[0], v1[1]); w.w = cvt_pk_bf16(v1[2], v1[3]);
;                 *(u32x4*)rowp = w; }
; template <class Epi, bool ALIGN_EPI>
; __device__ __forceinline__ void gemm_phase(LAS unsigned char* lds, const Gemm g, const StaticOrder& S, const Epi& E, const int tid) {
;     ...
;             PG8_WAIT_V(8); PG8_WAIT_L(0); PG8_BAR; PG8_MMA(1, 0, At, B0); PG8_MMA(1, 1, At, B1); PG8_BAR; PG8_SCHED;
	s_waitcnt lgkmcnt(0)
	v_mfma_f32_16x16x32_bf16 v[56:59], v[146:149], v[192:195], v[56:59]
	v_lshrrev_b32_e32 v171, 8, v170
	v_and_b32_e32 v234, 15, v170
	v_lshl_add_u32 v171, v171, 6, v234
	s_lshl_b32 s98, s64, 8
	v_add_u32_e32 v171, s98, v171
	v_mul_lo_u32 v171, v171, s28
	v_bfe_u32 v234, v170, 6, 2
	v_bfe_u32 v224, v170, 4, 2
	v_lshlrev_b32_e32 v234, 5, v234
	v_lshl_or_b32 v234, v224, 3, v234
	v_mfma_f32_16x16x32_bf16 v[48:51], v[158:161], v[192:195], v[48:51]
	s_lshl_b32 s98, s63, 7
	v_add_u32_e32 v234, s98, v234
	v_add_lshl_u32 v232, v171, v234, 1
	v_mov_b32_e32 v233, 0
	v_lshl_add_u64 v[232:233], v[232:233], 0, s[30:31]
	s_lshl_b32 s98, s28, 5
	s_mov_b32 s99, 0
	s_mov_b32 s100, 0xbfb8aa3b
	s_mov_b32 s101, 0xbfb8aa3b
	v_mul_f32_e32 v120, v172, v120
	v_mfma_f32_16x16x32_bf16 v[40:43], v[146:149], v[200:203], v[40:43]
	v_mul_f32_e32 v121, v172, v121
	v_mul_f32_e32 v122, v172, v122
	v_mul_f32_e32 v123, v172, v123
	v_mul_f32_e32 v124, v172, v124
	v_mul_f32_e32 v125, v172, v125
	v_mul_f32_e32 v126, v172, v126
	v_mul_f32_e32 v127, v172, v127
	v_mul_f32_e32 v224, s100, v120
	v_mul_f32_e32 v225, s101, v121
	v_mul_f32_e32 v228, s100, v122
	v_mfma_f32_16x16x32_bf16 v[32:35], v[158:161], v[200:203], v[32:35]
	v_mul_f32_e32 v229, s101, v123
	v_exp_f32_e32 v224, v224
	v_exp_f32_e32 v225, v225
	v_exp_f32_e32 v228, v228
	v_exp_f32_e32 v229, v229
	v_add_f32_e32 v224, 1.0, v224
	v_add_f32_e32 v225, 1.0, v225
	v_add_f32_e32 v228, 1.0, v228
	v_add_f32_e32 v229, 1.0, v229
	v_rcp_f32_e32 v224, v224
	v_mfma_f32_16x16x32_bf16 v[24:27], v[146:149], v[208:211], v[24:27]
	v_rcp_f32_e32 v225, v225
	v_rcp_f32_e32 v228, v228
	v_rcp_f32_e32 v229, v229
	v_nop
	v_mul_f32_e32 v120, v224, v120
	v_mul_f32_e32 v121, v225, v121
	v_mul_f32_e32 v122, v228, v122
	v_mul_f32_e32 v123, v229, v123
	v_mul_f32_e32 v120, v124, v120
	v_mul_f32_e32 v121, v125, v121
	v_mfma_f32_16x16x32_bf16 v[16:19], v[158:161], v[208:211], v[16:19]
	v_mul_f32_e32 v122, v126, v122
	v_mul_f32_e32 v123, v127, v123
	v_mul_f32_e32 v112, v172, v112
	v_mul_f32_e32 v113, v172, v113
	v_mul_f32_e32 v114, v172, v114
	v_mul_f32_e32 v115, v172, v115
	v_mul_f32_e32 v116, v172, v116
	v_mul_f32_e32 v117, v172, v117
	v_mul_f32_e32 v118, v172, v118
	v_mul_f32_e32 v119, v172, v119
	v_mfma_f32_16x16x32_bf16 v[8:11], v[146:149], v[216:219], v[8:11]
	v_mul_f32_e32 v224, s100, v112
	v_mul_f32_e32 v225, s101, v113
	v_mul_f32_e32 v228, s100, v114
	v_mul_f32_e32 v229, s101, v115
	v_exp_f32_e32 v224, v224
	v_exp_f32_e32 v225, v225
	v_exp_f32_e32 v228, v228
	v_exp_f32_e32 v229, v229
	v_add_f32_e32 v224, 1.0, v224
	v_add_f32_e32 v225, 1.0, v225
	v_mfma_f32_16x16x32_bf16 v[4:7], v[158:161], v[216:219], v[4:7]
	v_add_f32_e32 v228, 1.0, v228
	v_add_f32_e32 v229, 1.0, v229
	v_rcp_f32_e32 v224, v224
	v_rcp_f32_e32 v225, v225
	v_rcp_f32_e32 v228, v228
	v_rcp_f32_e32 v229, v229
	v_nop
	v_mul_f32_e32 v112, v224, v112
	v_mul_f32_e32 v113, v225, v113
	v_mul_f32_e32 v114, v228, v114
	v_mfma_f32_16x16x32_bf16 v[56:59], v[154:157], v[196:199], v[56:59]
	v_mul_f32_e32 v115, v229, v115
	v_mul_f32_e32 v112, v116, v112
	v_mul_f32_e32 v113, v117, v113
	v_mul_f32_e32 v114, v118, v114
	v_mul_f32_e32 v115, v119, v115
	v_cvt_pk_bf16_f32 v120, v120, v121
	v_cvt_pk_bf16_f32 v121, v122, v123
	v_cvt_pk_bf16_f32 v122, v112, v113
	v_cvt_pk_bf16_f32 v123, v114, v115
	global_store_dwordx4 v[232:233], v[120:123], off
	v_mfma_f32_16x16x32_bf16 v[48:51], v[162:165], v[196:199], v[48:51]
	v_lshl_add_u64 v[232:233], v[232:233], 0, s[98:99]
	v_mul_f32_e32 v104, v173, v104
	v_mul_f32_e32 v105, v173, v105
	v_mul_f32_e32 v106, v173, v106
	v_mul_f32_e32 v107, v173, v107
	v_mul_f32_e32 v108, v173, v108
	v_mul_f32_e32 v109, v173, v109
	v_mul_f32_e32 v110, v173, v110
	v_mul_f32_e32 v111, v173, v111
	v_mul_f32_e32 v224, s100, v104
	v_mfma_f32_16x16x32_bf16 v[40:43], v[154:157], v[204:207], v[40:43]
	v_mul_f32_e32 v225, s101, v105
	v_mul_f32_e32 v228, s100, v106
	v_mul_f32_e32 v229, s101, v107
	v_exp_f32_e32 v224, v224
	v_exp_f32_e32 v225, v225
	v_exp_f32_e32 v228, v228
	v_exp_f32_e32 v229, v229
	v_add_f32_e32 v224, 1.0, v224
	v_add_f32_e32 v225, 1.0, v225
	v_add_f32_e32 v228, 1.0, v228
	v_mfma_f32_16x16x32_bf16 v[32:35], v[162:165], v[204:207], v[32:35]
	v_add_f32_e32 v229, 1.0, v229
	v_rcp_f32_e32 v224, v224
	v_rcp_f32_e32 v225, v225
	v_rcp_f32_e32 v228, v228
	v_rcp_f32_e32 v229, v229
	v_nop
	v_mul_f32_e32 v104, v224, v104
	v_mul_f32_e32 v105, v225, v105
	v_mul_f32_e32 v106, v228, v106
	v_mul_f32_e32 v107, v229, v107
	v_mfma_f32_16x16x32_bf16 v[24:27], v[154:157], v[212:215], v[24:27]
	v_mul_f32_e32 v104, v108, v104
	v_mul_f32_e32 v105, v109, v105
	v_mul_f32_e32 v106, v110, v106
	v_mul_f32_e32 v107, v111, v107
	v_mul_f32_e32 v96, v173, v96
	v_mul_f32_e32 v97, v173, v97
	v_mul_f32_e32 v98, v173, v98
	v_mul_f32_e32 v99, v173, v99
	v_mul_f32_e32 v100, v173, v100
	v_mul_f32_e32 v101, v173, v101
	v_mfma_f32_16x16x32_bf16 v[16:19], v[162:165], v[212:215], v[16:19]
	v_mul_f32_e32 v102, v173, v102
	v_mul_f32_e32 v103, v173, v103
	v_mul_f32_e32 v224, s100, v96
	v_mul_f32_e32 v225, s101, v97
	v_mul_f32_e32 v228, s100, v98
	v_mul_f32_e32 v229, s101, v99
	v_exp_f32_e32 v224, v224
	v_exp_f32_e32 v225, v225
	v_exp_f32_e32 v228, v228
	v_exp_f32_e32 v229, v229
	v_mfma_f32_16x16x32_bf16 v[8:11], v[154:157], v[240:243], v[8:11]
	v_add_f32_e32 v224, 1.0, v224
	v_add_f32_e32 v225, 1.0, v225
	v_add_f32_e32 v228, 1.0, v228
	v_add_f32_e32 v229, 1.0, v229
	v_rcp_f32_e32 v224, v224
	v_rcp_f32_e32 v225, v225
	v_rcp_f32_e32 v228, v228
	v_rcp_f32_e32 v229, v229
	v_nop
	v_mul_f32_e32 v96, v224, v96
	v_mfma_f32_16x16x32_bf16 v[4:7], v[162:165], v[240:243], v[4:7]
	v_mul_f32_e32 v97, v225, v97
; __device__ __forceinline__ unsigned cvt_pk_bf16(float lo, float hi) { unsigned r; asm volatile("v_cvt_pk_bf16_f32 %0, %1, %2" : "=v"(r) : "v"(lo), "v"(hi)); return r; }
; __device__ __forceinline__ float siluf_(float x) { return x * sigmoidf_(x); }
; #define PG8_MMA(ai, bj, At, Bt) do { __builtin_amdgcn_s_setprio(1); _Pragma("unroll") for (int k = 0; k < 2; ++k) _Pragma("unroll") for (int m = 0; m < 4; ++m) _Pragma("unroll") for (int n = 0; n < 2; ++n) \
;         acc[ai][bj][m][n] = __builtin_amdgcn_mfma_f32_16x16x32_bf16(Bt[n][k], At[m][k], acc[ai][bj][m][n], 0, 0, 0); __builtin_amdgcn_s_setprio(0); } while (0)
; #define PG8_WAIT_V(n) asm volatile("s_waitcnt vmcnt(" #n ")" ::: "memory")
; #define PG8_WAIT_L(n) asm volatile("s_waitcnt lgkmcnt(" #n ")" ::: "memory")
; #define PG8_BAR __builtin_amdgcn_s_barrier()
; #define PG8_SCHED __builtin_amdgcn_sched_barrier(0)
;     __device__ __forceinline__ void operator()(const f32x4 (&acc)[2][2][4][2], const Unit& u, int wr, int wc, int fr, int fq) const {
;     ...
;             for (int m = 0; m < 4; ++m) { const int row = row0 + ai * HALF + m * 16; bf16_t* rowp = O + (size_t)row * ldc + col0; const float rs = rsv[ai][m];
;                 f32x4 v0, v1;
; #pragma unroll
;                 for (int j = 0; j < 4; ++j) { v0[j] = siluf_(acc[ai][0][m][0][j] * rs) * (acc[ai][1][m][0][j] * rs); v1[j] = siluf_(acc[ai][0][m][1][j] * rs) * (acc[ai][1][m][1][j] * rs); }
;                 u32x4 w; w.x = cvt_pk_bf16(v0[0], v0[1]); w.y = cvt_pk_bf16(v0[2], v0[3]); w.z = cvt_pk_bf16(v1[0], v1[1]); w.w = cvt_pk_bf16(v1[2], v1[3]);
;                 *(u32x4*)rowp = w; }
; template <class Epi, bool ALIGN_EPI>
; __device__ __forceinline__ void gemm_phase(LAS unsigned char* lds, const Gemm g, const StaticOrder& S, const Epi& E, const int tid) {
;     ...
;             PG8_WAIT_V(8); PG8_WAIT_L(0); PG8_BAR; PG8_MMA(1, 0, At, B0); PG8_MMA(1, 1, At, B1); PG8_BAR; PG8_SCHED;
	v_mul_f32_e32 v98, v228, v98
	v_mul_f32_e32 v99, v229, v99
	v_mul_f32_e32 v96, v100, v96
	v_mul_f32_e32 v97, v101, v97
	v_mul_f32_e32 v98, v102, v98
	v_mul_f32_e32 v99, v103, v99
	v_cvt_pk_bf16_f32 v104, v104, v105
	v_cvt_pk_bf16_f32 v105, v106, v107
	v_cvt_pk_bf16_f32 v106, v96, v97
	v_mfma_f32_16x16x32_bf16 v[60:63], v[176:179], v[192:195], v[60:63]
	v_cvt_pk_bf16_f32 v107, v98, v99
	global_store_dwordx4 v[232:233], v[104:107], off
	v_lshl_add_u64 v[232:233], v[232:233], 0, s[98:99]
	v_mul_f32_e32 v88, v236, v88
	v_mul_f32_e32 v89, v236, v89
	v_mul_f32_e32 v90, v236, v90
	v_mul_f32_e32 v91, v236, v91
	v_mul_f32_e32 v92, v236, v92
	v_mul_f32_e32 v93, v236, v93
	v_mul_f32_e32 v94, v236, v94
	v_mfma_f32_16x16x32_bf16 v[52:55], v[184:187], v[192:195], v[52:55]
	v_mul_f32_e32 v95, v236, v95
	v_mul_f32_e32 v224, s100, v88
	v_mul_f32_e32 v225, s101, v89
	v_mul_f32_e32 v228, s100, v90
	v_mul_f32_e32 v229, s101, v91
	v_exp_f32_e32 v224, v224
	v_exp_f32_e32 v225, v225
	v_exp_f32_e32 v228, v228
	v_exp_f32_e32 v229, v229
	v_add_f32_e32 v224, 1.0, v224
	v_mfma_f32_16x16x32_bf16 v[44:47], v[176:179], v[200:203], v[44:47]
	v_add_f32_e32 v225, 1.0, v225
	v_add_f32_e32 v228, 1.0, v228
	v_add_f32_e32 v229, 1.0, v229
	v_rcp_f32_e32 v224, v224
	v_rcp_f32_e32 v225, v225
	v_rcp_f32_e32 v228, v228
	v_rcp_f32_e32 v229, v229
	v_nop
	v_mul_f32_e32 v88, v224, v88
	v_mul_f32_e32 v89, v225, v89
	v_mfma_f32_16x16x32_bf16 v[36:39], v[184:187], v[200:203], v[36:39]
	v_mul_f32_e32 v90, v228, v90
	v_mul_f32_e32 v91, v229, v91
	v_mul_f32_e32 v88, v92, v88
	v_mul_f32_e32 v89, v93, v89
	v_mul_f32_e32 v90, v94, v90
	v_mul_f32_e32 v91, v95, v91
	v_mul_f32_e32 v80, v236, v80
	v_mul_f32_e32 v81, v236, v81
	v_mul_f32_e32 v82, v236, v82
	v_mul_f32_e32 v83, v236, v83
	v_mfma_f32_16x16x32_bf16 v[28:31], v[176:179], v[208:211], v[28:31]
	v_mul_f32_e32 v84, v236, v84
	v_mul_f32_e32 v85, v236, v85
	v_mul_f32_e32 v86, v236, v86
	v_mul_f32_e32 v87, v236, v87
	v_mul_f32_e32 v224, s100, v80
	v_mul_f32_e32 v225, s101, v81
	v_mul_f32_e32 v228, s100, v82
	v_mul_f32_e32 v229, s101, v83
	v_exp_f32_e32 v224, v224
	v_exp_f32_e32 v225, v225
	v_mfma_f32_16x16x32_bf16 v[20:23], v[184:187], v[208:211], v[20:23]
	v_exp_f32_e32 v228, v228
	v_exp_f32_e32 v229, v229
	v_add_f32_e32 v224, 1.0, v224
	v_add_f32_e32 v225, 1.0, v225
	v_add_f32_e32 v228, 1.0, v228
	v_add_f32_e32 v229, 1.0, v229
	v_rcp_f32_e32 v224, v224
	v_rcp_f32_e32 v225, v225
	v_rcp_f32_e32 v228, v228
	v_rcp_f32_e32 v229, v229
	v_mfma_f32_16x16x32_bf16 v[12:15], v[176:179], v[216:219], v[12:15]
	v_nop
	v_mul_f32_e32 v80, v224, v80
	v_mul_f32_e32 v81, v225, v81
	v_mul_f32_e32 v82, v228, v82
	v_mul_f32_e32 v83, v229, v83
	v_mul_f32_e32 v80, v84, v80
	v_mul_f32_e32 v81, v85, v81
	v_mul_f32_e32 v82, v86, v82
	v_mul_f32_e32 v83, v87, v83
	v_cvt_pk_bf16_f32 v88, v88, v89
	v_mfma_f32_16x16x32_bf16 v[0:3], v[184:187], v[216:219], v[0:3]
	v_cvt_pk_bf16_f32 v89, v90, v91
	v_cvt_pk_bf16_f32 v90, v80, v81
	v_cvt_pk_bf16_f32 v91, v82, v83
	global_store_dwordx4 v[232:233], v[88:91], off
	v_lshl_add_u64 v[232:233], v[232:233], 0, s[98:99]
	v_mul_f32_e32 v72, v237, v72
	v_mul_f32_e32 v73, v237, v73
	v_mul_f32_e32 v74, v237, v74
	v_mul_f32_e32 v75, v237, v75
	v_mul_f32_e32 v76, v237, v76
	v_mfma_f32_16x16x32_bf16 v[60:63], v[180:183], v[196:199], v[60:63]
	v_mul_f32_e32 v77, v237, v77
	v_mul_f32_e32 v78, v237, v78
	v_mul_f32_e32 v79, v237, v79
	v_mul_f32_e32 v224, s100, v72
	v_mul_f32_e32 v225, s101, v73
	v_mul_f32_e32 v228, s100, v74
	v_mul_f32_e32 v229, s101, v75
	v_exp_f32_e32 v224, v224
	v_exp_f32_e32 v225, v225
	v_exp_f32_e32 v228, v228
	v_mfma_f32_16x16x32_bf16 v[52:55], v[188:191], v[196:199], v[52:55]
	v_exp_f32_e32 v229, v229
	v_add_f32_e32 v224, 1.0, v224
	v_add_f32_e32 v225, 1.0, v225
	v_add_f32_e32 v228, 1.0, v228
	v_add_f32_e32 v229, 1.0, v229
	v_rcp_f32_e32 v224, v224
	v_rcp_f32_e32 v225, v225
	v_rcp_f32_e32 v228, v228
	v_rcp_f32_e32 v229, v229
	v_nop
	v_mfma_f32_16x16x32_bf16 v[44:47], v[180:183], v[204:207], v[44:47]
	v_mul_f32_e32 v72, v224, v72
	v_mul_f32_e32 v73, v225, v73
	v_mul_f32_e32 v74, v228, v74
	v_mul_f32_e32 v75, v229, v75
	v_mul_f32_e32 v72, v76, v72
	v_mul_f32_e32 v73, v77, v73
	v_mul_f32_e32 v74, v78, v74
	v_mul_f32_e32 v75, v79, v75
	v_mul_f32_e32 v64, v237, v64
	v_mul_f32_e32 v65, v237, v65
	v_mfma_f32_16x16x32_bf16 v[36:39], v[188:191], v[204:207], v[36:39]
	v_mul_f32_e32 v66, v237, v66
	v_mul_f32_e32 v67, v237, v67
	v_mul_f32_e32 v68, v237, v68
	v_mul_f32_e32 v69, v237, v69
	v_mul_f32_e32 v70, v237, v70
	v_mul_f32_e32 v71, v237, v71
	v_mul_f32_e32 v224, s100, v64
	v_mul_f32_e32 v225, s101, v65
	v_mul_f32_e32 v228, s100, v66
	v_mul_f32_e32 v229, s101, v67
	v_mfma_f32_16x16x32_bf16 v[28:31], v[180:183], v[212:215], v[28:31]
	v_exp_f32_e32 v224, v224
	v_exp_f32_e32 v225, v225
	v_exp_f32_e32 v228, v228
	v_exp_f32_e32 v229, v229
	v_add_f32_e32 v224, 1.0, v224
	v_add_f32_e32 v225, 1.0, v225
	v_add_f32_e32 v228, 1.0, v228
	v_add_f32_e32 v229, 1.0, v229
	v_rcp_f32_e32 v224, v224
	v_rcp_f32_e32 v225, v225
	v_mfma_f32_16x16x32_bf16 v[20:23], v[188:191], v[212:215], v[20:23]
	v_rcp_f32_e32 v228, v228
	v_rcp_f32_e32 v229, v229
	v_nop
	v_mul_f32_e32 v64, v224, v64
	v_mul_f32_e32 v65, v225, v65
	v_mul_f32_e32 v66, v228, v66
	v_mul_f32_e32 v67, v229, v67
	v_mul_f32_e32 v64, v68, v64
	v_mul_f32_e32 v65, v69, v65
	v_mul_f32_e32 v66, v70, v66
	v_mfma_f32_16x16x32_bf16 v[12:15], v[180:183], v[240:243], v[12:15]
	v_mul_f32_e32 v67, v71, v67
	v_cvt_pk_bf16_f32 v72, v72, v73
	v_cvt_pk_bf16_f32 v73, v74, v75
	v_cvt_pk_bf16_f32 v74, v64, v65
	v_cvt_pk_bf16_f32 v75, v66, v67
	global_store_dwordx4 v[232:233], v[72:75], off
	v_lshl_add_u64 v[232:233], v[232:233], 0, s[98:99]
	v_lshl_add_u64 v[232:233], v[232:233], 0, s[98:99]
	v_lshl_add_u64 v[232:233], v[232:233], 0, s[98:99]
	v_lshl_add_u64 v[232:233], v[232:233], 0, s[98:99]
	v_mfma_f32_16x16x32_bf16 v[0:3], v[188:191], v[240:243], v[0:3]
	v_lshl_add_u64 v[232:233], v[232:233], 0, s[98:99]
	s_barrier
	v_lshl_add_u64 v[142:143], v[142:143], 0, s[80:81]
	v_lshl_add_u64 v[144:145], v[144:145], 0, s[80:81]
	s_and_b64 vcc, exec, s[8:9]
	s_cbranch_vccnz .Lgu_notdefer
	s_cmp_lg_u32 s62, s64
	s_cbranch_scc1 .Lgu_notdefer
	s_mov_b32 s101, 1
	s_mov_b32 s63, s61
	s_mov_b32 s64, s62
	v_mov_b64_e32 v[144:145], v[140:141]
	v_mov_b64_e32 v[142:143], v[138:139]
	s_branch .LBB0_300

; #define PG8_STAGE(bufoff, gbase, voff) do { _Pragma("unroll") for (int _i = 0; _i < 2; ++_i) \
;         __builtin_amdgcn_global_load_lds((const unsigned*)((const char*)(gbase) + (voff)[_i]), (LAS unsigned*)(lds + (bufoff) + ldsw + _i * 8192), 16, 0, 0); } while (0)
; #define PG8_LDA(dst, b, h) do { _Pragma("unroll") for (int m = 0; m < 4; ++m) _Pragma("unroll") for (int k = 0; k < 2; ++k) dst[m][k] = *(const LAS bf16x8*)(lds + PG8_SA(b, h) + aoff + m * 2048 + k * 1024); } while (0)
; #define PG8_LDB(dst, b, h) do { _Pragma("unroll") for (int n = 0; n < 2; ++n) _Pragma("unroll") for (int k = 0; k < 2; ++k) dst[n][k] = *(const LAS bf16x8*)(lds + PG8_SB(b, h) + boff + n * 2048 + k * 1024); } while (0)
; #define PG8_MMA(ai, bj, At, Bt) do { __builtin_amdgcn_s_setprio(1); _Pragma("unroll") for (int k = 0; k < 2; ++k) _Pragma("unroll") for (int m = 0; m < 4; ++m) _Pragma("unroll") for (int n = 0; n < 2; ++n) \
;         acc[ai][bj][m][n] = __builtin_amdgcn_mfma_f32_16x16x32_bf16(Bt[n][k], At[m][k], acc[ai][bj][m][n], 0, 0, 0); __builtin_amdgcn_s_setprio(0); } while (0)
; #define PG8_WAIT_V(n) asm volatile("s_waitcnt vmcnt(" #n ")" ::: "memory")
; #define PG8_WAIT_L(n) asm volatile("s_waitcnt lgkmcnt(" #n ")" ::: "memory")
; #define PG8_BAR __builtin_amdgcn_s_barrier()
; #define PG8_SCHED __builtin_amdgcn_sched_barrier(0)
; template <class Epi, bool ALIGN_EPI>
; __device__ __forceinline__ void gemm_phase(LAS unsigned char* lds, const Gemm g, const StaticOrder& S, const Epi& E, const int tid) {
;     ...
;             PG8_LDB(B0, 0, 0); PG8_LDB(B1, 0, 1); PG8_SCHED; PG8_LDA(At, 0, 0); PG8_STAGE(PG8_SA(1, 1), a1 + hA, voffA);
;             PG8_WAIT_V(8); PG8_WAIT_L(0); PG8_BAR; PG8_MMA(0, 0, At, B0); PG8_MMA(0, 1, At, B1); PG8_BAR; PG8_SCHED;
;             PG8_LDA(At, 0, 1); PG8_STAGE(PG8_SB(0, 0), b2, voffB); PG8_STAGE(PG8_SB(0, 1), b2 + hB, voffB); PG8_STAGE(PG8_SA(0, 0), a2, voffA);
.LBB0_329:
	s_andn2_b64 vcc, exec, s[36:37]
	s_cbranch_vccnz .LBB0_332
	v_lshl_add_u64 v[142:143], v[142:143], 0, s[92:93]
	v_lshl_add_u64 v[144:145], v[144:145], 0, s[80:81]
	s_mov_b32 s10, 0
	s_add_i32 s11, s10, 2
	s_cmp_eq_u32 s58, s10
	v_lshl_add_u64 v[146:147], v[142:143], 0, s[92:93]
	s_cselect_b64 vcc, -1, 0
	v_add_u32_e32 v152, s33, v153
	s_add_i32 s10, 0, 0x14000
	v_cndmask_b32_e32 v151, v147, v139, vcc
	v_cndmask_b32_e32 v150, v146, v138, vcc
	ds_read_b128 v[146:149], v152
	ds_read_b128 v[156:159], v152 offset:1024
	ds_read_b128 v[160:163], v152 offset:2048
	ds_read_b128 v[164:167], v152 offset:3072
	v_add_u32_e32 v152, s10, v153
	ds_read_b128 v[176:179], v152
	ds_read_b128 v[180:183], v152 offset:1024
	ds_read_b128 v[184:187], v152 offset:2048
	ds_read_b128 v[188:191], v152 offset:3072
	v_cndmask_b32_e32 v221, v145, v141, vcc
	v_cndmask_b32_e32 v220, v144, v140, vcc
	v_lshl_add_u64 v[226:227], v[142:143], 0, v[134:135]
	s_add_i32 m0, s51, 0xc000
	ds_read_b128 v[192:195], v155
	ds_read_b128 v[196:199], v155 offset:1024
	ds_read_b128 v[200:203], v155 offset:2048
	ds_read_b128 v[204:207], v155 offset:3072
	ds_read_b128 v[208:211], v155 offset:4096
	ds_read_b128 v[212:215], v155 offset:5120
	ds_read_b128 v[216:219], v155 offset:6144
	ds_read_b128 v[240:243], v155 offset:7168
	global_load_lds_dwordx4 v[226:227], off
	v_lshl_add_u64 v[226:227], v[142:143], 0, v[136:137]
	s_add_i32 m0, s51, 0xe000
	s_nop 0
	global_load_lds_dwordx4 v[226:227], off
	s_waitcnt vmcnt(8)
	s_waitcnt lgkmcnt(0)
	s_barrier
	s_waitcnt lgkmcnt(0)
	v_mfma_f32_16x16x32_bf16 v[120:123], v[146:149], v[192:195], 0
	v_mfma_f32_16x16x32_bf16 v[124:127], v[160:163], v[192:195], 0
	v_mfma_f32_16x16x32_bf16 v[108:111], v[146:149], v[200:203], 0
	v_mfma_f32_16x16x32_bf16 v[104:107], v[160:163], v[200:203], 0
	v_mfma_f32_16x16x32_bf16 v[92:95], v[146:149], v[208:211], 0
	v_mfma_f32_16x16x32_bf16 v[88:91], v[160:163], v[208:211], 0
	v_mfma_f32_16x16x32_bf16 v[76:79], v[146:149], v[216:219], 0
	v_mfma_f32_16x16x32_bf16 v[72:75], v[160:163], v[216:219], 0
	v_mfma_f32_16x16x32_bf16 v[120:123], v[156:159], v[196:199], v[120:123]
	v_mfma_f32_16x16x32_bf16 v[124:127], v[164:167], v[196:199], v[124:127]
	v_mfma_f32_16x16x32_bf16 v[108:111], v[156:159], v[204:207], v[108:111]
	v_mfma_f32_16x16x32_bf16 v[104:107], v[164:167], v[204:207], v[104:107]
	v_mfma_f32_16x16x32_bf16 v[92:95], v[156:159], v[212:215], v[92:95]
	v_mfma_f32_16x16x32_bf16 v[88:91], v[164:167], v[212:215], v[88:91]
	v_mfma_f32_16x16x32_bf16 v[76:79], v[156:159], v[240:243], v[76:79]
	v_mfma_f32_16x16x32_bf16 v[72:75], v[164:167], v[240:243], v[72:75]
	v_mfma_f32_16x16x32_bf16 v[116:119], v[176:179], v[192:195], 0
	v_mfma_f32_16x16x32_bf16 v[112:115], v[184:187], v[192:195], 0
	v_mfma_f32_16x16x32_bf16 v[100:103], v[176:179], v[200:203], 0
	v_mfma_f32_16x16x32_bf16 v[96:99], v[184:187], v[200:203], 0
	v_mfma_f32_16x16x32_bf16 v[84:87], v[176:179], v[208:211], 0
	v_mfma_f32_16x16x32_bf16 v[80:83], v[184:187], v[208:211], 0
	v_mfma_f32_16x16x32_bf16 v[68:71], v[176:179], v[216:219], 0
	v_mfma_f32_16x16x32_bf16 v[64:67], v[184:187], v[216:219], 0
	v_mfma_f32_16x16x32_bf16 v[116:119], v[180:183], v[196:199], v[116:119]
	v_mfma_f32_16x16x32_bf16 v[112:115], v[188:191], v[196:199], v[112:115]
	v_mfma_f32_16x16x32_bf16 v[100:103], v[180:183], v[204:207], v[100:103]
	v_mfma_f32_16x16x32_bf16 v[96:99], v[188:191], v[204:207], v[96:99]
	v_mfma_f32_16x16x32_bf16 v[84:87], v[180:183], v[212:215], v[84:87]
	v_mfma_f32_16x16x32_bf16 v[80:83], v[188:191], v[212:215], v[80:83]
	v_mfma_f32_16x16x32_bf16 v[68:71], v[180:183], v[240:243], v[68:71]
	v_mfma_f32_16x16x32_bf16 v[64:67], v[188:191], v[240:243], v[64:67]
	s_barrier
	s_add_i32 s65, s33, s45
	v_lshl_add_u64 v[226:227], v[220:221], 0, v[168:169]
	s_mov_b32 m0, s65
	ds_read_b128 v[192:195], v155 offset:16384
	ds_read_b128 v[196:199], v155 offset:17408
	ds_read_b128 v[200:203], v155 offset:18432
	ds_read_b128 v[204:207], v155 offset:19456
	ds_read_b128 v[208:211], v155 offset:20480
	ds_read_b128 v[212:215], v155 offset:21504
	ds_read_b128 v[216:219], v155 offset:22528
	ds_read_b128 v[240:243], v155 offset:23552
	global_load_lds_dwordx4 v[226:227], off
	v_lshl_add_u64 v[244:245], v[220:221], 0, v[128:129]
	s_add_i32 m0, s65, 0x2000
	v_lshl_add_u64 v[220:221], v[220:221], 0, s[12:13]
	s_add_i32 s10, s10, s45
	global_load_lds_dwordx4 v[244:245], off
	v_lshl_add_u64 v[246:247], v[220:221], 0, v[168:169]
	s_mov_b32 m0, s10
	v_lshl_add_u64 v[220:221], v[220:221], 0, v[128:129]
	global_load_lds_dwordx4 v[246:247], off
	s_add_i32 m0, s10, 0x2000
	v_lshl_add_u64 v[248:249], v[150:151], 0, v[132:133]
	global_load_lds_dwordx4 v[220:221], off
	s_mov_b32 m0, s51
	v_lshl_add_u64 v[250:251], v[150:151], 0, v[130:131]
	global_load_lds_dwordx4 v[248:249], off
	s_mov_b32 m0, s52
	s_nop 0
	global_load_lds_dwordx4 v[250:251], off
	s_waitcnt vmcnt(8)
	s_waitcnt lgkmcnt(0)
	s_barrier
; #define PG8_STAGE(bufoff, gbase, voff) do { _Pragma("unroll") for (int _i = 0; _i < 2; ++_i) \
;         __builtin_amdgcn_global_load_lds((const unsigned*)((const char*)(gbase) + (voff)[_i]), (LAS unsigned*)(lds + (bufoff) + ldsw + _i * 8192), 16, 0, 0); } while (0)
; #define PG8_LDA(dst, b, h) do { _Pragma("unroll") for (int m = 0; m < 4; ++m) _Pragma("unroll") for (int k = 0; k < 2; ++k) dst[m][k] = *(const LAS bf16x8*)(lds + PG8_SA(b, h) + aoff + m * 2048 + k * 1024); } while (0)
; #define PG8_LDB(dst, b, h) do { _Pragma("unroll") for (int n = 0; n < 2; ++n) _Pragma("unroll") for (int k = 0; k < 2; ++k) dst[n][k] = *(const LAS bf16x8*)(lds + PG8_SB(b, h) + boff + n * 2048 + k * 1024); } while (0)
; #define PG8_MMA(ai, bj, At, Bt) do { __builtin_amdgcn_s_setprio(1); _Pragma("unroll") for (int k = 0; k < 2; ++k) _Pragma("unroll") for (int m = 0; m < 4; ++m) _Pragma("unroll") for (int n = 0; n < 2; ++n) \
;         acc[ai][bj][m][n] = __builtin_amdgcn_mfma_f32_16x16x32_bf16(Bt[n][k], At[m][k], acc[ai][bj][m][n], 0, 0, 0); __builtin_amdgcn_s_setprio(0); } while (0)
; #define PG8_WAIT_V(n) asm volatile("s_waitcnt vmcnt(" #n ")" ::: "memory")
; #define PG8_WAIT_L(n) asm volatile("s_waitcnt lgkmcnt(" #n ")" ::: "memory")
; #define PG8_BAR __builtin_amdgcn_s_barrier()
; #define PG8_SCHED __builtin_amdgcn_sched_barrier(0)
; template <class Epi, bool ALIGN_EPI>
; __device__ __forceinline__ void gemm_phase(LAS unsigned char* lds, const Gemm g, const StaticOrder& S, const Epi& E, const int tid) {
;     ...
;             PG8_WAIT_V(8); PG8_WAIT_L(0); PG8_BAR; PG8_MMA(1, 0, At, B0); PG8_MMA(1, 1, At, B1); PG8_BAR; PG8_SCHED;
;             PG8_LDB(B0, 1, 0); PG8_LDB(B1, 1, 1); PG8_SCHED; PG8_LDA(At, 1, 0); PG8_STAGE(PG8_SA(0, 1), a2 + hA, voffA);
;             PG8_WAIT_V(8); PG8_WAIT_L(0); PG8_BAR; PG8_MMA(0, 0, At, B0); PG8_MMA(0, 1, At, B1); PG8_BAR; PG8_SCHED;
	s_waitcnt lgkmcnt(0)
	v_mfma_f32_16x16x32_bf16 v[60:63], v[146:149], v[192:195], 0
	v_mfma_f32_16x16x32_bf16 v[56:59], v[160:163], v[192:195], 0
	v_mfma_f32_16x16x32_bf16 v[44:47], v[146:149], v[200:203], 0
	v_mfma_f32_16x16x32_bf16 v[40:43], v[160:163], v[200:203], 0
	v_mfma_f32_16x16x32_bf16 v[28:31], v[146:149], v[208:211], 0
	v_mfma_f32_16x16x32_bf16 v[24:27], v[160:163], v[208:211], 0
	v_mfma_f32_16x16x32_bf16 v[12:15], v[146:149], v[216:219], 0
	v_mfma_f32_16x16x32_bf16 v[8:11], v[160:163], v[216:219], 0
	v_mfma_f32_16x16x32_bf16 v[60:63], v[156:159], v[196:199], v[60:63]
	v_mfma_f32_16x16x32_bf16 v[56:59], v[164:167], v[196:199], v[56:59]
	v_mfma_f32_16x16x32_bf16 v[44:47], v[156:159], v[204:207], v[44:47]
	v_mfma_f32_16x16x32_bf16 v[40:43], v[164:167], v[204:207], v[40:43]
	v_mfma_f32_16x16x32_bf16 v[28:31], v[156:159], v[212:215], v[28:31]
	v_mfma_f32_16x16x32_bf16 v[24:27], v[164:167], v[212:215], v[24:27]
	v_mfma_f32_16x16x32_bf16 v[12:15], v[156:159], v[240:243], v[12:15]
	v_mfma_f32_16x16x32_bf16 v[8:11], v[164:167], v[240:243], v[8:11]
	v_mfma_f32_16x16x32_bf16 v[52:55], v[176:179], v[192:195], 0
	v_mfma_f32_16x16x32_bf16 v[48:51], v[184:187], v[192:195], 0
	v_mfma_f32_16x16x32_bf16 v[36:39], v[176:179], v[200:203], 0
	v_mfma_f32_16x16x32_bf16 v[32:35], v[184:187], v[200:203], 0
	v_mfma_f32_16x16x32_bf16 v[20:23], v[176:179], v[208:211], 0
	v_mfma_f32_16x16x32_bf16 v[16:19], v[184:187], v[208:211], 0
	v_mfma_f32_16x16x32_bf16 v[4:7], v[176:179], v[216:219], 0
	v_mfma_f32_16x16x32_bf16 v[0:3], v[184:187], v[216:219], 0
	v_mfma_f32_16x16x32_bf16 v[52:55], v[180:183], v[196:199], v[52:55]
	v_mfma_f32_16x16x32_bf16 v[48:51], v[188:191], v[196:199], v[48:51]
	v_mfma_f32_16x16x32_bf16 v[36:39], v[180:183], v[204:207], v[36:39]
	v_mfma_f32_16x16x32_bf16 v[32:35], v[188:191], v[204:207], v[32:35]
	v_mfma_f32_16x16x32_bf16 v[20:23], v[180:183], v[212:215], v[20:23]
	v_mfma_f32_16x16x32_bf16 v[16:19], v[188:191], v[212:215], v[16:19]
	v_mfma_f32_16x16x32_bf16 v[4:7], v[180:183], v[240:243], v[4:7]
	v_mfma_f32_16x16x32_bf16 v[0:3], v[188:191], v[240:243], v[0:3]
	s_barrier
	s_add_i32 s10, 0, 0x18000
	v_add_u32_e32 v152, s10, v153
	s_add_i32 s65, 0, 0x1c000
	ds_read_b128 v[146:149], v152
	ds_read_b128 v[156:159], v152 offset:1024
	ds_read_b128 v[160:163], v152 offset:2048
	ds_read_b128 v[164:167], v152 offset:3072
	v_add_u32_e32 v152, s65, v153
	ds_read_b128 v[176:179], v152
	ds_read_b128 v[180:183], v152 offset:1024
	ds_read_b128 v[184:187], v152 offset:2048
	ds_read_b128 v[188:191], v152 offset:3072
	v_lshl_add_u64 v[150:151], v[150:151], 0, s[94:95]
	s_mov_b32 m0, s53
	v_lshl_add_u64 v[252:253], v[150:151], 0, v[132:133]
	ds_read_b128 v[192:195], v155 offset:32768
	ds_read_b128 v[196:199], v155 offset:33792
	ds_read_b128 v[200:203], v155 offset:34816
	ds_read_b128 v[204:207], v155 offset:35840
	ds_read_b128 v[208:211], v155 offset:36864
	ds_read_b128 v[212:215], v155 offset:37888
	ds_read_b128 v[216:219], v155 offset:38912
	ds_read_b128 v[240:243], v155 offset:39936
	global_load_lds_dwordx4 v[252:253], off
	v_lshl_add_u64 v[150:151], v[150:151], 0, v[130:131]
	s_mov_b32 m0, s54
	s_nop 0
	global_load_lds_dwordx4 v[150:151], off
	s_waitcnt vmcnt(8)
	s_waitcnt lgkmcnt(0)
	s_barrier
	s_waitcnt lgkmcnt(0)
	v_mfma_f32_16x16x32_bf16 v[120:123], v[146:149], v[192:195], v[120:123]
	v_mfma_f32_16x16x32_bf16 v[124:127], v[160:163], v[192:195], v[124:127]
	v_mfma_f32_16x16x32_bf16 v[108:111], v[146:149], v[200:203], v[108:111]
	v_mfma_f32_16x16x32_bf16 v[104:107], v[160:163], v[200:203], v[104:107]
	v_mfma_f32_16x16x32_bf16 v[92:95], v[146:149], v[208:211], v[92:95]
	v_mfma_f32_16x16x32_bf16 v[88:91], v[160:163], v[208:211], v[88:91]
	v_mfma_f32_16x16x32_bf16 v[76:79], v[146:149], v[216:219], v[76:79]
	v_mfma_f32_16x16x32_bf16 v[72:75], v[160:163], v[216:219], v[72:75]
	v_mfma_f32_16x16x32_bf16 v[120:123], v[156:159], v[196:199], v[120:123]
	v_mfma_f32_16x16x32_bf16 v[124:127], v[164:167], v[196:199], v[124:127]
	v_mfma_f32_16x16x32_bf16 v[108:111], v[156:159], v[204:207], v[108:111]
	v_mfma_f32_16x16x32_bf16 v[104:107], v[164:167], v[204:207], v[104:107]
	v_mfma_f32_16x16x32_bf16 v[92:95], v[156:159], v[212:215], v[92:95]
	v_mfma_f32_16x16x32_bf16 v[88:91], v[164:167], v[212:215], v[88:91]
	v_mfma_f32_16x16x32_bf16 v[76:79], v[156:159], v[240:243], v[76:79]
	v_mfma_f32_16x16x32_bf16 v[72:75], v[164:167], v[240:243], v[72:75]
	v_mfma_f32_16x16x32_bf16 v[116:119], v[176:179], v[192:195], v[116:119]
	v_mfma_f32_16x16x32_bf16 v[112:115], v[184:187], v[192:195], v[112:115]
	v_mfma_f32_16x16x32_bf16 v[100:103], v[176:179], v[200:203], v[100:103]
	v_mfma_f32_16x16x32_bf16 v[96:99], v[184:187], v[200:203], v[96:99]
	v_mfma_f32_16x16x32_bf16 v[84:87], v[176:179], v[208:211], v[84:87]
	v_mfma_f32_16x16x32_bf16 v[80:83], v[184:187], v[208:211], v[80:83]
	v_mfma_f32_16x16x32_bf16 v[68:71], v[176:179], v[216:219], v[68:71]
	v_mfma_f32_16x16x32_bf16 v[64:67], v[184:187], v[216:219], v[64:67]
	v_mfma_f32_16x16x32_bf16 v[116:119], v[180:183], v[196:199], v[116:119]
	v_mfma_f32_16x16x32_bf16 v[112:115], v[188:191], v[196:199], v[112:115]
	v_mfma_f32_16x16x32_bf16 v[100:103], v[180:183], v[204:207], v[100:103]
	v_mfma_f32_16x16x32_bf16 v[96:99], v[188:191], v[204:207], v[96:99]
	v_mfma_f32_16x16x32_bf16 v[84:87], v[180:183], v[212:215], v[84:87]
	v_mfma_f32_16x16x32_bf16 v[80:83], v[188:191], v[212:215], v[80:83]
	v_mfma_f32_16x16x32_bf16 v[68:71], v[180:183], v[240:243], v[68:71]
	v_mfma_f32_16x16x32_bf16 v[64:67], v[188:191], v[240:243], v[64:67]
	s_barrier
; #define PG8_STAGE(bufoff, gbase, voff) do { _Pragma("unroll") for (int _i = 0; _i < 2; ++_i) \
;         __builtin_amdgcn_global_load_lds((const unsigned*)((const char*)(gbase) + (voff)[_i]), (LAS unsigned*)(lds + (bufoff) + ldsw + _i * 8192), 16, 0, 0); } while (0)
; #define PG8_LDA(dst, b, h) do { _Pragma("unroll") for (int m = 0; m < 4; ++m) _Pragma("unroll") for (int k = 0; k < 2; ++k) dst[m][k] = *(const LAS bf16x8*)(lds + PG8_SA(b, h) + aoff + m * 2048 + k * 1024); } while (0)
; #define PG8_LDB(dst, b, h) do { _Pragma("unroll") for (int n = 0; n < 2; ++n) _Pragma("unroll") for (int k = 0; k < 2; ++k) dst[n][k] = *(const LAS bf16x8*)(lds + PG8_SB(b, h) + boff + n * 2048 + k * 1024); } while (0)
; #define PG8_MMA(ai, bj, At, Bt) do { __builtin_amdgcn_s_setprio(1); _Pragma("unroll") for (int k = 0; k < 2; ++k) _Pragma("unroll") for (int m = 0; m < 4; ++m) _Pragma("unroll") for (int n = 0; n < 2; ++n) \
;         acc[ai][bj][m][n] = __builtin_amdgcn_mfma_f32_16x16x32_bf16(Bt[n][k], At[m][k], acc[ai][bj][m][n], 0, 0, 0); __builtin_amdgcn_s_setprio(0); } while (0)
; #define PG8_WAIT_V(n) asm volatile("s_waitcnt vmcnt(" #n ")" ::: "memory")
; #define PG8_WAIT_L(n) asm volatile("s_waitcnt lgkmcnt(" #n ")" ::: "memory")
; #define PG8_BAR __builtin_amdgcn_s_barrier()
; #define PG8_SCHED __builtin_amdgcn_sched_barrier(0)
; template <class Epi, bool ALIGN_EPI>
; __device__ __forceinline__ void gemm_phase(LAS unsigned char* lds, const Gemm g, const StaticOrder& S, const Epi& E, const int tid) {
;     ...
;             PG8_LDB(B0, 0, 0); PG8_LDB(B1, 0, 1); PG8_SCHED; PG8_LDA(At, 0, 0); PG8_STAGE(PG8_SA(1, 1), a1 + hA, voffA);
;     ...
;             PG8_LDA(At, 1, 1); PG8_STAGE(PG8_SB(1, 0), b3, voffB); PG8_STAGE(PG8_SB(1, 1), b3 + hB, voffB); PG8_STAGE(PG8_SA(1, 0), a3, voffA);
;             PG8_WAIT_V(8); PG8_WAIT_L(0); PG8_BAR; PG8_MMA(1, 0, At, B0); PG8_MMA(1, 1, At, B1); PG8_BAR; PG8_SCHED;
	s_add_i32 s10, s10, s45
	v_lshl_add_u64 v[150:151], v[226:227], 0, s[92:93]
	s_mov_b32 m0, s10
	ds_read_b128 v[192:195], v155 offset:49152
	ds_read_b128 v[196:199], v155 offset:50176
	ds_read_b128 v[200:203], v155 offset:51200
	ds_read_b128 v[204:207], v155 offset:52224
	ds_read_b128 v[208:211], v155 offset:53248
	ds_read_b128 v[212:215], v155 offset:54272
	ds_read_b128 v[216:219], v155 offset:55296
	ds_read_b128 v[240:243], v155 offset:56320
	global_load_lds_dwordx4 v[150:151], off
	v_lshl_add_u64 v[150:151], v[244:245], 0, s[92:93]
	s_add_i32 m0, s10, 0x2000
	s_add_i32 s10, s65, s45
	global_load_lds_dwordx4 v[150:151], off
	v_lshl_add_u64 v[150:151], v[246:247], 0, s[92:93]
	s_mov_b32 m0, s10
	s_nop 0
	global_load_lds_dwordx4 v[150:151], off
	v_lshl_add_u64 v[150:151], v[220:221], 0, s[92:93]
	s_add_i32 m0, s10, 0x2000
	s_nop 0
	global_load_lds_dwordx4 v[150:151], off
	v_lshl_add_u64 v[150:151], v[248:249], 0, s[92:93]
	s_mov_b32 m0, s56
	s_nop 0
	global_load_lds_dwordx4 v[150:151], off
	v_lshl_add_u64 v[150:151], v[250:251], 0, s[92:93]
	s_mov_b32 m0, s57
	s_nop 0
	global_load_lds_dwordx4 v[150:151], off
	s_waitcnt vmcnt(8)
	s_waitcnt lgkmcnt(0)
	s_barrier
	s_waitcnt lgkmcnt(0)
	v_mfma_f32_16x16x32_bf16 v[60:63], v[146:149], v[192:195], v[60:63]
	v_mfma_f32_16x16x32_bf16 v[56:59], v[160:163], v[192:195], v[56:59]
	v_mfma_f32_16x16x32_bf16 v[44:47], v[146:149], v[200:203], v[44:47]
	v_mfma_f32_16x16x32_bf16 v[40:43], v[160:163], v[200:203], v[40:43]
	v_mfma_f32_16x16x32_bf16 v[28:31], v[146:149], v[208:211], v[28:31]
	v_mfma_f32_16x16x32_bf16 v[24:27], v[160:163], v[208:211], v[24:27]
	v_mfma_f32_16x16x32_bf16 v[12:15], v[146:149], v[216:219], v[12:15]
	v_mfma_f32_16x16x32_bf16 v[8:11], v[160:163], v[216:219], v[8:11]
	v_mfma_f32_16x16x32_bf16 v[60:63], v[156:159], v[196:199], v[60:63]
	v_mfma_f32_16x16x32_bf16 v[56:59], v[164:167], v[196:199], v[56:59]
	v_mfma_f32_16x16x32_bf16 v[44:47], v[156:159], v[204:207], v[44:47]
	v_mfma_f32_16x16x32_bf16 v[40:43], v[164:167], v[204:207], v[40:43]
	v_mfma_f32_16x16x32_bf16 v[28:31], v[156:159], v[212:215], v[28:31]
	v_mfma_f32_16x16x32_bf16 v[24:27], v[164:167], v[212:215], v[24:27]
	v_mfma_f32_16x16x32_bf16 v[12:15], v[156:159], v[240:243], v[12:15]
	v_mfma_f32_16x16x32_bf16 v[8:11], v[164:167], v[240:243], v[8:11]
	v_mfma_f32_16x16x32_bf16 v[52:55], v[176:179], v[192:195], v[52:55]
	v_mfma_f32_16x16x32_bf16 v[48:51], v[184:187], v[192:195], v[48:51]
	v_mfma_f32_16x16x32_bf16 v[36:39], v[176:179], v[200:203], v[36:39]
	v_mfma_f32_16x16x32_bf16 v[32:35], v[184:187], v[200:203], v[32:35]
	v_mfma_f32_16x16x32_bf16 v[20:23], v[176:179], v[208:211], v[20:23]
	v_mfma_f32_16x16x32_bf16 v[16:19], v[184:187], v[208:211], v[16:19]
	v_mfma_f32_16x16x32_bf16 v[4:7], v[176:179], v[216:219], v[4:7]
	v_mfma_f32_16x16x32_bf16 v[0:3], v[184:187], v[216:219], v[0:3]
	v_mfma_f32_16x16x32_bf16 v[52:55], v[180:183], v[196:199], v[52:55]
	v_mfma_f32_16x16x32_bf16 v[48:51], v[188:191], v[196:199], v[48:51]
	v_mfma_f32_16x16x32_bf16 v[36:39], v[180:183], v[204:207], v[36:39]
	v_mfma_f32_16x16x32_bf16 v[32:35], v[188:191], v[204:207], v[32:35]
	v_mfma_f32_16x16x32_bf16 v[20:23], v[180:183], v[212:215], v[20:23]
	v_mfma_f32_16x16x32_bf16 v[16:19], v[188:191], v[212:215], v[16:19]
	v_mfma_f32_16x16x32_bf16 v[4:7], v[180:183], v[240:243], v[4:7]
	v_mfma_f32_16x16x32_bf16 v[0:3], v[188:191], v[240:243], v[0:3]
	s_barrier
	v_lshl_add_u64 v[142:143], v[142:143], 0, s[80:81]
	v_lshl_add_u64 v[144:145], v[144:145], 0, s[80:81]
	s_cmp_ge_u32 s11, s55
	s_mov_b32 s10, s11
	s_cbranch_scc1 .Lpl4_after
.LBB0_331:
	s_add_i32 s11, s10, 2
	s_cmp_eq_u32 s58, s10
	v_lshl_add_u64 v[146:147], v[142:143], 0, s[92:93]
	s_cselect_b64 vcc, -1, 0
	v_add_u32_e32 v152, s33, v153
	s_add_i32 s10, 0, 0x14000
	v_cndmask_b32_e32 v151, v147, v139, vcc
	v_cndmask_b32_e32 v150, v146, v138, vcc
	ds_read_b128 v[146:149], v152
	ds_read_b128 v[156:159], v152 offset:1024
	ds_read_b128 v[160:163], v152 offset:2048
	ds_read_b128 v[164:167], v152 offset:3072
	v_add_u32_e32 v152, s10, v153
	ds_read_b128 v[176:179], v152
	ds_read_b128 v[180:183], v152 offset:1024
	ds_read_b128 v[184:187], v152 offset:2048
	ds_read_b128 v[188:191], v152 offset:3072
	v_cndmask_b32_e32 v221, v145, v141, vcc
	v_cndmask_b32_e32 v220, v144, v140, vcc
	v_lshl_add_u64 v[226:227], v[142:143], 0, v[134:135]
	s_add_i32 m0, s51, 0xc000
	ds_read_b128 v[192:195], v155
	ds_read_b128 v[196:199], v155 offset:1024
	ds_read_b128 v[200:203], v155 offset:2048
	ds_read_b128 v[204:207], v155 offset:3072
	ds_read_b128 v[208:211], v155 offset:4096
	ds_read_b128 v[212:215], v155 offset:5120
	ds_read_b128 v[216:219], v155 offset:6144
	ds_read_b128 v[240:243], v155 offset:7168
	global_load_lds_dwordx4 v[226:227], off
	v_lshl_add_u64 v[226:227], v[142:143], 0, v[136:137]
	s_add_i32 m0, s51, 0xe000
	s_nop 0
	global_load_lds_dwordx4 v[226:227], off
	s_waitcnt vmcnt(8)
	s_waitcnt lgkmcnt(0)
	s_barrier
; #define PG8_STAGE(bufoff, gbase, voff) do { _Pragma("unroll") for (int _i = 0; _i < 2; ++_i) \
;         __builtin_amdgcn_global_load_lds((const unsigned*)((const char*)(gbase) + (voff)[_i]), (LAS unsigned*)(lds + (bufoff) + ldsw + _i * 8192), 16, 0, 0); } while (0)
; #define PG8_LDA(dst, b, h) do { _Pragma("unroll") for (int m = 0; m < 4; ++m) _Pragma("unroll") for (int k = 0; k < 2; ++k) dst[m][k] = *(const LAS bf16x8*)(lds + PG8_SA(b, h) + aoff + m * 2048 + k * 1024); } while (0)
; #define PG8_MMA(ai, bj, At, Bt) do { __builtin_amdgcn_s_setprio(1); _Pragma("unroll") for (int k = 0; k < 2; ++k) _Pragma("unroll") for (int m = 0; m < 4; ++m) _Pragma("unroll") for (int n = 0; n < 2; ++n) \
;         acc[ai][bj][m][n] = __builtin_amdgcn_mfma_f32_16x16x32_bf16(Bt[n][k], At[m][k], acc[ai][bj][m][n], 0, 0, 0); __builtin_amdgcn_s_setprio(0); } while (0)
; #define PG8_WAIT_V(n) asm volatile("s_waitcnt vmcnt(" #n ")" ::: "memory")
; #define PG8_WAIT_L(n) asm volatile("s_waitcnt lgkmcnt(" #n ")" ::: "memory")
; #define PG8_BAR __builtin_amdgcn_s_barrier()
; #define PG8_SCHED __builtin_amdgcn_sched_barrier(0)
; template <class Epi, bool ALIGN_EPI>
; __device__ __forceinline__ void gemm_phase(LAS unsigned char* lds, const Gemm g, const StaticOrder& S, const Epi& E, const int tid) {
;     ...
;             PG8_WAIT_V(8); PG8_WAIT_L(0); PG8_BAR; PG8_MMA(0, 0, At, B0); PG8_MMA(0, 1, At, B1); PG8_BAR; PG8_SCHED;
;             PG8_LDA(At, 0, 1); PG8_STAGE(PG8_SB(0, 0), b2, voffB); PG8_STAGE(PG8_SB(0, 1), b2 + hB, voffB); PG8_STAGE(PG8_SA(0, 0), a2, voffA);
;             PG8_WAIT_V(8); PG8_WAIT_L(0); PG8_BAR; PG8_MMA(1, 0, At, B0); PG8_MMA(1, 1, At, B1); PG8_BAR; PG8_SCHED;
	s_waitcnt lgkmcnt(0)
	v_mfma_f32_16x16x32_bf16 v[120:123], v[146:149], v[192:195], v[120:123]
	v_mfma_f32_16x16x32_bf16 v[124:127], v[160:163], v[192:195], v[124:127]
	v_mfma_f32_16x16x32_bf16 v[108:111], v[146:149], v[200:203], v[108:111]
	v_mfma_f32_16x16x32_bf16 v[104:107], v[160:163], v[200:203], v[104:107]
	v_mfma_f32_16x16x32_bf16 v[92:95], v[146:149], v[208:211], v[92:95]
	v_mfma_f32_16x16x32_bf16 v[88:91], v[160:163], v[208:211], v[88:91]
	v_mfma_f32_16x16x32_bf16 v[76:79], v[146:149], v[216:219], v[76:79]
	v_mfma_f32_16x16x32_bf16 v[72:75], v[160:163], v[216:219], v[72:75]
	v_mfma_f32_16x16x32_bf16 v[120:123], v[156:159], v[196:199], v[120:123]
	v_mfma_f32_16x16x32_bf16 v[124:127], v[164:167], v[196:199], v[124:127]
	v_mfma_f32_16x16x32_bf16 v[108:111], v[156:159], v[204:207], v[108:111]
	v_mfma_f32_16x16x32_bf16 v[104:107], v[164:167], v[204:207], v[104:107]
	v_mfma_f32_16x16x32_bf16 v[92:95], v[156:159], v[212:215], v[92:95]
	v_mfma_f32_16x16x32_bf16 v[88:91], v[164:167], v[212:215], v[88:91]
	v_mfma_f32_16x16x32_bf16 v[76:79], v[156:159], v[240:243], v[76:79]
	v_mfma_f32_16x16x32_bf16 v[72:75], v[164:167], v[240:243], v[72:75]
	v_mfma_f32_16x16x32_bf16 v[116:119], v[176:179], v[192:195], v[116:119]
	v_mfma_f32_16x16x32_bf16 v[112:115], v[184:187], v[192:195], v[112:115]
	v_mfma_f32_16x16x32_bf16 v[100:103], v[176:179], v[200:203], v[100:103]
	v_mfma_f32_16x16x32_bf16 v[96:99], v[184:187], v[200:203], v[96:99]
	v_mfma_f32_16x16x32_bf16 v[84:87], v[176:179], v[208:211], v[84:87]
	v_mfma_f32_16x16x32_bf16 v[80:83], v[184:187], v[208:211], v[80:83]
	v_mfma_f32_16x16x32_bf16 v[68:71], v[176:179], v[216:219], v[68:71]
	v_mfma_f32_16x16x32_bf16 v[64:67], v[184:187], v[216:219], v[64:67]
	v_mfma_f32_16x16x32_bf16 v[116:119], v[180:183], v[196:199], v[116:119]
	v_mfma_f32_16x16x32_bf16 v[112:115], v[188:191], v[196:199], v[112:115]
	v_mfma_f32_16x16x32_bf16 v[100:103], v[180:183], v[204:207], v[100:103]
	v_mfma_f32_16x16x32_bf16 v[96:99], v[188:191], v[204:207], v[96:99]
	v_mfma_f32_16x16x32_bf16 v[84:87], v[180:183], v[212:215], v[84:87]
	v_mfma_f32_16x16x32_bf16 v[80:83], v[188:191], v[212:215], v[80:83]
	v_mfma_f32_16x16x32_bf16 v[68:71], v[180:183], v[240:243], v[68:71]
	v_mfma_f32_16x16x32_bf16 v[64:67], v[188:191], v[240:243], v[64:67]
	s_barrier
	s_add_i32 s65, s33, s45
	v_lshl_add_u64 v[226:227], v[220:221], 0, v[168:169]
	s_mov_b32 m0, s65
	ds_read_b128 v[192:195], v155 offset:16384
	ds_read_b128 v[196:199], v155 offset:17408
	ds_read_b128 v[200:203], v155 offset:18432
	ds_read_b128 v[204:207], v155 offset:19456
	ds_read_b128 v[208:211], v155 offset:20480
	ds_read_b128 v[212:215], v155 offset:21504
	ds_read_b128 v[216:219], v155 offset:22528
	ds_read_b128 v[240:243], v155 offset:23552
	global_load_lds_dwordx4 v[226:227], off
	v_lshl_add_u64 v[244:245], v[220:221], 0, v[128:129]
	s_add_i32 m0, s65, 0x2000
	v_lshl_add_u64 v[220:221], v[220:221], 0, s[12:13]
	s_add_i32 s10, s10, s45
	global_load_lds_dwordx4 v[244:245], off
	v_lshl_add_u64 v[246:247], v[220:221], 0, v[168:169]
	s_mov_b32 m0, s10
	v_lshl_add_u64 v[220:221], v[220:221], 0, v[128:129]
	global_load_lds_dwordx4 v[246:247], off
	s_add_i32 m0, s10, 0x2000
	v_lshl_add_u64 v[248:249], v[150:151], 0, v[132:133]
	global_load_lds_dwordx4 v[220:221], off
	s_mov_b32 m0, s51
	v_lshl_add_u64 v[250:251], v[150:151], 0, v[130:131]
	global_load_lds_dwordx4 v[248:249], off
	s_mov_b32 m0, s52
	s_nop 0
	global_load_lds_dwordx4 v[250:251], off
	s_waitcnt vmcnt(8)
	s_waitcnt lgkmcnt(0)
	s_barrier
	s_waitcnt lgkmcnt(0)
	v_mfma_f32_16x16x32_bf16 v[60:63], v[146:149], v[192:195], v[60:63]
	v_mfma_f32_16x16x32_bf16 v[56:59], v[160:163], v[192:195], v[56:59]
	v_mfma_f32_16x16x32_bf16 v[44:47], v[146:149], v[200:203], v[44:47]
	v_mfma_f32_16x16x32_bf16 v[40:43], v[160:163], v[200:203], v[40:43]
	v_mfma_f32_16x16x32_bf16 v[28:31], v[146:149], v[208:211], v[28:31]
	v_mfma_f32_16x16x32_bf16 v[24:27], v[160:163], v[208:211], v[24:27]
	v_mfma_f32_16x16x32_bf16 v[12:15], v[146:149], v[216:219], v[12:15]
	v_mfma_f32_16x16x32_bf16 v[8:11], v[160:163], v[216:219], v[8:11]
	v_mfma_f32_16x16x32_bf16 v[60:63], v[156:159], v[196:199], v[60:63]
	v_mfma_f32_16x16x32_bf16 v[56:59], v[164:167], v[196:199], v[56:59]
	v_mfma_f32_16x16x32_bf16 v[44:47], v[156:159], v[204:207], v[44:47]
	v_mfma_f32_16x16x32_bf16 v[40:43], v[164:167], v[204:207], v[40:43]
	v_mfma_f32_16x16x32_bf16 v[28:31], v[156:159], v[212:215], v[28:31]
	v_mfma_f32_16x16x32_bf16 v[24:27], v[164:167], v[212:215], v[24:27]
	v_mfma_f32_16x16x32_bf16 v[12:15], v[156:159], v[240:243], v[12:15]
	v_mfma_f32_16x16x32_bf16 v[8:11], v[164:167], v[240:243], v[8:11]
	v_mfma_f32_16x16x32_bf16 v[52:55], v[176:179], v[192:195], v[52:55]
	v_mfma_f32_16x16x32_bf16 v[48:51], v[184:187], v[192:195], v[48:51]
	v_mfma_f32_16x16x32_bf16 v[36:39], v[176:179], v[200:203], v[36:39]
	v_mfma_f32_16x16x32_bf16 v[32:35], v[184:187], v[200:203], v[32:35]
	v_mfma_f32_16x16x32_bf16 v[20:23], v[176:179], v[208:211], v[20:23]
	v_mfma_f32_16x16x32_bf16 v[16:19], v[184:187], v[208:211], v[16:19]
	v_mfma_f32_16x16x32_bf16 v[4:7], v[176:179], v[216:219], v[4:7]
	v_mfma_f32_16x16x32_bf16 v[0:3], v[184:187], v[216:219], v[0:3]
	v_mfma_f32_16x16x32_bf16 v[52:55], v[180:183], v[196:199], v[52:55]
	v_mfma_f32_16x16x32_bf16 v[48:51], v[188:191], v[196:199], v[48:51]
	v_mfma_f32_16x16x32_bf16 v[36:39], v[180:183], v[204:207], v[36:39]
	v_mfma_f32_16x16x32_bf16 v[32:35], v[188:191], v[204:207], v[32:35]
	v_mfma_f32_16x16x32_bf16 v[20:23], v[180:183], v[212:215], v[20:23]
	v_mfma_f32_16x16x32_bf16 v[16:19], v[188:191], v[212:215], v[16:19]
	v_mfma_f32_16x16x32_bf16 v[4:7], v[180:183], v[240:243], v[4:7]
	v_mfma_f32_16x16x32_bf16 v[0:3], v[188:191], v[240:243], v[0:3]
	s_barrier
; #define PG8_STAGE(bufoff, gbase, voff) do { _Pragma("unroll") for (int _i = 0; _i < 2; ++_i) \
;         __builtin_amdgcn_global_load_lds((const unsigned*)((const char*)(gbase) + (voff)[_i]), (LAS unsigned*)(lds + (bufoff) + ldsw + _i * 8192), 16, 0, 0); } while (0)
; #define PG8_LDA(dst, b, h) do { _Pragma("unroll") for (int m = 0; m < 4; ++m) _Pragma("unroll") for (int k = 0; k < 2; ++k) dst[m][k] = *(const LAS bf16x8*)(lds + PG8_SA(b, h) + aoff + m * 2048 + k * 1024); } while (0)
; #define PG8_LDB(dst, b, h) do { _Pragma("unroll") for (int n = 0; n < 2; ++n) _Pragma("unroll") for (int k = 0; k < 2; ++k) dst[n][k] = *(const LAS bf16x8*)(lds + PG8_SB(b, h) + boff + n * 2048 + k * 1024); } while (0)
; #define PG8_MMA(ai, bj, At, Bt) do { __builtin_amdgcn_s_setprio(1); _Pragma("unroll") for (int k = 0; k < 2; ++k) _Pragma("unroll") for (int m = 0; m < 4; ++m) _Pragma("unroll") for (int n = 0; n < 2; ++n) \
;         acc[ai][bj][m][n] = __builtin_amdgcn_mfma_f32_16x16x32_bf16(Bt[n][k], At[m][k], acc[ai][bj][m][n], 0, 0, 0); __builtin_amdgcn_s_setprio(0); } while (0)
; #define PG8_WAIT_V(n) asm volatile("s_waitcnt vmcnt(" #n ")" ::: "memory")
; #define PG8_WAIT_L(n) asm volatile("s_waitcnt lgkmcnt(" #n ")" ::: "memory")
; #define PG8_BAR __builtin_amdgcn_s_barrier()
; #define PG8_SCHED __builtin_amdgcn_sched_barrier(0)
; template <class Epi, bool ALIGN_EPI>
; __device__ __forceinline__ void gemm_phase(LAS unsigned char* lds, const Gemm g, const StaticOrder& S, const Epi& E, const int tid) {
;     ...
;             PG8_LDB(B0, 1, 0); PG8_LDB(B1, 1, 1); PG8_SCHED; PG8_LDA(At, 1, 0); PG8_STAGE(PG8_SA(0, 1), a2 + hA, voffA);
;             PG8_WAIT_V(8); PG8_WAIT_L(0); PG8_BAR; PG8_MMA(0, 0, At, B0); PG8_MMA(0, 1, At, B1); PG8_BAR; PG8_SCHED;
;             PG8_LDA(At, 1, 1); PG8_STAGE(PG8_SB(1, 0), b3, voffB); PG8_STAGE(PG8_SB(1, 1), b3 + hB, voffB); PG8_STAGE(PG8_SA(1, 0), a3, voffA);
;             PG8_WAIT_V(8); PG8_WAIT_L(0); PG8_BAR; PG8_MMA(1, 0, At, B0); PG8_MMA(1, 1, At, B1); PG8_BAR; PG8_SCHED;
	s_add_i32 s10, 0, 0x18000
	v_add_u32_e32 v152, s10, v153
	s_add_i32 s65, 0, 0x1c000
	ds_read_b128 v[146:149], v152
	ds_read_b128 v[156:159], v152 offset:1024
	ds_read_b128 v[160:163], v152 offset:2048
	ds_read_b128 v[164:167], v152 offset:3072
	v_add_u32_e32 v152, s65, v153
	ds_read_b128 v[176:179], v152
	ds_read_b128 v[180:183], v152 offset:1024
	ds_read_b128 v[184:187], v152 offset:2048
	ds_read_b128 v[188:191], v152 offset:3072
	v_lshl_add_u64 v[150:151], v[150:151], 0, s[94:95]
	s_mov_b32 m0, s53
	v_lshl_add_u64 v[252:253], v[150:151], 0, v[132:133]
	ds_read_b128 v[192:195], v155 offset:32768
	ds_read_b128 v[196:199], v155 offset:33792
	ds_read_b128 v[200:203], v155 offset:34816
	ds_read_b128 v[204:207], v155 offset:35840
	ds_read_b128 v[208:211], v155 offset:36864
	ds_read_b128 v[212:215], v155 offset:37888
	ds_read_b128 v[216:219], v155 offset:38912
	ds_read_b128 v[240:243], v155 offset:39936
	global_load_lds_dwordx4 v[252:253], off
	v_lshl_add_u64 v[150:151], v[150:151], 0, v[130:131]
	s_mov_b32 m0, s54
	s_nop 0
	global_load_lds_dwordx4 v[150:151], off
	s_waitcnt vmcnt(8)
	s_waitcnt lgkmcnt(0)
	s_barrier
	s_waitcnt lgkmcnt(0)
	v_mfma_f32_16x16x32_bf16 v[120:123], v[146:149], v[192:195], v[120:123]
	v_mfma_f32_16x16x32_bf16 v[124:127], v[160:163], v[192:195], v[124:127]
	v_mfma_f32_16x16x32_bf16 v[108:111], v[146:149], v[200:203], v[108:111]
	v_mfma_f32_16x16x32_bf16 v[104:107], v[160:163], v[200:203], v[104:107]
	v_mfma_f32_16x16x32_bf16 v[92:95], v[146:149], v[208:211], v[92:95]
	v_mfma_f32_16x16x32_bf16 v[88:91], v[160:163], v[208:211], v[88:91]
	v_mfma_f32_16x16x32_bf16 v[76:79], v[146:149], v[216:219], v[76:79]
	v_mfma_f32_16x16x32_bf16 v[72:75], v[160:163], v[216:219], v[72:75]
	v_mfma_f32_16x16x32_bf16 v[120:123], v[156:159], v[196:199], v[120:123]
	v_mfma_f32_16x16x32_bf16 v[124:127], v[164:167], v[196:199], v[124:127]
	v_mfma_f32_16x16x32_bf16 v[108:111], v[156:159], v[204:207], v[108:111]
	v_mfma_f32_16x16x32_bf16 v[104:107], v[164:167], v[204:207], v[104:107]
	v_mfma_f32_16x16x32_bf16 v[92:95], v[156:159], v[212:215], v[92:95]
	v_mfma_f32_16x16x32_bf16 v[88:91], v[164:167], v[212:215], v[88:91]
	v_mfma_f32_16x16x32_bf16 v[76:79], v[156:159], v[240:243], v[76:79]
	v_mfma_f32_16x16x32_bf16 v[72:75], v[164:167], v[240:243], v[72:75]
	v_mfma_f32_16x16x32_bf16 v[116:119], v[176:179], v[192:195], v[116:119]
	v_mfma_f32_16x16x32_bf16 v[112:115], v[184:187], v[192:195], v[112:115]
	v_mfma_f32_16x16x32_bf16 v[100:103], v[176:179], v[200:203], v[100:103]
	v_mfma_f32_16x16x32_bf16 v[96:99], v[184:187], v[200:203], v[96:99]
	v_mfma_f32_16x16x32_bf16 v[84:87], v[176:179], v[208:211], v[84:87]
	v_mfma_f32_16x16x32_bf16 v[80:83], v[184:187], v[208:211], v[80:83]
	v_mfma_f32_16x16x32_bf16 v[68:71], v[176:179], v[216:219], v[68:71]
	v_mfma_f32_16x16x32_bf16 v[64:67], v[184:187], v[216:219], v[64:67]
	v_mfma_f32_16x16x32_bf16 v[116:119], v[180:183], v[196:199], v[116:119]
	v_mfma_f32_16x16x32_bf16 v[112:115], v[188:191], v[196:199], v[112:115]
	v_mfma_f32_16x16x32_bf16 v[100:103], v[180:183], v[204:207], v[100:103]
	v_mfma_f32_16x16x32_bf16 v[96:99], v[188:191], v[204:207], v[96:99]
	v_mfma_f32_16x16x32_bf16 v[84:87], v[180:183], v[212:215], v[84:87]
	v_mfma_f32_16x16x32_bf16 v[80:83], v[188:191], v[212:215], v[80:83]
	v_mfma_f32_16x16x32_bf16 v[68:71], v[180:183], v[240:243], v[68:71]
	v_mfma_f32_16x16x32_bf16 v[64:67], v[188:191], v[240:243], v[64:67]
	s_barrier
	s_add_i32 s10, s10, s45
	v_lshl_add_u64 v[150:151], v[226:227], 0, s[92:93]
	s_mov_b32 m0, s10
	ds_read_b128 v[192:195], v155 offset:49152
	ds_read_b128 v[196:199], v155 offset:50176
	ds_read_b128 v[200:203], v155 offset:51200
	ds_read_b128 v[204:207], v155 offset:52224
	ds_read_b128 v[208:211], v155 offset:53248
	ds_read_b128 v[212:215], v155 offset:54272
	ds_read_b128 v[216:219], v155 offset:55296
	ds_read_b128 v[240:243], v155 offset:56320
	global_load_lds_dwordx4 v[150:151], off
	v_lshl_add_u64 v[150:151], v[244:245], 0, s[92:93]
	s_add_i32 m0, s10, 0x2000
	s_add_i32 s10, s65, s45
	global_load_lds_dwordx4 v[150:151], off
	v_lshl_add_u64 v[150:151], v[246:247], 0, s[92:93]
	s_mov_b32 m0, s10
	s_nop 0
	global_load_lds_dwordx4 v[150:151], off
	v_lshl_add_u64 v[150:151], v[220:221], 0, s[92:93]
	s_add_i32 m0, s10, 0x2000
	s_nop 0
	global_load_lds_dwordx4 v[150:151], off
	v_lshl_add_u64 v[150:151], v[248:249], 0, s[92:93]
	s_mov_b32 m0, s56
	s_nop 0
	global_load_lds_dwordx4 v[150:151], off
	v_lshl_add_u64 v[150:151], v[250:251], 0, s[92:93]
	s_mov_b32 m0, s57
	s_nop 0
	global_load_lds_dwordx4 v[150:151], off
	s_waitcnt vmcnt(8)
	s_waitcnt lgkmcnt(0)
	s_barrier
	s_waitcnt lgkmcnt(0)
	v_mfma_f32_16x16x32_bf16 v[60:63], v[146:149], v[192:195], v[60:63]
	v_mfma_f32_16x16x32_bf16 v[56:59], v[160:163], v[192:195], v[56:59]
	v_mfma_f32_16x16x32_bf16 v[44:47], v[146:149], v[200:203], v[44:47]
	v_mfma_f32_16x16x32_bf16 v[40:43], v[160:163], v[200:203], v[40:43]
	v_mfma_f32_16x16x32_bf16 v[28:31], v[146:149], v[208:211], v[28:31]
	v_mfma_f32_16x16x32_bf16 v[24:27], v[160:163], v[208:211], v[24:27]
	v_mfma_f32_16x16x32_bf16 v[12:15], v[146:149], v[216:219], v[12:15]
	v_mfma_f32_16x16x32_bf16 v[8:11], v[160:163], v[216:219], v[8:11]
	v_mfma_f32_16x16x32_bf16 v[60:63], v[156:159], v[196:199], v[60:63]
	v_mfma_f32_16x16x32_bf16 v[56:59], v[164:167], v[196:199], v[56:59]
	v_mfma_f32_16x16x32_bf16 v[44:47], v[156:159], v[204:207], v[44:47]
	v_mfma_f32_16x16x32_bf16 v[40:43], v[164:167], v[204:207], v[40:43]
	v_mfma_f32_16x16x32_bf16 v[28:31], v[156:159], v[212:215], v[28:31]
	v_mfma_f32_16x16x32_bf16 v[24:27], v[164:167], v[212:215], v[24:27]
	v_mfma_f32_16x16x32_bf16 v[12:15], v[156:159], v[240:243], v[12:15]
	v_mfma_f32_16x16x32_bf16 v[8:11], v[164:167], v[240:243], v[8:11]
	v_mfma_f32_16x16x32_bf16 v[52:55], v[176:179], v[192:195], v[52:55]
	v_mfma_f32_16x16x32_bf16 v[48:51], v[184:187], v[192:195], v[48:51]
	v_mfma_f32_16x16x32_bf16 v[36:39], v[176:179], v[200:203], v[36:39]
	v_mfma_f32_16x16x32_bf16 v[32:35], v[184:187], v[200:203], v[32:35]
	v_mfma_f32_16x16x32_bf16 v[20:23], v[176:179], v[208:211], v[20:23]
	v_mfma_f32_16x16x32_bf16 v[16:19], v[184:187], v[208:211], v[16:19]
	v_mfma_f32_16x16x32_bf16 v[4:7], v[176:179], v[216:219], v[4:7]
	v_mfma_f32_16x16x32_bf16 v[0:3], v[184:187], v[216:219], v[0:3]
	v_mfma_f32_16x16x32_bf16 v[52:55], v[180:183], v[196:199], v[52:55]
	v_mfma_f32_16x16x32_bf16 v[48:51], v[188:191], v[196:199], v[48:51]
	v_mfma_f32_16x16x32_bf16 v[36:39], v[180:183], v[204:207], v[36:39]
	v_mfma_f32_16x16x32_bf16 v[32:35], v[188:191], v[204:207], v[32:35]
	v_mfma_f32_16x16x32_bf16 v[20:23], v[180:183], v[212:215], v[20:23]
	v_mfma_f32_16x16x32_bf16 v[16:19], v[188:191], v[212:215], v[16:19]
	v_mfma_f32_16x16x32_bf16 v[4:7], v[180:183], v[240:243], v[4:7]
	v_mfma_f32_16x16x32_bf16 v[0:3], v[188:191], v[240:243], v[0:3]
	s_barrier
	v_lshl_add_u64 v[142:143], v[142:143], 0, s[80:81]
	v_lshl_add_u64 v[144:145], v[144:145], 0, s[80:81]
	s_cmp_ge_u32 s11, s55
	s_mov_b32 s10, s11
	s_cbranch_scc0 .LBB0_331

; __device__ __forceinline__ unsigned cvt_pk_bf16(float lo, float hi) { unsigned r; asm volatile("v_cvt_pk_bf16_f32 %0, %1, %2" : "=v"(r) : "v"(lo), "v"(hi)); return r; }
; __device__ __forceinline__ float gelu_tanh(float x) { const float u = 0.7978845608028654f * (x + 0.044715f * x * x * x); return x * fast_rcp(1.0f + fast_exp2(-2.0f * LOG2E * u)); }
; #define PG8_STAGE(bufoff, gbase, voff) do { _Pragma("unroll") for (int _i = 0; _i < 2; ++_i) \
;         __builtin_amdgcn_global_load_lds((const unsigned*)((const char*)(gbase) + (voff)[_i]), (LAS unsigned*)(lds + (bufoff) + ldsw + _i * 8192), 16, 0, 0); } while (0)
; #define PG8_LDA(dst, b, h) do { _Pragma("unroll") for (int m = 0; m < 4; ++m) _Pragma("unroll") for (int k = 0; k < 2; ++k) dst[m][k] = *(const LAS bf16x8*)(lds + PG8_SA(b, h) + aoff + m * 2048 + k * 1024); } while (0)
; #define PG8_LDB(dst, b, h) do { _Pragma("unroll") for (int n = 0; n < 2; ++n) _Pragma("unroll") for (int k = 0; k < 2; ++k) dst[n][k] = *(const LAS bf16x8*)(lds + PG8_SB(b, h) + boff + n * 2048 + k * 1024); } while (0)
; #define PG8_WAIT_V(n) asm volatile("s_waitcnt vmcnt(" #n ")" ::: "memory")
;     __device__ __forceinline__ void operator()(const f32x4 (&acc)[2][2][4][2], const Unit& u, int wr, int wc, int fr, int fq) const {
;     ...
;             for (int m = 0; m < 4; ++m) { const int row = row0 + ai * HALF + m * 16; bf16_t* rowp = O + (size_t)row * ldc + col0; const float rs = rsv[ai][m];
; #pragma unroll
;                 for (int bj = 0; bj < 2; ++bj) { f32x4 v0 = acc[ai][bj][m][0] * rs, v1 = acc[ai][bj][m][1] * rs;
;                     if (ACT == 1) {
; #pragma unroll
;                         for (int j = 0; j < 4; ++j) { v0[j] = gelu_tanh(v0[j]); v1[j] = gelu_tanh(v1[j]); } }
;                     u32x4 w; w.x = cvt_pk_bf16(v0[0], v0[1]); w.y = cvt_pk_bf16(v0[2], v0[3]); w.z = cvt_pk_bf16(v1[0], v1[1]); w.w = cvt_pk_bf16(v1[2], v1[3]);
;                     *(u32x4*)(rowp + bj * HALF) = w; } }
; template <class Epi, bool ALIGN_EPI>
; __device__ __forceinline__ void gemm_phase(LAS unsigned char* lds, const Gemm g, const StaticOrder& S, const Epi& E, const int tid) {
;     ...
;             PG8_LDB(B0, 0, 0); PG8_LDB(B1, 0, 1); PG8_SCHED; PG8_LDA(At, 0, 0); PG8_STAGE(PG8_SA(1, 1), a1 + hA, voffA);
;             PG8_WAIT_V(8); PG8_WAIT_L(0); PG8_BAR; PG8_MMA(0, 0, At, B0); PG8_MMA(0, 1, At, B1); PG8_BAR; PG8_SCHED;
.Lq5_first_epi:
	s_add_i32 s11, s10, 2
	s_cmp_eq_u32 s55, s10
	s_cselect_b64 vcc, -1, 0
	v_add_u32_e32 v148, s33, v149
	s_add_i32 s10, 0, 0x14000
	ds_read_b128 v[152:155], v148
	ds_read_b128 v[156:159], v148 offset:1024
	ds_read_b128 v[160:163], v148 offset:2048
	ds_read_b128 v[164:167], v148 offset:3072
	v_add_u32_e32 v148, s10, v149
	ds_read_b128 v[176:179], v148
	ds_read_b128 v[180:183], v148 offset:1024
	ds_read_b128 v[184:187], v148 offset:2048
	ds_read_b128 v[188:191], v148 offset:3072
	v_lshl_add_u64 v[146:147], v[142:143], 0, s[92:93]
	v_cndmask_b32_e32 v147, v147, v139, vcc
	v_cndmask_b32_e32 v146, v146, v138, vcc
	v_cndmask_b32_e32 v221, v145, v141, vcc
	v_cndmask_b32_e32 v220, v144, v140, vcc
	v_lshl_add_u64 v[244:245], v[142:143], 0, v[134:135]
	s_add_i32 m0, s25, 0xc000
	ds_read_b128 v[192:195], v151
	ds_read_b128 v[196:199], v151 offset:1024
	ds_read_b128 v[200:203], v151 offset:2048
	ds_read_b128 v[204:207], v151 offset:3072
	ds_read_b128 v[208:211], v151 offset:4096
	ds_read_b128 v[212:215], v151 offset:5120
	ds_read_b128 v[216:219], v151 offset:6144
	ds_read_b128 v[240:243], v151 offset:7168
	global_load_lds_dwordx4 v[244:245], off
	v_lshl_add_u64 v[244:245], v[142:143], 0, v[136:137]
	s_add_i32 m0, s25, 0xe000
	s_nop 0
	global_load_lds_dwordx4 v[244:245], off
	s_waitcnt vmcnt(16)
	s_waitcnt lgkmcnt(0)
	s_barrier
	s_waitcnt lgkmcnt(0)
	v_mfma_f32_16x16x32_bf16 v[124:127], v[152:155], v[192:195], 0
	s_lshl_b32 s98, s28, 5
	s_mov_b32 s99, 0
	v_mul_f32_e32 v60, v238, v60
	v_mul_f32_e32 v61, v238, v61
	v_mfma_f32_16x16x32_bf16 v[120:123], v[160:163], v[192:195], 0
	v_mul_f32_e32 v62, v238, v62
	v_mul_f32_e32 v63, v238, v63
	v_mul_f32_e32 v56, v238, v56
	v_mul_f32_e32 v57, v238, v57
	v_mfma_f32_16x16x32_bf16 v[108:111], v[152:155], v[200:203], 0
	v_mul_f32_e32 v58, v238, v58
	v_mul_f32_e32 v59, v238, v59
	v_cvt_pk_bf16_f32 v60, v60, v61
	v_cvt_pk_bf16_f32 v61, v62, v63
	v_mfma_f32_16x16x32_bf16 v[104:107], v[160:163], v[200:203], 0
	v_cvt_pk_bf16_f32 v62, v56, v57
	v_cvt_pk_bf16_f32 v63, v58, v59
	global_store_dwordx4 v[232:233], v[60:63], off
	v_mul_f32_e32 v52, v238, v52
	v_mfma_f32_16x16x32_bf16 v[92:95], v[152:155], v[208:211], 0
	v_mul_f32_e32 v53, v238, v53
	v_mul_f32_e32 v54, v238, v54
	v_mul_f32_e32 v55, v238, v55
	v_mul_f32_e32 v48, v238, v48
	v_mfma_f32_16x16x32_bf16 v[88:91], v[160:163], v[208:211], 0
	v_mul_f32_e32 v49, v238, v49
	v_mul_f32_e32 v50, v238, v50
	v_mul_f32_e32 v51, v238, v51
	v_cvt_pk_bf16_f32 v52, v52, v53
	v_mfma_f32_16x16x32_bf16 v[76:79], v[152:155], v[216:219], 0
	v_cvt_pk_bf16_f32 v53, v54, v55
	v_cvt_pk_bf16_f32 v54, v48, v49
	v_cvt_pk_bf16_f32 v55, v50, v51
	global_store_dwordx4 v[232:233], v[52:55], off offset:256
	v_mfma_f32_16x16x32_bf16 v[72:75], v[160:163], v[216:219], 0
	v_lshl_add_u64 v[232:233], v[232:233], 0, s[98:99]
	v_mul_f32_e32 v44, v239, v44
	v_mul_f32_e32 v45, v239, v45
	v_mul_f32_e32 v46, v239, v46
	v_mfma_f32_16x16x32_bf16 v[124:127], v[156:159], v[196:199], v[124:127]
	v_mul_f32_e32 v47, v239, v47
	v_mul_f32_e32 v40, v239, v40
	v_mul_f32_e32 v41, v239, v41
	v_mul_f32_e32 v42, v239, v42
	v_mfma_f32_16x16x32_bf16 v[120:123], v[164:167], v[196:199], v[120:123]
	v_mul_f32_e32 v43, v239, v43
	v_cvt_pk_bf16_f32 v44, v44, v45
	v_cvt_pk_bf16_f32 v45, v46, v47
	v_cvt_pk_bf16_f32 v46, v40, v41
	v_mfma_f32_16x16x32_bf16 v[108:111], v[156:159], v[204:207], v[108:111]
	v_cvt_pk_bf16_f32 v47, v42, v43
	global_store_dwordx4 v[232:233], v[44:47], off
	v_mul_f32_e32 v36, v239, v36
	v_mul_f32_e32 v37, v239, v37
	v_mfma_f32_16x16x32_bf16 v[104:107], v[164:167], v[204:207], v[104:107]
	v_mul_f32_e32 v38, v239, v38
	v_mul_f32_e32 v39, v239, v39
	v_mul_f32_e32 v32, v239, v32
	v_mul_f32_e32 v33, v239, v33
	v_mfma_f32_16x16x32_bf16 v[92:95], v[156:159], v[212:215], v[92:95]
	v_mul_f32_e32 v34, v239, v34
	v_mul_f32_e32 v35, v239, v35
	v_cvt_pk_bf16_f32 v36, v36, v37
	v_cvt_pk_bf16_f32 v37, v38, v39
	v_mfma_f32_16x16x32_bf16 v[88:91], v[164:167], v[212:215], v[88:91]
	v_cvt_pk_bf16_f32 v38, v32, v33
	v_cvt_pk_bf16_f32 v39, v34, v35
	global_store_dwordx4 v[232:233], v[36:39], off offset:256
	v_lshl_add_u64 v[232:233], v[232:233], 0, s[98:99]
	v_mfma_f32_16x16x32_bf16 v[76:79], v[156:159], v[240:243], v[76:79]
	v_mul_f32_e32 v28, v230, v28
	v_mul_f32_e32 v29, v230, v29
	v_mul_f32_e32 v30, v230, v30
	v_mul_f32_e32 v31, v230, v31
	v_mfma_f32_16x16x32_bf16 v[72:75], v[164:167], v[240:243], v[72:75]
	v_mul_f32_e32 v24, v230, v24
	v_mul_f32_e32 v25, v230, v25
	v_mul_f32_e32 v26, v230, v26
	v_mul_f32_e32 v27, v230, v27
	v_mfma_f32_16x16x32_bf16 v[116:119], v[176:179], v[192:195], 0
	v_cvt_pk_bf16_f32 v28, v28, v29
	v_cvt_pk_bf16_f32 v29, v30, v31
	v_cvt_pk_bf16_f32 v30, v24, v25
	v_cvt_pk_bf16_f32 v31, v26, v27
	v_mfma_f32_16x16x32_bf16 v[112:115], v[184:187], v[192:195], 0
	global_store_dwordx4 v[232:233], v[28:31], off
	v_mul_f32_e32 v20, v230, v20
	v_mul_f32_e32 v21, v230, v21
	v_mul_f32_e32 v22, v230, v22
	v_mfma_f32_16x16x32_bf16 v[100:103], v[176:179], v[200:203], 0
	v_mul_f32_e32 v23, v230, v23
	v_mul_f32_e32 v16, v230, v16
	v_mul_f32_e32 v17, v230, v17
	v_mul_f32_e32 v18, v230, v18
	v_mfma_f32_16x16x32_bf16 v[96:99], v[184:187], v[200:203], 0
	v_mul_f32_e32 v19, v230, v19
	v_cvt_pk_bf16_f32 v20, v20, v21
	v_cvt_pk_bf16_f32 v21, v22, v23
	v_cvt_pk_bf16_f32 v22, v16, v17
	v_mfma_f32_16x16x32_bf16 v[84:87], v[176:179], v[208:211], 0
	v_cvt_pk_bf16_f32 v23, v18, v19
	global_store_dwordx4 v[232:233], v[20:23], off offset:256
	v_lshl_add_u64 v[232:233], v[232:233], 0, s[98:99]
	v_mul_f32_e32 v12, v231, v12
	v_mfma_f32_16x16x32_bf16 v[80:83], v[184:187], v[208:211], 0
	v_mul_f32_e32 v13, v231, v13
; #define PG8_STAGE(bufoff, gbase, voff) do { _Pragma("unroll") for (int _i = 0; _i < 2; ++_i) \
;         __builtin_amdgcn_global_load_lds((const unsigned*)((const char*)(gbase) + (voff)[_i]), (LAS unsigned*)(lds + (bufoff) + ldsw + _i * 8192), 16, 0, 0); } while (0)
; #define PG8_LDA(dst, b, h) do { _Pragma("unroll") for (int m = 0; m < 4; ++m) _Pragma("unroll") for (int k = 0; k < 2; ++k) dst[m][k] = *(const LAS bf16x8*)(lds + PG8_SA(b, h) + aoff + m * 2048 + k * 1024); } while (0)
; #define PG8_LDB(dst, b, h) do { _Pragma("unroll") for (int n = 0; n < 2; ++n) _Pragma("unroll") for (int k = 0; k < 2; ++k) dst[n][k] = *(const LAS bf16x8*)(lds + PG8_SB(b, h) + boff + n * 2048 + k * 1024); } while (0)
; #define PG8_MMA(ai, bj, At, Bt) do { __builtin_amdgcn_s_setprio(1); _Pragma("unroll") for (int k = 0; k < 2; ++k) _Pragma("unroll") for (int m = 0; m < 4; ++m) _Pragma("unroll") for (int n = 0; n < 2; ++n) \
;         acc[ai][bj][m][n] = __builtin_amdgcn_mfma_f32_16x16x32_bf16(Bt[n][k], At[m][k], acc[ai][bj][m][n], 0, 0, 0); __builtin_amdgcn_s_setprio(0); } while (0)
; #define PG8_WAIT_V(n) asm volatile("s_waitcnt vmcnt(" #n ")" ::: "memory")
; #define PG8_WAIT_L(n) asm volatile("s_waitcnt lgkmcnt(" #n ")" ::: "memory")
; #define PG8_BAR __builtin_amdgcn_s_barrier()
; #define PG8_SCHED __builtin_amdgcn_sched_barrier(0)
; template <class Epi, bool ALIGN_EPI>
; __device__ __forceinline__ void gemm_phase(LAS unsigned char* lds, const Gemm g, const StaticOrder& S, const Epi& E, const int tid) {
;     ...
;             PG8_WAIT_V(8); PG8_WAIT_L(0); PG8_BAR; PG8_MMA(0, 0, At, B0); PG8_MMA(0, 1, At, B1); PG8_BAR; PG8_SCHED;
;             PG8_LDA(At, 0, 1); PG8_STAGE(PG8_SB(0, 0), b2, voffB); PG8_STAGE(PG8_SB(0, 1), b2 + hB, voffB); PG8_STAGE(PG8_SA(0, 0), a2, voffA);
;             PG8_WAIT_V(8); PG8_WAIT_L(0); PG8_BAR; PG8_MMA(1, 0, At, B0); PG8_MMA(1, 1, At, B1); PG8_BAR; PG8_SCHED;
;             PG8_LDB(B0, 1, 0); PG8_LDB(B1, 1, 1); PG8_SCHED; PG8_LDA(At, 1, 0); PG8_STAGE(PG8_SA(0, 1), a2 + hA, voffA);
	v_mul_f32_e32 v14, v231, v14
	v_mul_f32_e32 v15, v231, v15
	v_mul_f32_e32 v8, v231, v8
	v_mfma_f32_16x16x32_bf16 v[68:71], v[176:179], v[216:219], 0
	v_mul_f32_e32 v9, v231, v9
	v_mul_f32_e32 v10, v231, v10
	v_mul_f32_e32 v11, v231, v11
	v_cvt_pk_bf16_f32 v12, v12, v13
	v_mfma_f32_16x16x32_bf16 v[64:67], v[184:187], v[216:219], 0
	v_cvt_pk_bf16_f32 v13, v14, v15
	v_cvt_pk_bf16_f32 v14, v8, v9
	v_cvt_pk_bf16_f32 v15, v10, v11
	global_store_dwordx4 v[232:233], v[12:15], off
	v_mfma_f32_16x16x32_bf16 v[116:119], v[180:183], v[196:199], v[116:119]
	v_mul_f32_e32 v4, v231, v4
	v_mul_f32_e32 v5, v231, v5
	v_mul_f32_e32 v6, v231, v6
	v_mul_f32_e32 v7, v231, v7
	v_mfma_f32_16x16x32_bf16 v[112:115], v[188:191], v[196:199], v[112:115]
	v_mul_f32_e32 v0, v231, v0
	v_mul_f32_e32 v1, v231, v1
	v_mul_f32_e32 v2, v231, v2
	v_mul_f32_e32 v3, v231, v3
	v_mfma_f32_16x16x32_bf16 v[100:103], v[180:183], v[204:207], v[100:103]
	v_cvt_pk_bf16_f32 v4, v4, v5
	v_cvt_pk_bf16_f32 v5, v6, v7
	v_cvt_pk_bf16_f32 v6, v0, v1
	v_cvt_pk_bf16_f32 v7, v2, v3
	v_mfma_f32_16x16x32_bf16 v[96:99], v[188:191], v[204:207], v[96:99]
	global_store_dwordx4 v[232:233], v[4:7], off offset:256
	v_mfma_f32_16x16x32_bf16 v[84:87], v[180:183], v[212:215], v[84:87]
	v_mfma_f32_16x16x32_bf16 v[80:83], v[188:191], v[212:215], v[80:83]
	v_mfma_f32_16x16x32_bf16 v[68:71], v[180:183], v[240:243], v[68:71]
	v_mfma_f32_16x16x32_bf16 v[64:67], v[188:191], v[240:243], v[64:67]
	s_barrier
	s_add_i32 s62, s33, s45
	v_lshl_add_u64 v[244:245], v[220:221], 0, v[168:169]
	s_mov_b32 m0, s62
	ds_read_b128 v[192:195], v151 offset:16384
	ds_read_b128 v[196:199], v151 offset:17408
	ds_read_b128 v[200:203], v151 offset:18432
	ds_read_b128 v[204:207], v151 offset:19456
	ds_read_b128 v[208:211], v151 offset:20480
	ds_read_b128 v[212:215], v151 offset:21504
	ds_read_b128 v[216:219], v151 offset:22528
	ds_read_b128 v[240:243], v151 offset:23552
	global_load_lds_dwordx4 v[244:245], off
	v_lshl_add_u64 v[246:247], v[220:221], 0, v[128:129]
	s_add_i32 m0, s62, 0x2000
	v_lshl_add_u64 v[220:221], v[220:221], 0, s[12:13]
	s_add_i32 s10, s10, s45
	global_load_lds_dwordx4 v[246:247], off
	v_lshl_add_u64 v[248:249], v[220:221], 0, v[168:169]
	s_mov_b32 m0, s10
	v_lshl_add_u64 v[220:221], v[220:221], 0, v[128:129]
	global_load_lds_dwordx4 v[248:249], off
	s_add_i32 m0, s10, 0x2000
	v_lshl_add_u64 v[250:251], v[146:147], 0, v[132:133]
	global_load_lds_dwordx4 v[220:221], off
	s_mov_b32 m0, s25
	v_lshl_add_u64 v[252:253], v[146:147], 0, v[130:131]
	global_load_lds_dwordx4 v[250:251], off
	s_mov_b32 m0, s50
	s_nop 0
	global_load_lds_dwordx4 v[252:253], off
	s_waitcnt vmcnt(24)
	s_waitcnt lgkmcnt(0)
	s_barrier
	s_waitcnt lgkmcnt(0)
	v_mfma_f32_16x16x32_bf16 v[60:63], v[152:155], v[192:195], 0
	v_mfma_f32_16x16x32_bf16 v[56:59], v[160:163], v[192:195], 0
	v_mfma_f32_16x16x32_bf16 v[44:47], v[152:155], v[200:203], 0
	v_mfma_f32_16x16x32_bf16 v[40:43], v[160:163], v[200:203], 0
	v_mfma_f32_16x16x32_bf16 v[28:31], v[152:155], v[208:211], 0
	v_mfma_f32_16x16x32_bf16 v[24:27], v[160:163], v[208:211], 0
	v_mfma_f32_16x16x32_bf16 v[12:15], v[152:155], v[216:219], 0
	v_mfma_f32_16x16x32_bf16 v[8:11], v[160:163], v[216:219], 0
	v_mfma_f32_16x16x32_bf16 v[60:63], v[156:159], v[196:199], v[60:63]
	v_mfma_f32_16x16x32_bf16 v[56:59], v[164:167], v[196:199], v[56:59]
	v_mfma_f32_16x16x32_bf16 v[44:47], v[156:159], v[204:207], v[44:47]
	v_mfma_f32_16x16x32_bf16 v[40:43], v[164:167], v[204:207], v[40:43]
	v_mfma_f32_16x16x32_bf16 v[28:31], v[156:159], v[212:215], v[28:31]
	v_mfma_f32_16x16x32_bf16 v[24:27], v[164:167], v[212:215], v[24:27]
	v_mfma_f32_16x16x32_bf16 v[12:15], v[156:159], v[240:243], v[12:15]
	v_mfma_f32_16x16x32_bf16 v[8:11], v[164:167], v[240:243], v[8:11]
	v_mfma_f32_16x16x32_bf16 v[52:55], v[176:179], v[192:195], 0
	v_mfma_f32_16x16x32_bf16 v[48:51], v[184:187], v[192:195], 0
	v_mfma_f32_16x16x32_bf16 v[36:39], v[176:179], v[200:203], 0
	v_mfma_f32_16x16x32_bf16 v[32:35], v[184:187], v[200:203], 0
	v_mfma_f32_16x16x32_bf16 v[20:23], v[176:179], v[208:211], 0
	v_mfma_f32_16x16x32_bf16 v[16:19], v[184:187], v[208:211], 0
	v_mfma_f32_16x16x32_bf16 v[4:7], v[176:179], v[216:219], 0
	v_mfma_f32_16x16x32_bf16 v[0:3], v[184:187], v[216:219], 0
	v_mfma_f32_16x16x32_bf16 v[52:55], v[180:183], v[196:199], v[52:55]
	v_mfma_f32_16x16x32_bf16 v[48:51], v[188:191], v[196:199], v[48:51]
	v_mfma_f32_16x16x32_bf16 v[36:39], v[180:183], v[204:207], v[36:39]
	v_mfma_f32_16x16x32_bf16 v[32:35], v[188:191], v[204:207], v[32:35]
	v_mfma_f32_16x16x32_bf16 v[20:23], v[180:183], v[212:215], v[20:23]
	v_mfma_f32_16x16x32_bf16 v[16:19], v[188:191], v[212:215], v[16:19]
	v_mfma_f32_16x16x32_bf16 v[4:7], v[180:183], v[240:243], v[4:7]
	v_mfma_f32_16x16x32_bf16 v[0:3], v[188:191], v[240:243], v[0:3]
	s_barrier
	s_add_i32 s10, 0, 0x18000
	v_add_u32_e32 v148, s10, v149
	s_add_i32 s62, 0, 0x1c000
	ds_read_b128 v[152:155], v148
	ds_read_b128 v[156:159], v148 offset:1024
	ds_read_b128 v[160:163], v148 offset:2048
	ds_read_b128 v[164:167], v148 offset:3072
	v_add_u32_e32 v148, s62, v149
	ds_read_b128 v[176:179], v148
	ds_read_b128 v[180:183], v148 offset:1024
	ds_read_b128 v[184:187], v148 offset:2048
	ds_read_b128 v[188:191], v148 offset:3072
	v_lshl_add_u64 v[146:147], v[146:147], 0, s[94:95]
	s_mov_b32 m0, s51
	v_lshl_add_u64 v[226:227], v[146:147], 0, v[132:133]
	ds_read_b128 v[192:195], v151 offset:32768
	ds_read_b128 v[196:199], v151 offset:33792
	ds_read_b128 v[200:203], v151 offset:34816
	ds_read_b128 v[204:207], v151 offset:35840
	ds_read_b128 v[208:211], v151 offset:36864
	ds_read_b128 v[212:215], v151 offset:37888
	ds_read_b128 v[216:219], v151 offset:38912
	ds_read_b128 v[240:243], v151 offset:39936
	global_load_lds_dwordx4 v[226:227], off
	v_lshl_add_u64 v[146:147], v[146:147], 0, v[130:131]
	s_mov_b32 m0, s52
	s_nop 0
	global_load_lds_dwordx4 v[146:147], off
	s_waitcnt vmcnt(16)
	s_waitcnt lgkmcnt(0)
	s_barrier
; #define PG8_STAGE(bufoff, gbase, voff) do { _Pragma("unroll") for (int _i = 0; _i < 2; ++_i) \
;         __builtin_amdgcn_global_load_lds((const unsigned*)((const char*)(gbase) + (voff)[_i]), (LAS unsigned*)(lds + (bufoff) + ldsw + _i * 8192), 16, 0, 0); } while (0)
; #define PG8_LDA(dst, b, h) do { _Pragma("unroll") for (int m = 0; m < 4; ++m) _Pragma("unroll") for (int k = 0; k < 2; ++k) dst[m][k] = *(const LAS bf16x8*)(lds + PG8_SA(b, h) + aoff + m * 2048 + k * 1024); } while (0)
; #define PG8_MMA(ai, bj, At, Bt) do { __builtin_amdgcn_s_setprio(1); _Pragma("unroll") for (int k = 0; k < 2; ++k) _Pragma("unroll") for (int m = 0; m < 4; ++m) _Pragma("unroll") for (int n = 0; n < 2; ++n) \
;         acc[ai][bj][m][n] = __builtin_amdgcn_mfma_f32_16x16x32_bf16(Bt[n][k], At[m][k], acc[ai][bj][m][n], 0, 0, 0); __builtin_amdgcn_s_setprio(0); } while (0)
; #define PG8_WAIT_V(n) asm volatile("s_waitcnt vmcnt(" #n ")" ::: "memory")
; #define PG8_WAIT_L(n) asm volatile("s_waitcnt lgkmcnt(" #n ")" ::: "memory")
; #define PG8_BAR __builtin_amdgcn_s_barrier()
; #define PG8_SCHED __builtin_amdgcn_sched_barrier(0)
; template <class Epi, bool ALIGN_EPI>
; __device__ __forceinline__ void gemm_phase(LAS unsigned char* lds, const Gemm g, const StaticOrder& S, const Epi& E, const int tid) {
;     ...
;             PG8_WAIT_V(8); PG8_WAIT_L(0); PG8_BAR; PG8_MMA(0, 0, At, B0); PG8_MMA(0, 1, At, B1); PG8_BAR; PG8_SCHED;
;             PG8_LDA(At, 1, 1); PG8_STAGE(PG8_SB(1, 0), b3, voffB); PG8_STAGE(PG8_SB(1, 1), b3 + hB, voffB); PG8_STAGE(PG8_SA(1, 0), a3, voffA);
;             PG8_WAIT_V(8); PG8_WAIT_L(0); PG8_BAR; PG8_MMA(1, 0, At, B0); PG8_MMA(1, 1, At, B1); PG8_BAR; PG8_SCHED;
	s_waitcnt lgkmcnt(0)
	v_mfma_f32_16x16x32_bf16 v[124:127], v[152:155], v[192:195], v[124:127]
	v_mfma_f32_16x16x32_bf16 v[120:123], v[160:163], v[192:195], v[120:123]
	v_mfma_f32_16x16x32_bf16 v[108:111], v[152:155], v[200:203], v[108:111]
	v_mfma_f32_16x16x32_bf16 v[104:107], v[160:163], v[200:203], v[104:107]
	v_mfma_f32_16x16x32_bf16 v[92:95], v[152:155], v[208:211], v[92:95]
	v_mfma_f32_16x16x32_bf16 v[88:91], v[160:163], v[208:211], v[88:91]
	v_mfma_f32_16x16x32_bf16 v[76:79], v[152:155], v[216:219], v[76:79]
	v_mfma_f32_16x16x32_bf16 v[72:75], v[160:163], v[216:219], v[72:75]
	v_mfma_f32_16x16x32_bf16 v[124:127], v[156:159], v[196:199], v[124:127]
	v_mfma_f32_16x16x32_bf16 v[120:123], v[164:167], v[196:199], v[120:123]
	v_mfma_f32_16x16x32_bf16 v[108:111], v[156:159], v[204:207], v[108:111]
	v_mfma_f32_16x16x32_bf16 v[104:107], v[164:167], v[204:207], v[104:107]
	v_mfma_f32_16x16x32_bf16 v[92:95], v[156:159], v[212:215], v[92:95]
	v_mfma_f32_16x16x32_bf16 v[88:91], v[164:167], v[212:215], v[88:91]
	v_mfma_f32_16x16x32_bf16 v[76:79], v[156:159], v[240:243], v[76:79]
	v_mfma_f32_16x16x32_bf16 v[72:75], v[164:167], v[240:243], v[72:75]
	v_mfma_f32_16x16x32_bf16 v[116:119], v[176:179], v[192:195], v[116:119]
	v_mfma_f32_16x16x32_bf16 v[112:115], v[184:187], v[192:195], v[112:115]
	v_mfma_f32_16x16x32_bf16 v[100:103], v[176:179], v[200:203], v[100:103]
	v_mfma_f32_16x16x32_bf16 v[96:99], v[184:187], v[200:203], v[96:99]
	v_mfma_f32_16x16x32_bf16 v[84:87], v[176:179], v[208:211], v[84:87]
	v_mfma_f32_16x16x32_bf16 v[80:83], v[184:187], v[208:211], v[80:83]
	v_mfma_f32_16x16x32_bf16 v[68:71], v[176:179], v[216:219], v[68:71]
	v_mfma_f32_16x16x32_bf16 v[64:67], v[184:187], v[216:219], v[64:67]
	v_mfma_f32_16x16x32_bf16 v[116:119], v[180:183], v[196:199], v[116:119]
	v_mfma_f32_16x16x32_bf16 v[112:115], v[188:191], v[196:199], v[112:115]
	v_mfma_f32_16x16x32_bf16 v[100:103], v[180:183], v[204:207], v[100:103]
	v_mfma_f32_16x16x32_bf16 v[96:99], v[188:191], v[204:207], v[96:99]
	v_mfma_f32_16x16x32_bf16 v[84:87], v[180:183], v[212:215], v[84:87]
	v_mfma_f32_16x16x32_bf16 v[80:83], v[188:191], v[212:215], v[80:83]
	v_mfma_f32_16x16x32_bf16 v[68:71], v[180:183], v[240:243], v[68:71]
	v_mfma_f32_16x16x32_bf16 v[64:67], v[188:191], v[240:243], v[64:67]
	s_barrier
	s_add_i32 s10, s10, s45
	v_lshl_add_u64 v[146:147], v[244:245], 0, s[92:93]
	s_mov_b32 m0, s10
	ds_read_b128 v[192:195], v151 offset:49152
	ds_read_b128 v[196:199], v151 offset:50176
	ds_read_b128 v[200:203], v151 offset:51200
	ds_read_b128 v[204:207], v151 offset:52224
	ds_read_b128 v[208:211], v151 offset:53248
	ds_read_b128 v[212:215], v151 offset:54272
	ds_read_b128 v[216:219], v151 offset:55296
	ds_read_b128 v[240:243], v151 offset:56320
	global_load_lds_dwordx4 v[146:147], off
	v_lshl_add_u64 v[146:147], v[246:247], 0, s[92:93]
	s_add_i32 m0, s10, 0x2000
	s_add_i32 s10, s62, s45
	global_load_lds_dwordx4 v[146:147], off
	v_lshl_add_u64 v[146:147], v[248:249], 0, s[92:93]
	s_mov_b32 m0, s10
	s_nop 0
	global_load_lds_dwordx4 v[146:147], off
	v_lshl_add_u64 v[146:147], v[220:221], 0, s[92:93]
	s_add_i32 m0, s10, 0x2000
	s_nop 0
	global_load_lds_dwordx4 v[146:147], off
	v_lshl_add_u64 v[146:147], v[250:251], 0, s[92:93]
	s_mov_b32 m0, s53
	s_nop 0
	global_load_lds_dwordx4 v[146:147], off
	v_lshl_add_u64 v[146:147], v[252:253], 0, s[92:93]
	s_mov_b32 m0, s54
	s_nop 0
	global_load_lds_dwordx4 v[146:147], off
	s_waitcnt vmcnt(8)
	s_waitcnt lgkmcnt(0)
	s_barrier
	s_waitcnt lgkmcnt(0)
	v_mfma_f32_16x16x32_bf16 v[60:63], v[152:155], v[192:195], v[60:63]
	v_mfma_f32_16x16x32_bf16 v[56:59], v[160:163], v[192:195], v[56:59]
	v_mfma_f32_16x16x32_bf16 v[44:47], v[152:155], v[200:203], v[44:47]
	v_mfma_f32_16x16x32_bf16 v[40:43], v[160:163], v[200:203], v[40:43]
	v_mfma_f32_16x16x32_bf16 v[28:31], v[152:155], v[208:211], v[28:31]
	v_mfma_f32_16x16x32_bf16 v[24:27], v[160:163], v[208:211], v[24:27]
	v_mfma_f32_16x16x32_bf16 v[12:15], v[152:155], v[216:219], v[12:15]
	v_mfma_f32_16x16x32_bf16 v[8:11], v[160:163], v[216:219], v[8:11]
	v_mfma_f32_16x16x32_bf16 v[60:63], v[156:159], v[196:199], v[60:63]
	v_mfma_f32_16x16x32_bf16 v[56:59], v[164:167], v[196:199], v[56:59]
	v_mfma_f32_16x16x32_bf16 v[44:47], v[156:159], v[204:207], v[44:47]
	v_mfma_f32_16x16x32_bf16 v[40:43], v[164:167], v[204:207], v[40:43]
	v_mfma_f32_16x16x32_bf16 v[28:31], v[156:159], v[212:215], v[28:31]
	v_mfma_f32_16x16x32_bf16 v[24:27], v[164:167], v[212:215], v[24:27]
	v_mfma_f32_16x16x32_bf16 v[12:15], v[156:159], v[240:243], v[12:15]
	v_mfma_f32_16x16x32_bf16 v[8:11], v[164:167], v[240:243], v[8:11]
	v_mfma_f32_16x16x32_bf16 v[52:55], v[176:179], v[192:195], v[52:55]
	v_mfma_f32_16x16x32_bf16 v[48:51], v[184:187], v[192:195], v[48:51]
	v_mfma_f32_16x16x32_bf16 v[36:39], v[176:179], v[200:203], v[36:39]
	v_mfma_f32_16x16x32_bf16 v[32:35], v[184:187], v[200:203], v[32:35]
	v_mfma_f32_16x16x32_bf16 v[20:23], v[176:179], v[208:211], v[20:23]
	v_mfma_f32_16x16x32_bf16 v[16:19], v[184:187], v[208:211], v[16:19]
	v_mfma_f32_16x16x32_bf16 v[4:7], v[176:179], v[216:219], v[4:7]
	v_mfma_f32_16x16x32_bf16 v[0:3], v[184:187], v[216:219], v[0:3]
	v_mfma_f32_16x16x32_bf16 v[52:55], v[180:183], v[196:199], v[52:55]
	v_mfma_f32_16x16x32_bf16 v[48:51], v[188:191], v[196:199], v[48:51]
	v_mfma_f32_16x16x32_bf16 v[36:39], v[180:183], v[204:207], v[36:39]
	v_mfma_f32_16x16x32_bf16 v[32:35], v[188:191], v[204:207], v[32:35]
	v_mfma_f32_16x16x32_bf16 v[20:23], v[180:183], v[212:215], v[20:23]
	v_mfma_f32_16x16x32_bf16 v[16:19], v[188:191], v[212:215], v[16:19]
	v_mfma_f32_16x16x32_bf16 v[4:7], v[180:183], v[240:243], v[4:7]
	v_mfma_f32_16x16x32_bf16 v[0:3], v[188:191], v[240:243], v[0:3]
	s_barrier
	v_lshl_add_u64 v[142:143], v[142:143], 0, s[80:81]
	v_lshl_add_u64 v[144:145], v[144:145], 0, s[80:81]
	s_mov_b32 s10, s11
	s_cmp_eq_u32 s10, s55
	s_cbranch_scc1 .Lq5_last
	s_branch .LBB0_354
; #define PG8_STAGE(bufoff, gbase, voff) do { _Pragma("unroll") for (int _i = 0; _i < 2; ++_i) \
;         __builtin_amdgcn_global_load_lds((const unsigned*)((const char*)(gbase) + (voff)[_i]), (LAS unsigned*)(lds + (bufoff) + ldsw + _i * 8192), 16, 0, 0); } while (0)
; #define PG8_LDA(dst, b, h) do { _Pragma("unroll") for (int m = 0; m < 4; ++m) _Pragma("unroll") for (int k = 0; k < 2; ++k) dst[m][k] = *(const LAS bf16x8*)(lds + PG8_SA(b, h) + aoff + m * 2048 + k * 1024); } while (0)
; #define PG8_LDB(dst, b, h) do { _Pragma("unroll") for (int n = 0; n < 2; ++n) _Pragma("unroll") for (int k = 0; k < 2; ++k) dst[n][k] = *(const LAS bf16x8*)(lds + PG8_SB(b, h) + boff + n * 2048 + k * 1024); } while (0)
; #define PG8_MMA(ai, bj, At, Bt) do { __builtin_amdgcn_s_setprio(1); _Pragma("unroll") for (int k = 0; k < 2; ++k) _Pragma("unroll") for (int m = 0; m < 4; ++m) _Pragma("unroll") for (int n = 0; n < 2; ++n) \
;         acc[ai][bj][m][n] = __builtin_amdgcn_mfma_f32_16x16x32_bf16(Bt[n][k], At[m][k], acc[ai][bj][m][n], 0, 0, 0); __builtin_amdgcn_s_setprio(0); } while (0)
; #define PG8_WAIT_V(n) asm volatile("s_waitcnt vmcnt(" #n ")" ::: "memory")
; #define PG8_WAIT_L(n) asm volatile("s_waitcnt lgkmcnt(" #n ")" ::: "memory")
; #define PG8_BAR __builtin_amdgcn_s_barrier()
; #define PG8_SCHED __builtin_amdgcn_sched_barrier(0)
; template <class Epi, bool ALIGN_EPI>
; __device__ __forceinline__ void gemm_phase(LAS unsigned char* lds, const Gemm g, const StaticOrder& S, const Epi& E, const int tid) {
;     ...
;             PG8_LDB(B0, 0, 0); PG8_LDB(B1, 0, 1); PG8_SCHED; PG8_LDA(At, 0, 0); PG8_STAGE(PG8_SA(1, 1), a1 + hA, voffA);
;             PG8_WAIT_V(8); PG8_WAIT_L(0); PG8_BAR; PG8_MMA(0, 0, At, B0); PG8_MMA(0, 1, At, B1); PG8_BAR; PG8_SCHED;
;             PG8_LDA(At, 0, 1); PG8_STAGE(PG8_SB(0, 0), b2, voffB); PG8_STAGE(PG8_SB(0, 1), b2 + hB, voffB); PG8_STAGE(PG8_SA(0, 0), a2, voffA);
.Lq5_first:
	s_add_i32 s11, s10, 2
	s_cmp_eq_u32 s55, s10
	s_cselect_b64 vcc, -1, 0
	v_add_u32_e32 v148, s33, v149
	s_add_i32 s10, 0, 0x14000
	ds_read_b128 v[152:155], v148
	ds_read_b128 v[156:159], v148 offset:1024
	ds_read_b128 v[160:163], v148 offset:2048
	ds_read_b128 v[164:167], v148 offset:3072
	v_add_u32_e32 v148, s10, v149
	ds_read_b128 v[176:179], v148
	ds_read_b128 v[180:183], v148 offset:1024
	ds_read_b128 v[184:187], v148 offset:2048
	ds_read_b128 v[188:191], v148 offset:3072
	v_lshl_add_u64 v[146:147], v[142:143], 0, s[92:93]
	v_cndmask_b32_e32 v147, v147, v139, vcc
	v_cndmask_b32_e32 v146, v146, v138, vcc
	v_cndmask_b32_e32 v221, v145, v141, vcc
	v_cndmask_b32_e32 v220, v144, v140, vcc
	v_lshl_add_u64 v[244:245], v[142:143], 0, v[134:135]
	s_add_i32 m0, s25, 0xc000
	ds_read_b128 v[192:195], v151
	ds_read_b128 v[196:199], v151 offset:1024
	ds_read_b128 v[200:203], v151 offset:2048
	ds_read_b128 v[204:207], v151 offset:3072
	ds_read_b128 v[208:211], v151 offset:4096
	ds_read_b128 v[212:215], v151 offset:5120
	ds_read_b128 v[216:219], v151 offset:6144
	ds_read_b128 v[240:243], v151 offset:7168
	global_load_lds_dwordx4 v[244:245], off
	v_lshl_add_u64 v[244:245], v[142:143], 0, v[136:137]
	s_add_i32 m0, s25, 0xe000
	s_nop 0
	global_load_lds_dwordx4 v[244:245], off
	s_waitcnt vmcnt(8)
	s_waitcnt lgkmcnt(0)
	s_barrier
	s_waitcnt lgkmcnt(0)
	v_mfma_f32_16x16x32_bf16 v[124:127], v[152:155], v[192:195], 0
	v_mfma_f32_16x16x32_bf16 v[120:123], v[160:163], v[192:195], 0
	v_mfma_f32_16x16x32_bf16 v[108:111], v[152:155], v[200:203], 0
	v_mfma_f32_16x16x32_bf16 v[104:107], v[160:163], v[200:203], 0
	v_mfma_f32_16x16x32_bf16 v[92:95], v[152:155], v[208:211], 0
	v_mfma_f32_16x16x32_bf16 v[88:91], v[160:163], v[208:211], 0
	v_mfma_f32_16x16x32_bf16 v[76:79], v[152:155], v[216:219], 0
	v_mfma_f32_16x16x32_bf16 v[72:75], v[160:163], v[216:219], 0
	v_mfma_f32_16x16x32_bf16 v[124:127], v[156:159], v[196:199], v[124:127]
	v_mfma_f32_16x16x32_bf16 v[120:123], v[164:167], v[196:199], v[120:123]
	v_mfma_f32_16x16x32_bf16 v[108:111], v[156:159], v[204:207], v[108:111]
	v_mfma_f32_16x16x32_bf16 v[104:107], v[164:167], v[204:207], v[104:107]
	v_mfma_f32_16x16x32_bf16 v[92:95], v[156:159], v[212:215], v[92:95]
	v_mfma_f32_16x16x32_bf16 v[88:91], v[164:167], v[212:215], v[88:91]
	v_mfma_f32_16x16x32_bf16 v[76:79], v[156:159], v[240:243], v[76:79]
	v_mfma_f32_16x16x32_bf16 v[72:75], v[164:167], v[240:243], v[72:75]
	v_mfma_f32_16x16x32_bf16 v[116:119], v[176:179], v[192:195], 0
	v_mfma_f32_16x16x32_bf16 v[112:115], v[184:187], v[192:195], 0
	v_mfma_f32_16x16x32_bf16 v[100:103], v[176:179], v[200:203], 0
	v_mfma_f32_16x16x32_bf16 v[96:99], v[184:187], v[200:203], 0
	v_mfma_f32_16x16x32_bf16 v[84:87], v[176:179], v[208:211], 0
	v_mfma_f32_16x16x32_bf16 v[80:83], v[184:187], v[208:211], 0
	v_mfma_f32_16x16x32_bf16 v[68:71], v[176:179], v[216:219], 0
	v_mfma_f32_16x16x32_bf16 v[64:67], v[184:187], v[216:219], 0
	v_mfma_f32_16x16x32_bf16 v[116:119], v[180:183], v[196:199], v[116:119]
	v_mfma_f32_16x16x32_bf16 v[112:115], v[188:191], v[196:199], v[112:115]
	v_mfma_f32_16x16x32_bf16 v[100:103], v[180:183], v[204:207], v[100:103]
	v_mfma_f32_16x16x32_bf16 v[96:99], v[188:191], v[204:207], v[96:99]
	v_mfma_f32_16x16x32_bf16 v[84:87], v[180:183], v[212:215], v[84:87]
	v_mfma_f32_16x16x32_bf16 v[80:83], v[188:191], v[212:215], v[80:83]
	v_mfma_f32_16x16x32_bf16 v[68:71], v[180:183], v[240:243], v[68:71]
	v_mfma_f32_16x16x32_bf16 v[64:67], v[188:191], v[240:243], v[64:67]
	s_barrier
	s_add_i32 s62, s33, s45
	v_lshl_add_u64 v[244:245], v[220:221], 0, v[168:169]
	s_mov_b32 m0, s62
	ds_read_b128 v[192:195], v151 offset:16384
	ds_read_b128 v[196:199], v151 offset:17408
	ds_read_b128 v[200:203], v151 offset:18432
	ds_read_b128 v[204:207], v151 offset:19456
	ds_read_b128 v[208:211], v151 offset:20480
	ds_read_b128 v[212:215], v151 offset:21504
	ds_read_b128 v[216:219], v151 offset:22528
	ds_read_b128 v[240:243], v151 offset:23552
	global_load_lds_dwordx4 v[244:245], off
	v_lshl_add_u64 v[246:247], v[220:221], 0, v[128:129]
	s_add_i32 m0, s62, 0x2000
	v_lshl_add_u64 v[220:221], v[220:221], 0, s[12:13]
	s_add_i32 s10, s10, s45
	global_load_lds_dwordx4 v[246:247], off
	v_lshl_add_u64 v[248:249], v[220:221], 0, v[168:169]
	s_mov_b32 m0, s10
	v_lshl_add_u64 v[220:221], v[220:221], 0, v[128:129]
	global_load_lds_dwordx4 v[248:249], off
	s_add_i32 m0, s10, 0x2000
	v_lshl_add_u64 v[250:251], v[146:147], 0, v[132:133]
	global_load_lds_dwordx4 v[220:221], off
	s_mov_b32 m0, s25
	v_lshl_add_u64 v[252:253], v[146:147], 0, v[130:131]
	global_load_lds_dwordx4 v[250:251], off
	s_mov_b32 m0, s50
	s_nop 0
	global_load_lds_dwordx4 v[252:253], off
	s_waitcnt vmcnt(8)
	s_waitcnt lgkmcnt(0)
	s_barrier
; #define PG8_STAGE(bufoff, gbase, voff) do { _Pragma("unroll") for (int _i = 0; _i < 2; ++_i) \
;         __builtin_amdgcn_global_load_lds((const unsigned*)((const char*)(gbase) + (voff)[_i]), (LAS unsigned*)(lds + (bufoff) + ldsw + _i * 8192), 16, 0, 0); } while (0)
; #define PG8_LDA(dst, b, h) do { _Pragma("unroll") for (int m = 0; m < 4; ++m) _Pragma("unroll") for (int k = 0; k < 2; ++k) dst[m][k] = *(const LAS bf16x8*)(lds + PG8_SA(b, h) + aoff + m * 2048 + k * 1024); } while (0)
; #define PG8_LDB(dst, b, h) do { _Pragma("unroll") for (int n = 0; n < 2; ++n) _Pragma("unroll") for (int k = 0; k < 2; ++k) dst[n][k] = *(const LAS bf16x8*)(lds + PG8_SB(b, h) + boff + n * 2048 + k * 1024); } while (0)
; #define PG8_MMA(ai, bj, At, Bt) do { __builtin_amdgcn_s_setprio(1); _Pragma("unroll") for (int k = 0; k < 2; ++k) _Pragma("unroll") for (int m = 0; m < 4; ++m) _Pragma("unroll") for (int n = 0; n < 2; ++n) \
;         acc[ai][bj][m][n] = __builtin_amdgcn_mfma_f32_16x16x32_bf16(Bt[n][k], At[m][k], acc[ai][bj][m][n], 0, 0, 0); __builtin_amdgcn_s_setprio(0); } while (0)
; #define PG8_WAIT_V(n) asm volatile("s_waitcnt vmcnt(" #n ")" ::: "memory")
; #define PG8_WAIT_L(n) asm volatile("s_waitcnt lgkmcnt(" #n ")" ::: "memory")
; #define PG8_BAR __builtin_amdgcn_s_barrier()
; #define PG8_SCHED __builtin_amdgcn_sched_barrier(0)
; template <class Epi, bool ALIGN_EPI>
; __device__ __forceinline__ void gemm_phase(LAS unsigned char* lds, const Gemm g, const StaticOrder& S, const Epi& E, const int tid) {
;     ...
;             PG8_WAIT_V(8); PG8_WAIT_L(0); PG8_BAR; PG8_MMA(1, 0, At, B0); PG8_MMA(1, 1, At, B1); PG8_BAR; PG8_SCHED;
;             PG8_LDB(B0, 1, 0); PG8_LDB(B1, 1, 1); PG8_SCHED; PG8_LDA(At, 1, 0); PG8_STAGE(PG8_SA(0, 1), a2 + hA, voffA);
;             PG8_WAIT_V(8); PG8_WAIT_L(0); PG8_BAR; PG8_MMA(0, 0, At, B0); PG8_MMA(0, 1, At, B1); PG8_BAR; PG8_SCHED;
	s_waitcnt lgkmcnt(0)
	v_mfma_f32_16x16x32_bf16 v[60:63], v[152:155], v[192:195], 0
	v_mfma_f32_16x16x32_bf16 v[56:59], v[160:163], v[192:195], 0
	v_mfma_f32_16x16x32_bf16 v[44:47], v[152:155], v[200:203], 0
	v_mfma_f32_16x16x32_bf16 v[40:43], v[160:163], v[200:203], 0
	v_mfma_f32_16x16x32_bf16 v[28:31], v[152:155], v[208:211], 0
	v_mfma_f32_16x16x32_bf16 v[24:27], v[160:163], v[208:211], 0
	v_mfma_f32_16x16x32_bf16 v[12:15], v[152:155], v[216:219], 0
	v_mfma_f32_16x16x32_bf16 v[8:11], v[160:163], v[216:219], 0
	v_mfma_f32_16x16x32_bf16 v[60:63], v[156:159], v[196:199], v[60:63]
	v_mfma_f32_16x16x32_bf16 v[56:59], v[164:167], v[196:199], v[56:59]
	v_mfma_f32_16x16x32_bf16 v[44:47], v[156:159], v[204:207], v[44:47]
	v_mfma_f32_16x16x32_bf16 v[40:43], v[164:167], v[204:207], v[40:43]
	v_mfma_f32_16x16x32_bf16 v[28:31], v[156:159], v[212:215], v[28:31]
	v_mfma_f32_16x16x32_bf16 v[24:27], v[164:167], v[212:215], v[24:27]
	v_mfma_f32_16x16x32_bf16 v[12:15], v[156:159], v[240:243], v[12:15]
	v_mfma_f32_16x16x32_bf16 v[8:11], v[164:167], v[240:243], v[8:11]
	v_mfma_f32_16x16x32_bf16 v[52:55], v[176:179], v[192:195], 0
	v_mfma_f32_16x16x32_bf16 v[48:51], v[184:187], v[192:195], 0
	v_mfma_f32_16x16x32_bf16 v[36:39], v[176:179], v[200:203], 0
	v_mfma_f32_16x16x32_bf16 v[32:35], v[184:187], v[200:203], 0
	v_mfma_f32_16x16x32_bf16 v[20:23], v[176:179], v[208:211], 0
	v_mfma_f32_16x16x32_bf16 v[16:19], v[184:187], v[208:211], 0
	v_mfma_f32_16x16x32_bf16 v[4:7], v[176:179], v[216:219], 0
	v_mfma_f32_16x16x32_bf16 v[0:3], v[184:187], v[216:219], 0
	v_mfma_f32_16x16x32_bf16 v[52:55], v[180:183], v[196:199], v[52:55]
	v_mfma_f32_16x16x32_bf16 v[48:51], v[188:191], v[196:199], v[48:51]
	v_mfma_f32_16x16x32_bf16 v[36:39], v[180:183], v[204:207], v[36:39]
	v_mfma_f32_16x16x32_bf16 v[32:35], v[188:191], v[204:207], v[32:35]
	v_mfma_f32_16x16x32_bf16 v[20:23], v[180:183], v[212:215], v[20:23]
	v_mfma_f32_16x16x32_bf16 v[16:19], v[188:191], v[212:215], v[16:19]
	v_mfma_f32_16x16x32_bf16 v[4:7], v[180:183], v[240:243], v[4:7]
	v_mfma_f32_16x16x32_bf16 v[0:3], v[188:191], v[240:243], v[0:3]
	s_barrier
	s_add_i32 s10, 0, 0x18000
	v_add_u32_e32 v148, s10, v149
	s_add_i32 s62, 0, 0x1c000
	ds_read_b128 v[152:155], v148
	ds_read_b128 v[156:159], v148 offset:1024
	ds_read_b128 v[160:163], v148 offset:2048
	ds_read_b128 v[164:167], v148 offset:3072
	v_add_u32_e32 v148, s62, v149
	ds_read_b128 v[176:179], v148
	ds_read_b128 v[180:183], v148 offset:1024
	ds_read_b128 v[184:187], v148 offset:2048
	ds_read_b128 v[188:191], v148 offset:3072
	v_lshl_add_u64 v[146:147], v[146:147], 0, s[94:95]
	s_mov_b32 m0, s51
	v_lshl_add_u64 v[226:227], v[146:147], 0, v[132:133]
	ds_read_b128 v[192:195], v151 offset:32768
	ds_read_b128 v[196:199], v151 offset:33792
	ds_read_b128 v[200:203], v151 offset:34816
	ds_read_b128 v[204:207], v151 offset:35840
	ds_read_b128 v[208:211], v151 offset:36864
	ds_read_b128 v[212:215], v151 offset:37888
	ds_read_b128 v[216:219], v151 offset:38912
	ds_read_b128 v[240:243], v151 offset:39936
	global_load_lds_dwordx4 v[226:227], off
	v_lshl_add_u64 v[146:147], v[146:147], 0, v[130:131]
	s_mov_b32 m0, s52
	s_nop 0
	global_load_lds_dwordx4 v[146:147], off
	s_waitcnt vmcnt(8)
	s_waitcnt lgkmcnt(0)
	s_barrier
	s_waitcnt lgkmcnt(0)
	v_mfma_f32_16x16x32_bf16 v[124:127], v[152:155], v[192:195], v[124:127]
	v_mfma_f32_16x16x32_bf16 v[120:123], v[160:163], v[192:195], v[120:123]
	v_mfma_f32_16x16x32_bf16 v[108:111], v[152:155], v[200:203], v[108:111]
	v_mfma_f32_16x16x32_bf16 v[104:107], v[160:163], v[200:203], v[104:107]
	v_mfma_f32_16x16x32_bf16 v[92:95], v[152:155], v[208:211], v[92:95]
	v_mfma_f32_16x16x32_bf16 v[88:91], v[160:163], v[208:211], v[88:91]
	v_mfma_f32_16x16x32_bf16 v[76:79], v[152:155], v[216:219], v[76:79]
	v_mfma_f32_16x16x32_bf16 v[72:75], v[160:163], v[216:219], v[72:75]
	v_mfma_f32_16x16x32_bf16 v[124:127], v[156:159], v[196:199], v[124:127]
	v_mfma_f32_16x16x32_bf16 v[120:123], v[164:167], v[196:199], v[120:123]
	v_mfma_f32_16x16x32_bf16 v[108:111], v[156:159], v[204:207], v[108:111]
	v_mfma_f32_16x16x32_bf16 v[104:107], v[164:167], v[204:207], v[104:107]
	v_mfma_f32_16x16x32_bf16 v[92:95], v[156:159], v[212:215], v[92:95]
	v_mfma_f32_16x16x32_bf16 v[88:91], v[164:167], v[212:215], v[88:91]
	v_mfma_f32_16x16x32_bf16 v[76:79], v[156:159], v[240:243], v[76:79]
	v_mfma_f32_16x16x32_bf16 v[72:75], v[164:167], v[240:243], v[72:75]
	v_mfma_f32_16x16x32_bf16 v[116:119], v[176:179], v[192:195], v[116:119]
	v_mfma_f32_16x16x32_bf16 v[112:115], v[184:187], v[192:195], v[112:115]
	v_mfma_f32_16x16x32_bf16 v[100:103], v[176:179], v[200:203], v[100:103]
	v_mfma_f32_16x16x32_bf16 v[96:99], v[184:187], v[200:203], v[96:99]
	v_mfma_f32_16x16x32_bf16 v[84:87], v[176:179], v[208:211], v[84:87]
	v_mfma_f32_16x16x32_bf16 v[80:83], v[184:187], v[208:211], v[80:83]
	v_mfma_f32_16x16x32_bf16 v[68:71], v[176:179], v[216:219], v[68:71]
	v_mfma_f32_16x16x32_bf16 v[64:67], v[184:187], v[216:219], v[64:67]
	v_mfma_f32_16x16x32_bf16 v[116:119], v[180:183], v[196:199], v[116:119]
	v_mfma_f32_16x16x32_bf16 v[112:115], v[188:191], v[196:199], v[112:115]
	v_mfma_f32_16x16x32_bf16 v[100:103], v[180:183], v[204:207], v[100:103]
	v_mfma_f32_16x16x32_bf16 v[96:99], v[188:191], v[204:207], v[96:99]
	v_mfma_f32_16x16x32_bf16 v[84:87], v[180:183], v[212:215], v[84:87]
	v_mfma_f32_16x16x32_bf16 v[80:83], v[188:191], v[212:215], v[80:83]
	v_mfma_f32_16x16x32_bf16 v[68:71], v[180:183], v[240:243], v[68:71]
	v_mfma_f32_16x16x32_bf16 v[64:67], v[188:191], v[240:243], v[64:67]
	s_barrier
; #define PG8_STAGE(bufoff, gbase, voff) do { _Pragma("unroll") for (int _i = 0; _i < 2; ++_i) \
;         __builtin_amdgcn_global_load_lds((const unsigned*)((const char*)(gbase) + (voff)[_i]), (LAS unsigned*)(lds + (bufoff) + ldsw + _i * 8192), 16, 0, 0); } while (0)
; #define PG8_LDA(dst, b, h) do { _Pragma("unroll") for (int m = 0; m < 4; ++m) _Pragma("unroll") for (int k = 0; k < 2; ++k) dst[m][k] = *(const LAS bf16x8*)(lds + PG8_SA(b, h) + aoff + m * 2048 + k * 1024); } while (0)
; #define PG8_LDB(dst, b, h) do { _Pragma("unroll") for (int n = 0; n < 2; ++n) _Pragma("unroll") for (int k = 0; k < 2; ++k) dst[n][k] = *(const LAS bf16x8*)(lds + PG8_SB(b, h) + boff + n * 2048 + k * 1024); } while (0)
; #define PG8_MMA(ai, bj, At, Bt) do { __builtin_amdgcn_s_setprio(1); _Pragma("unroll") for (int k = 0; k < 2; ++k) _Pragma("unroll") for (int m = 0; m < 4; ++m) _Pragma("unroll") for (int n = 0; n < 2; ++n) \
;         acc[ai][bj][m][n] = __builtin_amdgcn_mfma_f32_16x16x32_bf16(Bt[n][k], At[m][k], acc[ai][bj][m][n], 0, 0, 0); __builtin_amdgcn_s_setprio(0); } while (0)
; #define PG8_WAIT_V(n) asm volatile("s_waitcnt vmcnt(" #n ")" ::: "memory")
; #define PG8_WAIT_L(n) asm volatile("s_waitcnt lgkmcnt(" #n ")" ::: "memory")
; #define PG8_BAR __builtin_amdgcn_s_barrier()
; #define PG8_SCHED __builtin_amdgcn_sched_barrier(0)
; template <class Epi, bool ALIGN_EPI>
; __device__ __forceinline__ void gemm_phase(LAS unsigned char* lds, const Gemm g, const StaticOrder& S, const Epi& E, const int tid) {
;     ...
;             PG8_LDB(B0, 0, 0); PG8_LDB(B1, 0, 1); PG8_SCHED; PG8_LDA(At, 0, 0); PG8_STAGE(PG8_SA(1, 1), a1 + hA, voffA);
;     ...
;             PG8_LDA(At, 1, 1); PG8_STAGE(PG8_SB(1, 0), b3, voffB); PG8_STAGE(PG8_SB(1, 1), b3 + hB, voffB); PG8_STAGE(PG8_SA(1, 0), a3, voffA);
;             PG8_WAIT_V(8); PG8_WAIT_L(0); PG8_BAR; PG8_MMA(1, 0, At, B0); PG8_MMA(1, 1, At, B1); PG8_BAR; PG8_SCHED;
	s_add_i32 s10, s10, s45
	v_lshl_add_u64 v[146:147], v[244:245], 0, s[92:93]
	s_mov_b32 m0, s10
	ds_read_b128 v[192:195], v151 offset:49152
	ds_read_b128 v[196:199], v151 offset:50176
	ds_read_b128 v[200:203], v151 offset:51200
	ds_read_b128 v[204:207], v151 offset:52224
	ds_read_b128 v[208:211], v151 offset:53248
	ds_read_b128 v[212:215], v151 offset:54272
	ds_read_b128 v[216:219], v151 offset:55296
	ds_read_b128 v[240:243], v151 offset:56320
	global_load_lds_dwordx4 v[146:147], off
	v_lshl_add_u64 v[146:147], v[246:247], 0, s[92:93]
	s_add_i32 m0, s10, 0x2000
	s_add_i32 s10, s62, s45
	global_load_lds_dwordx4 v[146:147], off
	v_lshl_add_u64 v[146:147], v[248:249], 0, s[92:93]
	s_mov_b32 m0, s10
	s_nop 0
	global_load_lds_dwordx4 v[146:147], off
	v_lshl_add_u64 v[146:147], v[220:221], 0, s[92:93]
	s_add_i32 m0, s10, 0x2000
	s_nop 0
	global_load_lds_dwordx4 v[146:147], off
	v_lshl_add_u64 v[146:147], v[250:251], 0, s[92:93]
	s_mov_b32 m0, s53
	s_nop 0
	global_load_lds_dwordx4 v[146:147], off
	v_lshl_add_u64 v[146:147], v[252:253], 0, s[92:93]
	s_mov_b32 m0, s54
	s_nop 0
	global_load_lds_dwordx4 v[146:147], off
	s_waitcnt vmcnt(8)
	s_waitcnt lgkmcnt(0)
	s_barrier
	s_waitcnt lgkmcnt(0)
	v_mfma_f32_16x16x32_bf16 v[60:63], v[152:155], v[192:195], v[60:63]
	v_mfma_f32_16x16x32_bf16 v[56:59], v[160:163], v[192:195], v[56:59]
	v_mfma_f32_16x16x32_bf16 v[44:47], v[152:155], v[200:203], v[44:47]
	v_mfma_f32_16x16x32_bf16 v[40:43], v[160:163], v[200:203], v[40:43]
	v_mfma_f32_16x16x32_bf16 v[28:31], v[152:155], v[208:211], v[28:31]
	v_mfma_f32_16x16x32_bf16 v[24:27], v[160:163], v[208:211], v[24:27]
	v_mfma_f32_16x16x32_bf16 v[12:15], v[152:155], v[216:219], v[12:15]
	v_mfma_f32_16x16x32_bf16 v[8:11], v[160:163], v[216:219], v[8:11]
	v_mfma_f32_16x16x32_bf16 v[60:63], v[156:159], v[196:199], v[60:63]
	v_mfma_f32_16x16x32_bf16 v[56:59], v[164:167], v[196:199], v[56:59]
	v_mfma_f32_16x16x32_bf16 v[44:47], v[156:159], v[204:207], v[44:47]
	v_mfma_f32_16x16x32_bf16 v[40:43], v[164:167], v[204:207], v[40:43]
	v_mfma_f32_16x16x32_bf16 v[28:31], v[156:159], v[212:215], v[28:31]
	v_mfma_f32_16x16x32_bf16 v[24:27], v[164:167], v[212:215], v[24:27]
	v_mfma_f32_16x16x32_bf16 v[12:15], v[156:159], v[240:243], v[12:15]
	v_mfma_f32_16x16x32_bf16 v[8:11], v[164:167], v[240:243], v[8:11]
	v_mfma_f32_16x16x32_bf16 v[52:55], v[176:179], v[192:195], v[52:55]
	v_mfma_f32_16x16x32_bf16 v[48:51], v[184:187], v[192:195], v[48:51]
	v_mfma_f32_16x16x32_bf16 v[36:39], v[176:179], v[200:203], v[36:39]
	v_mfma_f32_16x16x32_bf16 v[32:35], v[184:187], v[200:203], v[32:35]
	v_mfma_f32_16x16x32_bf16 v[20:23], v[176:179], v[208:211], v[20:23]
	v_mfma_f32_16x16x32_bf16 v[16:19], v[184:187], v[208:211], v[16:19]
	v_mfma_f32_16x16x32_bf16 v[4:7], v[176:179], v[216:219], v[4:7]
	v_mfma_f32_16x16x32_bf16 v[0:3], v[184:187], v[216:219], v[0:3]
	v_mfma_f32_16x16x32_bf16 v[52:55], v[180:183], v[196:199], v[52:55]
	v_mfma_f32_16x16x32_bf16 v[48:51], v[188:191], v[196:199], v[48:51]
	v_mfma_f32_16x16x32_bf16 v[36:39], v[180:183], v[204:207], v[36:39]
	v_mfma_f32_16x16x32_bf16 v[32:35], v[188:191], v[204:207], v[32:35]
	v_mfma_f32_16x16x32_bf16 v[20:23], v[180:183], v[212:215], v[20:23]
	v_mfma_f32_16x16x32_bf16 v[16:19], v[188:191], v[212:215], v[16:19]
	v_mfma_f32_16x16x32_bf16 v[4:7], v[180:183], v[240:243], v[4:7]
	v_mfma_f32_16x16x32_bf16 v[0:3], v[188:191], v[240:243], v[0:3]
	s_barrier
	v_lshl_add_u64 v[142:143], v[142:143], 0, s[80:81]
	v_lshl_add_u64 v[144:145], v[144:145], 0, s[80:81]
	s_mov_b32 s10, s11
	s_cmp_eq_u32 s10, s55
	s_cbranch_scc1 .Lq5_last
.LBB0_354:
	s_add_i32 s11, s10, 2
	s_cmp_eq_u32 s55, s10
	s_cselect_b64 vcc, -1, 0
	v_add_u32_e32 v148, s33, v149
	s_add_i32 s10, 0, 0x14000
	ds_read_b128 v[152:155], v148
	ds_read_b128 v[156:159], v148 offset:1024
	ds_read_b128 v[160:163], v148 offset:2048
	ds_read_b128 v[164:167], v148 offset:3072
	v_add_u32_e32 v148, s10, v149
	ds_read_b128 v[176:179], v148
	ds_read_b128 v[180:183], v148 offset:1024
	ds_read_b128 v[184:187], v148 offset:2048
	ds_read_b128 v[188:191], v148 offset:3072
	v_lshl_add_u64 v[146:147], v[142:143], 0, s[92:93]
	v_cndmask_b32_e32 v147, v147, v139, vcc
	v_cndmask_b32_e32 v146, v146, v138, vcc
	v_cndmask_b32_e32 v221, v145, v141, vcc
	v_cndmask_b32_e32 v220, v144, v140, vcc
	v_lshl_add_u64 v[244:245], v[142:143], 0, v[134:135]
	s_add_i32 m0, s25, 0xc000
	ds_read_b128 v[192:195], v151
	ds_read_b128 v[196:199], v151 offset:1024
	ds_read_b128 v[200:203], v151 offset:2048
	ds_read_b128 v[204:207], v151 offset:3072
	ds_read_b128 v[208:211], v151 offset:4096
	ds_read_b128 v[212:215], v151 offset:5120
	ds_read_b128 v[216:219], v151 offset:6144
	ds_read_b128 v[240:243], v151 offset:7168
	global_load_lds_dwordx4 v[244:245], off
	v_lshl_add_u64 v[244:245], v[142:143], 0, v[136:137]
	s_add_i32 m0, s25, 0xe000
	s_nop 0
	global_load_lds_dwordx4 v[244:245], off
	s_waitcnt vmcnt(8)
	s_waitcnt lgkmcnt(0)
	s_barrier
; #define PG8_STAGE(bufoff, gbase, voff) do { _Pragma("unroll") for (int _i = 0; _i < 2; ++_i) \
;         __builtin_amdgcn_global_load_lds((const unsigned*)((const char*)(gbase) + (voff)[_i]), (LAS unsigned*)(lds + (bufoff) + ldsw + _i * 8192), 16, 0, 0); } while (0)
; #define PG8_LDA(dst, b, h) do { _Pragma("unroll") for (int m = 0; m < 4; ++m) _Pragma("unroll") for (int k = 0; k < 2; ++k) dst[m][k] = *(const LAS bf16x8*)(lds + PG8_SA(b, h) + aoff + m * 2048 + k * 1024); } while (0)
; #define PG8_MMA(ai, bj, At, Bt) do { __builtin_amdgcn_s_setprio(1); _Pragma("unroll") for (int k = 0; k < 2; ++k) _Pragma("unroll") for (int m = 0; m < 4; ++m) _Pragma("unroll") for (int n = 0; n < 2; ++n) \
;         acc[ai][bj][m][n] = __builtin_amdgcn_mfma_f32_16x16x32_bf16(Bt[n][k], At[m][k], acc[ai][bj][m][n], 0, 0, 0); __builtin_amdgcn_s_setprio(0); } while (0)
; #define PG8_WAIT_V(n) asm volatile("s_waitcnt vmcnt(" #n ")" ::: "memory")
; #define PG8_WAIT_L(n) asm volatile("s_waitcnt lgkmcnt(" #n ")" ::: "memory")
; #define PG8_BAR __builtin_amdgcn_s_barrier()
; #define PG8_SCHED __builtin_amdgcn_sched_barrier(0)
; template <class Epi, bool ALIGN_EPI>
; __device__ __forceinline__ void gemm_phase(LAS unsigned char* lds, const Gemm g, const StaticOrder& S, const Epi& E, const int tid) {
;     ...
;             PG8_WAIT_V(8); PG8_WAIT_L(0); PG8_BAR; PG8_MMA(0, 0, At, B0); PG8_MMA(0, 1, At, B1); PG8_BAR; PG8_SCHED;
;             PG8_LDA(At, 0, 1); PG8_STAGE(PG8_SB(0, 0), b2, voffB); PG8_STAGE(PG8_SB(0, 1), b2 + hB, voffB); PG8_STAGE(PG8_SA(0, 0), a2, voffA);
;             PG8_WAIT_V(8); PG8_WAIT_L(0); PG8_BAR; PG8_MMA(1, 0, At, B0); PG8_MMA(1, 1, At, B1); PG8_BAR; PG8_SCHED;
	s_waitcnt lgkmcnt(0)
	v_mfma_f32_16x16x32_bf16 v[124:127], v[152:155], v[192:195], v[124:127]
	v_mfma_f32_16x16x32_bf16 v[120:123], v[160:163], v[192:195], v[120:123]
	v_mfma_f32_16x16x32_bf16 v[108:111], v[152:155], v[200:203], v[108:111]
	v_mfma_f32_16x16x32_bf16 v[104:107], v[160:163], v[200:203], v[104:107]
	v_mfma_f32_16x16x32_bf16 v[92:95], v[152:155], v[208:211], v[92:95]
	v_mfma_f32_16x16x32_bf16 v[88:91], v[160:163], v[208:211], v[88:91]
	v_mfma_f32_16x16x32_bf16 v[76:79], v[152:155], v[216:219], v[76:79]
	v_mfma_f32_16x16x32_bf16 v[72:75], v[160:163], v[216:219], v[72:75]
	v_mfma_f32_16x16x32_bf16 v[124:127], v[156:159], v[196:199], v[124:127]
	v_mfma_f32_16x16x32_bf16 v[120:123], v[164:167], v[196:199], v[120:123]
	v_mfma_f32_16x16x32_bf16 v[108:111], v[156:159], v[204:207], v[108:111]
	v_mfma_f32_16x16x32_bf16 v[104:107], v[164:167], v[204:207], v[104:107]
	v_mfma_f32_16x16x32_bf16 v[92:95], v[156:159], v[212:215], v[92:95]
	v_mfma_f32_16x16x32_bf16 v[88:91], v[164:167], v[212:215], v[88:91]
	v_mfma_f32_16x16x32_bf16 v[76:79], v[156:159], v[240:243], v[76:79]
	v_mfma_f32_16x16x32_bf16 v[72:75], v[164:167], v[240:243], v[72:75]
	v_mfma_f32_16x16x32_bf16 v[116:119], v[176:179], v[192:195], v[116:119]
	v_mfma_f32_16x16x32_bf16 v[112:115], v[184:187], v[192:195], v[112:115]
	v_mfma_f32_16x16x32_bf16 v[100:103], v[176:179], v[200:203], v[100:103]
	v_mfma_f32_16x16x32_bf16 v[96:99], v[184:187], v[200:203], v[96:99]
	v_mfma_f32_16x16x32_bf16 v[84:87], v[176:179], v[208:211], v[84:87]
	v_mfma_f32_16x16x32_bf16 v[80:83], v[184:187], v[208:211], v[80:83]
	v_mfma_f32_16x16x32_bf16 v[68:71], v[176:179], v[216:219], v[68:71]
	v_mfma_f32_16x16x32_bf16 v[64:67], v[184:187], v[216:219], v[64:67]
	v_mfma_f32_16x16x32_bf16 v[116:119], v[180:183], v[196:199], v[116:119]
	v_mfma_f32_16x16x32_bf16 v[112:115], v[188:191], v[196:199], v[112:115]
	v_mfma_f32_16x16x32_bf16 v[100:103], v[180:183], v[204:207], v[100:103]
	v_mfma_f32_16x16x32_bf16 v[96:99], v[188:191], v[204:207], v[96:99]
	v_mfma_f32_16x16x32_bf16 v[84:87], v[180:183], v[212:215], v[84:87]
	v_mfma_f32_16x16x32_bf16 v[80:83], v[188:191], v[212:215], v[80:83]
	v_mfma_f32_16x16x32_bf16 v[68:71], v[180:183], v[240:243], v[68:71]
	v_mfma_f32_16x16x32_bf16 v[64:67], v[188:191], v[240:243], v[64:67]
	s_barrier
	s_add_i32 s62, s33, s45
	v_lshl_add_u64 v[244:245], v[220:221], 0, v[168:169]
	s_mov_b32 m0, s62
	ds_read_b128 v[192:195], v151 offset:16384
	ds_read_b128 v[196:199], v151 offset:17408
	ds_read_b128 v[200:203], v151 offset:18432
	ds_read_b128 v[204:207], v151 offset:19456
	ds_read_b128 v[208:211], v151 offset:20480
	ds_read_b128 v[212:215], v151 offset:21504
	ds_read_b128 v[216:219], v151 offset:22528
	ds_read_b128 v[240:243], v151 offset:23552
	global_load_lds_dwordx4 v[244:245], off
	v_lshl_add_u64 v[246:247], v[220:221], 0, v[128:129]
	s_add_i32 m0, s62, 0x2000
	v_lshl_add_u64 v[220:221], v[220:221], 0, s[12:13]
	s_add_i32 s10, s10, s45
	global_load_lds_dwordx4 v[246:247], off
	v_lshl_add_u64 v[248:249], v[220:221], 0, v[168:169]
	s_mov_b32 m0, s10
	v_lshl_add_u64 v[220:221], v[220:221], 0, v[128:129]
	global_load_lds_dwordx4 v[248:249], off
	s_add_i32 m0, s10, 0x2000
	v_lshl_add_u64 v[250:251], v[146:147], 0, v[132:133]
	global_load_lds_dwordx4 v[220:221], off
	s_mov_b32 m0, s25
	v_lshl_add_u64 v[252:253], v[146:147], 0, v[130:131]
	global_load_lds_dwordx4 v[250:251], off
	s_mov_b32 m0, s50
	s_nop 0
	global_load_lds_dwordx4 v[252:253], off
	s_waitcnt vmcnt(8)
	s_waitcnt lgkmcnt(0)
	s_barrier
	s_waitcnt lgkmcnt(0)
	v_mfma_f32_16x16x32_bf16 v[60:63], v[152:155], v[192:195], v[60:63]
	v_mfma_f32_16x16x32_bf16 v[56:59], v[160:163], v[192:195], v[56:59]
	v_mfma_f32_16x16x32_bf16 v[44:47], v[152:155], v[200:203], v[44:47]
	v_mfma_f32_16x16x32_bf16 v[40:43], v[160:163], v[200:203], v[40:43]
	v_mfma_f32_16x16x32_bf16 v[28:31], v[152:155], v[208:211], v[28:31]
	v_mfma_f32_16x16x32_bf16 v[24:27], v[160:163], v[208:211], v[24:27]
	v_mfma_f32_16x16x32_bf16 v[12:15], v[152:155], v[216:219], v[12:15]
	v_mfma_f32_16x16x32_bf16 v[8:11], v[160:163], v[216:219], v[8:11]
	v_mfma_f32_16x16x32_bf16 v[60:63], v[156:159], v[196:199], v[60:63]
	v_mfma_f32_16x16x32_bf16 v[56:59], v[164:167], v[196:199], v[56:59]
	v_mfma_f32_16x16x32_bf16 v[44:47], v[156:159], v[204:207], v[44:47]
	v_mfma_f32_16x16x32_bf16 v[40:43], v[164:167], v[204:207], v[40:43]
	v_mfma_f32_16x16x32_bf16 v[28:31], v[156:159], v[212:215], v[28:31]
	v_mfma_f32_16x16x32_bf16 v[24:27], v[164:167], v[212:215], v[24:27]
	v_mfma_f32_16x16x32_bf16 v[12:15], v[156:159], v[240:243], v[12:15]
	v_mfma_f32_16x16x32_bf16 v[8:11], v[164:167], v[240:243], v[8:11]
	v_mfma_f32_16x16x32_bf16 v[52:55], v[176:179], v[192:195], v[52:55]
	v_mfma_f32_16x16x32_bf16 v[48:51], v[184:187], v[192:195], v[48:51]
	v_mfma_f32_16x16x32_bf16 v[36:39], v[176:179], v[200:203], v[36:39]
	v_mfma_f32_16x16x32_bf16 v[32:35], v[184:187], v[200:203], v[32:35]
	v_mfma_f32_16x16x32_bf16 v[20:23], v[176:179], v[208:211], v[20:23]
	v_mfma_f32_16x16x32_bf16 v[16:19], v[184:187], v[208:211], v[16:19]
	v_mfma_f32_16x16x32_bf16 v[4:7], v[176:179], v[216:219], v[4:7]
	v_mfma_f32_16x16x32_bf16 v[0:3], v[184:187], v[216:219], v[0:3]
	v_mfma_f32_16x16x32_bf16 v[52:55], v[180:183], v[196:199], v[52:55]
	v_mfma_f32_16x16x32_bf16 v[48:51], v[188:191], v[196:199], v[48:51]
	v_mfma_f32_16x16x32_bf16 v[36:39], v[180:183], v[204:207], v[36:39]
	v_mfma_f32_16x16x32_bf16 v[32:35], v[188:191], v[204:207], v[32:35]
	v_mfma_f32_16x16x32_bf16 v[20:23], v[180:183], v[212:215], v[20:23]
	v_mfma_f32_16x16x32_bf16 v[16:19], v[188:191], v[212:215], v[16:19]
	v_mfma_f32_16x16x32_bf16 v[4:7], v[180:183], v[240:243], v[4:7]
	v_mfma_f32_16x16x32_bf16 v[0:3], v[188:191], v[240:243], v[0:3]
	s_barrier
; #define PG8_STAGE(bufoff, gbase, voff) do { _Pragma("unroll") for (int _i = 0; _i < 2; ++_i) \
;         __builtin_amdgcn_global_load_lds((const unsigned*)((const char*)(gbase) + (voff)[_i]), (LAS unsigned*)(lds + (bufoff) + ldsw + _i * 8192), 16, 0, 0); } while (0)
; #define PG8_LDA(dst, b, h) do { _Pragma("unroll") for (int m = 0; m < 4; ++m) _Pragma("unroll") for (int k = 0; k < 2; ++k) dst[m][k] = *(const LAS bf16x8*)(lds + PG8_SA(b, h) + aoff + m * 2048 + k * 1024); } while (0)
; #define PG8_LDB(dst, b, h) do { _Pragma("unroll") for (int n = 0; n < 2; ++n) _Pragma("unroll") for (int k = 0; k < 2; ++k) dst[n][k] = *(const LAS bf16x8*)(lds + PG8_SB(b, h) + boff + n * 2048 + k * 1024); } while (0)
; #define PG8_MMA(ai, bj, At, Bt) do { __builtin_amdgcn_s_setprio(1); _Pragma("unroll") for (int k = 0; k < 2; ++k) _Pragma("unroll") for (int m = 0; m < 4; ++m) _Pragma("unroll") for (int n = 0; n < 2; ++n) \
;         acc[ai][bj][m][n] = __builtin_amdgcn_mfma_f32_16x16x32_bf16(Bt[n][k], At[m][k], acc[ai][bj][m][n], 0, 0, 0); __builtin_amdgcn_s_setprio(0); } while (0)
; #define PG8_WAIT_V(n) asm volatile("s_waitcnt vmcnt(" #n ")" ::: "memory")
; #define PG8_BAR __builtin_amdgcn_s_barrier()
; template <class Epi, bool ALIGN_EPI>
; __device__ __forceinline__ void gemm_phase(LAS unsigned char* lds, const Gemm g, const StaticOrder& S, const Epi& E, const int tid) {
;     ...
;             PG8_LDB(B0, 0, 0); PG8_LDB(B1, 0, 1); PG8_SCHED; PG8_LDA(At, 0, 0); PG8_STAGE(PG8_SA(1, 1), a1 + hA, voffA);
;             PG8_WAIT_V(8); PG8_WAIT_L(0); PG8_BAR; PG8_MMA(0, 0, At, B0); PG8_MMA(0, 1, At, B1); PG8_BAR; PG8_SCHED;
;             PG8_LDA(At, 0, 1); PG8_STAGE(PG8_SB(0, 0), b2, voffB); PG8_STAGE(PG8_SB(0, 1), b2 + hB, voffB); PG8_STAGE(PG8_SA(0, 0), a2, voffA);
;             PG8_WAIT_V(8); PG8_WAIT_L(0); PG8_BAR; PG8_MMA(1, 0, At, B0); PG8_MMA(1, 1, At, B1); PG8_BAR; PG8_SCHED;
;             PG8_LDB(B0, 1, 0); PG8_LDB(B1, 1, 1); PG8_SCHED; PG8_LDA(At, 1, 0); PG8_STAGE(PG8_SA(0, 1), a2 + hA, voffA);
;             PG8_WAIT_V(8); PG8_WAIT_L(0); PG8_BAR; PG8_MMA(0, 0, At, B0); PG8_MMA(0, 1, At, B1); PG8_BAR; PG8_SCHED;
;             PG8_LDA(At, 1, 1); PG8_STAGE(PG8_SB(1, 0), b3, voffB); PG8_STAGE(PG8_SB(1, 1), b3 + hB, voffB); PG8_STAGE(PG8_SA(1, 0), a3, voffA);
;             PG8_WAIT_V(8); PG8_WAIT_L(0); PG8_BAR; PG8_MMA(1, 0, At, B0); PG8_MMA(1, 1, At, B1); PG8_BAR; PG8_SCHED;
	s_add_i32 s10, 0, 0x18000
	v_add_u32_e32 v148, s10, v149
	s_add_i32 s62, 0, 0x1c000
	ds_read_b128 v[152:155], v148
	ds_read_b128 v[156:159], v148 offset:1024
	ds_read_b128 v[160:163], v148 offset:2048
	ds_read_b128 v[164:167], v148 offset:3072
	v_add_u32_e32 v148, s62, v149
	ds_read_b128 v[176:179], v148
	ds_read_b128 v[180:183], v148 offset:1024
	ds_read_b128 v[184:187], v148 offset:2048
	ds_read_b128 v[188:191], v148 offset:3072
	v_lshl_add_u64 v[146:147], v[146:147], 0, s[94:95]
	s_mov_b32 m0, s51
	v_lshl_add_u64 v[226:227], v[146:147], 0, v[132:133]
	ds_read_b128 v[192:195], v151 offset:32768
	ds_read_b128 v[196:199], v151 offset:33792
	ds_read_b128 v[200:203], v151 offset:34816
	ds_read_b128 v[204:207], v151 offset:35840
	ds_read_b128 v[208:211], v151 offset:36864
	ds_read_b128 v[212:215], v151 offset:37888
	ds_read_b128 v[216:219], v151 offset:38912
	ds_read_b128 v[240:243], v151 offset:39936
	global_load_lds_dwordx4 v[226:227], off
	v_lshl_add_u64 v[146:147], v[146:147], 0, v[130:131]
	s_mov_b32 m0, s52
	s_nop 0
	global_load_lds_dwordx4 v[146:147], off
	s_waitcnt vmcnt(8)
	s_waitcnt lgkmcnt(0)
	s_barrier
	s_waitcnt lgkmcnt(0)
	v_mfma_f32_16x16x32_bf16 v[124:127], v[152:155], v[192:195], v[124:127]
	v_mfma_f32_16x16x32_bf16 v[120:123], v[160:163], v[192:195], v[120:123]
	v_mfma_f32_16x16x32_bf16 v[108:111], v[152:155], v[200:203], v[108:111]
	v_mfma_f32_16x16x32_bf16 v[104:107], v[160:163], v[200:203], v[104:107]
	v_mfma_f32_16x16x32_bf16 v[92:95], v[152:155], v[208:211], v[92:95]
	v_mfma_f32_16x16x32_bf16 v[88:91], v[160:163], v[208:211], v[88:91]
	v_mfma_f32_16x16x32_bf16 v[76:79], v[152:155], v[216:219], v[76:79]
	v_mfma_f32_16x16x32_bf16 v[72:75], v[160:163], v[216:219], v[72:75]
	v_mfma_f32_16x16x32_bf16 v[124:127], v[156:159], v[196:199], v[124:127]
	v_mfma_f32_16x16x32_bf16 v[120:123], v[164:167], v[196:199], v[120:123]
	v_mfma_f32_16x16x32_bf16 v[108:111], v[156:159], v[204:207], v[108:111]
	v_mfma_f32_16x16x32_bf16 v[104:107], v[164:167], v[204:207], v[104:107]
	v_mfma_f32_16x16x32_bf16 v[92:95], v[156:159], v[212:215], v[92:95]
	v_mfma_f32_16x16x32_bf16 v[88:91], v[164:167], v[212:215], v[88:91]
	v_mfma_f32_16x16x32_bf16 v[76:79], v[156:159], v[240:243], v[76:79]
	v_mfma_f32_16x16x32_bf16 v[72:75], v[164:167], v[240:243], v[72:75]
	v_mfma_f32_16x16x32_bf16 v[116:119], v[176:179], v[192:195], v[116:119]
	v_mfma_f32_16x16x32_bf16 v[112:115], v[184:187], v[192:195], v[112:115]
	v_mfma_f32_16x16x32_bf16 v[100:103], v[176:179], v[200:203], v[100:103]
	v_mfma_f32_16x16x32_bf16 v[96:99], v[184:187], v[200:203], v[96:99]
	v_mfma_f32_16x16x32_bf16 v[84:87], v[176:179], v[208:211], v[84:87]
	v_mfma_f32_16x16x32_bf16 v[80:83], v[184:187], v[208:211], v[80:83]
	v_mfma_f32_16x16x32_bf16 v[68:71], v[176:179], v[216:219], v[68:71]
	v_mfma_f32_16x16x32_bf16 v[64:67], v[184:187], v[216:219], v[64:67]
	v_mfma_f32_16x16x32_bf16 v[116:119], v[180:183], v[196:199], v[116:119]
	v_mfma_f32_16x16x32_bf16 v[112:115], v[188:191], v[196:199], v[112:115]
	v_mfma_f32_16x16x32_bf16 v[100:103], v[180:183], v[204:207], v[100:103]
	v_mfma_f32_16x16x32_bf16 v[96:99], v[188:191], v[204:207], v[96:99]
	v_mfma_f32_16x16x32_bf16 v[84:87], v[180:183], v[212:215], v[84:87]
	v_mfma_f32_16x16x32_bf16 v[80:83], v[188:191], v[212:215], v[80:83]
	v_mfma_f32_16x16x32_bf16 v[68:71], v[180:183], v[240:243], v[68:71]
	v_mfma_f32_16x16x32_bf16 v[64:67], v[188:191], v[240:243], v[64:67]
	s_barrier
	s_add_i32 s10, s10, s45
	v_lshl_add_u64 v[146:147], v[244:245], 0, s[92:93]
	s_mov_b32 m0, s10
	ds_read_b128 v[192:195], v151 offset:49152
	ds_read_b128 v[196:199], v151 offset:50176
	ds_read_b128 v[200:203], v151 offset:51200
	ds_read_b128 v[204:207], v151 offset:52224
	ds_read_b128 v[208:211], v151 offset:53248
	ds_read_b128 v[212:215], v151 offset:54272
	ds_read_b128 v[216:219], v151 offset:55296
	ds_read_b128 v[240:243], v151 offset:56320
	global_load_lds_dwordx4 v[146:147], off
	v_lshl_add_u64 v[146:147], v[246:247], 0, s[92:93]
	s_add_i32 m0, s10, 0x2000
	s_add_i32 s10, s62, s45
	global_load_lds_dwordx4 v[146:147], off
	v_lshl_add_u64 v[146:147], v[248:249], 0, s[92:93]
	s_mov_b32 m0, s10
	s_nop 0
	global_load_lds_dwordx4 v[146:147], off
	v_lshl_add_u64 v[146:147], v[220:221], 0, s[92:93]
	s_add_i32 m0, s10, 0x2000
	s_nop 0
	global_load_lds_dwordx4 v[146:147], off
	v_lshl_add_u64 v[146:147], v[250:251], 0, s[92:93]
	s_mov_b32 m0, s53
	s_nop 0
	global_load_lds_dwordx4 v[146:147], off
	v_lshl_add_u64 v[146:147], v[252:253], 0, s[92:93]
	s_mov_b32 m0, s54
	s_nop 0
	global_load_lds_dwordx4 v[146:147], off
	s_waitcnt vmcnt(8)
	s_waitcnt lgkmcnt(0)
	s_barrier
	s_waitcnt lgkmcnt(0)
	v_mfma_f32_16x16x32_bf16 v[60:63], v[152:155], v[192:195], v[60:63]
	v_mfma_f32_16x16x32_bf16 v[56:59], v[160:163], v[192:195], v[56:59]
	v_mfma_f32_16x16x32_bf16 v[44:47], v[152:155], v[200:203], v[44:47]
	v_mfma_f32_16x16x32_bf16 v[40:43], v[160:163], v[200:203], v[40:43]
	v_mfma_f32_16x16x32_bf16 v[28:31], v[152:155], v[208:211], v[28:31]
	v_mfma_f32_16x16x32_bf16 v[24:27], v[160:163], v[208:211], v[24:27]
	v_mfma_f32_16x16x32_bf16 v[12:15], v[152:155], v[216:219], v[12:15]
	v_mfma_f32_16x16x32_bf16 v[8:11], v[160:163], v[216:219], v[8:11]
	v_mfma_f32_16x16x32_bf16 v[60:63], v[156:159], v[196:199], v[60:63]
	v_mfma_f32_16x16x32_bf16 v[56:59], v[164:167], v[196:199], v[56:59]
	v_mfma_f32_16x16x32_bf16 v[44:47], v[156:159], v[204:207], v[44:47]
	v_mfma_f32_16x16x32_bf16 v[40:43], v[164:167], v[204:207], v[40:43]
	v_mfma_f32_16x16x32_bf16 v[28:31], v[156:159], v[212:215], v[28:31]
	v_mfma_f32_16x16x32_bf16 v[24:27], v[164:167], v[212:215], v[24:27]
	v_mfma_f32_16x16x32_bf16 v[12:15], v[156:159], v[240:243], v[12:15]
	v_mfma_f32_16x16x32_bf16 v[8:11], v[164:167], v[240:243], v[8:11]
	v_mfma_f32_16x16x32_bf16 v[52:55], v[176:179], v[192:195], v[52:55]
	v_mfma_f32_16x16x32_bf16 v[48:51], v[184:187], v[192:195], v[48:51]
	v_mfma_f32_16x16x32_bf16 v[36:39], v[176:179], v[200:203], v[36:39]
	v_mfma_f32_16x16x32_bf16 v[32:35], v[184:187], v[200:203], v[32:35]
	v_mfma_f32_16x16x32_bf16 v[20:23], v[176:179], v[208:211], v[20:23]
	v_mfma_f32_16x16x32_bf16 v[16:19], v[184:187], v[208:211], v[16:19]
	v_mfma_f32_16x16x32_bf16 v[4:7], v[176:179], v[216:219], v[4:7]
	v_mfma_f32_16x16x32_bf16 v[0:3], v[184:187], v[216:219], v[0:3]
	v_mfma_f32_16x16x32_bf16 v[52:55], v[180:183], v[196:199], v[52:55]
	v_mfma_f32_16x16x32_bf16 v[48:51], v[188:191], v[196:199], v[48:51]
	v_mfma_f32_16x16x32_bf16 v[36:39], v[180:183], v[204:207], v[36:39]
	v_mfma_f32_16x16x32_bf16 v[32:35], v[188:191], v[204:207], v[32:35]
	v_mfma_f32_16x16x32_bf16 v[20:23], v[180:183], v[212:215], v[20:23]
	v_mfma_f32_16x16x32_bf16 v[16:19], v[188:191], v[212:215], v[16:19]
	v_mfma_f32_16x16x32_bf16 v[4:7], v[180:183], v[240:243], v[4:7]
	v_mfma_f32_16x16x32_bf16 v[0:3], v[188:191], v[240:243], v[0:3]
	s_barrier
	v_lshl_add_u64 v[142:143], v[142:143], 0, s[80:81]
	v_lshl_add_u64 v[144:145], v[144:145], 0, s[80:81]
	s_mov_b32 s10, s11
	s_cmp_lg_u32 s10, s55
	s_cbranch_scc1 .LBB0_354
; #define PG8_STAGE(bufoff, gbase, voff) do { _Pragma("unroll") for (int _i = 0; _i < 2; ++_i) \
;         __builtin_amdgcn_global_load_lds((const unsigned*)((const char*)(gbase) + (voff)[_i]), (LAS unsigned*)(lds + (bufoff) + ldsw + _i * 8192), 16, 0, 0); } while (0)
; #define PG8_LDA(dst, b, h) do { _Pragma("unroll") for (int m = 0; m < 4; ++m) _Pragma("unroll") for (int k = 0; k < 2; ++k) dst[m][k] = *(const LAS bf16x8*)(lds + PG8_SA(b, h) + aoff + m * 2048 + k * 1024); } while (0)
; #define PG8_LDB(dst, b, h) do { _Pragma("unroll") for (int n = 0; n < 2; ++n) _Pragma("unroll") for (int k = 0; k < 2; ++k) dst[n][k] = *(const LAS bf16x8*)(lds + PG8_SB(b, h) + boff + n * 2048 + k * 1024); } while (0)
; #define PG8_MMA(ai, bj, At, Bt) do { __builtin_amdgcn_s_setprio(1); _Pragma("unroll") for (int k = 0; k < 2; ++k) _Pragma("unroll") for (int m = 0; m < 4; ++m) _Pragma("unroll") for (int n = 0; n < 2; ++n) \
;         acc[ai][bj][m][n] = __builtin_amdgcn_mfma_f32_16x16x32_bf16(Bt[n][k], At[m][k], acc[ai][bj][m][n], 0, 0, 0); __builtin_amdgcn_s_setprio(0); } while (0)
; #define PG8_WAIT_V(n) asm volatile("s_waitcnt vmcnt(" #n ")" ::: "memory")
; #define PG8_WAIT_L(n) asm volatile("s_waitcnt lgkmcnt(" #n ")" ::: "memory")
; #define PG8_BAR __builtin_amdgcn_s_barrier()
; #define PG8_SCHED __builtin_amdgcn_sched_barrier(0)
; template <class Epi, bool ALIGN_EPI>
; __device__ __forceinline__ void gemm_phase(LAS unsigned char* lds, const Gemm g, const StaticOrder& S, const Epi& E, const int tid) {
;     ...
;             const bool last = (t == nt - 2);
;             const char* a1 = cA + (size_t)(t + 1) * kstep;
;             const char* a2 = last ? nA : cA + (size_t)(t + 2) * kstep; const char* b2 = last ? nB : cB + (size_t)(t + 2) * kstep;
;             const char* a3 = a2 + kstep; const char* b3 = b2 + kstep;
;             PG8_LDB(B0, 0, 0); PG8_LDB(B1, 0, 1); PG8_SCHED; PG8_LDA(At, 0, 0); PG8_STAGE(PG8_SA(1, 1), a1 + hA, voffA);
;             PG8_WAIT_V(8); PG8_WAIT_L(0); PG8_BAR; PG8_MMA(0, 0, At, B0); PG8_MMA(0, 1, At, B1); PG8_BAR; PG8_SCHED;
;             PG8_LDA(At, 0, 1); PG8_STAGE(PG8_SB(0, 0), b2, voffB); PG8_STAGE(PG8_SB(0, 1), b2 + hB, voffB); PG8_STAGE(PG8_SA(0, 0), a2, voffA);
;             PG8_WAIT_V(8); PG8_WAIT_L(0); PG8_BAR; PG8_MMA(1, 0, At, B0); PG8_MMA(1, 1, At, B1); PG8_BAR; PG8_SCHED;
.Lq5_last:
	s_add_i32 s11, s10, 2
	s_cmp_eq_u32 s55, s10
	s_cselect_b64 vcc, -1, 0
	v_add_u32_e32 v148, s33, v149
	s_add_i32 s10, 0, 0x14000
	ds_read_b128 v[152:155], v148
	ds_read_b128 v[156:159], v148 offset:1024
	ds_read_b128 v[160:163], v148 offset:2048
	ds_read_b128 v[164:167], v148 offset:3072
	v_add_u32_e32 v148, s10, v149
	ds_read_b128 v[176:179], v148
	ds_read_b128 v[180:183], v148 offset:1024
	ds_read_b128 v[184:187], v148 offset:2048
	ds_read_b128 v[188:191], v148 offset:3072
	v_lshl_add_u64 v[146:147], v[142:143], 0, s[92:93]
	v_cndmask_b32_e32 v147, v147, v139, vcc
	v_cndmask_b32_e32 v146, v146, v138, vcc
	v_cndmask_b32_e32 v221, v145, v141, vcc
	v_cndmask_b32_e32 v220, v144, v140, vcc
	v_lshl_add_u64 v[244:245], v[142:143], 0, v[134:135]
	s_add_i32 m0, s25, 0xc000
	ds_read_b128 v[192:195], v151
	ds_read_b128 v[196:199], v151 offset:1024
	ds_read_b128 v[200:203], v151 offset:2048
	ds_read_b128 v[204:207], v151 offset:3072
	ds_read_b128 v[208:211], v151 offset:4096
	ds_read_b128 v[212:215], v151 offset:5120
	ds_read_b128 v[216:219], v151 offset:6144
	ds_read_b128 v[240:243], v151 offset:7168
	global_load_lds_dwordx4 v[244:245], off
	v_lshl_add_u64 v[244:245], v[142:143], 0, v[136:137]
	s_add_i32 m0, s25, 0xe000
	s_nop 0
	global_load_lds_dwordx4 v[244:245], off
	s_waitcnt vmcnt(8)
	s_waitcnt lgkmcnt(0)
	s_barrier
	s_waitcnt lgkmcnt(0)
	v_mfma_f32_16x16x32_bf16 v[124:127], v[152:155], v[192:195], v[124:127]
	v_mfma_f32_16x16x32_bf16 v[120:123], v[160:163], v[192:195], v[120:123]
	v_mfma_f32_16x16x32_bf16 v[108:111], v[152:155], v[200:203], v[108:111]
	v_mfma_f32_16x16x32_bf16 v[104:107], v[160:163], v[200:203], v[104:107]
	v_mfma_f32_16x16x32_bf16 v[92:95], v[152:155], v[208:211], v[92:95]
	v_mfma_f32_16x16x32_bf16 v[88:91], v[160:163], v[208:211], v[88:91]
	v_mfma_f32_16x16x32_bf16 v[76:79], v[152:155], v[216:219], v[76:79]
	v_mfma_f32_16x16x32_bf16 v[72:75], v[160:163], v[216:219], v[72:75]
	v_mfma_f32_16x16x32_bf16 v[124:127], v[156:159], v[196:199], v[124:127]
	v_mfma_f32_16x16x32_bf16 v[120:123], v[164:167], v[196:199], v[120:123]
	v_mfma_f32_16x16x32_bf16 v[108:111], v[156:159], v[204:207], v[108:111]
	v_mfma_f32_16x16x32_bf16 v[104:107], v[164:167], v[204:207], v[104:107]
	v_mfma_f32_16x16x32_bf16 v[92:95], v[156:159], v[212:215], v[92:95]
	v_mfma_f32_16x16x32_bf16 v[88:91], v[164:167], v[212:215], v[88:91]
	v_mfma_f32_16x16x32_bf16 v[76:79], v[156:159], v[240:243], v[76:79]
	v_mfma_f32_16x16x32_bf16 v[72:75], v[164:167], v[240:243], v[72:75]
	v_mfma_f32_16x16x32_bf16 v[116:119], v[176:179], v[192:195], v[116:119]
	v_mfma_f32_16x16x32_bf16 v[112:115], v[184:187], v[192:195], v[112:115]
	v_mfma_f32_16x16x32_bf16 v[100:103], v[176:179], v[200:203], v[100:103]
	v_mfma_f32_16x16x32_bf16 v[96:99], v[184:187], v[200:203], v[96:99]
	v_mfma_f32_16x16x32_bf16 v[84:87], v[176:179], v[208:211], v[84:87]
	v_mfma_f32_16x16x32_bf16 v[80:83], v[184:187], v[208:211], v[80:83]
	v_mfma_f32_16x16x32_bf16 v[68:71], v[176:179], v[216:219], v[68:71]
	v_mfma_f32_16x16x32_bf16 v[64:67], v[184:187], v[216:219], v[64:67]
	v_mfma_f32_16x16x32_bf16 v[116:119], v[180:183], v[196:199], v[116:119]
	v_mfma_f32_16x16x32_bf16 v[112:115], v[188:191], v[196:199], v[112:115]
	v_mfma_f32_16x16x32_bf16 v[100:103], v[180:183], v[204:207], v[100:103]
	v_mfma_f32_16x16x32_bf16 v[96:99], v[188:191], v[204:207], v[96:99]
	v_mfma_f32_16x16x32_bf16 v[84:87], v[180:183], v[212:215], v[84:87]
	v_mfma_f32_16x16x32_bf16 v[80:83], v[188:191], v[212:215], v[80:83]
	v_mfma_f32_16x16x32_bf16 v[68:71], v[180:183], v[240:243], v[68:71]
	v_mfma_f32_16x16x32_bf16 v[64:67], v[188:191], v[240:243], v[64:67]
	s_barrier
	s_add_i32 s62, s33, s45
	v_lshl_add_u64 v[244:245], v[220:221], 0, v[168:169]
	s_mov_b32 m0, s62
	ds_read_b128 v[192:195], v151 offset:16384
	ds_read_b128 v[196:199], v151 offset:17408
	ds_read_b128 v[200:203], v151 offset:18432
	ds_read_b128 v[204:207], v151 offset:19456
	ds_read_b128 v[208:211], v151 offset:20480
	ds_read_b128 v[212:215], v151 offset:21504
	ds_read_b128 v[216:219], v151 offset:22528
	ds_read_b128 v[240:243], v151 offset:23552
	global_load_lds_dwordx4 v[244:245], off
	v_lshl_add_u64 v[246:247], v[220:221], 0, v[128:129]
	s_add_i32 m0, s62, 0x2000
	v_lshl_add_u64 v[220:221], v[220:221], 0, s[12:13]
	s_add_i32 s10, s10, s45
	global_load_lds_dwordx4 v[246:247], off
	v_lshl_add_u64 v[248:249], v[220:221], 0, v[168:169]
	s_mov_b32 m0, s10
	v_lshl_add_u64 v[220:221], v[220:221], 0, v[128:129]
	global_load_lds_dwordx4 v[248:249], off
	s_add_i32 m0, s10, 0x2000
	v_lshl_add_u64 v[250:251], v[146:147], 0, v[132:133]
	global_load_lds_dwordx4 v[220:221], off
	s_mov_b32 m0, s25
	v_lshl_add_u64 v[252:253], v[146:147], 0, v[130:131]
	global_load_lds_dwordx4 v[250:251], off
	s_mov_b32 m0, s50
	s_nop 0
	global_load_lds_dwordx4 v[252:253], off
	s_waitcnt vmcnt(8)
	s_waitcnt lgkmcnt(0)
	s_barrier
; #define PG8_STAGE(bufoff, gbase, voff) do { _Pragma("unroll") for (int _i = 0; _i < 2; ++_i) \
;         __builtin_amdgcn_global_load_lds((const unsigned*)((const char*)(gbase) + (voff)[_i]), (LAS unsigned*)(lds + (bufoff) + ldsw + _i * 8192), 16, 0, 0); } while (0)
; #define PG8_LDA(dst, b, h) do { _Pragma("unroll") for (int m = 0; m < 4; ++m) _Pragma("unroll") for (int k = 0; k < 2; ++k) dst[m][k] = *(const LAS bf16x8*)(lds + PG8_SA(b, h) + aoff + m * 2048 + k * 1024); } while (0)
; #define PG8_LDB(dst, b, h) do { _Pragma("unroll") for (int n = 0; n < 2; ++n) _Pragma("unroll") for (int k = 0; k < 2; ++k) dst[n][k] = *(const LAS bf16x8*)(lds + PG8_SB(b, h) + boff + n * 2048 + k * 1024); } while (0)
; #define PG8_MMA(ai, bj, At, Bt) do { __builtin_amdgcn_s_setprio(1); _Pragma("unroll") for (int k = 0; k < 2; ++k) _Pragma("unroll") for (int m = 0; m < 4; ++m) _Pragma("unroll") for (int n = 0; n < 2; ++n) \
;         acc[ai][bj][m][n] = __builtin_amdgcn_mfma_f32_16x16x32_bf16(Bt[n][k], At[m][k], acc[ai][bj][m][n], 0, 0, 0); __builtin_amdgcn_s_setprio(0); } while (0)
; #define PG8_WAIT_V(n) asm volatile("s_waitcnt vmcnt(" #n ")" ::: "memory")
; #define PG8_WAIT_L(n) asm volatile("s_waitcnt lgkmcnt(" #n ")" ::: "memory")
; #define PG8_BAR __builtin_amdgcn_s_barrier()
; #define PG8_SCHED __builtin_amdgcn_sched_barrier(0)
; template <class Epi, bool ALIGN_EPI>
; __device__ __forceinline__ void gemm_phase(LAS unsigned char* lds, const Gemm g, const StaticOrder& S, const Epi& E, const int tid) {
;     ...
;             PG8_WAIT_V(8); PG8_WAIT_L(0); PG8_BAR; PG8_MMA(0, 0, At, B0); PG8_MMA(0, 1, At, B1); PG8_BAR; PG8_SCHED;
;             PG8_LDA(At, 0, 1); PG8_STAGE(PG8_SB(0, 0), b2, voffB); PG8_STAGE(PG8_SB(0, 1), b2 + hB, voffB); PG8_STAGE(PG8_SA(0, 0), a2, voffA);
;             PG8_WAIT_V(8); PG8_WAIT_L(0); PG8_BAR; PG8_MMA(1, 0, At, B0); PG8_MMA(1, 1, At, B1); PG8_BAR; PG8_SCHED;
;             PG8_LDB(B0, 1, 0); PG8_LDB(B1, 1, 1); PG8_SCHED; PG8_LDA(At, 1, 0); PG8_STAGE(PG8_SA(0, 1), a2 + hA, voffA);
;             PG8_WAIT_V(8); PG8_WAIT_L(0); PG8_BAR; PG8_MMA(0, 0, At, B0); PG8_MMA(0, 1, At, B1); PG8_BAR; PG8_SCHED;
	s_waitcnt lgkmcnt(0)
	v_mfma_f32_16x16x32_bf16 v[60:63], v[152:155], v[192:195], v[60:63]
	v_mfma_f32_16x16x32_bf16 v[56:59], v[160:163], v[192:195], v[56:59]
	v_mfma_f32_16x16x32_bf16 v[44:47], v[152:155], v[200:203], v[44:47]
	v_mfma_f32_16x16x32_bf16 v[40:43], v[160:163], v[200:203], v[40:43]
	v_mfma_f32_16x16x32_bf16 v[28:31], v[152:155], v[208:211], v[28:31]
	v_mfma_f32_16x16x32_bf16 v[24:27], v[160:163], v[208:211], v[24:27]
	v_mfma_f32_16x16x32_bf16 v[12:15], v[152:155], v[216:219], v[12:15]
	v_mfma_f32_16x16x32_bf16 v[8:11], v[160:163], v[216:219], v[8:11]
	v_mfma_f32_16x16x32_bf16 v[60:63], v[156:159], v[196:199], v[60:63]
	v_mfma_f32_16x16x32_bf16 v[56:59], v[164:167], v[196:199], v[56:59]
	v_mfma_f32_16x16x32_bf16 v[44:47], v[156:159], v[204:207], v[44:47]
	v_mfma_f32_16x16x32_bf16 v[40:43], v[164:167], v[204:207], v[40:43]
	v_mfma_f32_16x16x32_bf16 v[28:31], v[156:159], v[212:215], v[28:31]
	v_mfma_f32_16x16x32_bf16 v[24:27], v[164:167], v[212:215], v[24:27]
	v_mfma_f32_16x16x32_bf16 v[12:15], v[156:159], v[240:243], v[12:15]
	v_mfma_f32_16x16x32_bf16 v[8:11], v[164:167], v[240:243], v[8:11]
	v_mfma_f32_16x16x32_bf16 v[52:55], v[176:179], v[192:195], v[52:55]
	v_mfma_f32_16x16x32_bf16 v[48:51], v[184:187], v[192:195], v[48:51]
	v_mfma_f32_16x16x32_bf16 v[36:39], v[176:179], v[200:203], v[36:39]
	v_mfma_f32_16x16x32_bf16 v[32:35], v[184:187], v[200:203], v[32:35]
	v_mfma_f32_16x16x32_bf16 v[20:23], v[176:179], v[208:211], v[20:23]
	v_mfma_f32_16x16x32_bf16 v[16:19], v[184:187], v[208:211], v[16:19]
	v_mfma_f32_16x16x32_bf16 v[4:7], v[176:179], v[216:219], v[4:7]
	v_mfma_f32_16x16x32_bf16 v[0:3], v[184:187], v[216:219], v[0:3]
	v_mfma_f32_16x16x32_bf16 v[52:55], v[180:183], v[196:199], v[52:55]
	v_mfma_f32_16x16x32_bf16 v[48:51], v[188:191], v[196:199], v[48:51]
	v_mfma_f32_16x16x32_bf16 v[36:39], v[180:183], v[204:207], v[36:39]
	v_mfma_f32_16x16x32_bf16 v[32:35], v[188:191], v[204:207], v[32:35]
	v_mfma_f32_16x16x32_bf16 v[20:23], v[180:183], v[212:215], v[20:23]
	v_mfma_f32_16x16x32_bf16 v[16:19], v[188:191], v[212:215], v[16:19]
	v_mfma_f32_16x16x32_bf16 v[4:7], v[180:183], v[240:243], v[4:7]
	v_mfma_f32_16x16x32_bf16 v[0:3], v[188:191], v[240:243], v[0:3]
	s_barrier
	s_add_i32 s10, 0, 0x18000
	v_add_u32_e32 v148, s10, v149
	s_add_i32 s62, 0, 0x1c000
	ds_read_b128 v[152:155], v148
	ds_read_b128 v[156:159], v148 offset:1024
	ds_read_b128 v[160:163], v148 offset:2048
	ds_read_b128 v[164:167], v148 offset:3072
	v_add_u32_e32 v148, s62, v149
	ds_read_b128 v[176:179], v148
	ds_read_b128 v[180:183], v148 offset:1024
	ds_read_b128 v[184:187], v148 offset:2048
	ds_read_b128 v[188:191], v148 offset:3072
	v_lshl_add_u64 v[146:147], v[146:147], 0, s[94:95]
	s_mov_b32 m0, s51
	v_lshl_add_u64 v[226:227], v[146:147], 0, v[132:133]
	ds_read_b128 v[192:195], v151 offset:32768
	ds_read_b128 v[196:199], v151 offset:33792
	ds_read_b128 v[200:203], v151 offset:34816
	ds_read_b128 v[204:207], v151 offset:35840
	ds_read_b128 v[208:211], v151 offset:36864
	ds_read_b128 v[212:215], v151 offset:37888
	ds_read_b128 v[216:219], v151 offset:38912
	ds_read_b128 v[240:243], v151 offset:39936
	global_load_lds_dwordx4 v[226:227], off
	v_lshl_add_u64 v[146:147], v[146:147], 0, v[130:131]
	s_mov_b32 m0, s52
	s_nop 0
	global_load_lds_dwordx4 v[146:147], off
	s_waitcnt vmcnt(8)
	s_waitcnt lgkmcnt(0)
	s_barrier
	s_waitcnt lgkmcnt(0)
	v_mfma_f32_16x16x32_bf16 v[124:127], v[152:155], v[192:195], v[124:127]
	v_mfma_f32_16x16x32_bf16 v[120:123], v[160:163], v[192:195], v[120:123]
	v_mfma_f32_16x16x32_bf16 v[108:111], v[152:155], v[200:203], v[108:111]
	v_mfma_f32_16x16x32_bf16 v[104:107], v[160:163], v[200:203], v[104:107]
	v_mfma_f32_16x16x32_bf16 v[92:95], v[152:155], v[208:211], v[92:95]
	v_mfma_f32_16x16x32_bf16 v[88:91], v[160:163], v[208:211], v[88:91]
	v_mfma_f32_16x16x32_bf16 v[76:79], v[152:155], v[216:219], v[76:79]
	v_mfma_f32_16x16x32_bf16 v[72:75], v[160:163], v[216:219], v[72:75]
	v_mfma_f32_16x16x32_bf16 v[124:127], v[156:159], v[196:199], v[124:127]
	v_mfma_f32_16x16x32_bf16 v[120:123], v[164:167], v[196:199], v[120:123]
	v_mfma_f32_16x16x32_bf16 v[108:111], v[156:159], v[204:207], v[108:111]
	v_mfma_f32_16x16x32_bf16 v[104:107], v[164:167], v[204:207], v[104:107]
	v_mfma_f32_16x16x32_bf16 v[92:95], v[156:159], v[212:215], v[92:95]
	v_mfma_f32_16x16x32_bf16 v[88:91], v[164:167], v[212:215], v[88:91]
	v_mfma_f32_16x16x32_bf16 v[76:79], v[156:159], v[240:243], v[76:79]
	v_mfma_f32_16x16x32_bf16 v[72:75], v[164:167], v[240:243], v[72:75]
	v_mfma_f32_16x16x32_bf16 v[116:119], v[176:179], v[192:195], v[116:119]
	v_mfma_f32_16x16x32_bf16 v[112:115], v[184:187], v[192:195], v[112:115]
	v_mfma_f32_16x16x32_bf16 v[100:103], v[176:179], v[200:203], v[100:103]
	v_mfma_f32_16x16x32_bf16 v[96:99], v[184:187], v[200:203], v[96:99]
	v_mfma_f32_16x16x32_bf16 v[84:87], v[176:179], v[208:211], v[84:87]
	v_mfma_f32_16x16x32_bf16 v[80:83], v[184:187], v[208:211], v[80:83]
	v_mfma_f32_16x16x32_bf16 v[68:71], v[176:179], v[216:219], v[68:71]
	v_mfma_f32_16x16x32_bf16 v[64:67], v[184:187], v[216:219], v[64:67]
	v_mfma_f32_16x16x32_bf16 v[116:119], v[180:183], v[196:199], v[116:119]
	v_mfma_f32_16x16x32_bf16 v[112:115], v[188:191], v[196:199], v[112:115]
	v_mfma_f32_16x16x32_bf16 v[100:103], v[180:183], v[204:207], v[100:103]
	v_mfma_f32_16x16x32_bf16 v[96:99], v[188:191], v[204:207], v[96:99]
	v_mfma_f32_16x16x32_bf16 v[84:87], v[180:183], v[212:215], v[84:87]
	v_mfma_f32_16x16x32_bf16 v[80:83], v[188:191], v[212:215], v[80:83]
	v_mfma_f32_16x16x32_bf16 v[68:71], v[180:183], v[240:243], v[68:71]
	v_mfma_f32_16x16x32_bf16 v[64:67], v[188:191], v[240:243], v[64:67]
	s_barrier
; #define PG8_STAGE(bufoff, gbase, voff) do { _Pragma("unroll") for (int _i = 0; _i < 2; ++_i) \
;         __builtin_amdgcn_global_load_lds((const unsigned*)((const char*)(gbase) + (voff)[_i]), (LAS unsigned*)(lds + (bufoff) + ldsw + _i * 8192), 16, 0, 0); } while (0)
; #define PG8_LDA(dst, b, h) do { _Pragma("unroll") for (int m = 0; m < 4; ++m) _Pragma("unroll") for (int k = 0; k < 2; ++k) dst[m][k] = *(const LAS bf16x8*)(lds + PG8_SA(b, h) + aoff + m * 2048 + k * 1024); } while (0)
; template <class Epi, bool ALIGN_EPI>
; __device__ __forceinline__ void gemm_phase(LAS unsigned char* lds, const Gemm g, const StaticOrder& S, const Epi& E, const int tid) {
;     ...
;             PG8_LDA(At, 1, 1); PG8_STAGE(PG8_SB(1, 0), b3, voffB); PG8_STAGE(PG8_SB(1, 1), b3 + hB, voffB); PG8_STAGE(PG8_SA(1, 0), a3, voffA);
	s_add_i32 s10, s10, s45
	v_lshl_add_u64 v[146:147], v[244:245], 0, s[92:93]
	s_mov_b32 m0, s10
	ds_read_b128 v[192:195], v151 offset:49152
	ds_read_b128 v[196:199], v151 offset:50176
	ds_read_b128 v[200:203], v151 offset:51200
	ds_read_b128 v[204:207], v151 offset:52224
	ds_read_b128 v[208:211], v151 offset:53248
	ds_read_b128 v[212:215], v151 offset:54272
	ds_read_b128 v[216:219], v151 offset:55296
	ds_read_b128 v[240:243], v151 offset:56320
	global_load_lds_dwordx4 v[146:147], off
	v_lshl_add_u64 v[146:147], v[246:247], 0, s[92:93]
	s_add_i32 m0, s10, 0x2000
	s_add_i32 s10, s62, s45
	global_load_lds_dwordx4 v[146:147], off
	v_lshl_add_u64 v[146:147], v[248:249], 0, s[92:93]
	s_mov_b32 m0, s10
	s_nop 0
	global_load_lds_dwordx4 v[146:147], off
	v_lshl_add_u64 v[146:147], v[220:221], 0, s[92:93]
	s_add_i32 m0, s10, 0x2000
	s_nop 0
	global_load_lds_dwordx4 v[146:147], off
	v_lshl_add_u64 v[146:147], v[250:251], 0, s[92:93]
	s_mov_b32 m0, s53
	s_nop 0
	global_load_lds_dwordx4 v[146:147], off
	v_lshl_add_u64 v[146:147], v[252:253], 0, s[92:93]
	s_mov_b32 m0, s54
	s_nop 0
	global_load_lds_dwordx4 v[146:147], off
	s_waitcnt vmcnt(8)
	s_waitcnt lgkmcnt(0)
	s_barrier
; __device__ __forceinline__ unsigned cvt_pk_bf16(float lo, float hi) { unsigned r; asm volatile("v_cvt_pk_bf16_f32 %0, %1, %2" : "=v"(r) : "v"(lo), "v"(hi)); return r; }
; __device__ __forceinline__ float gelu_tanh(float x) { const float u = 0.7978845608028654f * (x + 0.044715f * x * x * x); return x * fast_rcp(1.0f + fast_exp2(-2.0f * LOG2E * u)); }
; #define PG8_MMA(ai, bj, At, Bt) do { __builtin_amdgcn_s_setprio(1); _Pragma("unroll") for (int k = 0; k < 2; ++k) _Pragma("unroll") for (int m = 0; m < 4; ++m) _Pragma("unroll") for (int n = 0; n < 2; ++n) \
;         acc[ai][bj][m][n] = __builtin_amdgcn_mfma_f32_16x16x32_bf16(Bt[n][k], At[m][k], acc[ai][bj][m][n], 0, 0, 0); __builtin_amdgcn_s_setprio(0); } while (0)
; #define PG8_WAIT_V(n) asm volatile("s_waitcnt vmcnt(" #n ")" ::: "memory")
; #define PG8_WAIT_L(n) asm volatile("s_waitcnt lgkmcnt(" #n ")" ::: "memory")
; #define PG8_BAR __builtin_amdgcn_s_barrier()
; #define PG8_SCHED __builtin_amdgcn_sched_barrier(0)
;     __device__ __forceinline__ void operator()(const f32x4 (&acc)[2][2][4][2], const Unit& u, int wr, int wc, int fr, int fq) const {
;         const int row0 = u.pm * BM + wr * 64 + fr, col0 = u.pn * BM + wc * 32 + 8 * fq;
;         float rsv[2][4]; load_rstd(rsv, ssq, row0);
; #pragma unroll
;         for (int ai = 0; ai < 2; ++ai)
; #pragma unroll
;             for (int m = 0; m < 4; ++m) { const int row = row0 + ai * HALF + m * 16; bf16_t* rowp = O + (size_t)row * ldc + col0; const float rs = rsv[ai][m];
; #pragma unroll
;                 for (int bj = 0; bj < 2; ++bj) { f32x4 v0 = acc[ai][bj][m][0] * rs, v1 = acc[ai][bj][m][1] * rs;
;                     if (ACT == 1) {
; #pragma unroll
;                         for (int j = 0; j < 4; ++j) { v0[j] = gelu_tanh(v0[j]); v1[j] = gelu_tanh(v1[j]); } }
;                     u32x4 w; w.x = cvt_pk_bf16(v0[0], v0[1]); w.y = cvt_pk_bf16(v0[2], v0[3]); w.z = cvt_pk_bf16(v1[0], v1[1]); w.w = cvt_pk_bf16(v1[2], v1[3]);
;                     *(u32x4*)(rowp + bj * HALF) = w; } }
; template <class Epi, bool ALIGN_EPI>
; __device__ __forceinline__ void gemm_phase(LAS unsigned char* lds, const Gemm g, const StaticOrder& S, const Epi& E, const int tid) {
;     ...
;             PG8_WAIT_V(8); PG8_WAIT_L(0); PG8_BAR; PG8_MMA(1, 0, At, B0); PG8_MMA(1, 1, At, B1); PG8_BAR; PG8_SCHED;
	s_waitcnt lgkmcnt(0)
	v_mfma_f32_16x16x32_bf16 v[60:63], v[152:155], v[192:195], v[60:63]
	v_lshrrev_b32_e32 v171, 8, v170
	v_and_b32_e32 v234, 15, v170
	v_lshl_add_u32 v171, v171, 6, v234
	s_lshl_b32 s98, s61, 8
	v_add_u32_e32 v171, s98, v171
	v_mfma_f32_16x16x32_bf16 v[56:59], v[160:163], v[192:195], v[56:59]
	v_mul_lo_u32 v171, v171, s28
	v_bfe_u32 v234, v170, 6, 2
	v_bfe_u32 v224, v170, 4, 2
	v_lshlrev_b32_e32 v234, 5, v234
	v_lshl_or_b32 v234, v224, 3, v234
	v_mfma_f32_16x16x32_bf16 v[44:47], v[152:155], v[200:203], v[44:47]
	s_lshl_b32 s98, s60, 8
	v_add_u32_e32 v234, s98, v234
	v_add_lshl_u32 v232, v171, v234, 1
	v_mov_b32_e32 v233, 0
	v_lshl_add_u64 v[232:233], v[232:233], 0, s[30:31]
	v_mfma_f32_16x16x32_bf16 v[40:43], v[160:163], v[200:203], v[40:43]
	s_lshl_b32 s98, s28, 5
	s_mov_b32 s99, 0
	v_mul_f32_e32 v124, v172, v124
	v_mul_f32_e32 v125, v172, v125
	v_mul_f32_e32 v126, v172, v126
	v_mfma_f32_16x16x32_bf16 v[28:31], v[152:155], v[208:211], v[28:31]
	v_mul_f32_e32 v127, v172, v127
	v_mul_f32_e32 v120, v172, v120
	v_mul_f32_e32 v121, v172, v121
	v_mul_f32_e32 v122, v172, v122
	v_mul_f32_e32 v123, v172, v123
	v_mfma_f32_16x16x32_bf16 v[24:27], v[160:163], v[208:211], v[24:27]
	v_cvt_pk_bf16_f32 v124, v124, v125
	v_cvt_pk_bf16_f32 v125, v126, v127
	v_cvt_pk_bf16_f32 v126, v120, v121
	v_cvt_pk_bf16_f32 v127, v122, v123
	global_store_dwordx4 v[232:233], v[124:127], off
	v_mfma_f32_16x16x32_bf16 v[12:15], v[152:155], v[216:219], v[12:15]
	v_mul_f32_e32 v116, v172, v116
	v_mul_f32_e32 v117, v172, v117
	v_mul_f32_e32 v118, v172, v118
	v_mul_f32_e32 v119, v172, v119
	v_mul_f32_e32 v112, v172, v112
	v_mfma_f32_16x16x32_bf16 v[8:11], v[160:163], v[216:219], v[8:11]
	v_mul_f32_e32 v113, v172, v113
	v_mul_f32_e32 v114, v172, v114
	v_mul_f32_e32 v115, v172, v115
	v_cvt_pk_bf16_f32 v116, v116, v117
	v_cvt_pk_bf16_f32 v117, v118, v119
	v_mfma_f32_16x16x32_bf16 v[60:63], v[156:159], v[196:199], v[60:63]
	v_cvt_pk_bf16_f32 v118, v112, v113
	v_cvt_pk_bf16_f32 v119, v114, v115
	global_store_dwordx4 v[232:233], v[116:119], off offset:256
	v_lshl_add_u64 v[232:233], v[232:233], 0, s[98:99]
	v_mul_f32_e32 v108, v173, v108
	v_mfma_f32_16x16x32_bf16 v[56:59], v[164:167], v[196:199], v[56:59]
	v_mul_f32_e32 v109, v173, v109
	v_mul_f32_e32 v110, v173, v110
	v_mul_f32_e32 v111, v173, v111
	v_mul_f32_e32 v104, v173, v104
	v_mul_f32_e32 v105, v173, v105
	v_mfma_f32_16x16x32_bf16 v[44:47], v[156:159], v[204:207], v[44:47]
	v_mul_f32_e32 v106, v173, v106
	v_mul_f32_e32 v107, v173, v107
	v_cvt_pk_bf16_f32 v108, v108, v109
	v_cvt_pk_bf16_f32 v109, v110, v111
	v_cvt_pk_bf16_f32 v110, v104, v105
	v_mfma_f32_16x16x32_bf16 v[40:43], v[164:167], v[204:207], v[40:43]
	v_cvt_pk_bf16_f32 v111, v106, v107
	global_store_dwordx4 v[232:233], v[108:111], off
	v_mul_f32_e32 v100, v173, v100
	v_mul_f32_e32 v101, v173, v101
	v_mul_f32_e32 v102, v173, v102
	v_mfma_f32_16x16x32_bf16 v[28:31], v[156:159], v[212:215], v[28:31]
	v_mul_f32_e32 v103, v173, v103
	v_mul_f32_e32 v96, v173, v96
	v_mul_f32_e32 v97, v173, v97
	v_mul_f32_e32 v98, v173, v98
	v_mul_f32_e32 v99, v173, v99
	v_mfma_f32_16x16x32_bf16 v[24:27], v[164:167], v[212:215], v[24:27]
	v_cvt_pk_bf16_f32 v100, v100, v101
	v_cvt_pk_bf16_f32 v101, v102, v103
	v_cvt_pk_bf16_f32 v102, v96, v97
	v_cvt_pk_bf16_f32 v103, v98, v99
	global_store_dwordx4 v[232:233], v[100:103], off offset:256
	v_mfma_f32_16x16x32_bf16 v[12:15], v[156:159], v[240:243], v[12:15]
	v_lshl_add_u64 v[232:233], v[232:233], 0, s[98:99]
	v_mul_f32_e32 v92, v236, v92
	v_mul_f32_e32 v93, v236, v93
	v_mul_f32_e32 v94, v236, v94
	v_mul_f32_e32 v95, v236, v95
	v_mfma_f32_16x16x32_bf16 v[8:11], v[164:167], v[240:243], v[8:11]
	v_mul_f32_e32 v88, v236, v88
	v_mul_f32_e32 v89, v236, v89
	v_mul_f32_e32 v90, v236, v90
	v_mul_f32_e32 v91, v236, v91
	v_cvt_pk_bf16_f32 v92, v92, v93
	v_mfma_f32_16x16x32_bf16 v[52:55], v[176:179], v[192:195], v[52:55]
	v_cvt_pk_bf16_f32 v93, v94, v95
	v_cvt_pk_bf16_f32 v94, v88, v89
	v_cvt_pk_bf16_f32 v95, v90, v91
	global_store_dwordx4 v[232:233], v[92:95], off
	v_mul_f32_e32 v84, v236, v84
	v_mfma_f32_16x16x32_bf16 v[48:51], v[184:187], v[192:195], v[48:51]
	v_mul_f32_e32 v85, v236, v85
	v_mul_f32_e32 v86, v236, v86
	v_mul_f32_e32 v87, v236, v87
	v_mul_f32_e32 v80, v236, v80
	v_mul_f32_e32 v81, v236, v81
	v_mfma_f32_16x16x32_bf16 v[36:39], v[176:179], v[200:203], v[36:39]
	v_mul_f32_e32 v82, v236, v82
	v_mul_f32_e32 v83, v236, v83
	v_cvt_pk_bf16_f32 v84, v84, v85
	v_cvt_pk_bf16_f32 v85, v86, v87
	v_cvt_pk_bf16_f32 v86, v80, v81
	v_mfma_f32_16x16x32_bf16 v[32:35], v[184:187], v[200:203], v[32:35]
	v_cvt_pk_bf16_f32 v87, v82, v83
	global_store_dwordx4 v[232:233], v[84:87], off offset:256
	v_lshl_add_u64 v[232:233], v[232:233], 0, s[98:99]
	v_mul_f32_e32 v76, v237, v76
	v_mul_f32_e32 v77, v237, v77
	v_mfma_f32_16x16x32_bf16 v[20:23], v[176:179], v[208:211], v[20:23]
	v_mul_f32_e32 v78, v237, v78
	v_mul_f32_e32 v79, v237, v79
	v_mul_f32_e32 v72, v237, v72
	v_mul_f32_e32 v73, v237, v73
	v_mul_f32_e32 v74, v237, v74
	v_mfma_f32_16x16x32_bf16 v[16:19], v[184:187], v[208:211], v[16:19]
	v_mul_f32_e32 v75, v237, v75
	v_cvt_pk_bf16_f32 v76, v76, v77
	v_cvt_pk_bf16_f32 v77, v78, v79
	v_cvt_pk_bf16_f32 v78, v72, v73
	v_cvt_pk_bf16_f32 v79, v74, v75
	v_mfma_f32_16x16x32_bf16 v[4:7], v[176:179], v[216:219], v[4:7]
	global_store_dwordx4 v[232:233], v[76:79], off
	v_mul_f32_e32 v68, v237, v68
	v_mul_f32_e32 v69, v237, v69
	v_mul_f32_e32 v70, v237, v70
	v_mul_f32_e32 v71, v237, v71
	v_mfma_f32_16x16x32_bf16 v[0:3], v[184:187], v[216:219], v[0:3]
	v_mul_f32_e32 v64, v237, v64
	v_mul_f32_e32 v65, v237, v65
	v_mul_f32_e32 v66, v237, v66
	v_mul_f32_e32 v67, v237, v67
	v_cvt_pk_bf16_f32 v68, v68, v69
	v_mfma_f32_16x16x32_bf16 v[52:55], v[180:183], v[196:199], v[52:55]
	v_cvt_pk_bf16_f32 v69, v70, v71
	v_cvt_pk_bf16_f32 v70, v64, v65
	v_cvt_pk_bf16_f32 v71, v66, v67
	global_store_dwordx4 v[232:233], v[68:71], off offset:256
	v_lshl_add_u64 v[232:233], v[232:233], 0, s[98:99]
	v_mfma_f32_16x16x32_bf16 v[48:51], v[188:191], v[196:199], v[48:51]
	v_lshl_add_u64 v[232:233], v[232:233], 0, s[98:99]
	v_lshl_add_u64 v[232:233], v[232:233], 0, s[98:99]
	v_lshl_add_u64 v[232:233], v[232:233], 0, s[98:99]
	v_lshl_add_u64 v[232:233], v[232:233], 0, s[98:99]
	v_mfma_f32_16x16x32_bf16 v[36:39], v[180:183], v[204:207], v[36:39]
	v_mfma_f32_16x16x32_bf16 v[32:35], v[188:191], v[204:207], v[32:35]
	v_mfma_f32_16x16x32_bf16 v[20:23], v[180:183], v[212:215], v[20:23]
	v_mfma_f32_16x16x32_bf16 v[16:19], v[188:191], v[212:215], v[16:19]
	v_mfma_f32_16x16x32_bf16 v[4:7], v[180:183], v[240:243], v[4:7]
	v_mfma_f32_16x16x32_bf16 v[0:3], v[188:191], v[240:243], v[0:3]
	s_barrier
	v_lshl_add_u64 v[142:143], v[142:143], 0, s[80:81]
	v_lshl_add_u64 v[144:145], v[144:145], 0, s[80:81]
	s_and_b64 vcc, exec, s[8:9]
	s_cbranch_vccnz .Lq5_notdefer
	s_cmp_lg_u32 s59, s61
	s_cbranch_scc1 .Lq5_notdefer
	s_mov_b32 s101, 1
	s_mov_b32 s60, s58
	s_mov_b32 s61, s59
	v_mov_b64_e32 v[144:145], v[140:141]
	v_mov_b64_e32 v[142:143], v[138:139]
	s_branch .LBB0_346

; #define PG8_STAGE(bufoff, gbase, voff) do { _Pragma("unroll") for (int _i = 0; _i < 2; ++_i) \
;         __builtin_amdgcn_global_load_lds((const unsigned*)((const char*)(gbase) + (voff)[_i]), (LAS unsigned*)(lds + (bufoff) + ldsw + _i * 8192), 16, 0, 0); } while (0)
; #define PG8_LDA(dst, b, h) do { _Pragma("unroll") for (int m = 0; m < 4; ++m) _Pragma("unroll") for (int k = 0; k < 2; ++k) dst[m][k] = *(const LAS bf16x8*)(lds + PG8_SA(b, h) + aoff + m * 2048 + k * 1024); } while (0)
; #define PG8_LDB(dst, b, h) do { _Pragma("unroll") for (int n = 0; n < 2; ++n) _Pragma("unroll") for (int k = 0; k < 2; ++k) dst[n][k] = *(const LAS bf16x8*)(lds + PG8_SB(b, h) + boff + n * 2048 + k * 1024); } while (0)
; #define PG8_MMA(ai, bj, At, Bt) do { __builtin_amdgcn_s_setprio(1); _Pragma("unroll") for (int k = 0; k < 2; ++k) _Pragma("unroll") for (int m = 0; m < 4; ++m) _Pragma("unroll") for (int n = 0; n < 2; ++n) \
;         acc[ai][bj][m][n] = __builtin_amdgcn_mfma_f32_16x16x32_bf16(Bt[n][k], At[m][k], acc[ai][bj][m][n], 0, 0, 0); __builtin_amdgcn_s_setprio(0); } while (0)
; template <class Epi, bool ALIGN_EPI>
; __device__ __forceinline__ void gemm_phase(LAS unsigned char* lds, const Gemm g, const StaticOrder& S, const Epi& E, const int tid) {
;     ...
;         const bool has_next = S.next(ui + 1, nxt);
;         const char* nA = has_next ? (const char*)g.A + (size_t)nxt.pm * tA + (size_t)nxt.pn * g.apn * 2 : cA; const char* nB = has_next ? (const char*)g.Bt + (size_t)nxt.pn * tB : cB;
;         for (int t = 0; t < nt; t += 2) {
;             const bool last = (t == nt - 2);
;             const char* a1 = cA + (size_t)(t + 1) * kstep;
;             const char* a2 = last ? nA : cA + (size_t)(t + 2) * kstep; const char* b2 = last ? nB : cB + (size_t)(t + 2) * kstep;
;             const char* a3 = a2 + kstep; const char* b3 = b2 + kstep;
;             PG8_LDB(B0, 0, 0); PG8_LDB(B1, 0, 1); PG8_SCHED; PG8_LDA(At, 0, 0); PG8_STAGE(PG8_SA(1, 1), a1 + hA, voffA);
;             PG8_WAIT_V(8); PG8_WAIT_L(0); PG8_BAR; PG8_MMA(0, 0, At, B0); PG8_MMA(0, 1, At, B1); PG8_BAR; PG8_SCHED;
;             PG8_LDA(At, 0, 1); PG8_STAGE(PG8_SB(0, 0), b2, voffB); PG8_STAGE(PG8_SB(0, 1), b2 + hB, voffB); PG8_STAGE(PG8_SA(0, 0), a2, voffA);
;             PG8_WAIT_V(8); PG8_WAIT_L(0); PG8_BAR; PG8_MMA(1, 0, At, B0); PG8_MMA(1, 1, At, B1); PG8_BAR; PG8_SCHED;
.LBB0_378:
	s_ashr_i32 s17, s16, 31
	s_lshl_b64 s[22:23], s[16:17], 17
	s_add_u32 s22, s4, s22
	s_addc_u32 s23, s5, s23
	s_and_b64 s[26:27], s[8:9], exec
	s_cselect_b32 s17, s23, s35
	s_cselect_b32 s59, s22, s34
	s_ashr_i32 s15, s14, 31
	s_lshl_b64 s[26:27], s[14:15], 17
	s_add_u32 s26, s7, s26
	s_addc_u32 s27, s25, s27
	s_and_b64 s[36:37], s[8:9], exec
	s_cselect_b32 s15, s27, s31
	s_cselect_b32 s60, s26, s30
	s_mov_b32 s40, 0
	s_mov_b64 s[36:37], -1
	s_mov_b64 s[38:39], 0
	s_add_u32 s41, s34, s40
	s_addc_u32 s46, s35, 0
	s_add_u32 s44, s41, 0x100
	s_addc_u32 s45, s46, 0
	s_and_b64 s[42:43], s[38:39], exec
	s_cselect_b32 s43, s17, s45
	s_cselect_b32 s42, s59, s44
	s_add_u32 s40, s30, s40
	s_addc_u32 s44, s31, 0
	s_add_u32 s40, s40, 0x100
	s_addc_u32 s44, s44, 0
	s_and_b64 s[38:39], s[38:39], exec
	s_cselect_b32 s45, s15, s44
	s_cselect_b32 s44, s60, s40
	s_add_i32 s39, 0, 0x14000
	s_add_u32 s48, s41, 0x10080
	s_addc_u32 s49, s46, 0
	s_add_i32 s68, s33, s50
	s_add_i32 m0, s51, 0xc000
	s_add_i32 s71, s51, 0xe000
	s_add_i32 s65, s68, 0x2000
	v_add_u32_e32 v138, s33, v141
	s_add_u32 s46, s44, 0x10000
	ds_read_b128 v[134:137], v138
	ds_read_b128 v[146:149], v138 offset:1024
	ds_read_b128 v[150:153], v138 offset:2048
	ds_read_b128 v[154:157], v138 offset:3072
	v_add_u32_e32 v138, s39, v141
	s_addc_u32 s47, s45, 0
	s_add_i32 s67, s39, s50
	ds_read_b128 v[158:161], v138
	ds_read_b128 v[162:165], v138 offset:1024
	ds_read_b128 v[174:177], v138 offset:2048
	ds_read_b128 v[178:181], v138 offset:3072
	s_add_i32 s66, s67, 0x2000
	s_add_i32 s64, 0, 0x18000
	s_add_i32 s63, 0, 0x1c000
	s_add_u32 s40, s42, 0x10000
	s_addc_u32 s41, s43, 0
	s_add_i32 s62, s64, s50
	s_add_i32 s61, s62, 0x2000
	s_add_u32 s38, s44, 0x10080
	s_addc_u32 s39, s45, 0
	s_add_i32 s70, s63, s50
	s_add_i32 s69, s70, 0x2000
	v_lshl_add_u64 v[138:139], s[48:49], 0, v[128:129]
	ds_read_b128 v[182:185], v145
	ds_read_b128 v[186:189], v145 offset:1024
	ds_read_b128 v[190:193], v145 offset:2048
	ds_read_b128 v[194:197], v145 offset:3072
	ds_read_b128 v[198:201], v145 offset:4096
	ds_read_b128 v[202:205], v145 offset:5120
	ds_read_b128 v[206:209], v145 offset:6144
	ds_read_b128 v[210:213], v145 offset:7168
	global_load_lds_dwordx4 v[138:139], off
	v_lshl_add_u64 v[138:139], s[48:49], 0, v[130:131]
	s_mov_b32 m0, s71
	s_nop 0
	global_load_lds_dwordx4 v[138:139], off
	s_waitcnt vmcnt(8)
	s_waitcnt lgkmcnt(0)
	s_barrier
	s_waitcnt lgkmcnt(0)
	v_mfma_f32_16x16x32_bf16 v[124:127], v[134:137], v[182:185], 0
	v_mfma_f32_16x16x32_bf16 v[120:123], v[150:153], v[182:185], 0
	v_mfma_f32_16x16x32_bf16 v[108:111], v[134:137], v[190:193], 0
	v_mfma_f32_16x16x32_bf16 v[104:107], v[150:153], v[190:193], 0
	v_mfma_f32_16x16x32_bf16 v[92:95], v[134:137], v[198:201], 0
	v_mfma_f32_16x16x32_bf16 v[88:91], v[150:153], v[198:201], 0
	v_mfma_f32_16x16x32_bf16 v[76:79], v[134:137], v[206:209], 0
	v_mfma_f32_16x16x32_bf16 v[72:75], v[150:153], v[206:209], 0
	v_mfma_f32_16x16x32_bf16 v[124:127], v[146:149], v[186:189], v[124:127]
	v_mfma_f32_16x16x32_bf16 v[120:123], v[154:157], v[186:189], v[120:123]
	v_mfma_f32_16x16x32_bf16 v[108:111], v[146:149], v[194:197], v[108:111]
	v_mfma_f32_16x16x32_bf16 v[104:107], v[154:157], v[194:197], v[104:107]
	v_mfma_f32_16x16x32_bf16 v[92:95], v[146:149], v[202:205], v[92:95]
	v_mfma_f32_16x16x32_bf16 v[88:91], v[154:157], v[202:205], v[88:91]
	v_mfma_f32_16x16x32_bf16 v[76:79], v[146:149], v[210:213], v[76:79]
	v_mfma_f32_16x16x32_bf16 v[72:75], v[154:157], v[210:213], v[72:75]
	v_mfma_f32_16x16x32_bf16 v[116:119], v[158:161], v[182:185], 0
	v_mfma_f32_16x16x32_bf16 v[112:115], v[174:177], v[182:185], 0
	v_mfma_f32_16x16x32_bf16 v[100:103], v[158:161], v[190:193], 0
	v_mfma_f32_16x16x32_bf16 v[96:99], v[174:177], v[190:193], 0
	v_mfma_f32_16x16x32_bf16 v[84:87], v[158:161], v[198:201], 0
	v_mfma_f32_16x16x32_bf16 v[80:83], v[174:177], v[198:201], 0
	v_mfma_f32_16x16x32_bf16 v[68:71], v[158:161], v[206:209], 0
	v_mfma_f32_16x16x32_bf16 v[64:67], v[174:177], v[206:209], 0
	v_mfma_f32_16x16x32_bf16 v[116:119], v[162:165], v[186:189], v[116:119]
	v_mfma_f32_16x16x32_bf16 v[112:115], v[178:181], v[186:189], v[112:115]
	v_mfma_f32_16x16x32_bf16 v[100:103], v[162:165], v[194:197], v[100:103]
	v_mfma_f32_16x16x32_bf16 v[96:99], v[178:181], v[194:197], v[96:99]
	v_mfma_f32_16x16x32_bf16 v[84:87], v[162:165], v[202:205], v[84:87]
	v_mfma_f32_16x16x32_bf16 v[80:83], v[178:181], v[202:205], v[80:83]
	v_mfma_f32_16x16x32_bf16 v[68:71], v[162:165], v[210:213], v[68:71]
	v_mfma_f32_16x16x32_bf16 v[64:67], v[178:181], v[210:213], v[64:67]
	s_barrier
	s_mov_b32 m0, s68
	v_lshl_add_u64 v[138:139], s[44:45], 0, v[168:169]
	ds_read_b128 v[182:185], v145 offset:16384
	ds_read_b128 v[186:189], v145 offset:17408
	ds_read_b128 v[190:193], v145 offset:18432
	ds_read_b128 v[194:197], v145 offset:19456
	ds_read_b128 v[198:201], v145 offset:20480
	ds_read_b128 v[202:205], v145 offset:21504
	ds_read_b128 v[206:209], v145 offset:22528
	ds_read_b128 v[210:213], v145 offset:23552
	global_load_lds_dwordx4 v[138:139], off
	v_lshl_add_u64 v[142:143], s[44:45], 0, v[132:133]
	s_mov_b32 m0, s65
	v_lshl_add_u64 v[166:167], s[46:47], 0, v[168:169]
	global_load_lds_dwordx4 v[142:143], off
	s_mov_b32 m0, s67
	v_lshl_add_u64 v[214:215], s[42:43], 0, v[130:131]
	global_load_lds_dwordx4 v[166:167], off
	v_lshl_add_u64 v[166:167], s[46:47], 0, v[132:133]
	s_mov_b32 m0, s66
	s_nop 0
	global_load_lds_dwordx4 v[166:167], off
	v_lshl_add_u64 v[166:167], s[42:43], 0, v[128:129]
	s_mov_b32 m0, s51
	s_nop 0
	global_load_lds_dwordx4 v[166:167], off
	s_mov_b32 m0, s52
	s_nop 0
	global_load_lds_dwordx4 v[214:215], off
	s_waitcnt vmcnt(8)
	s_waitcnt lgkmcnt(0)
	s_barrier
; #define PG8_STAGE(bufoff, gbase, voff) do { _Pragma("unroll") for (int _i = 0; _i < 2; ++_i) \
;         __builtin_amdgcn_global_load_lds((const unsigned*)((const char*)(gbase) + (voff)[_i]), (LAS unsigned*)(lds + (bufoff) + ldsw + _i * 8192), 16, 0, 0); } while (0)
; #define PG8_LDA(dst, b, h) do { _Pragma("unroll") for (int m = 0; m < 4; ++m) _Pragma("unroll") for (int k = 0; k < 2; ++k) dst[m][k] = *(const LAS bf16x8*)(lds + PG8_SA(b, h) + aoff + m * 2048 + k * 1024); } while (0)
; #define PG8_LDB(dst, b, h) do { _Pragma("unroll") for (int n = 0; n < 2; ++n) _Pragma("unroll") for (int k = 0; k < 2; ++k) dst[n][k] = *(const LAS bf16x8*)(lds + PG8_SB(b, h) + boff + n * 2048 + k * 1024); } while (0)
; #define PG8_MMA(ai, bj, At, Bt) do { __builtin_amdgcn_s_setprio(1); _Pragma("unroll") for (int k = 0; k < 2; ++k) _Pragma("unroll") for (int m = 0; m < 4; ++m) _Pragma("unroll") for (int n = 0; n < 2; ++n) \
;         acc[ai][bj][m][n] = __builtin_amdgcn_mfma_f32_16x16x32_bf16(Bt[n][k], At[m][k], acc[ai][bj][m][n], 0, 0, 0); __builtin_amdgcn_s_setprio(0); } while (0)
; #define PG8_WAIT_V(n) asm volatile("s_waitcnt vmcnt(" #n ")" ::: "memory")
; #define PG8_WAIT_L(n) asm volatile("s_waitcnt lgkmcnt(" #n ")" ::: "memory")
; #define PG8_BAR __builtin_amdgcn_s_barrier()
; #define PG8_SCHED __builtin_amdgcn_sched_barrier(0)
; template <class Epi, bool ALIGN_EPI>
; __device__ __forceinline__ void gemm_phase(LAS unsigned char* lds, const Gemm g, const StaticOrder& S, const Epi& E, const int tid) {
;     ...
;             PG8_WAIT_V(8); PG8_WAIT_L(0); PG8_BAR; PG8_MMA(1, 0, At, B0); PG8_MMA(1, 1, At, B1); PG8_BAR; PG8_SCHED;
;             PG8_LDB(B0, 1, 0); PG8_LDB(B1, 1, 1); PG8_SCHED; PG8_LDA(At, 1, 0); PG8_STAGE(PG8_SA(0, 1), a2 + hA, voffA);
;             PG8_WAIT_V(8); PG8_WAIT_L(0); PG8_BAR; PG8_MMA(0, 0, At, B0); PG8_MMA(0, 1, At, B1); PG8_BAR; PG8_SCHED;
	s_waitcnt lgkmcnt(0)
	v_mfma_f32_16x16x32_bf16 v[60:63], v[134:137], v[182:185], 0
	v_mfma_f32_16x16x32_bf16 v[56:59], v[150:153], v[182:185], 0
	v_mfma_f32_16x16x32_bf16 v[48:51], v[134:137], v[190:193], 0
	v_mfma_f32_16x16x32_bf16 v[40:43], v[150:153], v[190:193], 0
	v_mfma_f32_16x16x32_bf16 v[32:35], v[134:137], v[198:201], 0
	v_mfma_f32_16x16x32_bf16 v[24:27], v[150:153], v[198:201], 0
	v_mfma_f32_16x16x32_bf16 v[16:19], v[134:137], v[206:209], 0
	v_mfma_f32_16x16x32_bf16 v[8:11], v[150:153], v[206:209], 0
	v_mfma_f32_16x16x32_bf16 v[60:63], v[146:149], v[186:189], v[60:63]
	v_mfma_f32_16x16x32_bf16 v[56:59], v[154:157], v[186:189], v[56:59]
	v_mfma_f32_16x16x32_bf16 v[48:51], v[146:149], v[194:197], v[48:51]
	v_mfma_f32_16x16x32_bf16 v[40:43], v[154:157], v[194:197], v[40:43]
	v_mfma_f32_16x16x32_bf16 v[32:35], v[146:149], v[202:205], v[32:35]
	v_mfma_f32_16x16x32_bf16 v[24:27], v[154:157], v[202:205], v[24:27]
	v_mfma_f32_16x16x32_bf16 v[16:19], v[146:149], v[210:213], v[16:19]
	v_mfma_f32_16x16x32_bf16 v[8:11], v[154:157], v[210:213], v[8:11]
	v_mfma_f32_16x16x32_bf16 v[52:55], v[158:161], v[182:185], 0
	v_mfma_f32_16x16x32_bf16 v[44:47], v[174:177], v[182:185], 0
	v_mfma_f32_16x16x32_bf16 v[36:39], v[158:161], v[190:193], 0
	v_mfma_f32_16x16x32_bf16 v[28:31], v[174:177], v[190:193], 0
	v_mfma_f32_16x16x32_bf16 v[20:23], v[158:161], v[198:201], 0
	v_mfma_f32_16x16x32_bf16 v[12:15], v[174:177], v[198:201], 0
	v_mfma_f32_16x16x32_bf16 v[4:7], v[158:161], v[206:209], 0
	v_mfma_f32_16x16x32_bf16 v[0:3], v[174:177], v[206:209], 0
	v_mfma_f32_16x16x32_bf16 v[52:55], v[162:165], v[186:189], v[52:55]
	v_mfma_f32_16x16x32_bf16 v[44:47], v[178:181], v[186:189], v[44:47]
	v_mfma_f32_16x16x32_bf16 v[36:39], v[162:165], v[194:197], v[36:39]
	v_mfma_f32_16x16x32_bf16 v[28:31], v[178:181], v[194:197], v[28:31]
	v_mfma_f32_16x16x32_bf16 v[20:23], v[162:165], v[202:205], v[20:23]
	v_mfma_f32_16x16x32_bf16 v[12:15], v[178:181], v[202:205], v[12:15]
	v_mfma_f32_16x16x32_bf16 v[4:7], v[162:165], v[210:213], v[4:7]
	v_mfma_f32_16x16x32_bf16 v[0:3], v[178:181], v[210:213], v[0:3]
	s_barrier
	v_add_u32_e32 v140, s64, v141
	ds_read_b128 v[134:137], v140
	ds_read_b128 v[146:149], v140 offset:1024
	ds_read_b128 v[150:153], v140 offset:2048
	ds_read_b128 v[154:157], v140 offset:3072
	v_add_u32_e32 v140, s63, v141
	ds_read_b128 v[158:161], v140
	ds_read_b128 v[162:165], v140 offset:1024
	ds_read_b128 v[174:177], v140 offset:2048
	ds_read_b128 v[178:181], v140 offset:3072
	s_mov_b32 m0, s53
	v_lshl_add_u64 v[216:217], s[40:41], 0, v[128:129]
	ds_read_b128 v[182:185], v145 offset:32768
	ds_read_b128 v[186:189], v145 offset:33792
	ds_read_b128 v[190:193], v145 offset:34816
	ds_read_b128 v[194:197], v145 offset:35840
	ds_read_b128 v[198:201], v145 offset:36864
	ds_read_b128 v[202:205], v145 offset:37888
	ds_read_b128 v[206:209], v145 offset:38912
	ds_read_b128 v[210:213], v145 offset:39936
	global_load_lds_dwordx4 v[216:217], off
	v_lshl_add_u64 v[216:217], s[40:41], 0, v[130:131]
	s_mov_b32 m0, s54
	s_nop 0
	global_load_lds_dwordx4 v[216:217], off
	s_waitcnt vmcnt(8)
	s_waitcnt lgkmcnt(0)
	s_barrier
	s_waitcnt lgkmcnt(0)
	v_mfma_f32_16x16x32_bf16 v[124:127], v[134:137], v[182:185], v[124:127]
	v_mfma_f32_16x16x32_bf16 v[120:123], v[150:153], v[182:185], v[120:123]
	v_mfma_f32_16x16x32_bf16 v[108:111], v[134:137], v[190:193], v[108:111]
	v_mfma_f32_16x16x32_bf16 v[104:107], v[150:153], v[190:193], v[104:107]
	v_mfma_f32_16x16x32_bf16 v[92:95], v[134:137], v[198:201], v[92:95]
	v_mfma_f32_16x16x32_bf16 v[88:91], v[150:153], v[198:201], v[88:91]
	v_mfma_f32_16x16x32_bf16 v[76:79], v[134:137], v[206:209], v[76:79]
	v_mfma_f32_16x16x32_bf16 v[72:75], v[150:153], v[206:209], v[72:75]
	v_mfma_f32_16x16x32_bf16 v[124:127], v[146:149], v[186:189], v[124:127]
	v_mfma_f32_16x16x32_bf16 v[120:123], v[154:157], v[186:189], v[120:123]
	v_mfma_f32_16x16x32_bf16 v[108:111], v[146:149], v[194:197], v[108:111]
	v_mfma_f32_16x16x32_bf16 v[104:107], v[154:157], v[194:197], v[104:107]
	v_mfma_f32_16x16x32_bf16 v[92:95], v[146:149], v[202:205], v[92:95]
	v_mfma_f32_16x16x32_bf16 v[88:91], v[154:157], v[202:205], v[88:91]
	v_mfma_f32_16x16x32_bf16 v[76:79], v[146:149], v[210:213], v[76:79]
	v_mfma_f32_16x16x32_bf16 v[72:75], v[154:157], v[210:213], v[72:75]
	v_mfma_f32_16x16x32_bf16 v[116:119], v[158:161], v[182:185], v[116:119]
	v_mfma_f32_16x16x32_bf16 v[112:115], v[174:177], v[182:185], v[112:115]
	v_mfma_f32_16x16x32_bf16 v[100:103], v[158:161], v[190:193], v[100:103]
	v_mfma_f32_16x16x32_bf16 v[96:99], v[174:177], v[190:193], v[96:99]
	v_mfma_f32_16x16x32_bf16 v[84:87], v[158:161], v[198:201], v[84:87]
	v_mfma_f32_16x16x32_bf16 v[80:83], v[174:177], v[198:201], v[80:83]
	v_mfma_f32_16x16x32_bf16 v[68:71], v[158:161], v[206:209], v[68:71]
	v_mfma_f32_16x16x32_bf16 v[64:67], v[174:177], v[206:209], v[64:67]
	v_mfma_f32_16x16x32_bf16 v[116:119], v[162:165], v[186:189], v[116:119]
	v_mfma_f32_16x16x32_bf16 v[112:115], v[178:181], v[186:189], v[112:115]
	v_mfma_f32_16x16x32_bf16 v[100:103], v[162:165], v[194:197], v[100:103]
	v_mfma_f32_16x16x32_bf16 v[96:99], v[178:181], v[194:197], v[96:99]
	v_mfma_f32_16x16x32_bf16 v[84:87], v[162:165], v[202:205], v[84:87]
	v_mfma_f32_16x16x32_bf16 v[80:83], v[178:181], v[202:205], v[80:83]
	v_mfma_f32_16x16x32_bf16 v[68:71], v[162:165], v[210:213], v[68:71]
	v_mfma_f32_16x16x32_bf16 v[64:67], v[178:181], v[210:213], v[64:67]
	s_barrier
; #define PG8_STAGE(bufoff, gbase, voff) do { _Pragma("unroll") for (int _i = 0; _i < 2; ++_i) \
;         __builtin_amdgcn_global_load_lds((const unsigned*)((const char*)(gbase) + (voff)[_i]), (LAS unsigned*)(lds + (bufoff) + ldsw + _i * 8192), 16, 0, 0); } while (0)
; #define PG8_LDA(dst, b, h) do { _Pragma("unroll") for (int m = 0; m < 4; ++m) _Pragma("unroll") for (int k = 0; k < 2; ++k) dst[m][k] = *(const LAS bf16x8*)(lds + PG8_SA(b, h) + aoff + m * 2048 + k * 1024); } while (0)
; #define PG8_LDB(dst, b, h) do { _Pragma("unroll") for (int n = 0; n < 2; ++n) _Pragma("unroll") for (int k = 0; k < 2; ++k) dst[n][k] = *(const LAS bf16x8*)(lds + PG8_SB(b, h) + boff + n * 2048 + k * 1024); } while (0)
; #define PG8_WAIT_V(n) asm volatile("s_waitcnt vmcnt(" #n ")" ::: "memory")
; #define PG8_BAR __builtin_amdgcn_s_barrier()
; template <class Epi, bool ALIGN_EPI>
; __device__ __forceinline__ void gemm_phase(LAS unsigned char* lds, const Gemm g, const StaticOrder& S, const Epi& E, const int tid) {
;     ...
;         for (int t = 0; t < nt; t += 2) {
;             const bool last = (t == nt - 2);
;             const char* a1 = cA + (size_t)(t + 1) * kstep;
;             const char* a2 = last ? nA : cA + (size_t)(t + 2) * kstep; const char* b2 = last ? nB : cB + (size_t)(t + 2) * kstep;
;             const char* a3 = a2 + kstep; const char* b3 = b2 + kstep;
;             PG8_LDB(B0, 0, 0); PG8_LDB(B1, 0, 1); PG8_SCHED; PG8_LDA(At, 0, 0); PG8_STAGE(PG8_SA(1, 1), a1 + hA, voffA);
;             PG8_WAIT_V(8); PG8_WAIT_L(0); PG8_BAR; PG8_MMA(0, 0, At, B0); PG8_MMA(0, 1, At, B1); PG8_BAR; PG8_SCHED;
;             PG8_LDA(At, 0, 1); PG8_STAGE(PG8_SB(0, 0), b2, voffB); PG8_STAGE(PG8_SB(0, 1), b2 + hB, voffB); PG8_STAGE(PG8_SA(0, 0), a2, voffA);
;             PG8_WAIT_V(8); PG8_WAIT_L(0); PG8_BAR; PG8_MMA(1, 0, At, B0); PG8_MMA(1, 1, At, B1); PG8_BAR; PG8_SCHED;
;             PG8_LDB(B0, 1, 0); PG8_LDB(B1, 1, 1); PG8_SCHED; PG8_LDA(At, 1, 0); PG8_STAGE(PG8_SA(0, 1), a2 + hA, voffA);
;             PG8_WAIT_V(8); PG8_WAIT_L(0); PG8_BAR; PG8_MMA(0, 0, At, B0); PG8_MMA(0, 1, At, B1); PG8_BAR; PG8_SCHED;
;             PG8_LDA(At, 1, 1); PG8_STAGE(PG8_SB(1, 0), b3, voffB); PG8_STAGE(PG8_SB(1, 1), b3 + hB, voffB); PG8_STAGE(PG8_SA(1, 0), a3, voffA);
;             PG8_WAIT_V(8); PG8_WAIT_L(0); PG8_BAR; PG8_MMA(1, 0, At, B0); PG8_MMA(1, 1, At, B1); PG8_BAR; PG8_SCHED;
	s_mov_b32 m0, s62
	v_lshl_add_u64 v[138:139], v[138:139], 0, s[92:93]
	ds_read_b128 v[182:185], v145 offset:49152
	ds_read_b128 v[186:189], v145 offset:50176
	ds_read_b128 v[190:193], v145 offset:51200
	ds_read_b128 v[194:197], v145 offset:52224
	ds_read_b128 v[198:201], v145 offset:53248
	ds_read_b128 v[202:205], v145 offset:54272
	ds_read_b128 v[206:209], v145 offset:55296
	ds_read_b128 v[210:213], v145 offset:56320
	global_load_lds_dwordx4 v[138:139], off
	v_lshl_add_u64 v[138:139], v[142:143], 0, s[92:93]
	s_mov_b32 m0, s61
	s_nop 0
	global_load_lds_dwordx4 v[138:139], off
	v_lshl_add_u64 v[138:139], s[38:39], 0, v[168:169]
	s_mov_b32 m0, s70
	s_nop 0
	global_load_lds_dwordx4 v[138:139], off
	v_lshl_add_u64 v[138:139], s[38:39], 0, v[132:133]
	s_mov_b32 m0, s69
	s_nop 0
	global_load_lds_dwordx4 v[138:139], off
	v_lshl_add_u64 v[138:139], v[166:167], 0, s[92:93]
	s_mov_b32 m0, s55
	s_nop 0
	global_load_lds_dwordx4 v[138:139], off
	v_lshl_add_u64 v[138:139], v[214:215], 0, s[92:93]
	s_mov_b32 m0, s56
	s_nop 0
	global_load_lds_dwordx4 v[138:139], off
	s_waitcnt vmcnt(8)
	s_waitcnt lgkmcnt(0)
	s_barrier
	s_waitcnt lgkmcnt(0)
	v_mfma_f32_16x16x32_bf16 v[60:63], v[134:137], v[182:185], v[60:63]
	v_mfma_f32_16x16x32_bf16 v[56:59], v[150:153], v[182:185], v[56:59]
	v_mfma_f32_16x16x32_bf16 v[48:51], v[134:137], v[190:193], v[48:51]
	v_mfma_f32_16x16x32_bf16 v[40:43], v[150:153], v[190:193], v[40:43]
	v_mfma_f32_16x16x32_bf16 v[32:35], v[134:137], v[198:201], v[32:35]
	v_mfma_f32_16x16x32_bf16 v[24:27], v[150:153], v[198:201], v[24:27]
	v_mfma_f32_16x16x32_bf16 v[16:19], v[134:137], v[206:209], v[16:19]
	v_mfma_f32_16x16x32_bf16 v[8:11], v[150:153], v[206:209], v[8:11]
	v_mfma_f32_16x16x32_bf16 v[60:63], v[146:149], v[186:189], v[60:63]
	v_mfma_f32_16x16x32_bf16 v[56:59], v[154:157], v[186:189], v[56:59]
	v_mfma_f32_16x16x32_bf16 v[48:51], v[146:149], v[194:197], v[48:51]
	v_mfma_f32_16x16x32_bf16 v[40:43], v[154:157], v[194:197], v[40:43]
	v_mfma_f32_16x16x32_bf16 v[32:35], v[146:149], v[202:205], v[32:35]
	v_mfma_f32_16x16x32_bf16 v[24:27], v[154:157], v[202:205], v[24:27]
	v_mfma_f32_16x16x32_bf16 v[16:19], v[146:149], v[210:213], v[16:19]
	v_mfma_f32_16x16x32_bf16 v[8:11], v[154:157], v[210:213], v[8:11]
	v_mfma_f32_16x16x32_bf16 v[52:55], v[158:161], v[182:185], v[52:55]
	v_mfma_f32_16x16x32_bf16 v[44:47], v[174:177], v[182:185], v[44:47]
	v_mfma_f32_16x16x32_bf16 v[36:39], v[158:161], v[190:193], v[36:39]
	v_mfma_f32_16x16x32_bf16 v[28:31], v[174:177], v[190:193], v[28:31]
	v_mfma_f32_16x16x32_bf16 v[20:23], v[158:161], v[198:201], v[20:23]
	v_mfma_f32_16x16x32_bf16 v[12:15], v[174:177], v[198:201], v[12:15]
	v_mfma_f32_16x16x32_bf16 v[4:7], v[158:161], v[206:209], v[4:7]
	v_mfma_f32_16x16x32_bf16 v[0:3], v[174:177], v[206:209], v[0:3]
	v_mfma_f32_16x16x32_bf16 v[52:55], v[162:165], v[186:189], v[52:55]
	v_mfma_f32_16x16x32_bf16 v[44:47], v[178:181], v[186:189], v[44:47]
	v_mfma_f32_16x16x32_bf16 v[36:39], v[162:165], v[194:197], v[36:39]
	v_mfma_f32_16x16x32_bf16 v[28:31], v[178:181], v[194:197], v[28:31]
	v_mfma_f32_16x16x32_bf16 v[20:23], v[162:165], v[202:205], v[20:23]
	v_mfma_f32_16x16x32_bf16 v[12:15], v[178:181], v[202:205], v[12:15]
	v_mfma_f32_16x16x32_bf16 v[4:7], v[162:165], v[210:213], v[4:7]
	v_mfma_f32_16x16x32_bf16 v[0:3], v[178:181], v[210:213], v[0:3]
	s_barrier
	s_movk_i32 s40, 0x100
	s_andn2_b64 vcc, exec, s[36:37]
	s_mov_b64 s[38:39], -1
	s_mov_b64 s[36:37], 0
.LBB0_379:
	s_add_u32 s41, s34, s40
	s_addc_u32 s46, s35, 0
	s_add_u32 s44, s41, 0x100
	s_addc_u32 s45, s46, 0
	s_and_b64 s[42:43], s[38:39], exec
	s_cselect_b32 s43, s17, s45
	s_cselect_b32 s42, s59, s44
	s_add_u32 s40, s30, s40
	s_addc_u32 s44, s31, 0
	s_add_u32 s40, s40, 0x100
	s_addc_u32 s44, s44, 0
	s_and_b64 s[38:39], s[38:39], exec
	s_cselect_b32 s45, s15, s44
	s_cselect_b32 s44, s60, s40
	s_add_i32 s39, 0, 0x14000
	s_add_u32 s48, s41, 0x10080
	s_addc_u32 s49, s46, 0
	s_add_i32 s68, s33, s50
	s_add_i32 m0, s51, 0xc000
	s_add_i32 s71, s51, 0xe000
	s_add_i32 s65, s68, 0x2000
	v_add_u32_e32 v138, s33, v141
	s_add_u32 s46, s44, 0x10000
	ds_read_b128 v[134:137], v138
	ds_read_b128 v[146:149], v138 offset:1024
	ds_read_b128 v[150:153], v138 offset:2048
	ds_read_b128 v[154:157], v138 offset:3072
	v_add_u32_e32 v138, s39, v141
	s_addc_u32 s47, s45, 0
	s_add_i32 s67, s39, s50
	ds_read_b128 v[158:161], v138
	ds_read_b128 v[162:165], v138 offset:1024
	ds_read_b128 v[174:177], v138 offset:2048
	ds_read_b128 v[178:181], v138 offset:3072
	s_add_i32 s66, s67, 0x2000
	s_add_i32 s64, 0, 0x18000
	s_add_i32 s63, 0, 0x1c000
	s_add_u32 s40, s42, 0x10000
	s_addc_u32 s41, s43, 0
	s_add_i32 s62, s64, s50
	s_add_i32 s61, s62, 0x2000
	s_add_u32 s38, s44, 0x10080
	s_addc_u32 s39, s45, 0
	s_add_i32 s70, s63, s50
	s_add_i32 s69, s70, 0x2000
	v_lshl_add_u64 v[138:139], s[48:49], 0, v[128:129]
	ds_read_b128 v[182:185], v145
	ds_read_b128 v[186:189], v145 offset:1024
	ds_read_b128 v[190:193], v145 offset:2048
	ds_read_b128 v[194:197], v145 offset:3072
	ds_read_b128 v[198:201], v145 offset:4096
	ds_read_b128 v[202:205], v145 offset:5120
	ds_read_b128 v[206:209], v145 offset:6144
	ds_read_b128 v[210:213], v145 offset:7168
	global_load_lds_dwordx4 v[138:139], off
	v_lshl_add_u64 v[138:139], s[48:49], 0, v[130:131]
	s_mov_b32 m0, s71
	s_nop 0
	global_load_lds_dwordx4 v[138:139], off
	s_waitcnt vmcnt(8)
	s_waitcnt lgkmcnt(0)
	s_barrier
; #define PG8_STAGE(bufoff, gbase, voff) do { _Pragma("unroll") for (int _i = 0; _i < 2; ++_i) \
;         __builtin_amdgcn_global_load_lds((const unsigned*)((const char*)(gbase) + (voff)[_i]), (LAS unsigned*)(lds + (bufoff) + ldsw + _i * 8192), 16, 0, 0); } while (0)
; #define PG8_LDA(dst, b, h) do { _Pragma("unroll") for (int m = 0; m < 4; ++m) _Pragma("unroll") for (int k = 0; k < 2; ++k) dst[m][k] = *(const LAS bf16x8*)(lds + PG8_SA(b, h) + aoff + m * 2048 + k * 1024); } while (0)
; #define PG8_LDB(dst, b, h) do { _Pragma("unroll") for (int n = 0; n < 2; ++n) _Pragma("unroll") for (int k = 0; k < 2; ++k) dst[n][k] = *(const LAS bf16x8*)(lds + PG8_SB(b, h) + boff + n * 2048 + k * 1024); } while (0)
; #define PG8_MMA(ai, bj, At, Bt) do { __builtin_amdgcn_s_setprio(1); _Pragma("unroll") for (int k = 0; k < 2; ++k) _Pragma("unroll") for (int m = 0; m < 4; ++m) _Pragma("unroll") for (int n = 0; n < 2; ++n) \
;         acc[ai][bj][m][n] = __builtin_amdgcn_mfma_f32_16x16x32_bf16(Bt[n][k], At[m][k], acc[ai][bj][m][n], 0, 0, 0); __builtin_amdgcn_s_setprio(0); } while (0)
; #define PG8_WAIT_V(n) asm volatile("s_waitcnt vmcnt(" #n ")" ::: "memory")
; #define PG8_WAIT_L(n) asm volatile("s_waitcnt lgkmcnt(" #n ")" ::: "memory")
; #define PG8_BAR __builtin_amdgcn_s_barrier()
; #define PG8_SCHED __builtin_amdgcn_sched_barrier(0)
; template <class Epi, bool ALIGN_EPI>
; __device__ __forceinline__ void gemm_phase(LAS unsigned char* lds, const Gemm g, const StaticOrder& S, const Epi& E, const int tid) {
;     ...
;             PG8_LDB(B0, 0, 0); PG8_LDB(B1, 0, 1); PG8_SCHED; PG8_LDA(At, 0, 0); PG8_STAGE(PG8_SA(1, 1), a1 + hA, voffA);
;             PG8_WAIT_V(8); PG8_WAIT_L(0); PG8_BAR; PG8_MMA(0, 0, At, B0); PG8_MMA(0, 1, At, B1); PG8_BAR; PG8_SCHED;
;             PG8_LDA(At, 0, 1); PG8_STAGE(PG8_SB(0, 0), b2, voffB); PG8_STAGE(PG8_SB(0, 1), b2 + hB, voffB); PG8_STAGE(PG8_SA(0, 0), a2, voffA);
;             PG8_WAIT_V(8); PG8_WAIT_L(0); PG8_BAR; PG8_MMA(1, 0, At, B0); PG8_MMA(1, 1, At, B1); PG8_BAR; PG8_SCHED;
;             PG8_LDB(B0, 1, 0); PG8_LDB(B1, 1, 1); PG8_SCHED; PG8_LDA(At, 1, 0); PG8_STAGE(PG8_SA(0, 1), a2 + hA, voffA);
;             PG8_WAIT_V(8); PG8_WAIT_L(0); PG8_BAR; PG8_MMA(0, 0, At, B0); PG8_MMA(0, 1, At, B1); PG8_BAR; PG8_SCHED;
	s_waitcnt lgkmcnt(0)
	v_mfma_f32_16x16x32_bf16 v[124:127], v[134:137], v[182:185], v[124:127]
	v_mfma_f32_16x16x32_bf16 v[120:123], v[150:153], v[182:185], v[120:123]
	v_mfma_f32_16x16x32_bf16 v[108:111], v[134:137], v[190:193], v[108:111]
	v_mfma_f32_16x16x32_bf16 v[104:107], v[150:153], v[190:193], v[104:107]
	v_mfma_f32_16x16x32_bf16 v[92:95], v[134:137], v[198:201], v[92:95]
	v_mfma_f32_16x16x32_bf16 v[88:91], v[150:153], v[198:201], v[88:91]
	v_mfma_f32_16x16x32_bf16 v[76:79], v[134:137], v[206:209], v[76:79]
	v_mfma_f32_16x16x32_bf16 v[72:75], v[150:153], v[206:209], v[72:75]
	v_mfma_f32_16x16x32_bf16 v[124:127], v[146:149], v[186:189], v[124:127]
	v_mfma_f32_16x16x32_bf16 v[120:123], v[154:157], v[186:189], v[120:123]
	v_mfma_f32_16x16x32_bf16 v[108:111], v[146:149], v[194:197], v[108:111]
	v_mfma_f32_16x16x32_bf16 v[104:107], v[154:157], v[194:197], v[104:107]
	v_mfma_f32_16x16x32_bf16 v[92:95], v[146:149], v[202:205], v[92:95]
	v_mfma_f32_16x16x32_bf16 v[88:91], v[154:157], v[202:205], v[88:91]
	v_mfma_f32_16x16x32_bf16 v[76:79], v[146:149], v[210:213], v[76:79]
	v_mfma_f32_16x16x32_bf16 v[72:75], v[154:157], v[210:213], v[72:75]
	v_mfma_f32_16x16x32_bf16 v[116:119], v[158:161], v[182:185], v[116:119]
	v_mfma_f32_16x16x32_bf16 v[112:115], v[174:177], v[182:185], v[112:115]
	v_mfma_f32_16x16x32_bf16 v[100:103], v[158:161], v[190:193], v[100:103]
	v_mfma_f32_16x16x32_bf16 v[96:99], v[174:177], v[190:193], v[96:99]
	v_mfma_f32_16x16x32_bf16 v[84:87], v[158:161], v[198:201], v[84:87]
	v_mfma_f32_16x16x32_bf16 v[80:83], v[174:177], v[198:201], v[80:83]
	v_mfma_f32_16x16x32_bf16 v[68:71], v[158:161], v[206:209], v[68:71]
	v_mfma_f32_16x16x32_bf16 v[64:67], v[174:177], v[206:209], v[64:67]
	v_mfma_f32_16x16x32_bf16 v[116:119], v[162:165], v[186:189], v[116:119]
	v_mfma_f32_16x16x32_bf16 v[112:115], v[178:181], v[186:189], v[112:115]
	v_mfma_f32_16x16x32_bf16 v[100:103], v[162:165], v[194:197], v[100:103]
	v_mfma_f32_16x16x32_bf16 v[96:99], v[178:181], v[194:197], v[96:99]
	v_mfma_f32_16x16x32_bf16 v[84:87], v[162:165], v[202:205], v[84:87]
	v_mfma_f32_16x16x32_bf16 v[80:83], v[178:181], v[202:205], v[80:83]
	v_mfma_f32_16x16x32_bf16 v[68:71], v[162:165], v[210:213], v[68:71]
	v_mfma_f32_16x16x32_bf16 v[64:67], v[178:181], v[210:213], v[64:67]
	s_barrier
	s_mov_b32 m0, s68
	v_lshl_add_u64 v[138:139], s[44:45], 0, v[168:169]
	ds_read_b128 v[182:185], v145 offset:16384
	ds_read_b128 v[186:189], v145 offset:17408
	ds_read_b128 v[190:193], v145 offset:18432
	ds_read_b128 v[194:197], v145 offset:19456
	ds_read_b128 v[198:201], v145 offset:20480
	ds_read_b128 v[202:205], v145 offset:21504
	ds_read_b128 v[206:209], v145 offset:22528
	ds_read_b128 v[210:213], v145 offset:23552
	global_load_lds_dwordx4 v[138:139], off
	v_lshl_add_u64 v[142:143], s[44:45], 0, v[132:133]
	s_mov_b32 m0, s65
	v_lshl_add_u64 v[166:167], s[46:47], 0, v[168:169]
	global_load_lds_dwordx4 v[142:143], off
	s_mov_b32 m0, s67
	v_lshl_add_u64 v[214:215], s[42:43], 0, v[130:131]
	global_load_lds_dwordx4 v[166:167], off
	v_lshl_add_u64 v[166:167], s[46:47], 0, v[132:133]
	s_mov_b32 m0, s66
	s_nop 0
	global_load_lds_dwordx4 v[166:167], off
	v_lshl_add_u64 v[166:167], s[42:43], 0, v[128:129]
	s_mov_b32 m0, s51
	s_nop 0
	global_load_lds_dwordx4 v[166:167], off
	s_mov_b32 m0, s52
	s_nop 0
	global_load_lds_dwordx4 v[214:215], off
	s_waitcnt vmcnt(8)
	s_waitcnt lgkmcnt(0)
	s_barrier
	s_waitcnt lgkmcnt(0)
	v_mfma_f32_16x16x32_bf16 v[60:63], v[134:137], v[182:185], v[60:63]
	v_mfma_f32_16x16x32_bf16 v[56:59], v[150:153], v[182:185], v[56:59]
	v_mfma_f32_16x16x32_bf16 v[48:51], v[134:137], v[190:193], v[48:51]
	v_mfma_f32_16x16x32_bf16 v[40:43], v[150:153], v[190:193], v[40:43]
	v_mfma_f32_16x16x32_bf16 v[32:35], v[134:137], v[198:201], v[32:35]
	v_mfma_f32_16x16x32_bf16 v[24:27], v[150:153], v[198:201], v[24:27]
	v_mfma_f32_16x16x32_bf16 v[16:19], v[134:137], v[206:209], v[16:19]
	v_mfma_f32_16x16x32_bf16 v[8:11], v[150:153], v[206:209], v[8:11]
	v_mfma_f32_16x16x32_bf16 v[60:63], v[146:149], v[186:189], v[60:63]
	v_mfma_f32_16x16x32_bf16 v[56:59], v[154:157], v[186:189], v[56:59]
	v_mfma_f32_16x16x32_bf16 v[48:51], v[146:149], v[194:197], v[48:51]
	v_mfma_f32_16x16x32_bf16 v[40:43], v[154:157], v[194:197], v[40:43]
	v_mfma_f32_16x16x32_bf16 v[32:35], v[146:149], v[202:205], v[32:35]
	v_mfma_f32_16x16x32_bf16 v[24:27], v[154:157], v[202:205], v[24:27]
	v_mfma_f32_16x16x32_bf16 v[16:19], v[146:149], v[210:213], v[16:19]
	v_mfma_f32_16x16x32_bf16 v[8:11], v[154:157], v[210:213], v[8:11]
	v_mfma_f32_16x16x32_bf16 v[52:55], v[158:161], v[182:185], v[52:55]
	v_mfma_f32_16x16x32_bf16 v[44:47], v[174:177], v[182:185], v[44:47]
	v_mfma_f32_16x16x32_bf16 v[36:39], v[158:161], v[190:193], v[36:39]
	v_mfma_f32_16x16x32_bf16 v[28:31], v[174:177], v[190:193], v[28:31]
	v_mfma_f32_16x16x32_bf16 v[20:23], v[158:161], v[198:201], v[20:23]
	v_mfma_f32_16x16x32_bf16 v[12:15], v[174:177], v[198:201], v[12:15]
	v_mfma_f32_16x16x32_bf16 v[4:7], v[158:161], v[206:209], v[4:7]
	v_mfma_f32_16x16x32_bf16 v[0:3], v[174:177], v[206:209], v[0:3]
	v_mfma_f32_16x16x32_bf16 v[52:55], v[162:165], v[186:189], v[52:55]
	v_mfma_f32_16x16x32_bf16 v[44:47], v[178:181], v[186:189], v[44:47]
	v_mfma_f32_16x16x32_bf16 v[36:39], v[162:165], v[194:197], v[36:39]
	v_mfma_f32_16x16x32_bf16 v[28:31], v[178:181], v[194:197], v[28:31]
	v_mfma_f32_16x16x32_bf16 v[20:23], v[162:165], v[202:205], v[20:23]
	v_mfma_f32_16x16x32_bf16 v[12:15], v[178:181], v[202:205], v[12:15]
	v_mfma_f32_16x16x32_bf16 v[4:7], v[162:165], v[210:213], v[4:7]
	v_mfma_f32_16x16x32_bf16 v[0:3], v[178:181], v[210:213], v[0:3]
	s_barrier
; #define PG8_STAGE(bufoff, gbase, voff) do { _Pragma("unroll") for (int _i = 0; _i < 2; ++_i) \
;         __builtin_amdgcn_global_load_lds((const unsigned*)((const char*)(gbase) + (voff)[_i]), (LAS unsigned*)(lds + (bufoff) + ldsw + _i * 8192), 16, 0, 0); } while (0)
; #define PG8_LDA(dst, b, h) do { _Pragma("unroll") for (int m = 0; m < 4; ++m) _Pragma("unroll") for (int k = 0; k < 2; ++k) dst[m][k] = *(const LAS bf16x8*)(lds + PG8_SA(b, h) + aoff + m * 2048 + k * 1024); } while (0)
; #define PG8_LDB(dst, b, h) do { _Pragma("unroll") for (int n = 0; n < 2; ++n) _Pragma("unroll") for (int k = 0; k < 2; ++k) dst[n][k] = *(const LAS bf16x8*)(lds + PG8_SB(b, h) + boff + n * 2048 + k * 1024); } while (0)
; #define PG8_MMA(ai, bj, At, Bt) do { __builtin_amdgcn_s_setprio(1); _Pragma("unroll") for (int k = 0; k < 2; ++k) _Pragma("unroll") for (int m = 0; m < 4; ++m) _Pragma("unroll") for (int n = 0; n < 2; ++n) \
;         acc[ai][bj][m][n] = __builtin_amdgcn_mfma_f32_16x16x32_bf16(Bt[n][k], At[m][k], acc[ai][bj][m][n], 0, 0, 0); __builtin_amdgcn_s_setprio(0); } while (0)
; #define PG8_WAIT_V(n) asm volatile("s_waitcnt vmcnt(" #n ")" ::: "memory")
; #define PG8_WAIT_L(n) asm volatile("s_waitcnt lgkmcnt(" #n ")" ::: "memory")
; #define PG8_BAR __builtin_amdgcn_s_barrier()
; #define PG8_SCHED __builtin_amdgcn_sched_barrier(0)
; template <class Epi, bool ALIGN_EPI>
; __device__ __forceinline__ void gemm_phase(LAS unsigned char* lds, const Gemm g, const StaticOrder& S, const Epi& E, const int tid) {
;     ...
;             PG8_LDB(B0, 1, 0); PG8_LDB(B1, 1, 1); PG8_SCHED; PG8_LDA(At, 1, 0); PG8_STAGE(PG8_SA(0, 1), a2 + hA, voffA);
;             PG8_WAIT_V(8); PG8_WAIT_L(0); PG8_BAR; PG8_MMA(0, 0, At, B0); PG8_MMA(0, 1, At, B1); PG8_BAR; PG8_SCHED;
;             PG8_LDA(At, 1, 1); PG8_STAGE(PG8_SB(1, 0), b3, voffB); PG8_STAGE(PG8_SB(1, 1), b3 + hB, voffB); PG8_STAGE(PG8_SA(1, 0), a3, voffA);
;             PG8_WAIT_V(8); PG8_WAIT_L(0); PG8_BAR; PG8_MMA(1, 0, At, B0); PG8_MMA(1, 1, At, B1); PG8_BAR; PG8_SCHED;
;         }
	v_add_u32_e32 v140, s64, v141
	ds_read_b128 v[134:137], v140
	ds_read_b128 v[146:149], v140 offset:1024
	ds_read_b128 v[150:153], v140 offset:2048
	ds_read_b128 v[154:157], v140 offset:3072
	v_add_u32_e32 v140, s63, v141
	ds_read_b128 v[158:161], v140
	ds_read_b128 v[162:165], v140 offset:1024
	ds_read_b128 v[174:177], v140 offset:2048
	ds_read_b128 v[178:181], v140 offset:3072
	s_mov_b32 m0, s53
	v_lshl_add_u64 v[216:217], s[40:41], 0, v[128:129]
	ds_read_b128 v[182:185], v145 offset:32768
	ds_read_b128 v[186:189], v145 offset:33792
	ds_read_b128 v[190:193], v145 offset:34816
	ds_read_b128 v[194:197], v145 offset:35840
	ds_read_b128 v[198:201], v145 offset:36864
	ds_read_b128 v[202:205], v145 offset:37888
	ds_read_b128 v[206:209], v145 offset:38912
	ds_read_b128 v[210:213], v145 offset:39936
	global_load_lds_dwordx4 v[216:217], off
	v_lshl_add_u64 v[216:217], s[40:41], 0, v[130:131]
	s_mov_b32 m0, s54
	s_nop 0
	global_load_lds_dwordx4 v[216:217], off
	s_waitcnt vmcnt(8)
	s_waitcnt lgkmcnt(0)
	s_barrier
	s_waitcnt lgkmcnt(0)
	v_mfma_f32_16x16x32_bf16 v[124:127], v[134:137], v[182:185], v[124:127]
	v_mfma_f32_16x16x32_bf16 v[120:123], v[150:153], v[182:185], v[120:123]
	v_mfma_f32_16x16x32_bf16 v[108:111], v[134:137], v[190:193], v[108:111]
	v_mfma_f32_16x16x32_bf16 v[104:107], v[150:153], v[190:193], v[104:107]
	v_mfma_f32_16x16x32_bf16 v[92:95], v[134:137], v[198:201], v[92:95]
	v_mfma_f32_16x16x32_bf16 v[88:91], v[150:153], v[198:201], v[88:91]
	v_mfma_f32_16x16x32_bf16 v[76:79], v[134:137], v[206:209], v[76:79]
	v_mfma_f32_16x16x32_bf16 v[72:75], v[150:153], v[206:209], v[72:75]
	v_mfma_f32_16x16x32_bf16 v[124:127], v[146:149], v[186:189], v[124:127]
	v_mfma_f32_16x16x32_bf16 v[120:123], v[154:157], v[186:189], v[120:123]
	v_mfma_f32_16x16x32_bf16 v[108:111], v[146:149], v[194:197], v[108:111]
	v_mfma_f32_16x16x32_bf16 v[104:107], v[154:157], v[194:197], v[104:107]
	v_mfma_f32_16x16x32_bf16 v[92:95], v[146:149], v[202:205], v[92:95]
	v_mfma_f32_16x16x32_bf16 v[88:91], v[154:157], v[202:205], v[88:91]
	v_mfma_f32_16x16x32_bf16 v[76:79], v[146:149], v[210:213], v[76:79]
	v_mfma_f32_16x16x32_bf16 v[72:75], v[154:157], v[210:213], v[72:75]
	v_mfma_f32_16x16x32_bf16 v[116:119], v[158:161], v[182:185], v[116:119]
	v_mfma_f32_16x16x32_bf16 v[112:115], v[174:177], v[182:185], v[112:115]
	v_mfma_f32_16x16x32_bf16 v[100:103], v[158:161], v[190:193], v[100:103]
	v_mfma_f32_16x16x32_bf16 v[96:99], v[174:177], v[190:193], v[96:99]
	v_mfma_f32_16x16x32_bf16 v[84:87], v[158:161], v[198:201], v[84:87]
	v_mfma_f32_16x16x32_bf16 v[80:83], v[174:177], v[198:201], v[80:83]
	v_mfma_f32_16x16x32_bf16 v[68:71], v[158:161], v[206:209], v[68:71]
	v_mfma_f32_16x16x32_bf16 v[64:67], v[174:177], v[206:209], v[64:67]
	v_mfma_f32_16x16x32_bf16 v[116:119], v[162:165], v[186:189], v[116:119]
	v_mfma_f32_16x16x32_bf16 v[112:115], v[178:181], v[186:189], v[112:115]
	v_mfma_f32_16x16x32_bf16 v[100:103], v[162:165], v[194:197], v[100:103]
	v_mfma_f32_16x16x32_bf16 v[96:99], v[178:181], v[194:197], v[96:99]
	v_mfma_f32_16x16x32_bf16 v[84:87], v[162:165], v[202:205], v[84:87]
	v_mfma_f32_16x16x32_bf16 v[80:83], v[178:181], v[202:205], v[80:83]
	v_mfma_f32_16x16x32_bf16 v[68:71], v[162:165], v[210:213], v[68:71]
	v_mfma_f32_16x16x32_bf16 v[64:67], v[178:181], v[210:213], v[64:67]
	s_barrier
	s_mov_b32 m0, s62
	v_lshl_add_u64 v[138:139], v[138:139], 0, s[92:93]
	ds_read_b128 v[182:185], v145 offset:49152
	ds_read_b128 v[186:189], v145 offset:50176
	ds_read_b128 v[190:193], v145 offset:51200
	ds_read_b128 v[194:197], v145 offset:52224
	ds_read_b128 v[198:201], v145 offset:53248
	ds_read_b128 v[202:205], v145 offset:54272
	ds_read_b128 v[206:209], v145 offset:55296
	ds_read_b128 v[210:213], v145 offset:56320
	global_load_lds_dwordx4 v[138:139], off
	v_lshl_add_u64 v[138:139], v[142:143], 0, s[92:93]
	s_mov_b32 m0, s61
	s_nop 0
	global_load_lds_dwordx4 v[138:139], off
	v_lshl_add_u64 v[138:139], s[38:39], 0, v[168:169]
	s_mov_b32 m0, s70
	s_nop 0
	global_load_lds_dwordx4 v[138:139], off
	v_lshl_add_u64 v[138:139], s[38:39], 0, v[132:133]
	s_mov_b32 m0, s69
	s_nop 0
	global_load_lds_dwordx4 v[138:139], off
	v_lshl_add_u64 v[138:139], v[166:167], 0, s[92:93]
	s_mov_b32 m0, s55
	s_nop 0
	global_load_lds_dwordx4 v[138:139], off
	v_lshl_add_u64 v[138:139], v[214:215], 0, s[92:93]
	s_mov_b32 m0, s56
	s_nop 0
	global_load_lds_dwordx4 v[138:139], off
	s_waitcnt vmcnt(8)
	s_waitcnt lgkmcnt(0)
	s_barrier
	s_waitcnt lgkmcnt(0)
	v_mfma_f32_16x16x32_bf16 v[60:63], v[134:137], v[182:185], v[60:63]
	v_mfma_f32_16x16x32_bf16 v[56:59], v[150:153], v[182:185], v[56:59]
	v_mfma_f32_16x16x32_bf16 v[48:51], v[134:137], v[190:193], v[48:51]
	v_mfma_f32_16x16x32_bf16 v[40:43], v[150:153], v[190:193], v[40:43]
	v_mfma_f32_16x16x32_bf16 v[32:35], v[134:137], v[198:201], v[32:35]
	v_mfma_f32_16x16x32_bf16 v[24:27], v[150:153], v[198:201], v[24:27]
	v_mfma_f32_16x16x32_bf16 v[16:19], v[134:137], v[206:209], v[16:19]
	v_mfma_f32_16x16x32_bf16 v[8:11], v[150:153], v[206:209], v[8:11]
	v_mfma_f32_16x16x32_bf16 v[60:63], v[146:149], v[186:189], v[60:63]
	v_mfma_f32_16x16x32_bf16 v[56:59], v[154:157], v[186:189], v[56:59]
	v_mfma_f32_16x16x32_bf16 v[48:51], v[146:149], v[194:197], v[48:51]
	v_mfma_f32_16x16x32_bf16 v[40:43], v[154:157], v[194:197], v[40:43]
	v_mfma_f32_16x16x32_bf16 v[32:35], v[146:149], v[202:205], v[32:35]
	v_mfma_f32_16x16x32_bf16 v[24:27], v[154:157], v[202:205], v[24:27]
	v_mfma_f32_16x16x32_bf16 v[16:19], v[146:149], v[210:213], v[16:19]
	v_mfma_f32_16x16x32_bf16 v[8:11], v[154:157], v[210:213], v[8:11]
	v_mfma_f32_16x16x32_bf16 v[52:55], v[158:161], v[182:185], v[52:55]
	v_mfma_f32_16x16x32_bf16 v[44:47], v[174:177], v[182:185], v[44:47]
	v_mfma_f32_16x16x32_bf16 v[36:39], v[158:161], v[190:193], v[36:39]
	v_mfma_f32_16x16x32_bf16 v[28:31], v[174:177], v[190:193], v[28:31]
	v_mfma_f32_16x16x32_bf16 v[20:23], v[158:161], v[198:201], v[20:23]
	v_mfma_f32_16x16x32_bf16 v[12:15], v[174:177], v[198:201], v[12:15]
	v_mfma_f32_16x16x32_bf16 v[4:7], v[158:161], v[206:209], v[4:7]
	v_mfma_f32_16x16x32_bf16 v[0:3], v[174:177], v[206:209], v[0:3]
	v_mfma_f32_16x16x32_bf16 v[52:55], v[162:165], v[186:189], v[52:55]
	v_mfma_f32_16x16x32_bf16 v[44:47], v[178:181], v[186:189], v[44:47]
	v_mfma_f32_16x16x32_bf16 v[36:39], v[162:165], v[194:197], v[36:39]
	v_mfma_f32_16x16x32_bf16 v[28:31], v[178:181], v[194:197], v[28:31]
	v_mfma_f32_16x16x32_bf16 v[20:23], v[162:165], v[202:205], v[20:23]
	v_mfma_f32_16x16x32_bf16 v[12:15], v[178:181], v[202:205], v[12:15]
	v_mfma_f32_16x16x32_bf16 v[4:7], v[162:165], v[210:213], v[4:7]
	v_mfma_f32_16x16x32_bf16 v[0:3], v[178:181], v[210:213], v[0:3]
	s_barrier
	s_movk_i32 s40, 0x100
	s_andn2_b64 vcc, exec, s[36:37]
	s_mov_b64 s[38:39], -1
	s_mov_b64 s[36:37], 0
	s_cbranch_vccz .LBB0_379
	v_readlane_b32 s60, v255, 51
	s_and_b64 vcc, exec, s[12:13]
	v_readlane_b32 s61, v255, 52
	s_cbranch_vccz .LBB0_382
	s_barrier
